# GEMM loops: phase-1 next-tile pointer select + first m0 moved into the previous iteration's last MFMA block (6 of 7 loops)
# baseline (speedup 1.0000x reference)
.LBB0_86:
	v_mov_b64_e32 v[0:1], 0x800
	s_ashr_i32 s7, s6, 31
	v_cmp_lt_i64_e32 vcc, s[8:9], v[0:1]
	s_lshl_b64 s[8:9], s[6:7], 20
	s_add_u32 s8, s23, s8
	s_addc_u32 s9, s24, s9
	s_and_b64 s[10:11], vcc, exec
	s_cselect_b32 s7, s9, s15
	s_cselect_b32 s38, s8, s14
	s_ashr_i32 s5, s4, 31
	s_lshl_b64 s[10:11], s[4:5], 20
	s_add_u32 s10, s25, s10
	s_addc_u32 s11, s26, s11
	s_and_b64 s[18:19], vcc, exec
	s_cselect_b32 s5, s11, s17
	s_cselect_b32 s39, s10, s16
	s_add_u32 s14, s14, 0x80080
	s_addc_u32 s15, s15, 0
	s_add_u32 s40, s16, 0x100
	s_addc_u32 s41, s17, 0
	s_mov_b32 s42, -2
	s_mov_b64 s[48:49], 0x80
	v_add_u32_e32 v220, 0x10000, v183
	s_add_u32 s16, s14, 0xfff80080
	s_addc_u32 s17, s15, -1
	s_add_i32 s43, 0, 0x10000
	ds_read_b128 v[128:131], v220 offset:0
	ds_read_b128 v[132:135], v220 offset:1024
	ds_read_b128 v[136:139], v220 offset:2048
	ds_read_b128 v[140:143], v220 offset:3072
	s_cmp_eq_u32 s42, 28
	s_cselect_b32 s19, s7, s17
	s_cselect_b32 s18, s38, s16
	s_cselect_b32 s17, s5, s41
	s_cselect_b32 s16, s39, s40
	s_add_i32 m0, s28, 0xc000
	ds_read_b128 v[144:147], v185
	ds_read_b128 v[148:151], v185 offset:1024
	ds_read_b128 v[152:155], v185 offset:2048
	ds_read_b128 v[156:159], v185 offset:3072
	ds_read_b128 v[170:173], v185 offset:4096
	ds_read_b128 v[174:177], v185 offset:5120
	ds_read_b128 v[178:181], v185 offset:6144
	ds_read_b128 v[186:189], v185 offset:7168
	global_load_lds_dwordx4 v166, s[14:15]
	s_add_i32 m0, s28, 0xe000
	s_nop 0
	global_load_lds_dwordx4 v168, s[14:15]
	s_waitcnt lgkmcnt(8)
	s_barrier
	s_waitcnt lgkmcnt(0)
	v_mfma_f32_16x16x32_bf16 v[124:127], v[128:131], v[144:147], 0
	v_mfma_f32_16x16x32_bf16 v[120:123], v[136:139], v[144:147], 0
	v_mfma_f32_16x16x32_bf16 v[108:111], v[128:131], v[152:155], 0
	v_mfma_f32_16x16x32_bf16 v[104:107], v[136:139], v[152:155], 0
	s_add_i32 s46, 0, 0x14000
	s_add_i32 s43, s43, s27
	v_mfma_f32_16x16x32_bf16 v[92:95], v[128:131], v[170:173], 0
	s_mov_b32 m0, s43
	v_mfma_f32_16x16x32_bf16 v[88:91], v[136:139], v[170:173], 0
	v_mfma_f32_16x16x32_bf16 v[76:79], v[128:131], v[178:181], 0
	v_mfma_f32_16x16x32_bf16 v[72:75], v[136:139], v[178:181], 0
	v_mfma_f32_16x16x32_bf16 v[124:127], v[132:135], v[148:151], v[124:127]
	v_mfma_f32_16x16x32_bf16 v[120:123], v[140:143], v[148:151], v[120:123]
	v_mfma_f32_16x16x32_bf16 v[108:111], v[132:135], v[156:159], v[108:111]
	v_mfma_f32_16x16x32_bf16 v[104:107], v[140:143], v[156:159], v[104:107]
	v_mfma_f32_16x16x32_bf16 v[92:95], v[132:135], v[174:177], v[92:95]
	v_mfma_f32_16x16x32_bf16 v[88:91], v[140:143], v[174:177], v[88:91]
	v_mfma_f32_16x16x32_bf16 v[76:79], v[132:135], v[186:189], v[76:79]
	v_mfma_f32_16x16x32_bf16 v[72:75], v[140:143], v[186:189], v[72:75]
	s_barrier
	ds_read_b128 v[196:199], v220 offset:16384
	ds_read_b128 v[204:207], v220 offset:17408
	ds_read_b128 v[208:211], v220 offset:18432
	ds_read_b128 v[214:217], v220 offset:19456
	global_load_lds_dwordx4 v192, s[16:17]
	s_add_i32 m0, s43, 0x2000
	s_nop 0
	global_load_lds_dwordx4 v164, s[16:17]
	s_barrier
	s_waitcnt lgkmcnt(0)
	v_mfma_f32_16x16x32_bf16 v[116:119], v[196:199], v[144:147], 0
	v_mfma_f32_16x16x32_bf16 v[112:115], v[208:211], v[144:147], 0
	v_mfma_f32_16x16x32_bf16 v[100:103], v[196:199], v[152:155], 0
	v_mfma_f32_16x16x32_bf16 v[96:99], v[208:211], v[152:155], 0
	s_mov_b32 m0, s28
	v_mfma_f32_16x16x32_bf16 v[84:87], v[196:199], v[170:173], 0
	s_add_u32 s48, s18, 0x80
	s_addc_u32 s49, s19, 0
	v_mfma_f32_16x16x32_bf16 v[80:83], v[208:211], v[170:173], 0
	v_mfma_f32_16x16x32_bf16 v[68:71], v[196:199], v[178:181], 0
	v_mfma_f32_16x16x32_bf16 v[64:67], v[208:211], v[178:181], 0
	v_mfma_f32_16x16x32_bf16 v[116:119], v[204:207], v[148:151], v[116:119]
	v_mfma_f32_16x16x32_bf16 v[112:115], v[214:217], v[148:151], v[112:115]
	v_mfma_f32_16x16x32_bf16 v[100:103], v[204:207], v[156:159], v[100:103]
	v_mfma_f32_16x16x32_bf16 v[96:99], v[214:217], v[156:159], v[96:99]
	v_mfma_f32_16x16x32_bf16 v[84:87], v[204:207], v[174:177], v[84:87]
	v_mfma_f32_16x16x32_bf16 v[80:83], v[214:217], v[174:177], v[80:83]
	v_mfma_f32_16x16x32_bf16 v[68:71], v[204:207], v[186:189], v[68:71]
	v_mfma_f32_16x16x32_bf16 v[64:67], v[214:217], v[186:189], v[64:67]
	s_barrier
	ds_read_b128 v[144:147], v185 offset:16384
	ds_read_b128 v[148:151], v185 offset:17408
	ds_read_b128 v[152:155], v185 offset:18432
	ds_read_b128 v[156:159], v185 offset:19456
	ds_read_b128 v[170:173], v185 offset:20480
	ds_read_b128 v[174:177], v185 offset:21504
	ds_read_b128 v[178:181], v185 offset:22528
	ds_read_b128 v[186:189], v185 offset:23552
	global_load_lds_dwordx4 v160, s[18:19]
	s_mov_b32 m0, s29
	s_nop 0
	global_load_lds_dwordx4 v162, s[18:19]
	s_barrier
	s_waitcnt lgkmcnt(0)
	v_mfma_f32_16x16x32_bf16 v[60:63], v[128:131], v[144:147], 0
	v_mfma_f32_16x16x32_bf16 v[56:59], v[136:139], v[144:147], 0
	v_mfma_f32_16x16x32_bf16 v[44:47], v[128:131], v[152:155], 0
	v_mfma_f32_16x16x32_bf16 v[40:43], v[136:139], v[152:155], 0
	s_add_u32 s44, s16, 0x80000
	s_addc_u32 s45, s17, 0
	v_mfma_f32_16x16x32_bf16 v[28:31], v[128:131], v[170:173], 0
	s_add_i32 s43, s46, s27
	s_mov_b32 m0, s43
	v_mfma_f32_16x16x32_bf16 v[24:27], v[136:139], v[170:173], 0
	v_mfma_f32_16x16x32_bf16 v[12:15], v[128:131], v[178:181], 0
	v_mfma_f32_16x16x32_bf16 v[8:11], v[136:139], v[178:181], 0
	v_mfma_f32_16x16x32_bf16 v[60:63], v[132:135], v[148:151], v[60:63]
	v_mfma_f32_16x16x32_bf16 v[56:59], v[140:143], v[148:151], v[56:59]
	v_mfma_f32_16x16x32_bf16 v[44:47], v[132:135], v[156:159], v[44:47]
	v_mfma_f32_16x16x32_bf16 v[40:43], v[140:143], v[156:159], v[40:43]
	v_mfma_f32_16x16x32_bf16 v[28:31], v[132:135], v[174:177], v[28:31]
	v_mfma_f32_16x16x32_bf16 v[24:27], v[140:143], v[174:177], v[24:27]
	v_mfma_f32_16x16x32_bf16 v[12:15], v[132:135], v[186:189], v[12:15]
	v_mfma_f32_16x16x32_bf16 v[8:11], v[140:143], v[186:189], v[8:11]
	s_barrier
	global_load_lds_dwordx4 v192, s[44:45]
	s_add_i32 m0, s43, 0x2000
	s_nop 0
	global_load_lds_dwordx4 v164, s[44:45]
	s_waitcnt vmcnt(6)
	s_barrier
	v_mfma_f32_16x16x32_bf16 v[52:55], v[196:199], v[144:147], 0
	v_mfma_f32_16x16x32_bf16 v[48:51], v[208:211], v[144:147], 0
	v_mfma_f32_16x16x32_bf16 v[36:39], v[196:199], v[152:155], 0
	v_mfma_f32_16x16x32_bf16 v[32:35], v[208:211], v[152:155], 0
	s_add_i32 s43, 0, 0x18000
	v_mfma_f32_16x16x32_bf16 v[20:23], v[196:199], v[170:173], 0
	s_add_u32 s18, s18, 0x80000
	s_addc_u32 s19, s19, 0
	v_mfma_f32_16x16x32_bf16 v[16:19], v[208:211], v[170:173], 0
	s_mov_b32 m0, s30
	v_mfma_f32_16x16x32_bf16 v[4:7], v[196:199], v[178:181], 0
	v_mfma_f32_16x16x32_bf16 v[0:3], v[208:211], v[178:181], 0
	v_mfma_f32_16x16x32_bf16 v[52:55], v[204:207], v[148:151], v[52:55]
	v_mfma_f32_16x16x32_bf16 v[48:51], v[214:217], v[148:151], v[48:51]
	v_mfma_f32_16x16x32_bf16 v[36:39], v[204:207], v[156:159], v[36:39]
	v_mfma_f32_16x16x32_bf16 v[32:35], v[214:217], v[156:159], v[32:35]
	v_mfma_f32_16x16x32_bf16 v[20:23], v[204:207], v[174:177], v[20:23]
	v_mfma_f32_16x16x32_bf16 v[16:19], v[214:217], v[174:177], v[16:19]
	v_mfma_f32_16x16x32_bf16 v[4:7], v[204:207], v[186:189], v[4:7]
	v_mfma_f32_16x16x32_bf16 v[0:3], v[214:217], v[186:189], v[0:3]
	s_barrier
	ds_read_b128 v[128:131], v220 offset:32768
	ds_read_b128 v[132:135], v220 offset:33792
	ds_read_b128 v[136:139], v220 offset:34816
	ds_read_b128 v[140:143], v220 offset:35840
	ds_read_b128 v[144:147], v185 offset:32768
	ds_read_b128 v[148:151], v185 offset:33792
	ds_read_b128 v[152:155], v185 offset:34816
	ds_read_b128 v[156:159], v185 offset:35840
	ds_read_b128 v[170:173], v185 offset:36864
	ds_read_b128 v[174:177], v185 offset:37888
	ds_read_b128 v[178:181], v185 offset:38912
	ds_read_b128 v[186:189], v185 offset:39936
	global_load_lds_dwordx4 v160, s[18:19]
	s_mov_b32 m0, s31
	s_nop 0
	global_load_lds_dwordx4 v162, s[18:19]
	s_waitcnt lgkmcnt(8)
	s_barrier
	s_waitcnt lgkmcnt(0)
	v_mfma_f32_16x16x32_bf16 v[124:127], v[128:131], v[144:147], v[124:127]
	v_mfma_f32_16x16x32_bf16 v[120:123], v[136:139], v[144:147], v[120:123]
	v_mfma_f32_16x16x32_bf16 v[108:111], v[128:131], v[152:155], v[108:111]
	v_mfma_f32_16x16x32_bf16 v[104:107], v[136:139], v[152:155], v[104:107]
	s_add_i32 s18, 0, 0x1c000
	s_add_i32 s19, s43, s27
	v_mfma_f32_16x16x32_bf16 v[92:95], v[128:131], v[170:173], v[92:95]
	s_add_i32 m0, s19, 0xffffff80
	v_mfma_f32_16x16x32_bf16 v[88:91], v[136:139], v[170:173], v[88:91]
	v_mfma_f32_16x16x32_bf16 v[76:79], v[128:131], v[178:181], v[76:79]
	v_mfma_f32_16x16x32_bf16 v[72:75], v[136:139], v[178:181], v[72:75]
	v_mfma_f32_16x16x32_bf16 v[124:127], v[132:135], v[148:151], v[124:127]
	v_mfma_f32_16x16x32_bf16 v[120:123], v[140:143], v[148:151], v[120:123]
	v_mfma_f32_16x16x32_bf16 v[108:111], v[132:135], v[156:159], v[108:111]
	v_mfma_f32_16x16x32_bf16 v[104:107], v[140:143], v[156:159], v[104:107]
	v_mfma_f32_16x16x32_bf16 v[92:95], v[132:135], v[174:177], v[92:95]
	v_mfma_f32_16x16x32_bf16 v[88:91], v[140:143], v[174:177], v[88:91]
	v_mfma_f32_16x16x32_bf16 v[76:79], v[132:135], v[186:189], v[76:79]
	v_mfma_f32_16x16x32_bf16 v[72:75], v[140:143], v[186:189], v[72:75]
	s_barrier
	ds_read_b128 v[196:199], v220 offset:49152
	ds_read_b128 v[204:207], v220 offset:50176
	ds_read_b128 v[208:211], v220 offset:51200
	ds_read_b128 v[214:217], v220 offset:52224
	global_load_lds_dwordx4 v192, s[16:17] offset:128
	s_add_i32 m0, s19, 0x1f80
	s_nop 0
	global_load_lds_dwordx4 v164, s[16:17] offset:128
	s_barrier
	s_waitcnt lgkmcnt(0)
	v_mfma_f32_16x16x32_bf16 v[116:119], v[196:199], v[144:147], v[116:119]
	v_mfma_f32_16x16x32_bf16 v[112:115], v[208:211], v[144:147], v[112:115]
	v_mfma_f32_16x16x32_bf16 v[100:103], v[196:199], v[152:155], v[100:103]
	v_mfma_f32_16x16x32_bf16 v[96:99], v[208:211], v[152:155], v[96:99]
	s_mov_b32 m0, s35
	v_mfma_f32_16x16x32_bf16 v[84:87], v[196:199], v[170:173], v[84:87]
	v_mfma_f32_16x16x32_bf16 v[80:83], v[208:211], v[170:173], v[80:83]
	v_mfma_f32_16x16x32_bf16 v[68:71], v[196:199], v[178:181], v[68:71]
	v_mfma_f32_16x16x32_bf16 v[64:67], v[208:211], v[178:181], v[64:67]
	v_mfma_f32_16x16x32_bf16 v[116:119], v[204:207], v[148:151], v[116:119]
	v_mfma_f32_16x16x32_bf16 v[112:115], v[214:217], v[148:151], v[112:115]
	v_mfma_f32_16x16x32_bf16 v[100:103], v[204:207], v[156:159], v[100:103]
	v_mfma_f32_16x16x32_bf16 v[96:99], v[214:217], v[156:159], v[96:99]
	v_mfma_f32_16x16x32_bf16 v[84:87], v[204:207], v[174:177], v[84:87]
	v_mfma_f32_16x16x32_bf16 v[80:83], v[214:217], v[174:177], v[80:83]
	v_mfma_f32_16x16x32_bf16 v[68:71], v[204:207], v[186:189], v[68:71]
	v_mfma_f32_16x16x32_bf16 v[64:67], v[214:217], v[186:189], v[64:67]
	s_barrier
	ds_read_b128 v[144:147], v185 offset:49152
	ds_read_b128 v[148:151], v185 offset:50176
	ds_read_b128 v[152:155], v185 offset:51200
	ds_read_b128 v[156:159], v185 offset:52224
	ds_read_b128 v[170:173], v185 offset:53248
	ds_read_b128 v[174:177], v185 offset:54272
	ds_read_b128 v[178:181], v185 offset:55296
	ds_read_b128 v[186:189], v185 offset:56320
	global_load_lds_dwordx4 v160, s[48:49]
	s_mov_b32 m0, s36
	s_nop 0
	global_load_lds_dwordx4 v162, s[48:49]
	s_barrier
	s_waitcnt lgkmcnt(0)
	v_mfma_f32_16x16x32_bf16 v[60:63], v[128:131], v[144:147], v[60:63]
	v_mfma_f32_16x16x32_bf16 v[56:59], v[136:139], v[144:147], v[56:59]
	v_mfma_f32_16x16x32_bf16 v[44:47], v[128:131], v[152:155], v[44:47]
	v_mfma_f32_16x16x32_bf16 v[40:43], v[136:139], v[152:155], v[40:43]
	s_add_u32 s16, s16, 0x80080
	s_addc_u32 s17, s17, 0
	v_mfma_f32_16x16x32_bf16 v[28:31], v[128:131], v[170:173], v[28:31]
	s_add_i32 s18, s18, s27
	s_mov_b32 m0, s18
	v_mfma_f32_16x16x32_bf16 v[24:27], v[136:139], v[170:173], v[24:27]
	v_mfma_f32_16x16x32_bf16 v[12:15], v[128:131], v[178:181], v[12:15]
	v_mfma_f32_16x16x32_bf16 v[8:11], v[136:139], v[178:181], v[8:11]
	v_mfma_f32_16x16x32_bf16 v[60:63], v[132:135], v[148:151], v[60:63]
	v_mfma_f32_16x16x32_bf16 v[56:59], v[140:143], v[148:151], v[56:59]
	v_mfma_f32_16x16x32_bf16 v[44:47], v[132:135], v[156:159], v[44:47]
	v_mfma_f32_16x16x32_bf16 v[40:43], v[140:143], v[156:159], v[40:43]
	v_mfma_f32_16x16x32_bf16 v[28:31], v[132:135], v[174:177], v[28:31]
	v_mfma_f32_16x16x32_bf16 v[24:27], v[140:143], v[174:177], v[24:27]
	v_mfma_f32_16x16x32_bf16 v[12:15], v[132:135], v[186:189], v[12:15]
	v_mfma_f32_16x16x32_bf16 v[8:11], v[140:143], v[186:189], v[8:11]
	s_barrier
	global_load_lds_dwordx4 v192, s[16:17]
	s_add_i32 m0, s18, 0x2000
	s_nop 0
	global_load_lds_dwordx4 v164, s[16:17]
	s_waitcnt vmcnt(6)
	s_barrier
	v_mfma_f32_16x16x32_bf16 v[52:55], v[196:199], v[144:147], v[52:55]
	v_mfma_f32_16x16x32_bf16 v[48:51], v[208:211], v[144:147], v[48:51]
	v_mfma_f32_16x16x32_bf16 v[36:39], v[196:199], v[152:155], v[36:39]
	v_mfma_f32_16x16x32_bf16 v[32:35], v[208:211], v[152:155], v[32:35]
	s_add_i32 s42, s42, 2
	v_mfma_f32_16x16x32_bf16 v[20:23], v[196:199], v[170:173], v[20:23]
	s_add_u32 s14, s14, 0x100
	s_addc_u32 s15, s15, 0
	v_mfma_f32_16x16x32_bf16 v[16:19], v[208:211], v[170:173], v[16:19]
	s_add_u32 s40, s40, 0x100
	s_addc_u32 s41, s41, 0
	v_mfma_f32_16x16x32_bf16 v[4:7], v[196:199], v[178:181], v[4:7]
	s_add_u32 s16, s14, 0xfff80080
	s_addc_u32 s17, s15, -1
	v_mfma_f32_16x16x32_bf16 v[0:3], v[208:211], v[178:181], v[0:3]
	s_add_i32 s43, 0, 0x10000
	s_cmp_eq_u32 s42, 28
	v_mfma_f32_16x16x32_bf16 v[52:55], v[204:207], v[148:151], v[52:55]
	s_cselect_b32 s19, s7, s17
	s_cselect_b32 s18, s38, s16
	v_mfma_f32_16x16x32_bf16 v[48:51], v[214:217], v[148:151], v[48:51]
	s_cselect_b32 s17, s5, s41
	s_cselect_b32 s16, s39, s40
	v_mfma_f32_16x16x32_bf16 v[36:39], v[204:207], v[156:159], v[36:39]
	s_add_i32 m0, s28, 0xc000
	v_mfma_f32_16x16x32_bf16 v[32:35], v[214:217], v[156:159], v[32:35]
	v_mfma_f32_16x16x32_bf16 v[20:23], v[204:207], v[174:177], v[20:23]
	v_mfma_f32_16x16x32_bf16 v[16:19], v[214:217], v[174:177], v[16:19]
	v_mfma_f32_16x16x32_bf16 v[4:7], v[204:207], v[186:189], v[4:7]
	v_mfma_f32_16x16x32_bf16 v[0:3], v[214:217], v[186:189], v[0:3]
	s_cmp_gt_u32 s42, 29
	s_barrier
.LBB0_87:
	ds_read_b128 v[128:131], v220 offset:0
	ds_read_b128 v[132:135], v220 offset:1024
	ds_read_b128 v[136:139], v220 offset:2048
	ds_read_b128 v[140:143], v220 offset:3072
	ds_read_b128 v[144:147], v185
	ds_read_b128 v[148:151], v185 offset:1024
	ds_read_b128 v[152:155], v185 offset:2048
	ds_read_b128 v[156:159], v185 offset:3072
	ds_read_b128 v[170:173], v185 offset:4096
	ds_read_b128 v[174:177], v185 offset:5120
	ds_read_b128 v[178:181], v185 offset:6144
	ds_read_b128 v[186:189], v185 offset:7168
	global_load_lds_dwordx4 v166, s[14:15]
	s_add_i32 m0, s28, 0xe000
	s_nop 0
	global_load_lds_dwordx4 v168, s[14:15]
	s_waitcnt lgkmcnt(8)
	s_barrier
	s_waitcnt lgkmcnt(0)
	v_mfma_f32_16x16x32_bf16 v[124:127], v[128:131], v[144:147], v[124:127]
	v_mfma_f32_16x16x32_bf16 v[120:123], v[136:139], v[144:147], v[120:123]
	v_mfma_f32_16x16x32_bf16 v[108:111], v[128:131], v[152:155], v[108:111]
	v_mfma_f32_16x16x32_bf16 v[104:107], v[136:139], v[152:155], v[104:107]
	s_add_i32 s46, 0, 0x14000
	s_add_i32 s43, s43, s27
	v_mfma_f32_16x16x32_bf16 v[92:95], v[128:131], v[170:173], v[92:95]
	s_mov_b32 m0, s43
	v_mfma_f32_16x16x32_bf16 v[88:91], v[136:139], v[170:173], v[88:91]
	v_mfma_f32_16x16x32_bf16 v[76:79], v[128:131], v[178:181], v[76:79]
	v_mfma_f32_16x16x32_bf16 v[72:75], v[136:139], v[178:181], v[72:75]
	v_mfma_f32_16x16x32_bf16 v[124:127], v[132:135], v[148:151], v[124:127]
	v_mfma_f32_16x16x32_bf16 v[120:123], v[140:143], v[148:151], v[120:123]
	v_mfma_f32_16x16x32_bf16 v[108:111], v[132:135], v[156:159], v[108:111]
	v_mfma_f32_16x16x32_bf16 v[104:107], v[140:143], v[156:159], v[104:107]
	v_mfma_f32_16x16x32_bf16 v[92:95], v[132:135], v[174:177], v[92:95]
	v_mfma_f32_16x16x32_bf16 v[88:91], v[140:143], v[174:177], v[88:91]
	v_mfma_f32_16x16x32_bf16 v[76:79], v[132:135], v[186:189], v[76:79]
	v_mfma_f32_16x16x32_bf16 v[72:75], v[140:143], v[186:189], v[72:75]
	s_barrier
	ds_read_b128 v[196:199], v220 offset:16384
	ds_read_b128 v[204:207], v220 offset:17408
	ds_read_b128 v[208:211], v220 offset:18432
	ds_read_b128 v[214:217], v220 offset:19456
	global_load_lds_dwordx4 v192, s[16:17]
	s_add_i32 m0, s43, 0x2000
	s_nop 0
	global_load_lds_dwordx4 v164, s[16:17]
	s_barrier
	s_waitcnt lgkmcnt(0)
	v_mfma_f32_16x16x32_bf16 v[116:119], v[196:199], v[144:147], v[116:119]
	v_mfma_f32_16x16x32_bf16 v[112:115], v[208:211], v[144:147], v[112:115]
	v_mfma_f32_16x16x32_bf16 v[100:103], v[196:199], v[152:155], v[100:103]
	v_mfma_f32_16x16x32_bf16 v[96:99], v[208:211], v[152:155], v[96:99]
	s_mov_b32 m0, s28
	v_mfma_f32_16x16x32_bf16 v[84:87], v[196:199], v[170:173], v[84:87]
	s_add_u32 s48, s18, 0x80
	s_addc_u32 s49, s19, 0
	v_mfma_f32_16x16x32_bf16 v[80:83], v[208:211], v[170:173], v[80:83]
	v_mfma_f32_16x16x32_bf16 v[68:71], v[196:199], v[178:181], v[68:71]
	v_mfma_f32_16x16x32_bf16 v[64:67], v[208:211], v[178:181], v[64:67]
	v_mfma_f32_16x16x32_bf16 v[116:119], v[204:207], v[148:151], v[116:119]
	v_mfma_f32_16x16x32_bf16 v[112:115], v[214:217], v[148:151], v[112:115]
	v_mfma_f32_16x16x32_bf16 v[100:103], v[204:207], v[156:159], v[100:103]
	v_mfma_f32_16x16x32_bf16 v[96:99], v[214:217], v[156:159], v[96:99]
	v_mfma_f32_16x16x32_bf16 v[84:87], v[204:207], v[174:177], v[84:87]
	v_mfma_f32_16x16x32_bf16 v[80:83], v[214:217], v[174:177], v[80:83]
	v_mfma_f32_16x16x32_bf16 v[68:71], v[204:207], v[186:189], v[68:71]
	v_mfma_f32_16x16x32_bf16 v[64:67], v[214:217], v[186:189], v[64:67]
	s_barrier
	ds_read_b128 v[144:147], v185 offset:16384
	ds_read_b128 v[148:151], v185 offset:17408
	ds_read_b128 v[152:155], v185 offset:18432
	ds_read_b128 v[156:159], v185 offset:19456
	ds_read_b128 v[170:173], v185 offset:20480
	ds_read_b128 v[174:177], v185 offset:21504
	ds_read_b128 v[178:181], v185 offset:22528
	ds_read_b128 v[186:189], v185 offset:23552
	global_load_lds_dwordx4 v160, s[18:19]
	s_mov_b32 m0, s29
	s_nop 0
	global_load_lds_dwordx4 v162, s[18:19]
	s_barrier
	s_waitcnt lgkmcnt(0)
	v_mfma_f32_16x16x32_bf16 v[60:63], v[128:131], v[144:147], v[60:63]
	v_mfma_f32_16x16x32_bf16 v[56:59], v[136:139], v[144:147], v[56:59]
	v_mfma_f32_16x16x32_bf16 v[44:47], v[128:131], v[152:155], v[44:47]
	v_mfma_f32_16x16x32_bf16 v[40:43], v[136:139], v[152:155], v[40:43]
	s_add_u32 s44, s16, 0x80000
	s_addc_u32 s45, s17, 0
	v_mfma_f32_16x16x32_bf16 v[28:31], v[128:131], v[170:173], v[28:31]
	s_add_i32 s43, s46, s27
	s_mov_b32 m0, s43
	v_mfma_f32_16x16x32_bf16 v[24:27], v[136:139], v[170:173], v[24:27]
	v_mfma_f32_16x16x32_bf16 v[12:15], v[128:131], v[178:181], v[12:15]
	v_mfma_f32_16x16x32_bf16 v[8:11], v[136:139], v[178:181], v[8:11]
	v_mfma_f32_16x16x32_bf16 v[60:63], v[132:135], v[148:151], v[60:63]
	v_mfma_f32_16x16x32_bf16 v[56:59], v[140:143], v[148:151], v[56:59]
	v_mfma_f32_16x16x32_bf16 v[44:47], v[132:135], v[156:159], v[44:47]
	v_mfma_f32_16x16x32_bf16 v[40:43], v[140:143], v[156:159], v[40:43]
	v_mfma_f32_16x16x32_bf16 v[28:31], v[132:135], v[174:177], v[28:31]
	v_mfma_f32_16x16x32_bf16 v[24:27], v[140:143], v[174:177], v[24:27]
	v_mfma_f32_16x16x32_bf16 v[12:15], v[132:135], v[186:189], v[12:15]
	v_mfma_f32_16x16x32_bf16 v[8:11], v[140:143], v[186:189], v[8:11]
	s_barrier
	global_load_lds_dwordx4 v192, s[44:45]
	s_add_i32 m0, s43, 0x2000
	s_nop 0
	global_load_lds_dwordx4 v164, s[44:45]
	s_waitcnt vmcnt(6)
	s_barrier
	v_mfma_f32_16x16x32_bf16 v[52:55], v[196:199], v[144:147], v[52:55]
	v_mfma_f32_16x16x32_bf16 v[48:51], v[208:211], v[144:147], v[48:51]
	v_mfma_f32_16x16x32_bf16 v[36:39], v[196:199], v[152:155], v[36:39]
	v_mfma_f32_16x16x32_bf16 v[32:35], v[208:211], v[152:155], v[32:35]
	s_add_i32 s43, 0, 0x18000
	v_mfma_f32_16x16x32_bf16 v[20:23], v[196:199], v[170:173], v[20:23]
	s_add_u32 s18, s18, 0x80000
	s_addc_u32 s19, s19, 0
	v_mfma_f32_16x16x32_bf16 v[16:19], v[208:211], v[170:173], v[16:19]
	s_mov_b32 m0, s30
	v_mfma_f32_16x16x32_bf16 v[4:7], v[196:199], v[178:181], v[4:7]
	v_mfma_f32_16x16x32_bf16 v[0:3], v[208:211], v[178:181], v[0:3]
	v_mfma_f32_16x16x32_bf16 v[52:55], v[204:207], v[148:151], v[52:55]
	v_mfma_f32_16x16x32_bf16 v[48:51], v[214:217], v[148:151], v[48:51]
	v_mfma_f32_16x16x32_bf16 v[36:39], v[204:207], v[156:159], v[36:39]
	v_mfma_f32_16x16x32_bf16 v[32:35], v[214:217], v[156:159], v[32:35]
	v_mfma_f32_16x16x32_bf16 v[20:23], v[204:207], v[174:177], v[20:23]
	v_mfma_f32_16x16x32_bf16 v[16:19], v[214:217], v[174:177], v[16:19]
	v_mfma_f32_16x16x32_bf16 v[4:7], v[204:207], v[186:189], v[4:7]
	v_mfma_f32_16x16x32_bf16 v[0:3], v[214:217], v[186:189], v[0:3]
	s_barrier
	ds_read_b128 v[128:131], v220 offset:32768
	ds_read_b128 v[132:135], v220 offset:33792
	ds_read_b128 v[136:139], v220 offset:34816
	ds_read_b128 v[140:143], v220 offset:35840
	ds_read_b128 v[144:147], v185 offset:32768
	ds_read_b128 v[148:151], v185 offset:33792
	ds_read_b128 v[152:155], v185 offset:34816
	ds_read_b128 v[156:159], v185 offset:35840
	ds_read_b128 v[170:173], v185 offset:36864
	ds_read_b128 v[174:177], v185 offset:37888
	ds_read_b128 v[178:181], v185 offset:38912
	ds_read_b128 v[186:189], v185 offset:39936
	global_load_lds_dwordx4 v160, s[18:19]
	s_mov_b32 m0, s31
	s_nop 0
	global_load_lds_dwordx4 v162, s[18:19]
	s_waitcnt lgkmcnt(8)
	s_barrier
	s_waitcnt lgkmcnt(0)
	v_mfma_f32_16x16x32_bf16 v[124:127], v[128:131], v[144:147], v[124:127]
	v_mfma_f32_16x16x32_bf16 v[120:123], v[136:139], v[144:147], v[120:123]
	v_mfma_f32_16x16x32_bf16 v[108:111], v[128:131], v[152:155], v[108:111]
	v_mfma_f32_16x16x32_bf16 v[104:107], v[136:139], v[152:155], v[104:107]
	s_add_i32 s18, 0, 0x1c000
	s_add_i32 s19, s43, s27
	v_mfma_f32_16x16x32_bf16 v[92:95], v[128:131], v[170:173], v[92:95]
	s_add_i32 m0, s19, 0xffffff80
	v_mfma_f32_16x16x32_bf16 v[88:91], v[136:139], v[170:173], v[88:91]
	v_mfma_f32_16x16x32_bf16 v[76:79], v[128:131], v[178:181], v[76:79]
	v_mfma_f32_16x16x32_bf16 v[72:75], v[136:139], v[178:181], v[72:75]
	v_mfma_f32_16x16x32_bf16 v[124:127], v[132:135], v[148:151], v[124:127]
	v_mfma_f32_16x16x32_bf16 v[120:123], v[140:143], v[148:151], v[120:123]
	v_mfma_f32_16x16x32_bf16 v[108:111], v[132:135], v[156:159], v[108:111]
	v_mfma_f32_16x16x32_bf16 v[104:107], v[140:143], v[156:159], v[104:107]
	v_mfma_f32_16x16x32_bf16 v[92:95], v[132:135], v[174:177], v[92:95]
	v_mfma_f32_16x16x32_bf16 v[88:91], v[140:143], v[174:177], v[88:91]
	v_mfma_f32_16x16x32_bf16 v[76:79], v[132:135], v[186:189], v[76:79]
	v_mfma_f32_16x16x32_bf16 v[72:75], v[140:143], v[186:189], v[72:75]
	s_barrier
	ds_read_b128 v[196:199], v220 offset:49152
	ds_read_b128 v[204:207], v220 offset:50176
	ds_read_b128 v[208:211], v220 offset:51200
	ds_read_b128 v[214:217], v220 offset:52224
	global_load_lds_dwordx4 v192, s[16:17] offset:128
	s_add_i32 m0, s19, 0x1f80
	s_nop 0
	global_load_lds_dwordx4 v164, s[16:17] offset:128
	s_barrier
	s_waitcnt lgkmcnt(0)
	v_mfma_f32_16x16x32_bf16 v[116:119], v[196:199], v[144:147], v[116:119]
	v_mfma_f32_16x16x32_bf16 v[112:115], v[208:211], v[144:147], v[112:115]
	v_mfma_f32_16x16x32_bf16 v[100:103], v[196:199], v[152:155], v[100:103]
	v_mfma_f32_16x16x32_bf16 v[96:99], v[208:211], v[152:155], v[96:99]
	s_mov_b32 m0, s35
	v_mfma_f32_16x16x32_bf16 v[84:87], v[196:199], v[170:173], v[84:87]
	v_mfma_f32_16x16x32_bf16 v[80:83], v[208:211], v[170:173], v[80:83]
	v_mfma_f32_16x16x32_bf16 v[68:71], v[196:199], v[178:181], v[68:71]
	v_mfma_f32_16x16x32_bf16 v[64:67], v[208:211], v[178:181], v[64:67]
	v_mfma_f32_16x16x32_bf16 v[116:119], v[204:207], v[148:151], v[116:119]
	v_mfma_f32_16x16x32_bf16 v[112:115], v[214:217], v[148:151], v[112:115]
	v_mfma_f32_16x16x32_bf16 v[100:103], v[204:207], v[156:159], v[100:103]
	v_mfma_f32_16x16x32_bf16 v[96:99], v[214:217], v[156:159], v[96:99]
	v_mfma_f32_16x16x32_bf16 v[84:87], v[204:207], v[174:177], v[84:87]
	v_mfma_f32_16x16x32_bf16 v[80:83], v[214:217], v[174:177], v[80:83]
	v_mfma_f32_16x16x32_bf16 v[68:71], v[204:207], v[186:189], v[68:71]
	v_mfma_f32_16x16x32_bf16 v[64:67], v[214:217], v[186:189], v[64:67]
	s_barrier
	ds_read_b128 v[144:147], v185 offset:49152
	ds_read_b128 v[148:151], v185 offset:50176
	ds_read_b128 v[152:155], v185 offset:51200
	ds_read_b128 v[156:159], v185 offset:52224
	ds_read_b128 v[170:173], v185 offset:53248
	ds_read_b128 v[174:177], v185 offset:54272
	ds_read_b128 v[178:181], v185 offset:55296
	ds_read_b128 v[186:189], v185 offset:56320
	global_load_lds_dwordx4 v160, s[48:49]
	s_mov_b32 m0, s36
	s_nop 0
	global_load_lds_dwordx4 v162, s[48:49]
	s_barrier
	s_waitcnt lgkmcnt(0)
	v_mfma_f32_16x16x32_bf16 v[60:63], v[128:131], v[144:147], v[60:63]
	v_mfma_f32_16x16x32_bf16 v[56:59], v[136:139], v[144:147], v[56:59]
	v_mfma_f32_16x16x32_bf16 v[44:47], v[128:131], v[152:155], v[44:47]
	v_mfma_f32_16x16x32_bf16 v[40:43], v[136:139], v[152:155], v[40:43]
	s_add_u32 s16, s16, 0x80080
	s_addc_u32 s17, s17, 0
	v_mfma_f32_16x16x32_bf16 v[28:31], v[128:131], v[170:173], v[28:31]
	s_add_i32 s18, s18, s27
	s_mov_b32 m0, s18
	v_mfma_f32_16x16x32_bf16 v[24:27], v[136:139], v[170:173], v[24:27]
	v_mfma_f32_16x16x32_bf16 v[12:15], v[128:131], v[178:181], v[12:15]
	v_mfma_f32_16x16x32_bf16 v[8:11], v[136:139], v[178:181], v[8:11]
	v_mfma_f32_16x16x32_bf16 v[60:63], v[132:135], v[148:151], v[60:63]
	v_mfma_f32_16x16x32_bf16 v[56:59], v[140:143], v[148:151], v[56:59]
	v_mfma_f32_16x16x32_bf16 v[44:47], v[132:135], v[156:159], v[44:47]
	v_mfma_f32_16x16x32_bf16 v[40:43], v[140:143], v[156:159], v[40:43]
	v_mfma_f32_16x16x32_bf16 v[28:31], v[132:135], v[174:177], v[28:31]
	v_mfma_f32_16x16x32_bf16 v[24:27], v[140:143], v[174:177], v[24:27]
	v_mfma_f32_16x16x32_bf16 v[12:15], v[132:135], v[186:189], v[12:15]
	v_mfma_f32_16x16x32_bf16 v[8:11], v[140:143], v[186:189], v[8:11]
	s_barrier
	global_load_lds_dwordx4 v192, s[16:17]
	s_add_i32 m0, s18, 0x2000
	s_nop 0
	global_load_lds_dwordx4 v164, s[16:17]
	s_waitcnt vmcnt(6)
	s_barrier
	v_mfma_f32_16x16x32_bf16 v[52:55], v[196:199], v[144:147], v[52:55]
	v_mfma_f32_16x16x32_bf16 v[48:51], v[208:211], v[144:147], v[48:51]
	v_mfma_f32_16x16x32_bf16 v[36:39], v[196:199], v[152:155], v[36:39]
	v_mfma_f32_16x16x32_bf16 v[32:35], v[208:211], v[152:155], v[32:35]
	s_add_i32 s42, s42, 2
	v_mfma_f32_16x16x32_bf16 v[20:23], v[196:199], v[170:173], v[20:23]
	s_add_u32 s14, s14, 0x100
	s_addc_u32 s15, s15, 0
	v_mfma_f32_16x16x32_bf16 v[16:19], v[208:211], v[170:173], v[16:19]
	s_add_u32 s40, s40, 0x100
	s_addc_u32 s41, s41, 0
	v_mfma_f32_16x16x32_bf16 v[4:7], v[196:199], v[178:181], v[4:7]
	s_add_u32 s16, s14, 0xfff80080
	s_addc_u32 s17, s15, -1
	v_mfma_f32_16x16x32_bf16 v[0:3], v[208:211], v[178:181], v[0:3]
	s_add_i32 s43, 0, 0x10000
	s_cmp_eq_u32 s42, 28
	v_mfma_f32_16x16x32_bf16 v[52:55], v[204:207], v[148:151], v[52:55]
	s_cselect_b32 s19, s7, s17
	s_cselect_b32 s18, s38, s16
	v_mfma_f32_16x16x32_bf16 v[48:51], v[214:217], v[148:151], v[48:51]
	s_cselect_b32 s17, s5, s41
	s_cselect_b32 s16, s39, s40
	v_mfma_f32_16x16x32_bf16 v[36:39], v[204:207], v[156:159], v[36:39]
	s_add_i32 m0, s28, 0xc000
	v_mfma_f32_16x16x32_bf16 v[32:35], v[214:217], v[156:159], v[32:35]
	v_mfma_f32_16x16x32_bf16 v[20:23], v[204:207], v[174:177], v[20:23]
	v_mfma_f32_16x16x32_bf16 v[16:19], v[214:217], v[174:177], v[16:19]
	v_mfma_f32_16x16x32_bf16 v[4:7], v[204:207], v[186:189], v[4:7]
	v_mfma_f32_16x16x32_bf16 v[0:3], v[214:217], v[186:189], v[0:3]
	s_cmp_gt_u32 s42, 29
	s_barrier
	s_cbranch_scc0 .LBB0_87
	v_lshl_or_b32 v128, s13, 8, v184
	v_lshl_add_u32 v172, s12, 8, v182
	v_ashrrev_i32_e32 v129, 31, v128
	v_lshlrev_b64 v[170:171], 1, v[128:129]
	v_ashrrev_i32_e32 v173, 31, v172
	v_lshl_add_u64 v[174:175], s[2:3], 0, v[170:171]
	v_lshlrev_b64 v[128:129], 13, v[172:173]
	v_lshl_add_u64 v[130:131], v[174:175], 0, v[128:129]
	global_load_dwordx4 v[186:189], v[130:131], off
	global_load_dwordx4 v[196:199], v[130:131], off offset:256
	s_lshl_b32 s5, s13, 1
	v_mul_f32_e32 v133, 0xbfb8aa3b, v124
	v_mul_f32_e32 v135, 0xbfb8aa3b, v125
	v_mul_f32_e32 v137, 0xbfb8aa3b, v126
	v_mul_f32_e32 v138, 0xbfb8aa3b, v127
	v_mul_f32_e32 v139, 0xbfb8aa3b, v120
	v_mul_f32_e32 v140, 0xbfb8aa3b, v121
	s_and_b32 s12, s5, -4
	v_or_b32_e32 v132, 16, v172
	v_or_b32_e32 v136, 48, v172
	v_exp_f32_e32 v148, v133
	v_exp_f32_e32 v149, v135
	v_exp_f32_e32 v150, v137
	v_exp_f32_e32 v151, v138
	v_exp_f32_e32 v204, v139
	v_exp_f32_e32 v205, v140
	s_ashr_i32 s13, s12, 31
	v_or_b32_e32 v134, 32, v172
	v_ashrrev_i32_e32 v133, 31, v132
	v_ashrrev_i32_e32 v137, 31, v136
	s_lshl_b64 s[12:13], s[12:13], 2
	v_mul_f32_e32 v141, 0xbfb8aa3b, v122
	v_ashrrev_i32_e32 v135, 31, v134
	v_lshlrev_b64 v[180:181], 13, v[132:133]
	v_lshlrev_b64 v[176:177], 13, v[136:137]
	s_add_u32 s12, s33, s12
	v_exp_f32_e32 v212, v141
	v_lshlrev_b64 v[138:139], 7, v[172:173]
	v_lshlrev_b64 v[140:141], 7, v[132:133]
	v_lshlrev_b64 v[142:143], 7, v[134:135]
	v_lshlrev_b64 v[178:179], 13, v[134:135]
	v_lshlrev_b64 v[144:145], 7, v[136:137]
	v_lshl_add_u64 v[128:129], s[2:3], 0, v[128:129]
	v_lshl_add_u64 v[130:131], v[174:175], 0, v[180:181]
	v_lshl_add_u64 v[136:137], v[174:175], 0, v[176:177]
	s_addc_u32 s13, s34, s13
	v_lshl_add_u64 v[146:147], v[174:175], 0, v[178:179]
	v_lshl_add_u64 v[190:191], v[128:129], 0, v[170:171]
	global_load_dwordx4 v[156:159], v[130:131], off
	global_load_dwordx4 v[152:155], v[130:131], off offset:256
	global_load_dwordx4 v[132:135], v[136:137], off
	s_nop 0
	global_load_dwordx4 v[128:131], v[136:137], off offset:256
	v_add_f32_e32 v148, 1.0, v148
	v_add_f32_e32 v149, 1.0, v149
	v_add_f32_e32 v150, 1.0, v150
	v_add_f32_e32 v151, 1.0, v151
	v_add_f32_e32 v173, 1.0, v204
	v_add_f32_e32 v204, 1.0, v205
	v_lshl_add_u64 v[136:137], s[12:13], 0, v[138:139]
	v_lshl_add_u64 v[138:139], s[12:13], 0, v[140:141]
	v_lshl_add_u64 v[140:141], s[12:13], 0, v[142:143]
	v_lshl_add_u64 v[144:145], s[12:13], 0, v[144:145]
	v_rcp_f32_e32 v214, v148
	v_rcp_f32_e32 v215, v149
	v_rcp_f32_e32 v216, v150
	v_rcp_f32_e32 v217, v151
	v_rcp_f32_e32 v218, v204
	global_load_dwordx4 v[204:207], v[136:137], off
	global_load_dwordx4 v[208:211], v[138:139], off
	s_nop 0
	global_load_dwordx4 v[136:139], v[140:141], off
	global_load_dwordx4 v[148:151], v[146:147], off
	s_nop 0
	global_load_dwordx4 v[140:143], v[146:147], off offset:256
	s_nop 0
	global_load_dwordx4 v[144:147], v[144:145], off
	v_rcp_f32_e32 v173, v173
	v_mul_f32_e32 v124, v124, v214
	v_mul_f32_e32 v125, v125, v215
	v_mul_f32_e32 v127, v127, v217
	v_mul_f32_e32 v120, v120, v173
	v_mul_f32_e32 v121, v121, v218
	s_mov_b32 s14, 0x358637bd
	s_mov_b32 s5, 0x800000
	v_mul_f32_e32 v126, v126, v216
	s_mov_b64 s[16:17], s[10:11]
	s_mov_b32 s11, 0xc000
	s_waitcnt vmcnt(0)
	v_lshlrev_b32_e32 v173, 16, v186
	v_and_b32_e32 v186, 0xffff0000, v186
	v_lshlrev_b32_e32 v214, 16, v187
	v_and_b32_e32 v187, 0xffff0000, v187
	v_mul_f32_e32 v125, v125, v186
	v_mul_f32_e32 v127, v127, v187
	v_add_f32_e32 v186, 1.0, v212
	v_mul_f32_e32 v187, 0xbfb8aa3b, v123
	v_rcp_f32_e32 v186, v186
	v_exp_f32_e32 v187, v187
	v_mul_f32_e32 v124, v124, v173
	v_and_b32_e32 v173, 0xffff0000, v188
	v_mul_f32_e32 v122, v122, v186
	v_add_f32_e32 v186, 1.0, v187
	v_mul_f32_e32 v187, 0xbfb8aa3b, v116
	v_rcp_f32_e32 v186, v186
	v_exp_f32_e32 v187, v187
	v_mul_f32_e32 v121, v121, v173
	v_lshlrev_b32_e32 v173, 16, v189
	v_mul_f32_e32 v123, v123, v186
	v_add_f32_e32 v186, 1.0, v187
	v_mul_f32_e32 v187, 0xbfb8aa3b, v117
	v_rcp_f32_e32 v186, v186
	v_exp_f32_e32 v187, v187
	v_mul_f32_e32 v122, v122, v173
	v_and_b32_e32 v173, 0xffff0000, v189
	v_mul_f32_e32 v116, v116, v186
	v_add_f32_e32 v186, 1.0, v187
	v_mul_f32_e32 v187, 0xbfb8aa3b, v118
	v_rcp_f32_e32 v186, v186
	v_exp_f32_e32 v187, v187
	v_mul_f32_e32 v123, v123, v173
	v_lshlrev_b32_e32 v173, 16, v196
	v_mul_f32_e32 v173, v116, v173
	v_mul_f32_e32 v116, v117, v186
	v_add_f32_e32 v186, 1.0, v187
	v_mul_f32_e32 v187, 0xbfb8aa3b, v119
	v_rcp_f32_e32 v186, v186
	v_exp_f32_e32 v187, v187
	v_and_b32_e32 v117, 0xffff0000, v196
	v_lshlrev_b32_e32 v215, 16, v188
	v_mul_f32_e32 v188, v116, v117
	v_mul_f32_e32 v116, v118, v186
	v_add_f32_e32 v118, 1.0, v187
	v_rcp_f32_e32 v118, v118
	v_mul_f32_e32 v186, 0xbfb8aa3b, v112
	v_exp_f32_e32 v186, v186
	v_lshlrev_b32_e32 v117, 16, v197
	v_mul_f32_e32 v187, v116, v117
	v_mul_f32_e32 v116, v119, v118
	v_mul_f32_e32 v119, 0xbfb8aa3b, v113
	v_add_f32_e32 v118, 1.0, v186
	v_exp_f32_e32 v119, v119
	v_rcp_f32_e32 v118, v118
	v_and_b32_e32 v117, 0xffff0000, v197
	v_mul_f32_e32 v186, v116, v117
	v_add_f32_e32 v117, 1.0, v119
	v_mul_f32_e32 v112, v112, v118
	v_rcp_f32_e32 v117, v117
	v_mul_f32_e32 v118, 0xbfb8aa3b, v114
	v_exp_f32_e32 v118, v118
	v_lshlrev_b32_e32 v116, 16, v198
	v_mul_f32_e32 v189, v112, v116
	v_mul_f32_e32 v112, v113, v117
	v_and_b32_e32 v113, 0xffff0000, v198
	v_add_f32_e32 v116, 1.0, v118
	v_mul_f32_e32 v196, v112, v113
	v_mul_f32_e32 v112, 0xbfb8aa3b, v115
	v_rcp_f32_e32 v116, v116
	v_exp_f32_e32 v112, v112
	v_mov_b32_e32 v117, v206
	v_mov_b32_e32 v206, v211
	v_mul_f32_e32 v113, v114, v116
	v_lshlrev_b32_e32 v114, 16, v199
	v_add_f32_e32 v112, 1.0, v112
	v_mul_f32_e32 v197, v113, v114
	v_rcp_f32_e32 v114, v112
	v_mov_b32_e32 v112, v208
	v_mov_b32_e32 v113, v204
	v_mov_b32_e32 v204, v209
	v_pk_add_f32 v[112:113], v[112:113], v[204:205]
	v_mov_b32_e32 v116, v210
	v_pk_add_f32 v[112:113], v[116:117], v[112:113]
	v_mul_f32_e32 v114, v115, v114
	v_pk_add_f32 v[116:117], v[206:207], v[112:113]
	v_mov_b64_e32 v[112:113], s[14:15]
	s_mov_b32 s14, 0x3b000000
	v_pk_fma_f32 v[118:119], v[116:117], s[14:15], v[112:113] op_sel_hi:[1,0,0]
	v_and_b32_e32 v115, 0xffff0000, v199
	v_mul_f32_e32 v116, 0x4b800000, v119
	v_cmp_gt_f32_e32 vcc, s5, v119
	v_mul_f32_e32 v126, v126, v214
	v_mul_f32_e32 v120, v120, v215
	v_cndmask_b32_e32 v116, v119, v116, vcc
	v_rsq_f32_e32 v116, v116
	v_mul_f32_e32 v119, v114, v115
	v_mul_f32_e32 v114, 0x45800000, v116
	v_cndmask_b32_e32 v198, v116, v114, vcc
	v_mul_f32_e32 v114, v124, v198
	v_mul_f32_e32 v115, v125, v198
	v_cvt_pk_bf16_f32 v114, v114, v115
	v_mul_f32_e32 v115, v126, v198
	v_mul_f32_e32 v116, v127, v198
	v_cvt_pk_bf16_f32 v115, v115, v116
	v_mul_f32_e32 v116, v120, v198
	v_mul_f32_e32 v117, v121, v198
	v_cvt_pk_bf16_f32 v116, v116, v117
	v_mul_f32_e32 v117, v122, v198
	v_mul_f32_e32 v120, v123, v198
	v_cvt_pk_bf16_f32 v117, v117, v120
	global_store_dwordx4 v[190:191], v[114:117], off
	v_mul_f32_e32 v119, v119, v198
	v_cmp_gt_f32_e32 vcc, s5, v118
	v_mul_f32_e32 v114, v173, v198
	v_mul_f32_e32 v115, v188, v198
	v_cvt_pk_bf16_f32 v114, v114, v115
	v_mul_f32_e32 v115, v187, v198
	v_mul_f32_e32 v116, v186, v198
	v_cvt_pk_bf16_f32 v115, v115, v116
	v_mul_f32_e32 v116, v189, v198
	v_mul_f32_e32 v117, v196, v198
	v_cvt_pk_bf16_f32 v116, v116, v117
	v_mul_f32_e32 v117, v197, v198
	v_cvt_pk_bf16_f32 v117, v117, v119
	v_mul_f32_e32 v119, 0x4b800000, v118
	v_cndmask_b32_e32 v118, v118, v119, vcc
	global_store_dwordx4 v[190:191], v[114:117], off offset:256
	v_rsq_f32_e32 v118, v118
	v_mul_f32_e32 v123, 0xbfb8aa3b, v61
	v_mul_f32_e32 v114, 0xbfb8aa3b, v108
	v_exp_f32_e32 v116, v114
	v_mul_f32_e32 v114, 0x45800000, v118
	v_cndmask_b32_e32 v117, v118, v114, vcc
	v_mul_f32_e32 v118, 0xbfb8aa3b, v109
	v_add_f32_e32 v116, 1.0, v116
	v_rcp_f32_e32 v116, v116
	v_exp_f32_e32 v118, v118
	v_lshl_add_u64 v[114:115], s[2:3], 0, v[180:181]
	v_lshl_add_u64 v[114:115], v[114:115], 0, v[170:171]
	v_mul_f32_e32 v108, v108, v116
	v_lshlrev_b32_e32 v116, 16, v156
	v_mul_f32_e32 v108, v108, v116
	v_add_f32_e32 v116, 1.0, v118
	v_rcp_f32_e32 v116, v116
	v_mul_f32_e32 v118, 0xbfb8aa3b, v110
	v_exp_f32_e32 v118, v118
	v_mul_f32_e32 v108, v108, v117
	v_mul_f32_e32 v109, v109, v116
	v_and_b32_e32 v116, 0xffff0000, v156
	v_mul_f32_e32 v109, v109, v116
	v_add_f32_e32 v116, 1.0, v118
	v_mul_f32_e32 v118, 0xbfb8aa3b, v111
	v_rcp_f32_e32 v116, v116
	v_exp_f32_e32 v118, v118
	v_mul_f32_e32 v109, v109, v117
	v_cvt_pk_bf16_f32 v108, v108, v109
	v_mul_f32_e32 v109, v110, v116
	v_add_f32_e32 v110, 1.0, v118
	v_rcp_f32_e32 v110, v110
	v_lshlrev_b32_e32 v116, 16, v157
	v_mul_f32_e32 v109, v109, v116
	v_and_b32_e32 v116, 0xffff0000, v157
	v_mul_f32_e32 v110, v111, v110
	v_mul_f32_e32 v111, 0xbfb8aa3b, v104
	v_exp_f32_e32 v111, v111
	v_mul_f32_e32 v110, v110, v116
	v_mul_f32_e32 v109, v109, v117
	v_mul_f32_e32 v110, v110, v117
	v_add_f32_e32 v111, 1.0, v111
	v_cvt_pk_bf16_f32 v109, v109, v110
	v_mul_f32_e32 v110, 0xbfb8aa3b, v105
	v_rcp_f32_e32 v111, v111
	v_exp_f32_e32 v110, v110
	v_exp_f32_e32 v123, v123
	v_mul_f32_e32 v124, 0xbfb8aa3b, v62
	v_mul_f32_e32 v104, v104, v111
	v_lshlrev_b32_e32 v111, 16, v158
	v_add_f32_e32 v110, 1.0, v110
	v_mul_f32_e32 v104, v104, v111
	v_rcp_f32_e32 v110, v110
	v_mul_f32_e32 v111, 0xbfb8aa3b, v106
	v_exp_f32_e32 v111, v111
	v_mul_f32_e32 v104, v104, v117
	v_mul_f32_e32 v105, v105, v110
	v_and_b32_e32 v110, 0xffff0000, v158
	v_mul_f32_e32 v105, v105, v110
	v_add_f32_e32 v110, 1.0, v111
	v_rcp_f32_e32 v111, v110
	v_mul_f32_e32 v110, 0xbfb8aa3b, v107
	v_exp_f32_e32 v116, v110
	v_mul_f32_e32 v105, v105, v117
	v_cvt_pk_bf16_f32 v110, v104, v105
	v_mul_f32_e32 v104, v106, v111
	v_add_f32_e32 v105, 1.0, v116
	v_rcp_f32_e32 v105, v105
	v_lshlrev_b32_e32 v106, 16, v159
	v_mul_f32_e32 v104, v104, v106
	v_and_b32_e32 v106, 0xffff0000, v159
	v_mul_f32_e32 v105, v107, v105
	v_mul_f32_e32 v107, 0xbfb8aa3b, v100
	v_exp_f32_e32 v107, v107
	v_mul_f32_e32 v104, v104, v117
	v_mul_f32_e32 v105, v105, v106
	v_mul_f32_e32 v105, v105, v117
	v_cvt_pk_bf16_f32 v111, v104, v105
	v_add_f32_e32 v104, 1.0, v107
	v_rcp_f32_e32 v104, v104
	v_mul_f32_e32 v105, 0xbfb8aa3b, v101
	v_exp_f32_e32 v105, v105
	global_store_dwordx4 v[114:115], v[108:111], off
	v_mul_f32_e32 v100, v100, v104
	v_lshlrev_b32_e32 v104, 16, v152
	v_mul_f32_e32 v100, v100, v104
	v_add_f32_e32 v104, 1.0, v105
	v_rcp_f32_e32 v104, v104
	v_mul_f32_e32 v105, 0xbfb8aa3b, v102
	v_exp_f32_e32 v105, v105
	v_mul_f32_e32 v100, v100, v117
	v_mul_f32_e32 v101, v101, v104
	v_and_b32_e32 v104, 0xffff0000, v152
	v_mul_f32_e32 v101, v101, v104
	v_add_f32_e32 v104, 1.0, v105
	v_mul_f32_e32 v105, 0xbfb8aa3b, v103
	v_rcp_f32_e32 v104, v104
	v_exp_f32_e32 v105, v105
	v_mul_f32_e32 v101, v101, v117
	v_cvt_pk_bf16_f32 v100, v100, v101
	v_mul_f32_e32 v101, v102, v104
	v_add_f32_e32 v102, 1.0, v105
	v_rcp_f32_e32 v102, v102
	v_lshlrev_b32_e32 v104, 16, v153
	v_mul_f32_e32 v101, v101, v104
	v_and_b32_e32 v104, 0xffff0000, v153
	v_mul_f32_e32 v102, v103, v102
	v_mul_f32_e32 v103, 0xbfb8aa3b, v96
	v_exp_f32_e32 v103, v103
	v_mul_f32_e32 v102, v102, v104
	v_mul_f32_e32 v101, v101, v117
	v_mul_f32_e32 v102, v102, v117
	v_add_f32_e32 v103, 1.0, v103
	v_cvt_pk_bf16_f32 v101, v101, v102
	v_mul_f32_e32 v102, 0xbfb8aa3b, v97
	v_rcp_f32_e32 v103, v103
	v_exp_f32_e32 v102, v102
	v_add_f32_e32 v123, 1.0, v123
	v_rcp_f32_e32 v123, v123
	v_mul_f32_e32 v96, v96, v103
	v_lshlrev_b32_e32 v103, 16, v154
	v_add_f32_e32 v102, 1.0, v102
	v_mul_f32_e32 v96, v96, v103
	v_rcp_f32_e32 v102, v102
	v_mul_f32_e32 v103, 0xbfb8aa3b, v98
	v_exp_f32_e32 v103, v103
	v_mul_f32_e32 v96, v96, v117
	v_mul_f32_e32 v97, v97, v102
	v_and_b32_e32 v102, 0xffff0000, v154
	v_mul_f32_e32 v97, v97, v102
	v_add_f32_e32 v102, 1.0, v103
	v_rcp_f32_e32 v103, v102
	v_mul_f32_e32 v102, 0xbfb8aa3b, v99
	v_exp_f32_e32 v104, v102
	v_mul_f32_e32 v97, v97, v117
	v_cvt_pk_bf16_f32 v102, v96, v97
	v_mul_f32_e32 v96, v98, v103
	v_add_f32_e32 v97, 1.0, v104
	v_rcp_f32_e32 v97, v97
	v_lshlrev_b32_e32 v98, 16, v155
	v_mul_f32_e32 v96, v96, v98
	v_and_b32_e32 v98, 0xffff0000, v155
	v_mul_f32_e32 v97, v99, v97
	v_mul_f32_e32 v99, 0xbfb8aa3b, v93
	v_exp_f32_e32 v99, v99
	v_mul_f32_e32 v97, v97, v98
	v_mul_f32_e32 v96, v96, v117
	v_mul_f32_e32 v97, v97, v117
	v_cvt_pk_bf16_f32 v103, v96, v97
	global_store_dwordx4 v[114:115], v[100:103], off offset:256
	v_add_f32_e32 v99, 1.0, v99
	v_rcp_f32_e32 v99, v99
	v_mul_f32_e32 v100, 0xbfb8aa3b, v94
	v_exp_f32_e32 v100, v100
	v_mul_f32_e32 v98, 0xbfb8aa3b, v92
	v_mul_f32_e32 v93, v93, v99
	v_exp_f32_e32 v98, v98
	v_add_f32_e32 v99, 1.0, v100
	v_mul_f32_e32 v100, 0xbfb8aa3b, v95
	v_rcp_f32_e32 v99, v99
	v_exp_f32_e32 v100, v100
	v_add_f32_e32 v98, 1.0, v98
	v_rcp_f32_e32 v98, v98
	v_mul_f32_e32 v94, v94, v99
	v_add_f32_e32 v99, 1.0, v100
	v_mul_f32_e32 v100, 0xbfb8aa3b, v88
	v_rcp_f32_e32 v99, v99
	v_exp_f32_e32 v100, v100
	v_mul_f32_e32 v92, v92, v98
	v_lshlrev_b32_e32 v98, 16, v148
	v_mul_f32_e32 v95, v95, v99
	v_add_f32_e32 v99, 1.0, v100
	v_mul_f32_e32 v100, 0xbfb8aa3b, v89
	v_rcp_f32_e32 v99, v99
	v_exp_f32_e32 v100, v100
	v_mul_f32_e32 v92, v92, v98
	v_and_b32_e32 v98, 0xffff0000, v148
	v_mul_f32_e32 v88, v88, v99
	v_add_f32_e32 v99, 1.0, v100
	v_mul_f32_e32 v100, 0xbfb8aa3b, v90
	v_rcp_f32_e32 v99, v99
	v_exp_f32_e32 v100, v100
	v_mul_f32_e32 v93, v93, v98
	v_lshlrev_b32_e32 v98, 16, v149
	v_mul_f32_e32 v89, v89, v99
	v_add_f32_e32 v99, 1.0, v100
	v_mul_f32_e32 v100, 0xbfb8aa3b, v91
	v_rcp_f32_e32 v99, v99
	v_exp_f32_e32 v100, v100
	v_mul_f32_e32 v94, v94, v98
	v_and_b32_e32 v98, 0xffff0000, v149
	v_mul_f32_e32 v90, v90, v99
	v_add_f32_e32 v99, 1.0, v100
	v_mul_f32_e32 v100, 0xbfb8aa3b, v84
	v_rcp_f32_e32 v99, v99
	v_exp_f32_e32 v100, v100
	v_mul_f32_e32 v95, v95, v98
	v_lshlrev_b32_e32 v98, 16, v150
	v_mul_f32_e32 v91, v91, v99
	v_add_f32_e32 v99, 1.0, v100
	v_mul_f32_e32 v100, 0xbfb8aa3b, v85
	v_rcp_f32_e32 v99, v99
	v_exp_f32_e32 v100, v100
	v_mul_f32_e32 v88, v88, v98
	v_and_b32_e32 v98, 0xffff0000, v150
	v_mul_f32_e32 v84, v84, v99
	v_add_f32_e32 v99, 1.0, v100
	v_mul_f32_e32 v100, 0xbfb8aa3b, v86
	v_rcp_f32_e32 v99, v99
	v_exp_f32_e32 v100, v100
	v_mul_f32_e32 v89, v89, v98
	v_lshlrev_b32_e32 v98, 16, v151
	v_mul_f32_e32 v90, v90, v98
	v_and_b32_e32 v98, 0xffff0000, v151
	v_mul_f32_e32 v91, v91, v98
	v_lshlrev_b32_e32 v98, 16, v140
	v_mul_f32_e32 v98, v84, v98
	v_mul_f32_e32 v84, v85, v99
	v_add_f32_e32 v99, 1.0, v100
	v_mul_f32_e32 v100, 0xbfb8aa3b, v87
	v_rcp_f32_e32 v99, v99
	v_exp_f32_e32 v100, v100
	v_and_b32_e32 v85, 0xffff0000, v140
	v_mul_f32_e32 v101, v84, v85
	v_mul_f32_e32 v84, v86, v99
	v_add_f32_e32 v86, 1.0, v100
	v_rcp_f32_e32 v86, v86
	v_mul_f32_e32 v99, 0xbfb8aa3b, v80
	v_exp_f32_e32 v99, v99
	v_lshlrev_b32_e32 v85, 16, v141
	v_mul_f32_e32 v100, v84, v85
	v_mul_f32_e32 v84, v87, v86
	v_mul_f32_e32 v87, 0xbfb8aa3b, v81
	v_add_f32_e32 v86, 1.0, v99
	v_exp_f32_e32 v87, v87
	v_rcp_f32_e32 v86, v86
	v_and_b32_e32 v85, 0xffff0000, v141
	v_mul_f32_e32 v99, v84, v85
	v_add_f32_e32 v85, 1.0, v87
	v_mul_f32_e32 v80, v80, v86
	v_rcp_f32_e32 v85, v85
	v_mul_f32_e32 v86, 0xbfb8aa3b, v82
	v_exp_f32_e32 v86, v86
	v_lshlrev_b32_e32 v84, 16, v142
	v_mul_f32_e32 v87, v80, v84
	v_mul_f32_e32 v80, v81, v85
	v_and_b32_e32 v81, 0xffff0000, v142
	v_add_f32_e32 v84, 1.0, v86
	v_mul_f32_e32 v86, v80, v81
	v_mul_f32_e32 v80, 0xbfb8aa3b, v83
	v_rcp_f32_e32 v84, v84
	v_exp_f32_e32 v80, v80
	v_mov_b32_e32 v85, v138
	v_mov_b32_e32 v138, v147
	v_mul_f32_e32 v81, v82, v84
	v_lshlrev_b32_e32 v82, 16, v143
	v_add_f32_e32 v80, 1.0, v80
	v_mul_f32_e32 v102, v81, v82
	v_rcp_f32_e32 v82, v80
	v_mov_b32_e32 v80, v144
	v_mov_b32_e32 v81, v136
	v_mov_b32_e32 v136, v145
	v_pk_add_f32 v[80:81], v[80:81], v[136:137]
	v_mov_b32_e32 v84, v146
	v_pk_add_f32 v[80:81], v[84:85], v[80:81]
	v_lshl_add_u64 v[96:97], s[2:3], 0, v[178:179]
	v_pk_add_f32 v[80:81], v[138:139], v[80:81]
	v_lshl_add_u64 v[96:97], v[96:97], 0, v[170:171]
	v_pk_fma_f32 v[84:85], v[80:81], s[14:15], v[112:113] op_sel_hi:[1,0,0]
	v_mul_f32_e32 v81, v83, v82
	v_mul_f32_e32 v80, 0x4b800000, v85
	v_cmp_gt_f32_e32 vcc, s5, v85
	v_and_b32_e32 v82, 0xffff0000, v143
	v_exp_f32_e32 v124, v124
	v_cndmask_b32_e32 v80, v85, v80, vcc
	v_rsq_f32_e32 v80, v80
	v_mul_f32_e32 v85, v81, v82
	v_mul_f32_e32 v61, v61, v123
	v_mul_f32_e32 v123, 0xbfb8aa3b, v63
	v_mul_f32_e32 v81, 0x45800000, v80
	v_cndmask_b32_e32 v103, v80, v81, vcc
	v_mul_f32_e32 v80, v92, v103
	v_mul_f32_e32 v81, v93, v103
	v_cvt_pk_bf16_f32 v80, v80, v81
	v_mul_f32_e32 v81, v94, v103
	v_mul_f32_e32 v82, v95, v103
	v_cvt_pk_bf16_f32 v81, v81, v82
	v_mul_f32_e32 v82, v88, v103
	v_mul_f32_e32 v83, v89, v103
	v_cvt_pk_bf16_f32 v82, v82, v83
	v_mul_f32_e32 v83, v90, v103
	v_mul_f32_e32 v88, v91, v103
	v_cvt_pk_bf16_f32 v83, v83, v88
	global_store_dwordx4 v[96:97], v[80:83], off
	v_mul_f32_e32 v85, v85, v103
	v_cmp_gt_f32_e32 vcc, s5, v84
	v_mul_f32_e32 v80, v98, v103
	v_mul_f32_e32 v81, v101, v103
	v_cvt_pk_bf16_f32 v80, v80, v81
	v_mul_f32_e32 v81, v100, v103
	v_mul_f32_e32 v82, v99, v103
	v_cvt_pk_bf16_f32 v81, v81, v82
	v_mul_f32_e32 v82, v87, v103
	v_mul_f32_e32 v83, v86, v103
	v_cvt_pk_bf16_f32 v82, v82, v83
	v_mul_f32_e32 v83, v102, v103
	v_cvt_pk_bf16_f32 v83, v83, v85
	v_mul_f32_e32 v85, 0x4b800000, v84
	v_cndmask_b32_e32 v84, v84, v85, vcc
	global_store_dwordx4 v[96:97], v[80:83], off offset:256
	v_rsq_f32_e32 v84, v84
	v_exp_f32_e32 v123, v123
	v_mul_f32_e32 v80, 0xbfb8aa3b, v76
	v_exp_f32_e32 v82, v80
	v_mul_f32_e32 v80, 0x45800000, v84
	v_cndmask_b32_e32 v83, v84, v80, vcc
	v_mul_f32_e32 v84, 0xbfb8aa3b, v77
	v_add_f32_e32 v82, 1.0, v82
	v_rcp_f32_e32 v82, v82
	v_exp_f32_e32 v84, v84
	v_lshl_add_u64 v[80:81], s[2:3], 0, v[176:177]
	v_lshl_add_u64 v[80:81], v[80:81], 0, v[170:171]
	v_mul_f32_e32 v76, v76, v82
	v_lshlrev_b32_e32 v82, 16, v132
	v_mul_f32_e32 v76, v76, v82
	v_add_f32_e32 v82, 1.0, v84
	v_rcp_f32_e32 v82, v82
	v_mul_f32_e32 v84, 0xbfb8aa3b, v78
	v_exp_f32_e32 v84, v84
	v_mul_f32_e32 v76, v76, v83
	v_mul_f32_e32 v77, v77, v82
	v_and_b32_e32 v82, 0xffff0000, v132
	v_mul_f32_e32 v77, v77, v82
	v_add_f32_e32 v82, 1.0, v84
	v_mul_f32_e32 v84, 0xbfb8aa3b, v79
	v_rcp_f32_e32 v82, v82
	v_exp_f32_e32 v84, v84
	v_mul_f32_e32 v77, v77, v83
	v_cvt_pk_bf16_f32 v76, v76, v77
	v_mul_f32_e32 v77, v78, v82
	v_add_f32_e32 v78, 1.0, v84
	v_rcp_f32_e32 v78, v78
	v_lshlrev_b32_e32 v82, 16, v133
	v_mul_f32_e32 v77, v77, v82
	v_and_b32_e32 v82, 0xffff0000, v133
	v_mul_f32_e32 v78, v79, v78
	v_mul_f32_e32 v79, 0xbfb8aa3b, v72
	v_exp_f32_e32 v79, v79
	v_mul_f32_e32 v78, v78, v82
	v_mul_f32_e32 v77, v77, v83
	v_mul_f32_e32 v78, v78, v83
	v_add_f32_e32 v79, 1.0, v79
	v_cvt_pk_bf16_f32 v77, v77, v78
	v_mul_f32_e32 v78, 0xbfb8aa3b, v73
	v_rcp_f32_e32 v79, v79
	v_exp_f32_e32 v78, v78
	v_mul_f32_e32 v72, v72, v79
	v_lshlrev_b32_e32 v79, 16, v134
	v_add_f32_e32 v78, 1.0, v78
	v_mul_f32_e32 v72, v72, v79
	v_rcp_f32_e32 v78, v78
	v_mul_f32_e32 v79, 0xbfb8aa3b, v74
	v_exp_f32_e32 v79, v79
	v_mul_f32_e32 v72, v72, v83
	v_mul_f32_e32 v73, v73, v78
	v_and_b32_e32 v78, 0xffff0000, v134
	v_mul_f32_e32 v73, v73, v78
	v_add_f32_e32 v78, 1.0, v79
	v_rcp_f32_e32 v79, v78
	v_mul_f32_e32 v78, 0xbfb8aa3b, v75
	v_exp_f32_e32 v82, v78
	v_mul_f32_e32 v73, v73, v83
	v_cvt_pk_bf16_f32 v78, v72, v73
	v_mul_f32_e32 v72, v74, v79
	v_add_f32_e32 v73, 1.0, v82
	v_rcp_f32_e32 v73, v73
	v_lshlrev_b32_e32 v74, 16, v135
	v_mul_f32_e32 v72, v72, v74
	v_and_b32_e32 v74, 0xffff0000, v135
	v_mul_f32_e32 v73, v75, v73
	v_mul_f32_e32 v75, 0xbfb8aa3b, v68
	v_exp_f32_e32 v75, v75
	v_mul_f32_e32 v72, v72, v83
	v_mul_f32_e32 v73, v73, v74
	v_mul_f32_e32 v73, v73, v83
	v_cvt_pk_bf16_f32 v79, v72, v73
	v_add_f32_e32 v72, 1.0, v75
	v_rcp_f32_e32 v72, v72
	v_mul_f32_e32 v73, 0xbfb8aa3b, v69
	v_exp_f32_e32 v73, v73
	global_store_dwordx4 v[80:81], v[76:79], off
	v_mul_f32_e32 v68, v68, v72
	v_lshlrev_b32_e32 v72, 16, v128
	v_mul_f32_e32 v68, v68, v72
	v_add_f32_e32 v72, 1.0, v73
	v_rcp_f32_e32 v72, v72
	v_mul_f32_e32 v73, 0xbfb8aa3b, v70
	v_exp_f32_e32 v73, v73
	v_mul_f32_e32 v68, v68, v83
	v_mul_f32_e32 v69, v69, v72
	v_and_b32_e32 v72, 0xffff0000, v128
	v_mul_f32_e32 v69, v69, v72
	v_add_f32_e32 v72, 1.0, v73
	v_mul_f32_e32 v73, 0xbfb8aa3b, v71
	v_rcp_f32_e32 v72, v72
	v_exp_f32_e32 v73, v73
	v_mul_f32_e32 v69, v69, v83
	v_cvt_pk_bf16_f32 v68, v68, v69
	v_mul_f32_e32 v69, v70, v72
	v_add_f32_e32 v70, 1.0, v73
	v_rcp_f32_e32 v70, v70
	v_lshlrev_b32_e32 v72, 16, v129
	v_mul_f32_e32 v69, v69, v72
	v_and_b32_e32 v72, 0xffff0000, v129
	v_mul_f32_e32 v70, v71, v70
	v_mul_f32_e32 v71, 0xbfb8aa3b, v64
	v_exp_f32_e32 v71, v71
	v_mul_f32_e32 v70, v70, v72
	v_mul_f32_e32 v69, v69, v83
	v_mul_f32_e32 v70, v70, v83
	v_add_f32_e32 v71, 1.0, v71
	v_cvt_pk_bf16_f32 v69, v69, v70
	v_mul_f32_e32 v70, 0xbfb8aa3b, v65
	v_rcp_f32_e32 v71, v71
	v_exp_f32_e32 v70, v70
	v_mul_f32_e32 v64, v64, v71
	v_lshlrev_b32_e32 v71, 16, v130
	v_add_f32_e32 v70, 1.0, v70
	v_mul_f32_e32 v64, v64, v71
	v_rcp_f32_e32 v70, v70
	v_mul_f32_e32 v71, 0xbfb8aa3b, v66
	v_exp_f32_e32 v71, v71
	v_mul_f32_e32 v64, v64, v83
	v_mul_f32_e32 v65, v65, v70
	v_and_b32_e32 v70, 0xffff0000, v130
	v_mul_f32_e32 v65, v65, v70
	v_add_f32_e32 v70, 1.0, v71
	v_rcp_f32_e32 v71, v70
	v_mul_f32_e32 v70, 0xbfb8aa3b, v67
	v_exp_f32_e32 v72, v70
	v_mul_f32_e32 v65, v65, v83
	v_cvt_pk_bf16_f32 v70, v64, v65
	v_mul_f32_e32 v64, v66, v71
	v_add_f32_e32 v65, 1.0, v72
	v_rcp_f32_e32 v65, v65
	v_lshlrev_b32_e32 v66, 16, v131
	v_mul_f32_e32 v64, v64, v66
	v_and_b32_e32 v66, 0xffff0000, v131
	v_mul_f32_e32 v65, v67, v65
	v_mul_f32_e32 v64, v64, v83
	v_mul_f32_e32 v65, v65, v66
	v_mul_f32_e32 v65, v65, v83
	v_cvt_pk_bf16_f32 v71, v64, v65
	v_add_u32_e32 v64, 0x80, v172
	v_ashrrev_i32_e32 v65, 31, v64
	v_lshlrev_b64 v[110:111], 13, v[64:65]
	v_lshl_add_u64 v[66:67], v[174:175], 0, v[110:111]
	global_load_dwordx4 v[102:105], v[66:67], off
	v_lshlrev_b64 v[64:65], 7, v[64:65]
	global_store_dwordx4 v[80:81], v[68:71], off offset:256
	v_lshl_add_u64 v[64:65], s[12:13], 0, v[64:65]
	global_load_dwordx4 v[106:109], v[64:65], off
	v_add_u32_e32 v64, 0x90, v172
	v_ashrrev_i32_e32 v65, 31, v64
	v_lshlrev_b64 v[68:69], 7, v[64:65]
	v_lshl_add_u64 v[68:69], s[12:13], 0, v[68:69]
	global_load_dwordx4 v[114:117], v[66:67], off offset:256
	global_load_dwordx4 v[118:121], v[68:69], off
	v_lshlrev_b64 v[100:101], 13, v[64:65]
	v_lshl_add_u64 v[64:65], v[174:175], 0, v[100:101]
	global_load_dwordx4 v[92:95], v[64:65], off
	global_load_dwordx4 v[88:91], v[64:65], off offset:256
	v_add_u32_e32 v64, 0xa0, v172
	v_ashrrev_i32_e32 v65, 31, v64
	v_lshlrev_b64 v[66:67], 7, v[64:65]
	v_lshl_add_u64 v[66:67], s[12:13], 0, v[66:67]
	v_lshlrev_b64 v[98:99], 13, v[64:65]
	v_lshl_add_u64 v[64:65], v[174:175], 0, v[98:99]
	global_load_dwordx4 v[72:75], v[66:67], off
	global_load_dwordx4 v[84:87], v[64:65], off
	v_add_u32_e32 v66, 0xb0, v172
	v_ashrrev_i32_e32 v67, 31, v66
	v_lshlrev_b64 v[68:69], 7, v[66:67]
	v_lshlrev_b64 v[96:97], 13, v[66:67]
	v_mul_f32_e32 v66, 0xbfb8aa3b, v60
	v_exp_f32_e32 v122, v66
	v_lshl_add_u64 v[68:69], s[12:13], 0, v[68:69]
	global_load_dwordx4 v[76:79], v[64:65], off offset:256
	global_load_dwordx4 v[80:83], v[68:69], off
	v_lshl_add_u64 v[64:65], v[174:175], 0, v[96:97]
	v_add_f32_e32 v122, 1.0, v122
	v_rcp_f32_e32 v122, v122
	global_load_dwordx4 v[68:71], v[64:65], off
	s_nop 0
	global_load_dwordx4 v[64:67], v[64:65], off offset:256
	v_lshl_add_u64 v[110:111], s[2:3], 0, v[110:111]
	v_lshl_add_u64 v[110:111], v[110:111], 0, v[170:171]
	v_mul_f32_e32 v60, v60, v122
	s_mov_b32 s13, s4
	s_mov_b32 s12, s6
	s_waitcnt vmcnt(0)
	v_lshlrev_b32_e32 v122, 16, v102
	v_mul_f32_e32 v60, v60, v122
	v_add_f32_e32 v122, 1.0, v124
	v_rcp_f32_e32 v122, v122
	v_and_b32_e32 v102, 0xffff0000, v102
	v_mul_f32_e32 v61, v61, v102
	v_lshlrev_b32_e32 v102, 16, v103
	v_mul_f32_e32 v62, v62, v122
	v_add_f32_e32 v122, 1.0, v123
	v_mul_f32_e32 v123, 0xbfb8aa3b, v56
	v_rcp_f32_e32 v122, v122
	v_exp_f32_e32 v123, v123
	v_mul_f32_e32 v62, v62, v102
	v_and_b32_e32 v102, 0xffff0000, v103
	v_mul_f32_e32 v63, v63, v122
	v_add_f32_e32 v103, 1.0, v123
	v_mul_f32_e32 v122, 0xbfb8aa3b, v57
	v_rcp_f32_e32 v103, v103
	v_exp_f32_e32 v122, v122
	v_mul_f32_e32 v63, v63, v102
	v_lshlrev_b32_e32 v102, 16, v104
	v_mul_f32_e32 v56, v56, v103
	v_add_f32_e32 v103, 1.0, v122
	v_mul_f32_e32 v122, 0xbfb8aa3b, v58
	v_rcp_f32_e32 v103, v103
	v_exp_f32_e32 v122, v122
	v_mul_f32_e32 v56, v56, v102
	v_and_b32_e32 v102, 0xffff0000, v104
	v_mul_f32_e32 v57, v57, v103
	v_add_f32_e32 v103, 1.0, v122
	v_mul_f32_e32 v104, 0xbfb8aa3b, v59
	v_rcp_f32_e32 v103, v103
	v_exp_f32_e32 v104, v104
	v_mul_f32_e32 v57, v57, v102
	v_lshlrev_b32_e32 v102, 16, v105
	v_mul_f32_e32 v58, v58, v103
	v_add_f32_e32 v103, 1.0, v104
	v_mul_f32_e32 v104, 0xbfb8aa3b, v52
	v_rcp_f32_e32 v103, v103
	v_exp_f32_e32 v104, v104
	v_mul_f32_e32 v58, v58, v102
	v_and_b32_e32 v102, 0xffff0000, v105
	v_mul_f32_e32 v59, v59, v103
	v_add_f32_e32 v103, 1.0, v104
	v_mul_f32_e32 v104, 0xbfb8aa3b, v53
	v_rcp_f32_e32 v103, v103
	v_exp_f32_e32 v104, v104
	v_mul_f32_e32 v59, v59, v102
	v_lshlrev_b32_e32 v102, 16, v114
	v_mul_f32_e32 v52, v52, v103
	v_add_f32_e32 v103, 1.0, v104
	v_mul_f32_e32 v104, 0xbfb8aa3b, v54
	v_rcp_f32_e32 v103, v103
	v_exp_f32_e32 v104, v104
	v_mul_f32_e32 v102, v52, v102
	v_mul_f32_e32 v52, v53, v103
	v_add_f32_e32 v103, 1.0, v104
	v_mul_f32_e32 v104, 0xbfb8aa3b, v55
	v_rcp_f32_e32 v103, v103
	v_exp_f32_e32 v104, v104
	v_and_b32_e32 v53, 0xffff0000, v114
	v_mul_f32_e32 v105, v52, v53
	v_mul_f32_e32 v52, v54, v103
	v_add_f32_e32 v54, 1.0, v104
	v_rcp_f32_e32 v54, v54
	v_mul_f32_e32 v103, 0xbfb8aa3b, v48
	v_exp_f32_e32 v103, v103
	v_lshlrev_b32_e32 v53, 16, v115
	v_mul_f32_e32 v104, v52, v53
	v_mul_f32_e32 v52, v55, v54
	v_mul_f32_e32 v55, 0xbfb8aa3b, v49
	v_add_f32_e32 v54, 1.0, v103
	v_exp_f32_e32 v55, v55
	v_rcp_f32_e32 v54, v54
	v_and_b32_e32 v53, 0xffff0000, v115
	v_mul_f32_e32 v103, v52, v53
	v_add_f32_e32 v53, 1.0, v55
	v_mul_f32_e32 v48, v48, v54
	v_rcp_f32_e32 v53, v53
	v_mul_f32_e32 v54, 0xbfb8aa3b, v50
	v_exp_f32_e32 v54, v54
	v_lshlrev_b32_e32 v52, 16, v116
	v_mul_f32_e32 v55, v48, v52
	v_mul_f32_e32 v48, v49, v53
	v_and_b32_e32 v49, 0xffff0000, v116
	v_add_f32_e32 v52, 1.0, v54
	v_mul_f32_e32 v54, v48, v49
	v_mul_f32_e32 v48, 0xbfb8aa3b, v51
	v_rcp_f32_e32 v52, v52
	v_exp_f32_e32 v48, v48
	v_mov_b32_e32 v53, v108
	v_mov_b32_e32 v108, v121
	v_mul_f32_e32 v49, v50, v52
	v_lshlrev_b32_e32 v50, 16, v117
	v_add_f32_e32 v48, 1.0, v48
	v_mul_f32_e32 v114, v49, v50
	v_rcp_f32_e32 v50, v48
	v_mov_b32_e32 v48, v118
	v_mov_b32_e32 v49, v106
	v_mov_b32_e32 v106, v119
	v_pk_add_f32 v[48:49], v[48:49], v[106:107]
	v_mov_b32_e32 v52, v120
	v_pk_add_f32 v[48:49], v[52:53], v[48:49]
	s_nop 0
	v_pk_add_f32 v[48:49], v[108:109], v[48:49]
	s_nop 0
	v_pk_fma_f32 v[52:53], v[48:49], s[14:15], v[112:113] op_sel_hi:[1,0,0]
	v_mul_f32_e32 v49, v51, v50
	v_mul_f32_e32 v48, 0x4b800000, v53
	v_cmp_gt_f32_e32 vcc, s5, v53
	v_and_b32_e32 v50, 0xffff0000, v117
	s_nop 0
	v_cndmask_b32_e32 v48, v53, v48, vcc
	v_rsq_f32_e32 v48, v48
	v_mul_f32_e32 v53, v49, v50
	v_mul_f32_e32 v49, 0x45800000, v48
	v_cndmask_b32_e32 v106, v48, v49, vcc
	v_mul_f32_e32 v48, v60, v106
	v_mul_f32_e32 v49, v61, v106
	v_cvt_pk_bf16_f32 v48, v48, v49
	v_mul_f32_e32 v49, v62, v106
	v_mul_f32_e32 v50, v63, v106
	v_cvt_pk_bf16_f32 v49, v49, v50
	v_mul_f32_e32 v50, v56, v106
	v_mul_f32_e32 v51, v57, v106
	v_cvt_pk_bf16_f32 v50, v50, v51
	v_mul_f32_e32 v51, v58, v106
	v_mul_f32_e32 v56, v59, v106
	v_cvt_pk_bf16_f32 v51, v51, v56
	global_store_dwordx4 v[110:111], v[48:51], off
	v_mul_f32_e32 v53, v53, v106
	v_cmp_gt_f32_e32 vcc, s5, v52
	v_mul_f32_e32 v48, v102, v106
	v_mul_f32_e32 v49, v105, v106
	v_cvt_pk_bf16_f32 v48, v48, v49
	v_mul_f32_e32 v49, v104, v106
	v_mul_f32_e32 v50, v103, v106
	v_cvt_pk_bf16_f32 v49, v49, v50
	v_mul_f32_e32 v50, v55, v106
	v_mul_f32_e32 v51, v54, v106
	v_cvt_pk_bf16_f32 v50, v50, v51
	v_mul_f32_e32 v51, v114, v106
	v_cvt_pk_bf16_f32 v51, v51, v53
	v_mul_f32_e32 v53, 0x4b800000, v52
	v_cndmask_b32_e32 v52, v52, v53, vcc
	global_store_dwordx4 v[110:111], v[48:51], off offset:256
	v_rsq_f32_e32 v52, v52
	s_nop 0
	v_mul_f32_e32 v48, 0xbfb8aa3b, v44
	v_exp_f32_e32 v50, v48
	v_mul_f32_e32 v48, 0x45800000, v52
	v_cndmask_b32_e32 v51, v52, v48, vcc
	v_mul_f32_e32 v52, 0xbfb8aa3b, v45
	v_add_f32_e32 v50, 1.0, v50
	v_rcp_f32_e32 v50, v50
	v_exp_f32_e32 v52, v52
	v_lshl_add_u64 v[48:49], s[2:3], 0, v[100:101]
	v_lshl_add_u64 v[48:49], v[48:49], 0, v[170:171]
	v_mul_f32_e32 v44, v44, v50
	v_lshlrev_b32_e32 v50, 16, v92
	v_mul_f32_e32 v44, v44, v50
	v_add_f32_e32 v50, 1.0, v52
	v_rcp_f32_e32 v50, v50
	v_mul_f32_e32 v52, 0xbfb8aa3b, v46
	v_exp_f32_e32 v52, v52
	v_mul_f32_e32 v44, v44, v51
	v_mul_f32_e32 v45, v45, v50
	v_and_b32_e32 v50, 0xffff0000, v92
	v_mul_f32_e32 v45, v45, v50
	v_add_f32_e32 v50, 1.0, v52
	v_mul_f32_e32 v52, 0xbfb8aa3b, v47
	v_rcp_f32_e32 v50, v50
	v_exp_f32_e32 v52, v52
	v_mul_f32_e32 v45, v45, v51
	v_cvt_pk_bf16_f32 v44, v44, v45
	v_mul_f32_e32 v45, v46, v50
	v_add_f32_e32 v46, 1.0, v52
	v_rcp_f32_e32 v46, v46
	v_lshlrev_b32_e32 v50, 16, v93
	v_mul_f32_e32 v45, v45, v50
	v_and_b32_e32 v50, 0xffff0000, v93
	v_mul_f32_e32 v46, v47, v46
	v_mul_f32_e32 v47, 0xbfb8aa3b, v40
	v_exp_f32_e32 v47, v47
	v_mul_f32_e32 v46, v46, v50
	v_mul_f32_e32 v45, v45, v51
	v_mul_f32_e32 v46, v46, v51
	v_add_f32_e32 v47, 1.0, v47
	v_cvt_pk_bf16_f32 v45, v45, v46
	v_mul_f32_e32 v46, 0xbfb8aa3b, v41
	v_rcp_f32_e32 v47, v47
	v_exp_f32_e32 v46, v46
	v_mul_f32_e32 v40, v40, v47
	v_lshlrev_b32_e32 v47, 16, v94
	v_add_f32_e32 v46, 1.0, v46
	v_mul_f32_e32 v40, v40, v47
	v_rcp_f32_e32 v46, v46
	v_mul_f32_e32 v47, 0xbfb8aa3b, v42
	v_exp_f32_e32 v47, v47
	v_mul_f32_e32 v40, v40, v51
	v_mul_f32_e32 v41, v41, v46
	v_and_b32_e32 v46, 0xffff0000, v94
	v_mul_f32_e32 v41, v41, v46
	v_add_f32_e32 v46, 1.0, v47
	v_rcp_f32_e32 v47, v46
	v_mul_f32_e32 v46, 0xbfb8aa3b, v43
	v_exp_f32_e32 v50, v46
	v_mul_f32_e32 v41, v41, v51
	v_cvt_pk_bf16_f32 v46, v40, v41
	v_mul_f32_e32 v40, v42, v47
	v_add_f32_e32 v41, 1.0, v50
	v_rcp_f32_e32 v41, v41
	v_lshlrev_b32_e32 v42, 16, v95
	v_mul_f32_e32 v40, v40, v42
	v_and_b32_e32 v42, 0xffff0000, v95
	v_mul_f32_e32 v41, v43, v41
	v_mul_f32_e32 v43, 0xbfb8aa3b, v36
	v_exp_f32_e32 v43, v43
	v_mul_f32_e32 v40, v40, v51
	v_mul_f32_e32 v41, v41, v42
	v_mul_f32_e32 v41, v41, v51
	v_cvt_pk_bf16_f32 v47, v40, v41
	v_add_f32_e32 v40, 1.0, v43
	v_rcp_f32_e32 v40, v40
	v_mul_f32_e32 v41, 0xbfb8aa3b, v37
	v_exp_f32_e32 v41, v41
	global_store_dwordx4 v[48:49], v[44:47], off
	v_mul_f32_e32 v36, v36, v40
	v_lshlrev_b32_e32 v40, 16, v88
	v_mul_f32_e32 v36, v36, v40
	v_add_f32_e32 v40, 1.0, v41
	v_rcp_f32_e32 v40, v40
	v_mul_f32_e32 v41, 0xbfb8aa3b, v38
	v_exp_f32_e32 v41, v41
	v_mul_f32_e32 v36, v36, v51
	v_mul_f32_e32 v37, v37, v40
	v_and_b32_e32 v40, 0xffff0000, v88
	v_mul_f32_e32 v37, v37, v40
	v_add_f32_e32 v40, 1.0, v41
	v_mul_f32_e32 v41, 0xbfb8aa3b, v39
	v_rcp_f32_e32 v40, v40
	v_exp_f32_e32 v41, v41
	v_mul_f32_e32 v37, v37, v51
	v_cvt_pk_bf16_f32 v36, v36, v37
	v_mul_f32_e32 v37, v38, v40
	v_add_f32_e32 v38, 1.0, v41
	v_rcp_f32_e32 v38, v38
	v_lshlrev_b32_e32 v40, 16, v89
	v_mul_f32_e32 v37, v37, v40
	v_and_b32_e32 v40, 0xffff0000, v89
	v_mul_f32_e32 v38, v39, v38
	v_mul_f32_e32 v39, 0xbfb8aa3b, v32
	v_exp_f32_e32 v39, v39
	v_mul_f32_e32 v38, v38, v40
	v_mul_f32_e32 v37, v37, v51
	v_mul_f32_e32 v38, v38, v51
	v_add_f32_e32 v39, 1.0, v39
	v_cvt_pk_bf16_f32 v37, v37, v38
	v_mul_f32_e32 v38, 0xbfb8aa3b, v33
	v_rcp_f32_e32 v39, v39
	v_exp_f32_e32 v38, v38
	v_mul_f32_e32 v32, v32, v39
	v_lshlrev_b32_e32 v39, 16, v90
	v_add_f32_e32 v38, 1.0, v38
	v_mul_f32_e32 v32, v32, v39
	v_rcp_f32_e32 v38, v38
	v_mul_f32_e32 v39, 0xbfb8aa3b, v34
	v_exp_f32_e32 v39, v39
	v_mul_f32_e32 v32, v32, v51
	v_mul_f32_e32 v33, v33, v38
	v_and_b32_e32 v38, 0xffff0000, v90
	v_mul_f32_e32 v33, v33, v38
	v_add_f32_e32 v38, 1.0, v39
	v_rcp_f32_e32 v39, v38
	v_mul_f32_e32 v38, 0xbfb8aa3b, v35
	v_exp_f32_e32 v40, v38
	v_mul_f32_e32 v33, v33, v51
	v_cvt_pk_bf16_f32 v38, v32, v33
	v_mul_f32_e32 v32, v34, v39
	v_add_f32_e32 v33, 1.0, v40
	v_rcp_f32_e32 v33, v33
	v_lshlrev_b32_e32 v34, 16, v91
	v_mul_f32_e32 v32, v32, v34
	v_and_b32_e32 v34, 0xffff0000, v91
	v_mul_f32_e32 v33, v35, v33
	v_mul_f32_e32 v35, 0xbfb8aa3b, v29
	v_exp_f32_e32 v35, v35
	v_mul_f32_e32 v33, v33, v34
	v_mul_f32_e32 v32, v32, v51
	v_mul_f32_e32 v33, v33, v51
	v_cvt_pk_bf16_f32 v39, v32, v33
	global_store_dwordx4 v[48:49], v[36:39], off offset:256
	v_add_f32_e32 v35, 1.0, v35
	v_rcp_f32_e32 v35, v35
	v_mul_f32_e32 v36, 0xbfb8aa3b, v30
	v_exp_f32_e32 v36, v36
	v_mul_f32_e32 v34, 0xbfb8aa3b, v28
	v_mul_f32_e32 v29, v29, v35
	v_exp_f32_e32 v34, v34
	v_add_f32_e32 v35, 1.0, v36
	v_mul_f32_e32 v36, 0xbfb8aa3b, v31
	v_rcp_f32_e32 v35, v35
	v_exp_f32_e32 v36, v36
	v_add_f32_e32 v34, 1.0, v34
	v_rcp_f32_e32 v34, v34
	v_mul_f32_e32 v30, v30, v35
	v_add_f32_e32 v35, 1.0, v36
	v_mul_f32_e32 v36, 0xbfb8aa3b, v24
	v_rcp_f32_e32 v35, v35
	v_exp_f32_e32 v36, v36
	v_mul_f32_e32 v28, v28, v34
	v_lshlrev_b32_e32 v34, 16, v84
	v_mul_f32_e32 v31, v31, v35
	v_add_f32_e32 v35, 1.0, v36
	v_mul_f32_e32 v36, 0xbfb8aa3b, v25
	v_rcp_f32_e32 v35, v35
	v_exp_f32_e32 v36, v36
	v_mul_f32_e32 v28, v28, v34
	v_and_b32_e32 v34, 0xffff0000, v84
	v_mul_f32_e32 v24, v24, v35
	v_add_f32_e32 v35, 1.0, v36
	v_mul_f32_e32 v36, 0xbfb8aa3b, v26
	v_rcp_f32_e32 v35, v35
	v_exp_f32_e32 v36, v36
	v_mul_f32_e32 v29, v29, v34
	v_lshlrev_b32_e32 v34, 16, v85
	v_mul_f32_e32 v25, v25, v35
	v_add_f32_e32 v35, 1.0, v36
	v_mul_f32_e32 v36, 0xbfb8aa3b, v27
	v_rcp_f32_e32 v35, v35
	v_exp_f32_e32 v36, v36
	v_mul_f32_e32 v30, v30, v34
	v_and_b32_e32 v34, 0xffff0000, v85
	v_mul_f32_e32 v26, v26, v35
	v_add_f32_e32 v35, 1.0, v36
	v_mul_f32_e32 v36, 0xbfb8aa3b, v20
	v_rcp_f32_e32 v35, v35
	v_exp_f32_e32 v36, v36
	v_mul_f32_e32 v31, v31, v34
	v_lshlrev_b32_e32 v34, 16, v86
	v_mul_f32_e32 v27, v27, v35
	v_add_f32_e32 v35, 1.0, v36
	v_mul_f32_e32 v36, 0xbfb8aa3b, v21
	v_rcp_f32_e32 v35, v35
	v_exp_f32_e32 v36, v36
	v_mul_f32_e32 v24, v24, v34
	v_and_b32_e32 v34, 0xffff0000, v86
	v_mul_f32_e32 v20, v20, v35
	v_add_f32_e32 v35, 1.0, v36
	v_mul_f32_e32 v36, 0xbfb8aa3b, v22
	v_rcp_f32_e32 v35, v35
	v_exp_f32_e32 v36, v36
	v_mul_f32_e32 v25, v25, v34
	v_lshlrev_b32_e32 v34, 16, v87
	v_mul_f32_e32 v26, v26, v34
	v_and_b32_e32 v34, 0xffff0000, v87
	v_mul_f32_e32 v27, v27, v34
	v_lshlrev_b32_e32 v34, 16, v76
	v_mul_f32_e32 v34, v20, v34
	v_mul_f32_e32 v20, v21, v35
	v_add_f32_e32 v35, 1.0, v36
	v_mul_f32_e32 v36, 0xbfb8aa3b, v23
	v_rcp_f32_e32 v35, v35
	v_exp_f32_e32 v36, v36
	v_and_b32_e32 v21, 0xffff0000, v76
	v_mul_f32_e32 v37, v20, v21
	v_mul_f32_e32 v20, v22, v35
	v_add_f32_e32 v22, 1.0, v36
	v_rcp_f32_e32 v22, v22
	v_mul_f32_e32 v35, 0xbfb8aa3b, v16
	v_exp_f32_e32 v35, v35
	v_lshlrev_b32_e32 v21, 16, v77
	v_mul_f32_e32 v36, v20, v21
	v_mul_f32_e32 v20, v23, v22
	v_mul_f32_e32 v23, 0xbfb8aa3b, v17
	v_add_f32_e32 v22, 1.0, v35
	v_exp_f32_e32 v23, v23
	v_rcp_f32_e32 v22, v22
	v_and_b32_e32 v21, 0xffff0000, v77
	v_mul_f32_e32 v35, v20, v21
	v_add_f32_e32 v21, 1.0, v23
	v_mul_f32_e32 v16, v16, v22
	v_rcp_f32_e32 v21, v21
	v_mul_f32_e32 v22, 0xbfb8aa3b, v18
	v_exp_f32_e32 v22, v22
	v_lshlrev_b32_e32 v20, 16, v78
	v_mul_f32_e32 v23, v16, v20
	v_mul_f32_e32 v16, v17, v21
	v_and_b32_e32 v17, 0xffff0000, v78
	v_add_f32_e32 v20, 1.0, v22
	v_mul_f32_e32 v22, v16, v17
	v_mul_f32_e32 v16, 0xbfb8aa3b, v19
	v_rcp_f32_e32 v20, v20
	v_exp_f32_e32 v16, v16
	v_mov_b32_e32 v21, v74
	v_mov_b32_e32 v74, v83
	v_mul_f32_e32 v17, v18, v20
	v_lshlrev_b32_e32 v18, 16, v79
	v_add_f32_e32 v16, 1.0, v16
	v_mul_f32_e32 v38, v17, v18
	v_rcp_f32_e32 v18, v16
	v_mov_b32_e32 v16, v80
	v_mov_b32_e32 v17, v72
	v_mov_b32_e32 v72, v81
	v_pk_add_f32 v[16:17], v[16:17], v[72:73]
	v_mov_b32_e32 v20, v82
	v_pk_add_f32 v[16:17], v[20:21], v[16:17]
	v_lshl_add_u64 v[32:33], s[2:3], 0, v[98:99]
	v_pk_add_f32 v[16:17], v[74:75], v[16:17]
	v_lshl_add_u64 v[32:33], v[32:33], 0, v[170:171]
	v_pk_fma_f32 v[20:21], v[16:17], s[14:15], v[112:113] op_sel_hi:[1,0,0]
	v_mul_f32_e32 v17, v19, v18
	v_mul_f32_e32 v16, 0x4b800000, v21
	v_cmp_gt_f32_e32 vcc, s5, v21
	v_and_b32_e32 v18, 0xffff0000, v79
	s_mov_b64 s[14:15], s[8:9]
	v_cndmask_b32_e32 v16, v21, v16, vcc
	v_rsq_f32_e32 v16, v16
	v_mul_f32_e32 v21, v17, v18
	v_mul_f32_e32 v17, 0x45800000, v16
	v_cndmask_b32_e32 v39, v16, v17, vcc
	v_mul_f32_e32 v16, v28, v39
	v_mul_f32_e32 v17, v29, v39
	v_cvt_pk_bf16_f32 v16, v16, v17
	v_mul_f32_e32 v17, v30, v39
	v_mul_f32_e32 v18, v31, v39
	v_cvt_pk_bf16_f32 v17, v17, v18
	v_mul_f32_e32 v18, v24, v39
	v_mul_f32_e32 v19, v25, v39
	v_cvt_pk_bf16_f32 v18, v18, v19
	v_mul_f32_e32 v19, v26, v39
	v_mul_f32_e32 v24, v27, v39
	v_cvt_pk_bf16_f32 v19, v19, v24
	global_store_dwordx4 v[32:33], v[16:19], off
	v_mul_f32_e32 v21, v21, v39
	v_cmp_gt_f32_e32 vcc, s5, v20
	v_mul_f32_e32 v16, v34, v39
	v_mul_f32_e32 v17, v37, v39
	v_cvt_pk_bf16_f32 v16, v16, v17
	v_mul_f32_e32 v17, v36, v39
	v_mul_f32_e32 v18, v35, v39
	v_cvt_pk_bf16_f32 v17, v17, v18
	v_mul_f32_e32 v18, v23, v39
	v_mul_f32_e32 v19, v22, v39
	v_cvt_pk_bf16_f32 v18, v18, v19
	v_mul_f32_e32 v19, v38, v39
	v_cvt_pk_bf16_f32 v19, v19, v21
	v_mul_f32_e32 v21, 0x4b800000, v20
	v_cndmask_b32_e32 v20, v20, v21, vcc
	global_store_dwordx4 v[32:33], v[16:19], off offset:256
	v_rsq_f32_e32 v20, v20
	s_nop 0
	v_mul_f32_e32 v16, 0xbfb8aa3b, v12
	v_exp_f32_e32 v18, v16
	v_mul_f32_e32 v16, 0x45800000, v20
	v_cndmask_b32_e32 v19, v20, v16, vcc
	v_mul_f32_e32 v20, 0xbfb8aa3b, v13
	v_add_f32_e32 v18, 1.0, v18
	v_rcp_f32_e32 v18, v18
	v_exp_f32_e32 v20, v20
	v_lshl_add_u64 v[16:17], s[2:3], 0, v[96:97]
	v_lshl_add_u64 v[16:17], v[16:17], 0, v[170:171]
	v_mul_f32_e32 v12, v12, v18
	v_lshlrev_b32_e32 v18, 16, v68
	v_mul_f32_e32 v12, v12, v18
	v_add_f32_e32 v18, 1.0, v20
	v_rcp_f32_e32 v18, v18
	v_mul_f32_e32 v20, 0xbfb8aa3b, v14
	v_exp_f32_e32 v20, v20
	v_mul_f32_e32 v12, v12, v19
	v_mul_f32_e32 v13, v13, v18
	v_and_b32_e32 v18, 0xffff0000, v68
	v_mul_f32_e32 v13, v13, v18
	v_add_f32_e32 v18, 1.0, v20
	v_mul_f32_e32 v20, 0xbfb8aa3b, v15
	v_rcp_f32_e32 v18, v18
	v_exp_f32_e32 v20, v20
	v_mul_f32_e32 v13, v13, v19
	v_cvt_pk_bf16_f32 v12, v12, v13
	v_mul_f32_e32 v13, v14, v18
	v_add_f32_e32 v14, 1.0, v20
	v_rcp_f32_e32 v14, v14
	v_lshlrev_b32_e32 v18, 16, v69
	v_mul_f32_e32 v13, v13, v18
	v_and_b32_e32 v18, 0xffff0000, v69
	v_mul_f32_e32 v14, v15, v14
	v_mul_f32_e32 v15, 0xbfb8aa3b, v8
	v_exp_f32_e32 v15, v15
	v_mul_f32_e32 v14, v14, v18
	v_mul_f32_e32 v13, v13, v19
	v_mul_f32_e32 v14, v14, v19
	v_add_f32_e32 v15, 1.0, v15
	v_cvt_pk_bf16_f32 v13, v13, v14
	v_mul_f32_e32 v14, 0xbfb8aa3b, v9
	v_rcp_f32_e32 v15, v15
	v_exp_f32_e32 v14, v14
	s_and_b64 vcc, exec, s[0:1]
	v_mul_f32_e32 v8, v8, v15
	v_lshlrev_b32_e32 v15, 16, v70
	v_add_f32_e32 v14, 1.0, v14
	v_mul_f32_e32 v8, v8, v15
	v_rcp_f32_e32 v14, v14
	v_mul_f32_e32 v15, 0xbfb8aa3b, v10
	v_exp_f32_e32 v15, v15
	v_mul_f32_e32 v8, v8, v19
	v_mul_f32_e32 v9, v9, v14
	v_and_b32_e32 v14, 0xffff0000, v70
	v_mul_f32_e32 v9, v9, v14
	v_add_f32_e32 v14, 1.0, v15
	v_rcp_f32_e32 v15, v14
	v_mul_f32_e32 v14, 0xbfb8aa3b, v11
	v_exp_f32_e32 v18, v14
	v_mul_f32_e32 v9, v9, v19
	v_cvt_pk_bf16_f32 v14, v8, v9
	v_mul_f32_e32 v8, v10, v15
	v_add_f32_e32 v9, 1.0, v18
	v_rcp_f32_e32 v9, v9
	v_lshlrev_b32_e32 v10, 16, v71
	v_mul_f32_e32 v8, v8, v10
	v_and_b32_e32 v10, 0xffff0000, v71
	v_mul_f32_e32 v9, v11, v9
	v_mul_f32_e32 v11, 0xbfb8aa3b, v4
	v_exp_f32_e32 v11, v11
	v_mul_f32_e32 v8, v8, v19
	v_mul_f32_e32 v9, v9, v10
	v_mul_f32_e32 v9, v9, v19
	v_cvt_pk_bf16_f32 v15, v8, v9
	v_add_f32_e32 v8, 1.0, v11
	v_rcp_f32_e32 v8, v8
	v_mul_f32_e32 v9, 0xbfb8aa3b, v5
	v_exp_f32_e32 v9, v9
	global_store_dwordx4 v[16:17], v[12:15], off
	v_mul_f32_e32 v4, v4, v8
	v_lshlrev_b32_e32 v8, 16, v64
	v_mul_f32_e32 v4, v4, v8
	v_add_f32_e32 v8, 1.0, v9
	v_rcp_f32_e32 v8, v8
	v_mul_f32_e32 v9, 0xbfb8aa3b, v6
	v_exp_f32_e32 v9, v9
	v_mul_f32_e32 v4, v4, v19
	v_mul_f32_e32 v5, v5, v8
	v_and_b32_e32 v8, 0xffff0000, v64
	v_mul_f32_e32 v5, v5, v8
	v_add_f32_e32 v8, 1.0, v9
	v_mul_f32_e32 v9, 0xbfb8aa3b, v7
	v_rcp_f32_e32 v8, v8
	v_exp_f32_e32 v9, v9
	v_mul_f32_e32 v5, v5, v19
	v_cvt_pk_bf16_f32 v4, v4, v5
	v_mul_f32_e32 v5, v6, v8
	v_add_f32_e32 v6, 1.0, v9
	v_rcp_f32_e32 v6, v6
	v_lshlrev_b32_e32 v8, 16, v65
	v_mul_f32_e32 v5, v5, v8
	v_and_b32_e32 v8, 0xffff0000, v65
	v_mul_f32_e32 v6, v7, v6
	v_mul_f32_e32 v7, 0xbfb8aa3b, v0
	v_exp_f32_e32 v7, v7
	v_mul_f32_e32 v6, v6, v8
	v_mul_f32_e32 v5, v5, v19
	v_mul_f32_e32 v6, v6, v19
	v_add_f32_e32 v7, 1.0, v7
	v_cvt_pk_bf16_f32 v5, v5, v6
	v_mul_f32_e32 v6, 0xbfb8aa3b, v1
	v_rcp_f32_e32 v7, v7
	v_exp_f32_e32 v6, v6
	v_mul_f32_e32 v0, v0, v7
	v_lshlrev_b32_e32 v7, 16, v66
	v_add_f32_e32 v6, 1.0, v6
	v_mul_f32_e32 v0, v0, v7
	v_rcp_f32_e32 v6, v6
	v_mul_f32_e32 v7, 0xbfb8aa3b, v2
	v_exp_f32_e32 v7, v7
	v_mul_f32_e32 v0, v0, v19
	v_mul_f32_e32 v1, v1, v6
	v_and_b32_e32 v6, 0xffff0000, v66
	v_mul_f32_e32 v1, v1, v6
	v_add_f32_e32 v6, 1.0, v7
	v_rcp_f32_e32 v7, v6
	v_mul_f32_e32 v6, 0xbfb8aa3b, v3
	v_exp_f32_e32 v8, v6
	v_mul_f32_e32 v1, v1, v19
	v_cvt_pk_bf16_f32 v6, v0, v1
	v_mul_f32_e32 v0, v2, v7
	v_add_f32_e32 v1, 1.0, v8
	v_rcp_f32_e32 v1, v1
	v_lshlrev_b32_e32 v2, 16, v67
	v_mul_f32_e32 v0, v0, v2
	v_and_b32_e32 v2, 0xffff0000, v67
	v_mul_f32_e32 v1, v3, v1
	v_mul_f32_e32 v1, v1, v2
	v_mul_f32_e32 v0, v0, v19
	v_mul_f32_e32 v1, v1, v19
	v_cvt_pk_bf16_f32 v7, v0, v1
	global_store_dwordx4 v[16:17], v[4:7], off offset:256
	s_cbranch_vccz .LBB0_80
	s_waitcnt vmcnt(0)
	s_cmpk_gt_u32 s21, 0xff
	s_cbranch_scc1 .LBB0_91
	s_barrier

.LBB0_199:
	v_mov_b64_e32 v[0:1], 0x1000
	s_ashr_i32 s9, s8, 31
	v_cmp_lt_i64_e32 vcc, s[10:11], v[0:1]
	s_lshl_b64 s[10:11], s[8:9], 20
	s_add_u32 s10, s23, s10
	s_addc_u32 s11, s24, s11
	s_and_b64 s[12:13], vcc, exec
	s_cselect_b32 s5, s11, s15
	s_cselect_b32 s9, s10, s14
	s_ashr_i32 s7, s6, 31
	s_lshl_b64 s[12:13], s[6:7], 20
	s_add_u32 s12, s25, s12
	s_addc_u32 s13, s26, s13
	s_and_b64 s[18:19], vcc, exec
	s_cselect_b32 s7, s13, s17
	s_cselect_b32 s37, s12, s16
	s_add_u32 s14, s14, 0x80080
	s_addc_u32 s15, s15, 0
	s_add_u32 s38, s16, 0x100
	s_addc_u32 s39, s17, 0
	s_mov_b32 s40, -2
	s_mov_b64 s[48:49], 0x80
	v_add_u32_e32 v222, 0x10000, v238
	s_add_u32 s16, s14, 0xfff80080
	s_addc_u32 s17, s15, -1
	s_add_i32 s41, 0, 0x10000
	ds_read_b128 v[128:131], v222 offset:0
	ds_read_b128 v[132:135], v222 offset:1024
	ds_read_b128 v[136:139], v222 offset:2048
	ds_read_b128 v[140:143], v222 offset:3072
	s_cmp_eq_u32 s40, 28
	s_cselect_b32 s19, s5, s17
	s_cselect_b32 s18, s9, s16
	s_cselect_b32 s17, s7, s39
	s_cselect_b32 s16, s37, s38
	s_add_i32 m0, s28, 0xc000
	ds_read_b128 v[144:147], v240
	ds_read_b128 v[148:151], v240 offset:1024
	ds_read_b128 v[152:155], v240 offset:2048
	ds_read_b128 v[156:159], v240 offset:3072
	ds_read_b128 v[160:163], v240 offset:4096
	ds_read_b128 v[164:167], v240 offset:5120
	ds_read_b128 v[168:171], v240 offset:6144
	ds_read_b128 v[172:175], v240 offset:7168
	global_load_lds_dwordx4 v218, s[14:15]
	s_add_i32 m0, s28, 0xe000
	s_nop 0
	global_load_lds_dwordx4 v220, s[14:15]
	s_waitcnt lgkmcnt(8)
	s_barrier
	s_waitcnt lgkmcnt(0)
	v_mfma_f32_16x16x32_bf16 v[124:127], v[128:131], v[144:147], 0
	v_mfma_f32_16x16x32_bf16 v[120:123], v[136:139], v[144:147], 0
	v_mfma_f32_16x16x32_bf16 v[116:119], v[128:131], v[152:155], 0
	v_mfma_f32_16x16x32_bf16 v[108:111], v[136:139], v[152:155], 0
	s_add_i32 s44, 0, 0x14000
	s_add_i32 s41, s41, s27
	v_mfma_f32_16x16x32_bf16 v[100:103], v[128:131], v[160:163], 0
	s_mov_b32 m0, s41
	v_mfma_f32_16x16x32_bf16 v[92:95], v[136:139], v[160:163], 0
	v_mfma_f32_16x16x32_bf16 v[84:87], v[128:131], v[168:171], 0
	v_mfma_f32_16x16x32_bf16 v[76:79], v[136:139], v[168:171], 0
	v_mfma_f32_16x16x32_bf16 v[124:127], v[132:135], v[148:151], v[124:127]
	v_mfma_f32_16x16x32_bf16 v[120:123], v[140:143], v[148:151], v[120:123]
	v_mfma_f32_16x16x32_bf16 v[116:119], v[132:135], v[156:159], v[116:119]
	v_mfma_f32_16x16x32_bf16 v[108:111], v[140:143], v[156:159], v[108:111]
	v_mfma_f32_16x16x32_bf16 v[100:103], v[132:135], v[164:167], v[100:103]
	v_mfma_f32_16x16x32_bf16 v[92:95], v[140:143], v[164:167], v[92:95]
	v_mfma_f32_16x16x32_bf16 v[84:87], v[132:135], v[172:175], v[84:87]
	v_mfma_f32_16x16x32_bf16 v[76:79], v[140:143], v[172:175], v[76:79]
	s_barrier
	ds_read_b128 v[176:179], v222 offset:16384
	ds_read_b128 v[180:183], v222 offset:17408
	ds_read_b128 v[184:187], v222 offset:18432
	ds_read_b128 v[188:191], v222 offset:19456
	global_load_lds_dwordx4 v206, s[16:17]
	s_add_i32 m0, s41, 0x2000
	s_nop 0
	global_load_lds_dwordx4 v210, s[16:17]
	s_barrier
	s_waitcnt lgkmcnt(0)
	v_mfma_f32_16x16x32_bf16 v[112:115], v[176:179], v[144:147], 0
	v_mfma_f32_16x16x32_bf16 v[104:107], v[184:187], v[144:147], 0
	v_mfma_f32_16x16x32_bf16 v[96:99], v[176:179], v[152:155], 0
	v_mfma_f32_16x16x32_bf16 v[88:91], v[184:187], v[152:155], 0
	s_mov_b32 m0, s28
	v_mfma_f32_16x16x32_bf16 v[80:83], v[176:179], v[160:163], 0
	s_add_u32 s48, s18, 0x80
	s_addc_u32 s49, s19, 0
	v_mfma_f32_16x16x32_bf16 v[72:75], v[184:187], v[160:163], 0
	v_mfma_f32_16x16x32_bf16 v[68:71], v[176:179], v[168:171], 0
	v_mfma_f32_16x16x32_bf16 v[64:67], v[184:187], v[168:171], 0
	v_mfma_f32_16x16x32_bf16 v[112:115], v[180:183], v[148:151], v[112:115]
	v_mfma_f32_16x16x32_bf16 v[104:107], v[188:191], v[148:151], v[104:107]
	v_mfma_f32_16x16x32_bf16 v[96:99], v[180:183], v[156:159], v[96:99]
	v_mfma_f32_16x16x32_bf16 v[88:91], v[188:191], v[156:159], v[88:91]
	v_mfma_f32_16x16x32_bf16 v[80:83], v[180:183], v[164:167], v[80:83]
	v_mfma_f32_16x16x32_bf16 v[72:75], v[188:191], v[164:167], v[72:75]
	v_mfma_f32_16x16x32_bf16 v[68:71], v[180:183], v[172:175], v[68:71]
	v_mfma_f32_16x16x32_bf16 v[64:67], v[188:191], v[172:175], v[64:67]
	s_barrier
	ds_read_b128 v[144:147], v240 offset:16384
	ds_read_b128 v[148:151], v240 offset:17408
	ds_read_b128 v[152:155], v240 offset:18432
	ds_read_b128 v[156:159], v240 offset:19456
	ds_read_b128 v[160:163], v240 offset:20480
	ds_read_b128 v[164:167], v240 offset:21504
	ds_read_b128 v[168:171], v240 offset:22528
	ds_read_b128 v[172:175], v240 offset:23552
	global_load_lds_dwordx4 v204, s[18:19]
	s_mov_b32 m0, s29
	s_nop 0
	global_load_lds_dwordx4 v208, s[18:19]
	s_barrier
	s_waitcnt lgkmcnt(0)
	v_mfma_f32_16x16x32_bf16 v[60:63], v[128:131], v[144:147], 0
	v_mfma_f32_16x16x32_bf16 v[56:59], v[136:139], v[144:147], 0
	v_mfma_f32_16x16x32_bf16 v[52:55], v[128:131], v[152:155], 0
	v_mfma_f32_16x16x32_bf16 v[44:47], v[136:139], v[152:155], 0
	s_add_u32 s42, s16, 0x80000
	s_addc_u32 s43, s17, 0
	v_mfma_f32_16x16x32_bf16 v[36:39], v[128:131], v[160:163], 0
	s_add_i32 s41, s44, s27
	s_mov_b32 m0, s41
	v_mfma_f32_16x16x32_bf16 v[28:31], v[136:139], v[160:163], 0
	v_mfma_f32_16x16x32_bf16 v[20:23], v[128:131], v[168:171], 0
	v_mfma_f32_16x16x32_bf16 v[12:15], v[136:139], v[168:171], 0
	v_mfma_f32_16x16x32_bf16 v[60:63], v[132:135], v[148:151], v[60:63]
	v_mfma_f32_16x16x32_bf16 v[56:59], v[140:143], v[148:151], v[56:59]
	v_mfma_f32_16x16x32_bf16 v[52:55], v[132:135], v[156:159], v[52:55]
	v_mfma_f32_16x16x32_bf16 v[44:47], v[140:143], v[156:159], v[44:47]
	v_mfma_f32_16x16x32_bf16 v[36:39], v[132:135], v[164:167], v[36:39]
	v_mfma_f32_16x16x32_bf16 v[28:31], v[140:143], v[164:167], v[28:31]
	v_mfma_f32_16x16x32_bf16 v[20:23], v[132:135], v[172:175], v[20:23]
	v_mfma_f32_16x16x32_bf16 v[12:15], v[140:143], v[172:175], v[12:15]
	s_barrier
	global_load_lds_dwordx4 v206, s[42:43]
	s_add_i32 m0, s41, 0x2000
	s_nop 0
	global_load_lds_dwordx4 v210, s[42:43]
	s_waitcnt vmcnt(6)
	s_barrier
	v_mfma_f32_16x16x32_bf16 v[48:51], v[176:179], v[144:147], 0
	v_mfma_f32_16x16x32_bf16 v[40:43], v[184:187], v[144:147], 0
	v_mfma_f32_16x16x32_bf16 v[32:35], v[176:179], v[152:155], 0
	v_mfma_f32_16x16x32_bf16 v[24:27], v[184:187], v[152:155], 0
	s_add_i32 s41, 0, 0x18000
	v_mfma_f32_16x16x32_bf16 v[16:19], v[176:179], v[160:163], 0
	s_add_u32 s18, s18, 0x80000
	s_addc_u32 s19, s19, 0
	v_mfma_f32_16x16x32_bf16 v[8:11], v[184:187], v[160:163], 0
	s_mov_b32 m0, s30
	v_mfma_f32_16x16x32_bf16 v[4:7], v[176:179], v[168:171], 0
	v_mfma_f32_16x16x32_bf16 v[0:3], v[184:187], v[168:171], 0
	v_mfma_f32_16x16x32_bf16 v[48:51], v[180:183], v[148:151], v[48:51]
	v_mfma_f32_16x16x32_bf16 v[40:43], v[188:191], v[148:151], v[40:43]
	v_mfma_f32_16x16x32_bf16 v[32:35], v[180:183], v[156:159], v[32:35]
	v_mfma_f32_16x16x32_bf16 v[24:27], v[188:191], v[156:159], v[24:27]
	v_mfma_f32_16x16x32_bf16 v[16:19], v[180:183], v[164:167], v[16:19]
	v_mfma_f32_16x16x32_bf16 v[8:11], v[188:191], v[164:167], v[8:11]
	v_mfma_f32_16x16x32_bf16 v[4:7], v[180:183], v[172:175], v[4:7]
	v_mfma_f32_16x16x32_bf16 v[0:3], v[188:191], v[172:175], v[0:3]
	s_barrier
	ds_read_b128 v[128:131], v222 offset:32768
	ds_read_b128 v[132:135], v222 offset:33792
	ds_read_b128 v[136:139], v222 offset:34816
	ds_read_b128 v[140:143], v222 offset:35840
	ds_read_b128 v[144:147], v240 offset:32768
	ds_read_b128 v[148:151], v240 offset:33792
	ds_read_b128 v[152:155], v240 offset:34816
	ds_read_b128 v[156:159], v240 offset:35840
	ds_read_b128 v[160:163], v240 offset:36864
	ds_read_b128 v[164:167], v240 offset:37888
	ds_read_b128 v[168:171], v240 offset:38912
	ds_read_b128 v[172:175], v240 offset:39936
	global_load_lds_dwordx4 v204, s[18:19]
	s_mov_b32 m0, s31
	s_nop 0
	global_load_lds_dwordx4 v208, s[18:19]
	s_waitcnt lgkmcnt(8)
	s_barrier
	s_waitcnt lgkmcnt(0)
	v_mfma_f32_16x16x32_bf16 v[124:127], v[128:131], v[144:147], v[124:127]
	v_mfma_f32_16x16x32_bf16 v[120:123], v[136:139], v[144:147], v[120:123]
	v_mfma_f32_16x16x32_bf16 v[116:119], v[128:131], v[152:155], v[116:119]
	v_mfma_f32_16x16x32_bf16 v[108:111], v[136:139], v[152:155], v[108:111]
	s_add_i32 s18, 0, 0x1c000
	s_add_i32 s19, s41, s27
	v_mfma_f32_16x16x32_bf16 v[100:103], v[128:131], v[160:163], v[100:103]
	s_add_i32 m0, s19, 0xffffff80
	v_mfma_f32_16x16x32_bf16 v[92:95], v[136:139], v[160:163], v[92:95]
	v_mfma_f32_16x16x32_bf16 v[84:87], v[128:131], v[168:171], v[84:87]
	v_mfma_f32_16x16x32_bf16 v[76:79], v[136:139], v[168:171], v[76:79]
	v_mfma_f32_16x16x32_bf16 v[124:127], v[132:135], v[148:151], v[124:127]
	v_mfma_f32_16x16x32_bf16 v[120:123], v[140:143], v[148:151], v[120:123]
	v_mfma_f32_16x16x32_bf16 v[116:119], v[132:135], v[156:159], v[116:119]
	v_mfma_f32_16x16x32_bf16 v[108:111], v[140:143], v[156:159], v[108:111]
	v_mfma_f32_16x16x32_bf16 v[100:103], v[132:135], v[164:167], v[100:103]
	v_mfma_f32_16x16x32_bf16 v[92:95], v[140:143], v[164:167], v[92:95]
	v_mfma_f32_16x16x32_bf16 v[84:87], v[132:135], v[172:175], v[84:87]
	v_mfma_f32_16x16x32_bf16 v[76:79], v[140:143], v[172:175], v[76:79]
	s_barrier
	ds_read_b128 v[176:179], v222 offset:49152
	ds_read_b128 v[180:183], v222 offset:50176
	ds_read_b128 v[184:187], v222 offset:51200
	ds_read_b128 v[188:191], v222 offset:52224
	global_load_lds_dwordx4 v206, s[16:17] offset:128
	s_add_i32 m0, s19, 0x1f80
	s_nop 0
	global_load_lds_dwordx4 v210, s[16:17] offset:128
	s_barrier
	s_waitcnt lgkmcnt(0)
	v_mfma_f32_16x16x32_bf16 v[112:115], v[176:179], v[144:147], v[112:115]
	v_mfma_f32_16x16x32_bf16 v[104:107], v[184:187], v[144:147], v[104:107]
	v_mfma_f32_16x16x32_bf16 v[96:99], v[176:179], v[152:155], v[96:99]
	v_mfma_f32_16x16x32_bf16 v[88:91], v[184:187], v[152:155], v[88:91]
	s_mov_b32 m0, s33
	v_mfma_f32_16x16x32_bf16 v[80:83], v[176:179], v[160:163], v[80:83]
	v_mfma_f32_16x16x32_bf16 v[72:75], v[184:187], v[160:163], v[72:75]
	v_mfma_f32_16x16x32_bf16 v[68:71], v[176:179], v[168:171], v[68:71]
	v_mfma_f32_16x16x32_bf16 v[64:67], v[184:187], v[168:171], v[64:67]
	v_mfma_f32_16x16x32_bf16 v[112:115], v[180:183], v[148:151], v[112:115]
	v_mfma_f32_16x16x32_bf16 v[104:107], v[188:191], v[148:151], v[104:107]
	v_mfma_f32_16x16x32_bf16 v[96:99], v[180:183], v[156:159], v[96:99]
	v_mfma_f32_16x16x32_bf16 v[88:91], v[188:191], v[156:159], v[88:91]
	v_mfma_f32_16x16x32_bf16 v[80:83], v[180:183], v[164:167], v[80:83]
	v_mfma_f32_16x16x32_bf16 v[72:75], v[188:191], v[164:167], v[72:75]
	v_mfma_f32_16x16x32_bf16 v[68:71], v[180:183], v[172:175], v[68:71]
	v_mfma_f32_16x16x32_bf16 v[64:67], v[188:191], v[172:175], v[64:67]
	s_barrier
	ds_read_b128 v[144:147], v240 offset:49152
	ds_read_b128 v[148:151], v240 offset:50176
	ds_read_b128 v[152:155], v240 offset:51200
	ds_read_b128 v[156:159], v240 offset:52224
	ds_read_b128 v[160:163], v240 offset:53248
	ds_read_b128 v[164:167], v240 offset:54272
	ds_read_b128 v[168:171], v240 offset:55296
	ds_read_b128 v[172:175], v240 offset:56320
	global_load_lds_dwordx4 v204, s[48:49]
	s_mov_b32 m0, s34
	s_nop 0
	global_load_lds_dwordx4 v208, s[48:49]
	s_barrier
	s_waitcnt lgkmcnt(0)
	v_mfma_f32_16x16x32_bf16 v[60:63], v[128:131], v[144:147], v[60:63]
	v_mfma_f32_16x16x32_bf16 v[56:59], v[136:139], v[144:147], v[56:59]
	v_mfma_f32_16x16x32_bf16 v[52:55], v[128:131], v[152:155], v[52:55]
	v_mfma_f32_16x16x32_bf16 v[44:47], v[136:139], v[152:155], v[44:47]
	s_add_u32 s16, s16, 0x80080
	s_addc_u32 s17, s17, 0
	v_mfma_f32_16x16x32_bf16 v[36:39], v[128:131], v[160:163], v[36:39]
	s_add_i32 s18, s18, s27
	s_mov_b32 m0, s18
	v_mfma_f32_16x16x32_bf16 v[28:31], v[136:139], v[160:163], v[28:31]
	v_mfma_f32_16x16x32_bf16 v[20:23], v[128:131], v[168:171], v[20:23]
	v_mfma_f32_16x16x32_bf16 v[12:15], v[136:139], v[168:171], v[12:15]
	v_mfma_f32_16x16x32_bf16 v[60:63], v[132:135], v[148:151], v[60:63]
	v_mfma_f32_16x16x32_bf16 v[56:59], v[140:143], v[148:151], v[56:59]
	v_mfma_f32_16x16x32_bf16 v[52:55], v[132:135], v[156:159], v[52:55]
	v_mfma_f32_16x16x32_bf16 v[44:47], v[140:143], v[156:159], v[44:47]
	v_mfma_f32_16x16x32_bf16 v[36:39], v[132:135], v[164:167], v[36:39]
	v_mfma_f32_16x16x32_bf16 v[28:31], v[140:143], v[164:167], v[28:31]
	v_mfma_f32_16x16x32_bf16 v[20:23], v[132:135], v[172:175], v[20:23]
	v_mfma_f32_16x16x32_bf16 v[12:15], v[140:143], v[172:175], v[12:15]
	s_barrier
	global_load_lds_dwordx4 v206, s[16:17]
	s_add_i32 m0, s18, 0x2000
	s_nop 0
	global_load_lds_dwordx4 v210, s[16:17]
	s_waitcnt vmcnt(6)
	s_barrier
	v_mfma_f32_16x16x32_bf16 v[48:51], v[176:179], v[144:147], v[48:51]
	v_mfma_f32_16x16x32_bf16 v[40:43], v[184:187], v[144:147], v[40:43]
	v_mfma_f32_16x16x32_bf16 v[32:35], v[176:179], v[152:155], v[32:35]
	v_mfma_f32_16x16x32_bf16 v[24:27], v[184:187], v[152:155], v[24:27]
	s_add_i32 s40, s40, 2
	v_mfma_f32_16x16x32_bf16 v[16:19], v[176:179], v[160:163], v[16:19]
	s_add_u32 s14, s14, 0x100
	s_addc_u32 s15, s15, 0
	v_mfma_f32_16x16x32_bf16 v[8:11], v[184:187], v[160:163], v[8:11]
	s_add_u32 s38, s38, 0x100
	s_addc_u32 s39, s39, 0
	v_mfma_f32_16x16x32_bf16 v[4:7], v[176:179], v[168:171], v[4:7]
	s_add_u32 s16, s14, 0xfff80080
	s_addc_u32 s17, s15, -1
	v_mfma_f32_16x16x32_bf16 v[0:3], v[184:187], v[168:171], v[0:3]
	s_add_i32 s41, 0, 0x10000
	s_cmp_eq_u32 s40, 28
	v_mfma_f32_16x16x32_bf16 v[48:51], v[180:183], v[148:151], v[48:51]
	s_cselect_b32 s19, s5, s17
	s_cselect_b32 s18, s9, s16
	v_mfma_f32_16x16x32_bf16 v[40:43], v[188:191], v[148:151], v[40:43]
	s_cselect_b32 s17, s7, s39
	s_cselect_b32 s16, s37, s38
	v_mfma_f32_16x16x32_bf16 v[32:35], v[180:183], v[156:159], v[32:35]
	s_add_i32 m0, s28, 0xc000
	v_mfma_f32_16x16x32_bf16 v[24:27], v[188:191], v[156:159], v[24:27]
	v_mfma_f32_16x16x32_bf16 v[16:19], v[180:183], v[164:167], v[16:19]
	v_mfma_f32_16x16x32_bf16 v[8:11], v[188:191], v[164:167], v[8:11]
	v_mfma_f32_16x16x32_bf16 v[4:7], v[180:183], v[172:175], v[4:7]
	v_mfma_f32_16x16x32_bf16 v[0:3], v[188:191], v[172:175], v[0:3]
	s_cmp_gt_u32 s40, 29
	s_barrier
.LBB0_200:
	ds_read_b128 v[128:131], v222 offset:0
	ds_read_b128 v[132:135], v222 offset:1024
	ds_read_b128 v[136:139], v222 offset:2048
	ds_read_b128 v[140:143], v222 offset:3072
	ds_read_b128 v[144:147], v240
	ds_read_b128 v[148:151], v240 offset:1024
	ds_read_b128 v[152:155], v240 offset:2048
	ds_read_b128 v[156:159], v240 offset:3072
	ds_read_b128 v[160:163], v240 offset:4096
	ds_read_b128 v[164:167], v240 offset:5120
	ds_read_b128 v[168:171], v240 offset:6144
	ds_read_b128 v[172:175], v240 offset:7168
	global_load_lds_dwordx4 v218, s[14:15]
	s_add_i32 m0, s28, 0xe000
	s_nop 0
	global_load_lds_dwordx4 v220, s[14:15]
	s_waitcnt lgkmcnt(8)
	s_barrier
	s_waitcnt lgkmcnt(0)
	v_mfma_f32_16x16x32_bf16 v[124:127], v[128:131], v[144:147], v[124:127]
	v_mfma_f32_16x16x32_bf16 v[120:123], v[136:139], v[144:147], v[120:123]
	v_mfma_f32_16x16x32_bf16 v[116:119], v[128:131], v[152:155], v[116:119]
	v_mfma_f32_16x16x32_bf16 v[108:111], v[136:139], v[152:155], v[108:111]
	s_add_i32 s44, 0, 0x14000
	s_add_i32 s41, s41, s27
	v_mfma_f32_16x16x32_bf16 v[100:103], v[128:131], v[160:163], v[100:103]
	s_mov_b32 m0, s41
	v_mfma_f32_16x16x32_bf16 v[92:95], v[136:139], v[160:163], v[92:95]
	v_mfma_f32_16x16x32_bf16 v[84:87], v[128:131], v[168:171], v[84:87]
	v_mfma_f32_16x16x32_bf16 v[76:79], v[136:139], v[168:171], v[76:79]
	v_mfma_f32_16x16x32_bf16 v[124:127], v[132:135], v[148:151], v[124:127]
	v_mfma_f32_16x16x32_bf16 v[120:123], v[140:143], v[148:151], v[120:123]
	v_mfma_f32_16x16x32_bf16 v[116:119], v[132:135], v[156:159], v[116:119]
	v_mfma_f32_16x16x32_bf16 v[108:111], v[140:143], v[156:159], v[108:111]
	v_mfma_f32_16x16x32_bf16 v[100:103], v[132:135], v[164:167], v[100:103]
	v_mfma_f32_16x16x32_bf16 v[92:95], v[140:143], v[164:167], v[92:95]
	v_mfma_f32_16x16x32_bf16 v[84:87], v[132:135], v[172:175], v[84:87]
	v_mfma_f32_16x16x32_bf16 v[76:79], v[140:143], v[172:175], v[76:79]
	s_barrier
	ds_read_b128 v[176:179], v222 offset:16384
	ds_read_b128 v[180:183], v222 offset:17408
	ds_read_b128 v[184:187], v222 offset:18432
	ds_read_b128 v[188:191], v222 offset:19456
	global_load_lds_dwordx4 v206, s[16:17]
	s_add_i32 m0, s41, 0x2000
	s_nop 0
	global_load_lds_dwordx4 v210, s[16:17]
	s_barrier
	s_waitcnt lgkmcnt(0)
	v_mfma_f32_16x16x32_bf16 v[112:115], v[176:179], v[144:147], v[112:115]
	v_mfma_f32_16x16x32_bf16 v[104:107], v[184:187], v[144:147], v[104:107]
	v_mfma_f32_16x16x32_bf16 v[96:99], v[176:179], v[152:155], v[96:99]
	v_mfma_f32_16x16x32_bf16 v[88:91], v[184:187], v[152:155], v[88:91]
	s_mov_b32 m0, s28
	v_mfma_f32_16x16x32_bf16 v[80:83], v[176:179], v[160:163], v[80:83]
	s_add_u32 s48, s18, 0x80
	s_addc_u32 s49, s19, 0
	v_mfma_f32_16x16x32_bf16 v[72:75], v[184:187], v[160:163], v[72:75]
	v_mfma_f32_16x16x32_bf16 v[68:71], v[176:179], v[168:171], v[68:71]
	v_mfma_f32_16x16x32_bf16 v[64:67], v[184:187], v[168:171], v[64:67]
	v_mfma_f32_16x16x32_bf16 v[112:115], v[180:183], v[148:151], v[112:115]
	v_mfma_f32_16x16x32_bf16 v[104:107], v[188:191], v[148:151], v[104:107]
	v_mfma_f32_16x16x32_bf16 v[96:99], v[180:183], v[156:159], v[96:99]
	v_mfma_f32_16x16x32_bf16 v[88:91], v[188:191], v[156:159], v[88:91]
	v_mfma_f32_16x16x32_bf16 v[80:83], v[180:183], v[164:167], v[80:83]
	v_mfma_f32_16x16x32_bf16 v[72:75], v[188:191], v[164:167], v[72:75]
	v_mfma_f32_16x16x32_bf16 v[68:71], v[180:183], v[172:175], v[68:71]
	v_mfma_f32_16x16x32_bf16 v[64:67], v[188:191], v[172:175], v[64:67]
	s_barrier
	ds_read_b128 v[144:147], v240 offset:16384
	ds_read_b128 v[148:151], v240 offset:17408
	ds_read_b128 v[152:155], v240 offset:18432
	ds_read_b128 v[156:159], v240 offset:19456
	ds_read_b128 v[160:163], v240 offset:20480
	ds_read_b128 v[164:167], v240 offset:21504
	ds_read_b128 v[168:171], v240 offset:22528
	ds_read_b128 v[172:175], v240 offset:23552
	global_load_lds_dwordx4 v204, s[18:19]
	s_mov_b32 m0, s29
	s_nop 0
	global_load_lds_dwordx4 v208, s[18:19]
	s_barrier
	s_waitcnt lgkmcnt(0)
	v_mfma_f32_16x16x32_bf16 v[60:63], v[128:131], v[144:147], v[60:63]
	v_mfma_f32_16x16x32_bf16 v[56:59], v[136:139], v[144:147], v[56:59]
	v_mfma_f32_16x16x32_bf16 v[52:55], v[128:131], v[152:155], v[52:55]
	v_mfma_f32_16x16x32_bf16 v[44:47], v[136:139], v[152:155], v[44:47]
	s_add_u32 s42, s16, 0x80000
	s_addc_u32 s43, s17, 0
	v_mfma_f32_16x16x32_bf16 v[36:39], v[128:131], v[160:163], v[36:39]
	s_add_i32 s41, s44, s27
	s_mov_b32 m0, s41
	v_mfma_f32_16x16x32_bf16 v[28:31], v[136:139], v[160:163], v[28:31]
	v_mfma_f32_16x16x32_bf16 v[20:23], v[128:131], v[168:171], v[20:23]
	v_mfma_f32_16x16x32_bf16 v[12:15], v[136:139], v[168:171], v[12:15]
	v_mfma_f32_16x16x32_bf16 v[60:63], v[132:135], v[148:151], v[60:63]
	v_mfma_f32_16x16x32_bf16 v[56:59], v[140:143], v[148:151], v[56:59]
	v_mfma_f32_16x16x32_bf16 v[52:55], v[132:135], v[156:159], v[52:55]
	v_mfma_f32_16x16x32_bf16 v[44:47], v[140:143], v[156:159], v[44:47]
	v_mfma_f32_16x16x32_bf16 v[36:39], v[132:135], v[164:167], v[36:39]
	v_mfma_f32_16x16x32_bf16 v[28:31], v[140:143], v[164:167], v[28:31]
	v_mfma_f32_16x16x32_bf16 v[20:23], v[132:135], v[172:175], v[20:23]
	v_mfma_f32_16x16x32_bf16 v[12:15], v[140:143], v[172:175], v[12:15]
	s_barrier
	global_load_lds_dwordx4 v206, s[42:43]
	s_add_i32 m0, s41, 0x2000
	s_nop 0
	global_load_lds_dwordx4 v210, s[42:43]
	s_waitcnt vmcnt(6)
	s_barrier
	v_mfma_f32_16x16x32_bf16 v[48:51], v[176:179], v[144:147], v[48:51]
	v_mfma_f32_16x16x32_bf16 v[40:43], v[184:187], v[144:147], v[40:43]
	v_mfma_f32_16x16x32_bf16 v[32:35], v[176:179], v[152:155], v[32:35]
	v_mfma_f32_16x16x32_bf16 v[24:27], v[184:187], v[152:155], v[24:27]
	s_add_i32 s41, 0, 0x18000
	v_mfma_f32_16x16x32_bf16 v[16:19], v[176:179], v[160:163], v[16:19]
	s_add_u32 s18, s18, 0x80000
	s_addc_u32 s19, s19, 0
	v_mfma_f32_16x16x32_bf16 v[8:11], v[184:187], v[160:163], v[8:11]
	s_mov_b32 m0, s30
	v_mfma_f32_16x16x32_bf16 v[4:7], v[176:179], v[168:171], v[4:7]
	v_mfma_f32_16x16x32_bf16 v[0:3], v[184:187], v[168:171], v[0:3]
	v_mfma_f32_16x16x32_bf16 v[48:51], v[180:183], v[148:151], v[48:51]
	v_mfma_f32_16x16x32_bf16 v[40:43], v[188:191], v[148:151], v[40:43]
	v_mfma_f32_16x16x32_bf16 v[32:35], v[180:183], v[156:159], v[32:35]
	v_mfma_f32_16x16x32_bf16 v[24:27], v[188:191], v[156:159], v[24:27]
	v_mfma_f32_16x16x32_bf16 v[16:19], v[180:183], v[164:167], v[16:19]
	v_mfma_f32_16x16x32_bf16 v[8:11], v[188:191], v[164:167], v[8:11]
	v_mfma_f32_16x16x32_bf16 v[4:7], v[180:183], v[172:175], v[4:7]
	v_mfma_f32_16x16x32_bf16 v[0:3], v[188:191], v[172:175], v[0:3]
	s_barrier
	ds_read_b128 v[128:131], v222 offset:32768
	ds_read_b128 v[132:135], v222 offset:33792
	ds_read_b128 v[136:139], v222 offset:34816
	ds_read_b128 v[140:143], v222 offset:35840
	ds_read_b128 v[144:147], v240 offset:32768
	ds_read_b128 v[148:151], v240 offset:33792
	ds_read_b128 v[152:155], v240 offset:34816
	ds_read_b128 v[156:159], v240 offset:35840
	ds_read_b128 v[160:163], v240 offset:36864
	ds_read_b128 v[164:167], v240 offset:37888
	ds_read_b128 v[168:171], v240 offset:38912
	ds_read_b128 v[172:175], v240 offset:39936
	global_load_lds_dwordx4 v204, s[18:19]
	s_mov_b32 m0, s31
	s_nop 0
	global_load_lds_dwordx4 v208, s[18:19]
	s_waitcnt lgkmcnt(8)
	s_barrier
	s_waitcnt lgkmcnt(0)
	v_mfma_f32_16x16x32_bf16 v[124:127], v[128:131], v[144:147], v[124:127]
	v_mfma_f32_16x16x32_bf16 v[120:123], v[136:139], v[144:147], v[120:123]
	v_mfma_f32_16x16x32_bf16 v[116:119], v[128:131], v[152:155], v[116:119]
	v_mfma_f32_16x16x32_bf16 v[108:111], v[136:139], v[152:155], v[108:111]
	s_add_i32 s18, 0, 0x1c000
	s_add_i32 s19, s41, s27
	v_mfma_f32_16x16x32_bf16 v[100:103], v[128:131], v[160:163], v[100:103]
	s_add_i32 m0, s19, 0xffffff80
	v_mfma_f32_16x16x32_bf16 v[92:95], v[136:139], v[160:163], v[92:95]
	v_mfma_f32_16x16x32_bf16 v[84:87], v[128:131], v[168:171], v[84:87]
	v_mfma_f32_16x16x32_bf16 v[76:79], v[136:139], v[168:171], v[76:79]
	v_mfma_f32_16x16x32_bf16 v[124:127], v[132:135], v[148:151], v[124:127]
	v_mfma_f32_16x16x32_bf16 v[120:123], v[140:143], v[148:151], v[120:123]
	v_mfma_f32_16x16x32_bf16 v[116:119], v[132:135], v[156:159], v[116:119]
	v_mfma_f32_16x16x32_bf16 v[108:111], v[140:143], v[156:159], v[108:111]
	v_mfma_f32_16x16x32_bf16 v[100:103], v[132:135], v[164:167], v[100:103]
	v_mfma_f32_16x16x32_bf16 v[92:95], v[140:143], v[164:167], v[92:95]
	v_mfma_f32_16x16x32_bf16 v[84:87], v[132:135], v[172:175], v[84:87]
	v_mfma_f32_16x16x32_bf16 v[76:79], v[140:143], v[172:175], v[76:79]
	s_barrier
	ds_read_b128 v[176:179], v222 offset:49152
	ds_read_b128 v[180:183], v222 offset:50176
	ds_read_b128 v[184:187], v222 offset:51200
	ds_read_b128 v[188:191], v222 offset:52224
	global_load_lds_dwordx4 v206, s[16:17] offset:128
	s_add_i32 m0, s19, 0x1f80
	s_nop 0
	global_load_lds_dwordx4 v210, s[16:17] offset:128
	s_barrier
	s_waitcnt lgkmcnt(0)
	v_mfma_f32_16x16x32_bf16 v[112:115], v[176:179], v[144:147], v[112:115]
	v_mfma_f32_16x16x32_bf16 v[104:107], v[184:187], v[144:147], v[104:107]
	v_mfma_f32_16x16x32_bf16 v[96:99], v[176:179], v[152:155], v[96:99]
	v_mfma_f32_16x16x32_bf16 v[88:91], v[184:187], v[152:155], v[88:91]
	s_mov_b32 m0, s33
	v_mfma_f32_16x16x32_bf16 v[80:83], v[176:179], v[160:163], v[80:83]
	v_mfma_f32_16x16x32_bf16 v[72:75], v[184:187], v[160:163], v[72:75]
	v_mfma_f32_16x16x32_bf16 v[68:71], v[176:179], v[168:171], v[68:71]
	v_mfma_f32_16x16x32_bf16 v[64:67], v[184:187], v[168:171], v[64:67]
	v_mfma_f32_16x16x32_bf16 v[112:115], v[180:183], v[148:151], v[112:115]
	v_mfma_f32_16x16x32_bf16 v[104:107], v[188:191], v[148:151], v[104:107]
	v_mfma_f32_16x16x32_bf16 v[96:99], v[180:183], v[156:159], v[96:99]
	v_mfma_f32_16x16x32_bf16 v[88:91], v[188:191], v[156:159], v[88:91]
	v_mfma_f32_16x16x32_bf16 v[80:83], v[180:183], v[164:167], v[80:83]
	v_mfma_f32_16x16x32_bf16 v[72:75], v[188:191], v[164:167], v[72:75]
	v_mfma_f32_16x16x32_bf16 v[68:71], v[180:183], v[172:175], v[68:71]
	v_mfma_f32_16x16x32_bf16 v[64:67], v[188:191], v[172:175], v[64:67]
	s_barrier
	ds_read_b128 v[144:147], v240 offset:49152
	ds_read_b128 v[148:151], v240 offset:50176
	ds_read_b128 v[152:155], v240 offset:51200
	ds_read_b128 v[156:159], v240 offset:52224
	ds_read_b128 v[160:163], v240 offset:53248
	ds_read_b128 v[164:167], v240 offset:54272
	ds_read_b128 v[168:171], v240 offset:55296
	ds_read_b128 v[172:175], v240 offset:56320
	global_load_lds_dwordx4 v204, s[48:49]
	s_mov_b32 m0, s34
	s_nop 0
	global_load_lds_dwordx4 v208, s[48:49]
	s_barrier
	s_waitcnt lgkmcnt(0)
	v_mfma_f32_16x16x32_bf16 v[60:63], v[128:131], v[144:147], v[60:63]
	v_mfma_f32_16x16x32_bf16 v[56:59], v[136:139], v[144:147], v[56:59]
	v_mfma_f32_16x16x32_bf16 v[52:55], v[128:131], v[152:155], v[52:55]
	v_mfma_f32_16x16x32_bf16 v[44:47], v[136:139], v[152:155], v[44:47]
	s_add_u32 s16, s16, 0x80080
	s_addc_u32 s17, s17, 0
	v_mfma_f32_16x16x32_bf16 v[36:39], v[128:131], v[160:163], v[36:39]
	s_add_i32 s18, s18, s27
	s_mov_b32 m0, s18
	v_mfma_f32_16x16x32_bf16 v[28:31], v[136:139], v[160:163], v[28:31]
	v_mfma_f32_16x16x32_bf16 v[20:23], v[128:131], v[168:171], v[20:23]
	v_mfma_f32_16x16x32_bf16 v[12:15], v[136:139], v[168:171], v[12:15]
	v_mfma_f32_16x16x32_bf16 v[60:63], v[132:135], v[148:151], v[60:63]
	v_mfma_f32_16x16x32_bf16 v[56:59], v[140:143], v[148:151], v[56:59]
	v_mfma_f32_16x16x32_bf16 v[52:55], v[132:135], v[156:159], v[52:55]
	v_mfma_f32_16x16x32_bf16 v[44:47], v[140:143], v[156:159], v[44:47]
	v_mfma_f32_16x16x32_bf16 v[36:39], v[132:135], v[164:167], v[36:39]
	v_mfma_f32_16x16x32_bf16 v[28:31], v[140:143], v[164:167], v[28:31]
	v_mfma_f32_16x16x32_bf16 v[20:23], v[132:135], v[172:175], v[20:23]
	v_mfma_f32_16x16x32_bf16 v[12:15], v[140:143], v[172:175], v[12:15]
	s_barrier
	global_load_lds_dwordx4 v206, s[16:17]
	s_add_i32 m0, s18, 0x2000
	s_nop 0
	global_load_lds_dwordx4 v210, s[16:17]
	s_waitcnt vmcnt(6)
	s_barrier
	v_mfma_f32_16x16x32_bf16 v[48:51], v[176:179], v[144:147], v[48:51]
	v_mfma_f32_16x16x32_bf16 v[40:43], v[184:187], v[144:147], v[40:43]
	v_mfma_f32_16x16x32_bf16 v[32:35], v[176:179], v[152:155], v[32:35]
	v_mfma_f32_16x16x32_bf16 v[24:27], v[184:187], v[152:155], v[24:27]
	s_add_i32 s40, s40, 2
	v_mfma_f32_16x16x32_bf16 v[16:19], v[176:179], v[160:163], v[16:19]
	s_add_u32 s14, s14, 0x100
	s_addc_u32 s15, s15, 0
	v_mfma_f32_16x16x32_bf16 v[8:11], v[184:187], v[160:163], v[8:11]
	s_add_u32 s38, s38, 0x100
	s_addc_u32 s39, s39, 0
	v_mfma_f32_16x16x32_bf16 v[4:7], v[176:179], v[168:171], v[4:7]
	s_add_u32 s16, s14, 0xfff80080
	s_addc_u32 s17, s15, -1
	v_mfma_f32_16x16x32_bf16 v[0:3], v[184:187], v[168:171], v[0:3]
	s_add_i32 s41, 0, 0x10000
	s_cmp_eq_u32 s40, 28
	v_mfma_f32_16x16x32_bf16 v[48:51], v[180:183], v[148:151], v[48:51]
	s_cselect_b32 s19, s5, s17
	s_cselect_b32 s18, s9, s16
	v_mfma_f32_16x16x32_bf16 v[40:43], v[188:191], v[148:151], v[40:43]
	s_cselect_b32 s17, s7, s39
	s_cselect_b32 s16, s37, s38
	v_mfma_f32_16x16x32_bf16 v[32:35], v[180:183], v[156:159], v[32:35]
	s_add_i32 m0, s28, 0xc000
	v_mfma_f32_16x16x32_bf16 v[24:27], v[188:191], v[156:159], v[24:27]
	v_mfma_f32_16x16x32_bf16 v[16:19], v[180:183], v[164:167], v[16:19]
	v_mfma_f32_16x16x32_bf16 v[8:11], v[188:191], v[164:167], v[8:11]
	v_mfma_f32_16x16x32_bf16 v[4:7], v[180:183], v[172:175], v[4:7]
	v_mfma_f32_16x16x32_bf16 v[0:3], v[188:191], v[172:175], v[0:3]
	s_cmp_gt_u32 s40, 29
	s_barrier
	s_cbranch_scc0 .LBB0_200
	v_lshl_add_u32 v228, s4, 8, v237
	v_or_b32_e32 v226, 16, v228
	s_mov_b64 s[4:5], -1
	s_cmp_lt_i32 s36, 16
	v_ashrrev_i32_e32 v229, 31, v228
	v_lshlrev_b32_e32 v192, 1, v212
	v_ashrrev_i32_e32 v227, 31, v226
	v_or_b32_e32 v224, 32, v228
	v_or_b32_e32 v222, 48, v228
	s_cbranch_scc0 .LBB0_203
	s_and_b32 s7, s36, 7
	s_cmp_gt_i32 s36, 7
	s_cselect_b64 vcc, -1, 0
	s_and_b64 s[4:5], vcc, exec
	s_mov_b32 s4, 0x15000000
	s_cselect_b32 s4, s4, 0xd000000
	s_add_u32 s4, s50, s4
	s_addc_u32 s5, s51, 0
	s_lshl_b32 s9, s7, 9
	s_add_u32 s4, s4, s9
	v_cvt_f32_ubyte0_e32 v128, s7
	s_addc_u32 s5, s5, 0
	v_sub_f32_e32 v128, 0xc0a00000, v128
	s_mov_b32 s7, 0xc2fc0000
	v_lshl_add_u64 v[230:231], s[4:5], 0, v[192:193]
	v_cmp_gt_f32_e64 s[4:5], s7, v128
	v_ashrrev_i32_e32 v225, 31, v224
	s_nop 0
	v_cndmask_b32_e64 v129, 0, v234, s[4:5]
	v_add_f32_e32 v128, v128, v129
	v_exp_f32_e32 v128, v128
	s_and_b64 s[4:5], s[4:5], exec
	s_cselect_b32 s4, 0xffffffc0, 0
	v_mov_b32_e32 v129, v193
	v_ldexp_f32 v128, v128, s4
	v_sub_f32_e32 v128, 1.0, v128
	v_log_f32_e32 v241, v128
	v_lshlrev_b32_e32 v128, 9, v228
	v_and_b32_e32 v128, 0x1f9e00, v128
	v_lshl_add_u64 v[130:131], v[214:215], 0, v[128:129]
	v_lshl_add_u64 v[132:133], v[216:217], 0, v[128:129]
	global_load_dwordx4 v[180:183], v[130:131], off offset:16
	global_load_dwordx4 v[188:191], v[130:131], off
	global_load_dwordx4 v[176:179], v[132:133], off offset:16
	global_load_dwordx4 v[184:187], v[132:133], off
	v_or_b32_e32 v130, 0x2000, v128
	v_mov_b32_e32 v131, v193
	v_lshl_add_u64 v[132:133], v[214:215], 0, v[130:131]
	v_lshl_add_u64 v[130:131], v[216:217], 0, v[130:131]
	global_load_dwordx4 v[164:167], v[132:133], off offset:16
	global_load_dwordx4 v[172:175], v[132:133], off
	global_load_dwordx4 v[160:163], v[130:131], off offset:16
	global_load_dwordx4 v[168:171], v[130:131], off
	v_mul_f32_e64 v196, v241, -v239
	v_cmp_gt_f32_e64 s[4:5], s7, v196
	v_or_b32_e32 v130, 0x4000, v128
	v_mov_b32_e32 v131, v193
	v_cndmask_b32_e64 v196, 0, v234, s[4:5]
	v_fma_f32 v196, v241, -v239, v196
	v_exp_f32_e32 v196, v196
	v_cndmask_b32_e64 v197, 0, v235, s[4:5]
	v_lshl_add_u64 v[132:133], v[214:215], 0, v[130:131]
	v_lshl_add_u64 v[130:131], v[216:217], 0, v[130:131]
	v_ldexp_f32 v196, v196, v197
	v_mul_f32_e32 v196, 0x3d800000, v196
	v_cndmask_b32_e32 v242, 1.0, v196, vcc
	v_mov_b32_e32 v196, v124
	v_mov_b32_e32 v197, v112
	global_load_dwordx4 v[148:151], v[132:133], off offset:16
	global_load_dwordx4 v[156:159], v[132:133], off
	global_load_dwordx4 v[144:147], v[130:131], off offset:16
	global_load_dwordx4 v[152:155], v[130:131], off
	v_or_b32_e32 v128, 0x6000, v128
	v_lshl_add_u64 v[130:131], v[214:215], 0, v[128:129]
	v_lshl_add_u64 v[136:137], v[216:217], 0, v[128:129]
	global_load_dwordx4 v[132:135], v[130:131], off offset:16
	global_load_dwordx4 v[140:143], v[130:131], off
	s_nop 0
	global_load_dwordx4 v[128:131], v[136:137], off offset:16
	s_nop 0
	global_load_dwordx4 v[136:139], v[136:137], off
	s_movk_i32 s4, 0x5f
	s_waitcnt vmcnt(0)
	v_mov_b32_e32 v198, v188
	v_mov_b32_e32 v199, v184
	v_pk_mul_f32 v[196:197], v[196:197], v[198:199]
	s_nop 0
	v_sub_f32_e32 v184, v196, v197
	v_mov_b32_e32 v196, v112
	v_mov_b32_e32 v197, v124
	v_pk_mul_f32 v[196:197], v[196:197], v[198:199]
	v_mul_f32_e32 v223, v242, v184
	v_add_f32_e32 v184, v196, v197
	v_mul_f32_e32 v198, v242, v184
	v_mov_b32_e32 v196, v125
	v_mov_b32_e32 v197, v113
	v_mov_b32_e32 v184, v189
	v_pk_mul_f32 v[188:189], v[196:197], v[184:185]
	s_nop 0
	v_sub_f32_e32 v188, v188, v189
	v_mul_f32_e32 v196, v242, v188
	v_mov_b32_e32 v188, v113
	v_mov_b32_e32 v189, v125
	v_pk_mul_f32 v[184:185], v[188:189], v[184:185]
	v_mov_b32_e32 v188, v190
	v_add_f32_e32 v184, v184, v185
	v_mul_f32_e32 v197, v242, v184
	v_mov_b32_e32 v184, v126
	v_mov_b32_e32 v185, v114
	v_mov_b32_e32 v189, v186
	v_pk_mul_f32 v[184:185], v[184:185], v[188:189]
	v_mov_b32_e32 v186, v191
	v_sub_f32_e32 v184, v184, v185
	v_mul_f32_e32 v190, v242, v184
	v_mov_b32_e32 v184, v114
	v_mov_b32_e32 v185, v126
	v_pk_mul_f32 v[184:185], v[184:185], v[188:189]
	s_nop 0
	v_add_f32_e32 v184, v184, v185
	v_mul_f32_e32 v188, v242, v184
	v_mov_b32_e32 v184, v127
	v_mov_b32_e32 v185, v115
	v_pk_mul_f32 v[184:185], v[184:185], v[186:187]
	s_nop 0
	v_sub_f32_e32 v184, v184, v185
	v_mul_f32_e32 v189, v242, v184
	v_mov_b32_e32 v184, v115
	v_mov_b32_e32 v185, v127
	v_pk_mul_f32 v[184:185], v[184:185], v[186:187]
	v_mov_b32_e32 v186, v180
	v_add_f32_e32 v184, v184, v185
	v_mul_f32_e32 v191, v242, v184
	v_mov_b32_e32 v184, v120
	v_mov_b32_e32 v185, v104
	v_mov_b32_e32 v187, v176
	v_pk_mul_f32 v[184:185], v[184:185], v[186:187]
	s_nop 0
	v_sub_f32_e32 v176, v184, v185
	v_mov_b32_e32 v184, v104
	v_mov_b32_e32 v185, v120
	v_pk_mul_f32 v[184:185], v[184:185], v[186:187]
	v_mul_f32_e32 v199, v242, v176
	v_add_f32_e32 v176, v184, v185
	v_mul_f32_e32 v186, v242, v176
	v_mov_b32_e32 v184, v121
	v_mov_b32_e32 v185, v105
	v_mov_b32_e32 v176, v181
	v_pk_mul_f32 v[180:181], v[184:185], v[176:177]
	s_nop 0
	v_sub_f32_e32 v180, v180, v181
	v_mul_f32_e32 v184, v242, v180
	v_mov_b32_e32 v180, v105
	v_mov_b32_e32 v181, v121
	v_pk_mul_f32 v[176:177], v[180:181], v[176:177]
	v_mov_b32_e32 v180, v182
	v_add_f32_e32 v176, v176, v177
	v_mul_f32_e32 v185, v242, v176
	v_mov_b32_e32 v176, v122
	v_mov_b32_e32 v177, v106
	v_mov_b32_e32 v181, v178
	v_pk_mul_f32 v[176:177], v[176:177], v[180:181]
	v_mov_b32_e32 v178, v183
	v_sub_f32_e32 v176, v176, v177
	v_mul_f32_e32 v182, v242, v176
	v_mov_b32_e32 v176, v106
	v_mov_b32_e32 v177, v122
	v_pk_mul_f32 v[176:177], v[176:177], v[180:181]
	s_nop 0
	v_add_f32_e32 v176, v176, v177
	v_mul_f32_e32 v187, v242, v176
	v_mov_b32_e32 v176, v123
	v_mov_b32_e32 v177, v107
	v_pk_mul_f32 v[176:177], v[176:177], v[178:179]
	s_nop 0
	v_sub_f32_e32 v176, v176, v177
	v_mul_f32_e32 v181, v242, v176
	v_mov_b32_e32 v176, v107
	v_mov_b32_e32 v177, v123
	v_pk_mul_f32 v[176:177], v[176:177], v[178:179]
	v_cvt_pk_bf16_f32 v178, v223, v196
	v_cvt_pk_bf16_f32 v179, v190, v189
	v_cvt_pk_bf16_f32 v180, v199, v184
	v_cvt_pk_bf16_f32 v181, v182, v181
	v_cvt_pk_bf16_f32 v182, v198, v197
	s_nop 0
	v_add_f32_e32 v176, v176, v177
	v_mul_f32_e32 v176, v242, v176
	v_cvt_pk_bf16_f32 v183, v188, v191
	v_cvt_pk_bf16_f32 v184, v186, v185
	v_cvt_pk_bf16_f32 v185, v187, v176
	v_lshlrev_b64 v[176:177], 12, v[228:229]
	v_lshl_add_u64 v[176:177], v[230:231], 0, v[176:177]
	global_store_dwordx4 v[176:177], v[178:181], off
	global_store_dwordx4 v[176:177], v[182:185], off offset:256
	v_ashrrev_i32_e32 v223, 31, v222
	v_bitop3_b32 v178, v228, s4, 16 bitop3:0xc8
	v_add_u32_e32 v178, 1, v178
	v_cvt_f32_ubyte0_e32 v178, v178
	v_mul_f32_e64 v179, v241, -v178
	v_cmp_gt_f32_e64 s[4:5], s7, v179
	v_mov_b32_e32 v181, v168
	v_mov_b32_e32 v190, v60
	v_cndmask_b32_e64 v180, 0, v234, s[4:5]
	v_fma_f32 v178, v241, -v178, v180
	v_exp_f32_e32 v178, v178
	v_cndmask_b32_e64 v179, 0, v235, s[4:5]
	v_mov_b32_e32 v180, v172
	s_movk_i32 s4, 0x6f
	v_ldexp_f32 v178, v178, v179
	v_mul_f32_e32 v178, 0x3d800000, v178
	v_cndmask_b32_e32 v182, 1.0, v178, vcc
	v_mov_b32_e32 v178, v116
	v_mov_b32_e32 v179, v96
	v_pk_mul_f32 v[178:179], v[178:179], v[180:181]
	v_mov_b32_e32 v191, v48
	v_sub_f32_e32 v168, v178, v179
	v_mov_b32_e32 v178, v96
	v_mov_b32_e32 v179, v116
	v_pk_mul_f32 v[178:179], v[178:179], v[180:181]
	v_mul_f32_e32 v183, v182, v168
	v_add_f32_e32 v168, v178, v179
	v_mul_f32_e32 v180, v182, v168
	v_mov_b32_e32 v178, v117
	v_mov_b32_e32 v179, v97
	v_mov_b32_e32 v168, v173
	v_pk_mul_f32 v[172:173], v[178:179], v[168:169]
	s_nop 0
	v_sub_f32_e32 v172, v172, v173
	v_mul_f32_e32 v178, v182, v172
	v_mov_b32_e32 v172, v97
	v_mov_b32_e32 v173, v117
	v_pk_mul_f32 v[168:169], v[172:173], v[168:169]
	v_mov_b32_e32 v172, v174
	v_add_f32_e32 v168, v168, v169
	v_mul_f32_e32 v179, v182, v168
	v_mov_b32_e32 v168, v118
	v_mov_b32_e32 v169, v98
	v_mov_b32_e32 v173, v170
	v_pk_mul_f32 v[168:169], v[168:169], v[172:173]
	v_mov_b32_e32 v170, v175
	v_sub_f32_e32 v168, v168, v169
	v_mul_f32_e32 v174, v182, v168
	v_mov_b32_e32 v168, v98
	v_mov_b32_e32 v169, v118
	v_pk_mul_f32 v[168:169], v[168:169], v[172:173]
	s_nop 0
	v_add_f32_e32 v168, v168, v169
	v_mul_f32_e32 v172, v182, v168
	v_mov_b32_e32 v168, v119
	v_mov_b32_e32 v169, v99
	v_pk_mul_f32 v[168:169], v[168:169], v[170:171]
	s_nop 0
	v_sub_f32_e32 v168, v168, v169
	v_mul_f32_e32 v173, v182, v168
	v_mov_b32_e32 v168, v99
	v_mov_b32_e32 v169, v119
	v_pk_mul_f32 v[168:169], v[168:169], v[170:171]
	v_mov_b32_e32 v170, v164
	v_add_f32_e32 v168, v168, v169
	v_mul_f32_e32 v175, v182, v168
	v_mov_b32_e32 v168, v108
	v_mov_b32_e32 v169, v88
	v_mov_b32_e32 v171, v160
	v_pk_mul_f32 v[168:169], v[168:169], v[170:171]
	s_nop 0
	v_sub_f32_e32 v160, v168, v169
	v_mov_b32_e32 v168, v88
	v_mov_b32_e32 v169, v108
	v_pk_mul_f32 v[168:169], v[168:169], v[170:171]
	v_mul_f32_e32 v181, v182, v160
	v_add_f32_e32 v160, v168, v169
	v_mul_f32_e32 v170, v182, v160
	v_mov_b32_e32 v168, v109
	v_mov_b32_e32 v169, v89
	v_mov_b32_e32 v160, v165
	v_pk_mul_f32 v[164:165], v[168:169], v[160:161]
	s_nop 0
	v_sub_f32_e32 v164, v164, v165
	v_mul_f32_e32 v168, v182, v164
	v_mov_b32_e32 v164, v89
	v_mov_b32_e32 v165, v109
	v_pk_mul_f32 v[160:161], v[164:165], v[160:161]
	v_mov_b32_e32 v164, v166
	v_add_f32_e32 v160, v160, v161
	v_mul_f32_e32 v169, v182, v160
	v_mov_b32_e32 v160, v110
	v_mov_b32_e32 v161, v90
	v_mov_b32_e32 v165, v162
	v_pk_mul_f32 v[160:161], v[160:161], v[164:165]
	v_mov_b32_e32 v162, v167
	v_sub_f32_e32 v160, v160, v161
	v_mul_f32_e32 v166, v182, v160
	v_mov_b32_e32 v160, v90
	v_mov_b32_e32 v161, v110
	v_pk_mul_f32 v[160:161], v[160:161], v[164:165]
	s_nop 0
	v_add_f32_e32 v160, v160, v161
	v_mul_f32_e32 v171, v182, v160
	v_mov_b32_e32 v160, v111
	v_mov_b32_e32 v161, v91
	v_pk_mul_f32 v[160:161], v[160:161], v[162:163]
	s_nop 0
	v_sub_f32_e32 v160, v160, v161
	v_mul_f32_e32 v164, v182, v160
	v_mov_b32_e32 v160, v91
	v_mov_b32_e32 v161, v111
	v_pk_mul_f32 v[160:161], v[160:161], v[162:163]
	s_nop 0
	v_add_f32_e32 v160, v160, v161
	v_mul_f32_e32 v167, v182, v160
	v_cvt_pk_bf16_f32 v160, v183, v178
	v_cvt_pk_bf16_f32 v161, v174, v173
	v_cvt_pk_bf16_f32 v162, v181, v168
	v_cvt_pk_bf16_f32 v163, v166, v164
	v_cvt_pk_bf16_f32 v164, v180, v179
	v_cvt_pk_bf16_f32 v165, v172, v175
	v_cvt_pk_bf16_f32 v166, v170, v169
	v_lshlrev_b64 v[168:169], 12, v[226:227]
	v_lshl_add_u64 v[168:169], v[230:231], 0, v[168:169]
	v_cvt_pk_bf16_f32 v167, v171, v167
	global_store_dwordx4 v[168:169], v[160:163], off
	global_store_dwordx4 v[168:169], v[164:167], off offset:256
	s_nop 0
	v_bitop3_b32 v160, v228, s4, 32 bitop3:0xc8
	v_add_u32_e32 v160, 1, v160
	v_cvt_f32_ubyte0_e32 v160, v160
	v_mul_f32_e64 v161, v241, -v160
	v_cmp_gt_f32_e64 s[4:5], s7, v161
	v_mov_b32_e32 v163, v152
	s_nop 0
	v_cndmask_b32_e64 v162, 0, v234, s[4:5]
	v_fma_f32 v160, v241, -v160, v162
	v_exp_f32_e32 v160, v160
	v_cndmask_b32_e64 v161, 0, v235, s[4:5]
	v_mov_b32_e32 v162, v156
	s_movk_i32 s4, 0x7f
	v_ldexp_f32 v160, v160, v161
	v_mul_f32_e32 v160, 0x3d800000, v160
	v_cndmask_b32_e32 v164, 1.0, v160, vcc
	v_mov_b32_e32 v160, v100
	v_mov_b32_e32 v161, v80
	v_pk_mul_f32 v[160:161], v[160:161], v[162:163]
	s_nop 0
	v_sub_f32_e32 v152, v160, v161
	v_mov_b32_e32 v160, v80
	v_mov_b32_e32 v161, v100
	v_pk_mul_f32 v[160:161], v[160:161], v[162:163]
	v_mul_f32_e32 v165, v164, v152
	v_add_f32_e32 v152, v160, v161
	v_mul_f32_e32 v162, v164, v152
	v_mov_b32_e32 v160, v101
	v_mov_b32_e32 v161, v81
	v_mov_b32_e32 v152, v157
	v_pk_mul_f32 v[156:157], v[160:161], v[152:153]
	s_nop 0
	v_sub_f32_e32 v156, v156, v157
	v_mul_f32_e32 v160, v164, v156
	v_mov_b32_e32 v156, v81
	v_mov_b32_e32 v157, v101
	v_pk_mul_f32 v[152:153], v[156:157], v[152:153]
	v_mov_b32_e32 v156, v158
	v_add_f32_e32 v152, v152, v153
	v_mul_f32_e32 v161, v164, v152
	v_mov_b32_e32 v152, v102
	v_mov_b32_e32 v153, v82
	v_mov_b32_e32 v157, v154
	v_pk_mul_f32 v[152:153], v[152:153], v[156:157]
	v_mov_b32_e32 v154, v159
	v_sub_f32_e32 v152, v152, v153
	v_mul_f32_e32 v158, v164, v152
	v_mov_b32_e32 v152, v82
	v_mov_b32_e32 v153, v102
	v_pk_mul_f32 v[152:153], v[152:153], v[156:157]
	s_nop 0
	v_add_f32_e32 v152, v152, v153
	v_mul_f32_e32 v156, v164, v152
	v_mov_b32_e32 v152, v103
	v_mov_b32_e32 v153, v83
	v_pk_mul_f32 v[152:153], v[152:153], v[154:155]
	s_nop 0
	v_sub_f32_e32 v152, v152, v153
	v_mul_f32_e32 v157, v164, v152
	v_mov_b32_e32 v152, v83
	v_mov_b32_e32 v153, v103
	v_pk_mul_f32 v[152:153], v[152:153], v[154:155]
	v_mov_b32_e32 v154, v148
	v_add_f32_e32 v152, v152, v153
	v_mul_f32_e32 v159, v164, v152
	v_mov_b32_e32 v152, v92
	v_mov_b32_e32 v153, v72
	v_mov_b32_e32 v155, v144
	v_pk_mul_f32 v[152:153], v[152:153], v[154:155]
	s_nop 0
	v_sub_f32_e32 v144, v152, v153
	v_mov_b32_e32 v152, v72
	v_mov_b32_e32 v153, v92
	v_pk_mul_f32 v[152:153], v[152:153], v[154:155]
	v_mul_f32_e32 v163, v164, v144
	v_add_f32_e32 v144, v152, v153
	v_mul_f32_e32 v154, v164, v144
	v_mov_b32_e32 v152, v93
	v_mov_b32_e32 v153, v73
	v_mov_b32_e32 v144, v149
	v_pk_mul_f32 v[148:149], v[152:153], v[144:145]
	s_nop 0
	v_sub_f32_e32 v148, v148, v149
	v_mul_f32_e32 v152, v164, v148
	v_mov_b32_e32 v148, v73
	v_mov_b32_e32 v149, v93
	v_pk_mul_f32 v[144:145], v[148:149], v[144:145]
	v_mov_b32_e32 v148, v150
	v_add_f32_e32 v144, v144, v145
	v_mul_f32_e32 v153, v164, v144
	v_mov_b32_e32 v144, v94
	v_mov_b32_e32 v145, v74
	v_mov_b32_e32 v149, v146
	v_pk_mul_f32 v[144:145], v[144:145], v[148:149]
	v_mov_b32_e32 v146, v151
	v_sub_f32_e32 v144, v144, v145
	v_mul_f32_e32 v150, v164, v144
	v_mov_b32_e32 v144, v74
	v_mov_b32_e32 v145, v94
	v_pk_mul_f32 v[144:145], v[144:145], v[148:149]
	s_nop 0
	v_add_f32_e32 v144, v144, v145
	v_mul_f32_e32 v155, v164, v144
	v_mov_b32_e32 v144, v95
	v_mov_b32_e32 v145, v75
	v_pk_mul_f32 v[144:145], v[144:145], v[146:147]
	s_nop 0
	v_sub_f32_e32 v144, v144, v145
	v_mul_f32_e32 v148, v164, v144
	v_mov_b32_e32 v144, v75
	v_mov_b32_e32 v145, v95
	v_pk_mul_f32 v[144:145], v[144:145], v[146:147]
	s_nop 0
	v_add_f32_e32 v144, v144, v145
	v_mul_f32_e32 v151, v164, v144
	v_cvt_pk_bf16_f32 v144, v165, v160
	v_cvt_pk_bf16_f32 v145, v158, v157
	v_cvt_pk_bf16_f32 v146, v163, v152
	v_cvt_pk_bf16_f32 v147, v150, v148
	v_cvt_pk_bf16_f32 v148, v162, v161
	v_cvt_pk_bf16_f32 v149, v156, v159
	v_cvt_pk_bf16_f32 v150, v154, v153
	v_lshlrev_b64 v[152:153], 12, v[224:225]
	v_lshl_add_u64 v[152:153], v[230:231], 0, v[152:153]
	v_cvt_pk_bf16_f32 v151, v155, v151
	global_store_dwordx4 v[152:153], v[144:147], off
	global_store_dwordx4 v[152:153], v[148:151], off offset:256
	s_nop 0
	v_bitop3_b32 v144, v228, s4, 48 bitop3:0xc8
	v_add_u32_e32 v144, 1, v144
	v_cvt_f32_ubyte0_e32 v144, v144
	v_mul_f32_e64 v145, v241, -v144
	v_cmp_gt_f32_e64 s[4:5], s7, v145
	v_mov_b32_e32 v147, v136
	s_nop 0
	v_cndmask_b32_e64 v146, 0, v234, s[4:5]
	v_fma_f32 v144, v241, -v144, v146
	v_exp_f32_e32 v144, v144
	v_cndmask_b32_e64 v145, 0, v235, s[4:5]
	v_mov_b32_e32 v146, v140
	s_mov_b64 s[4:5], 0x80000
	v_ldexp_f32 v144, v144, v145
	v_mul_f32_e32 v144, 0x3d800000, v144
	v_cndmask_b32_e32 v148, 1.0, v144, vcc
	v_mov_b32_e32 v144, v84
	v_mov_b32_e32 v145, v68
	v_pk_mul_f32 v[144:145], v[144:145], v[146:147]
	s_nop 0
	v_sub_f32_e32 v136, v144, v145
	v_mov_b32_e32 v144, v68
	v_mov_b32_e32 v145, v84
	v_pk_mul_f32 v[144:145], v[144:145], v[146:147]
	v_mul_f32_e32 v149, v148, v136
	v_add_f32_e32 v136, v144, v145
	v_mul_f32_e32 v146, v148, v136
	v_mov_b32_e32 v144, v85
	v_mov_b32_e32 v145, v69
	v_mov_b32_e32 v136, v141
	v_pk_mul_f32 v[140:141], v[144:145], v[136:137]
	s_nop 0
	v_sub_f32_e32 v140, v140, v141
	v_mul_f32_e32 v144, v148, v140
	v_mov_b32_e32 v140, v69
	v_mov_b32_e32 v141, v85
	v_pk_mul_f32 v[136:137], v[140:141], v[136:137]
	v_mov_b32_e32 v140, v142
	v_add_f32_e32 v136, v136, v137
	v_mul_f32_e32 v145, v148, v136
	v_mov_b32_e32 v136, v86
	v_mov_b32_e32 v137, v70
	v_mov_b32_e32 v141, v138
	v_pk_mul_f32 v[136:137], v[136:137], v[140:141]
	v_mov_b32_e32 v138, v143
	v_sub_f32_e32 v136, v136, v137
	v_mul_f32_e32 v142, v148, v136
	v_mov_b32_e32 v136, v70
	v_mov_b32_e32 v137, v86
	v_pk_mul_f32 v[136:137], v[136:137], v[140:141]
	s_nop 0
	v_add_f32_e32 v136, v136, v137
	v_mul_f32_e32 v140, v148, v136
	v_mov_b32_e32 v136, v87
	v_mov_b32_e32 v137, v71
	v_pk_mul_f32 v[136:137], v[136:137], v[138:139]
	s_nop 0
	v_sub_f32_e32 v136, v136, v137
	v_mul_f32_e32 v141, v148, v136
	v_mov_b32_e32 v136, v71
	v_mov_b32_e32 v137, v87
	v_pk_mul_f32 v[136:137], v[136:137], v[138:139]
	v_mov_b32_e32 v138, v132
	v_add_f32_e32 v136, v136, v137
	v_mul_f32_e32 v143, v148, v136
	v_mov_b32_e32 v136, v76
	v_mov_b32_e32 v137, v64
	v_mov_b32_e32 v139, v128
	v_pk_mul_f32 v[136:137], v[136:137], v[138:139]
	s_nop 0
	v_sub_f32_e32 v128, v136, v137
	v_mov_b32_e32 v136, v64
	v_mov_b32_e32 v137, v76
	v_pk_mul_f32 v[136:137], v[136:137], v[138:139]
	v_mul_f32_e32 v147, v148, v128
	v_add_f32_e32 v128, v136, v137
	v_mul_f32_e32 v138, v148, v128
	v_mov_b32_e32 v136, v77
	v_mov_b32_e32 v137, v65
	v_mov_b32_e32 v128, v133
	v_pk_mul_f32 v[132:133], v[136:137], v[128:129]
	s_nop 0
	v_sub_f32_e32 v132, v132, v133
	v_mul_f32_e32 v136, v148, v132
	v_mov_b32_e32 v132, v65
	v_mov_b32_e32 v133, v77
	v_pk_mul_f32 v[128:129], v[132:133], v[128:129]
	v_mov_b32_e32 v132, v134
	v_add_f32_e32 v128, v128, v129
	v_mul_f32_e32 v137, v148, v128
	v_mov_b32_e32 v128, v78
	v_mov_b32_e32 v129, v66
	v_mov_b32_e32 v133, v130
	v_pk_mul_f32 v[128:129], v[128:129], v[132:133]
	v_mov_b32_e32 v130, v135
	v_sub_f32_e32 v128, v128, v129
	v_mul_f32_e32 v134, v148, v128
	v_mov_b32_e32 v128, v66
	v_mov_b32_e32 v129, v78
	v_pk_mul_f32 v[128:129], v[128:129], v[132:133]
	s_nop 0
	v_add_f32_e32 v128, v128, v129
	v_mul_f32_e32 v139, v148, v128
	v_mov_b32_e32 v128, v79
	v_mov_b32_e32 v129, v67
	v_pk_mul_f32 v[128:129], v[128:129], v[130:131]
	s_nop 0
	v_sub_f32_e32 v128, v128, v129
	v_mul_f32_e32 v132, v148, v128
	v_mov_b32_e32 v128, v67
	v_mov_b32_e32 v129, v79
	v_pk_mul_f32 v[128:129], v[128:129], v[130:131]
	s_nop 0
	v_add_f32_e32 v128, v128, v129
	v_mul_f32_e32 v135, v148, v128
	v_cvt_pk_bf16_f32 v128, v149, v144
	v_cvt_pk_bf16_f32 v129, v142, v141
	v_cvt_pk_bf16_f32 v130, v147, v136
	v_cvt_pk_bf16_f32 v131, v134, v132
	v_cvt_pk_bf16_f32 v132, v146, v145
	v_cvt_pk_bf16_f32 v133, v140, v143
	v_cvt_pk_bf16_f32 v134, v138, v137
	v_lshlrev_b64 v[136:137], 12, v[222:223]
	v_lshl_add_u64 v[136:137], v[230:231], 0, v[136:137]
	v_cvt_pk_bf16_f32 v135, v139, v135
	global_store_dwordx4 v[136:137], v[128:131], off
	global_store_dwordx4 v[136:137], v[132:135], off offset:256
	s_nop 0
	v_mov_b32_e32 v128, 0x4000
	v_lshl_add_u32 v128, v228, 7, v128
	v_and_b32_e32 v128, 0x7e780, v128
	v_lshlrev_b32_e32 v128, 2, v128
	v_mov_b32_e32 v129, v193
	v_lshl_add_u64 v[130:131], v[214:215], 0, v[128:129]
	v_lshl_add_u64 v[132:133], v[216:217], 0, v[128:129]
	global_load_dwordx4 v[168:171], v[130:131], off offset:16
	global_load_dwordx4 v[172:175], v[130:131], off
	global_load_dwordx4 v[178:181], v[132:133], off offset:16
	global_load_dwordx4 v[182:185], v[132:133], off
	v_or_b32_e32 v130, 0x2000, v128
	v_mov_b32_e32 v131, v193
	v_lshl_add_u64 v[132:133], v[214:215], 0, v[130:131]
	v_lshl_add_u64 v[130:131], v[216:217], 0, v[130:131]
	global_load_dwordx4 v[164:167], v[132:133], off offset:16
	global_load_dwordx4 v[186:189], v[132:133], off
	global_load_dwordx4 v[160:163], v[130:131], off offset:16
	global_load_dwordx4 v[196:199], v[130:131], off
	v_or_b32_e32 v130, 0x4000, v128
	v_mov_b32_e32 v131, v193
	v_lshl_add_u64 v[132:133], v[214:215], 0, v[130:131]
	v_lshl_add_u64 v[130:131], v[216:217], 0, v[130:131]
	global_load_dwordx4 v[148:151], v[132:133], off offset:16
	global_load_dwordx4 v[156:159], v[132:133], off
	global_load_dwordx4 v[144:147], v[130:131], off offset:16
	global_load_dwordx4 v[152:155], v[130:131], off
	v_or_b32_e32 v128, 0x6000, v128
	v_lshl_add_u64 v[130:131], v[214:215], 0, v[128:129]
	v_lshl_add_u64 v[136:137], v[216:217], 0, v[128:129]
	global_load_dwordx4 v[132:135], v[130:131], off offset:16
	global_load_dwordx4 v[140:143], v[130:131], off
	s_nop 0
	global_load_dwordx4 v[128:131], v[136:137], off offset:16
	s_nop 0
	global_load_dwordx4 v[136:139], v[136:137], off
	s_waitcnt vmcnt(0)
	v_mov_b32_e32 v244, v172
	v_mov_b32_e32 v245, v182
	v_pk_mul_f32 v[190:191], v[190:191], v[244:245]
	v_mov_b32_e32 v182, v173
	v_sub_f32_e32 v172, v190, v191
	v_mov_b32_e32 v190, v48
	v_mov_b32_e32 v191, v60
	v_pk_mul_f32 v[190:191], v[190:191], v[244:245]
	v_mul_f32_e32 v223, v242, v172
	v_add_f32_e32 v172, v190, v191
	v_mov_b32_e32 v190, v61
	v_mov_b32_e32 v191, v49
	v_mul_f32_e32 v225, v242, v172
	v_pk_mul_f32 v[172:173], v[190:191], v[182:183]
	s_nop 0
	v_sub_f32_e32 v172, v172, v173
	v_mul_f32_e32 v190, v242, v172
	v_mov_b32_e32 v172, v49
	v_mov_b32_e32 v173, v61
	v_pk_mul_f32 v[172:173], v[172:173], v[182:183]
	v_mov_b32_e32 v182, v174
	v_add_f32_e32 v172, v172, v173
	v_mul_f32_e32 v191, v242, v172
	v_mov_b32_e32 v172, v62
	v_mov_b32_e32 v173, v50
	v_mov_b32_e32 v183, v184
	v_pk_mul_f32 v[172:173], v[172:173], v[182:183]
	v_mov_b32_e32 v184, v175
	v_sub_f32_e32 v172, v172, v173
	v_mul_f32_e32 v243, v242, v172
	v_mov_b32_e32 v172, v50
	v_mov_b32_e32 v173, v62
	v_pk_mul_f32 v[172:173], v[172:173], v[182:183]
	v_mov_b32_e32 v174, v168
	v_add_f32_e32 v172, v172, v173
	v_mul_f32_e32 v182, v242, v172
	v_mov_b32_e32 v172, v63
	v_mov_b32_e32 v173, v51
	v_pk_mul_f32 v[172:173], v[172:173], v[184:185]
	v_mov_b32_e32 v175, v178
	v_sub_f32_e32 v172, v172, v173
	v_mul_f32_e32 v183, v242, v172
	v_mov_b32_e32 v172, v51
	v_mov_b32_e32 v173, v63
	v_pk_mul_f32 v[172:173], v[172:173], v[184:185]
	v_mov_b32_e32 v178, v169
	v_add_f32_e32 v172, v172, v173
	v_mul_f32_e32 v184, v242, v172
	v_mov_b32_e32 v172, v56
	v_mov_b32_e32 v173, v40
	v_pk_mul_f32 v[172:173], v[172:173], v[174:175]
	s_nop 0
	v_sub_f32_e32 v168, v172, v173
	v_mov_b32_e32 v172, v40
	v_mov_b32_e32 v173, v56
	v_pk_mul_f32 v[172:173], v[172:173], v[174:175]
	v_mul_f32_e32 v185, v242, v168
	v_add_f32_e32 v168, v172, v173
	v_mov_b32_e32 v172, v57
	v_mov_b32_e32 v173, v41
	v_mul_f32_e32 v174, v242, v168
	v_pk_mul_f32 v[168:169], v[172:173], v[178:179]
	v_mov_b32_e32 v172, v170
	v_sub_f32_e32 v168, v168, v169
	v_mul_f32_e32 v175, v242, v168
	v_mov_b32_e32 v168, v41
	v_mov_b32_e32 v169, v57
	v_pk_mul_f32 v[168:169], v[168:169], v[178:179]
	v_mov_b32_e32 v173, v180
	v_add_f32_e32 v168, v168, v169
	v_mul_f32_e32 v178, v242, v168
	v_mov_b32_e32 v168, v58
	v_mov_b32_e32 v169, v42
	v_pk_mul_f32 v[168:169], v[168:169], v[172:173]
	v_mov_b32_e32 v180, v171
	v_sub_f32_e32 v168, v168, v169
	v_mul_f32_e32 v179, v242, v168
	v_mov_b32_e32 v168, v42
	v_mov_b32_e32 v169, v58
	v_pk_mul_f32 v[168:169], v[168:169], v[172:173]
	s_nop 0
	v_add_f32_e32 v168, v168, v169
	v_mul_f32_e32 v244, v242, v168
	v_mov_b32_e32 v168, v59
	v_mov_b32_e32 v169, v43
	v_pk_mul_f32 v[168:169], v[168:169], v[180:181]
	s_nop 0
	v_sub_f32_e32 v168, v168, v169
	v_mul_f32_e32 v171, v242, v168
	v_mov_b32_e32 v168, v43
	v_mov_b32_e32 v169, v59
	v_pk_mul_f32 v[168:169], v[168:169], v[180:181]
	s_nop 0
	v_add_f32_e32 v168, v168, v169
	v_mul_f32_e32 v180, v242, v168
	v_cvt_pk_bf16_f32 v168, v223, v190
	v_cvt_pk_bf16_f32 v169, v243, v183
	v_cvt_pk_bf16_f32 v170, v185, v175
	v_cvt_pk_bf16_f32 v171, v179, v171
	v_cvt_pk_bf16_f32 v172, v225, v191
	v_cvt_pk_bf16_f32 v173, v182, v184
	v_cvt_pk_bf16_f32 v174, v174, v178
	v_lshl_add_u64 v[178:179], v[176:177], 0, s[4:5]
	s_mov_b32 s4, 0x80000
	v_add_co_u32_e64 v176, s[4:5], s4, v176
	v_cvt_pk_bf16_f32 v175, v244, v180
	s_nop 1
	v_addc_co_u32_e64 v177, s[4:5], 0, v177, s[4:5]
	global_store_dwordx4 v[176:177], v[168:171], off
	global_store_dwordx4 v[178:179], v[172:175], off offset:256
	s_nop 0
	v_add_u32_e32 v168, 0x90, v228
	v_and_b32_e32 v169, 0x5f, v168
	v_add_u32_e32 v169, 1, v169
	v_cvt_f32_ubyte0_e32 v169, v169
	v_mul_f32_e64 v170, v241, -v169
	v_cmp_gt_f32_e64 s[4:5], s7, v170
	v_mov_b32_e32 v171, v32
	v_mov_b32_e32 v172, v186
	v_cndmask_b32_e64 v170, 0, v234, s[4:5]
	v_fma_f32 v169, v241, -v169, v170
	v_exp_f32_e32 v169, v169
	v_cndmask_b32_e64 v170, 0, v235, s[4:5]
	v_mov_b32_e32 v173, v196
	v_mov_b32_e32 v196, v187
	v_ldexp_f32 v169, v169, v170
	v_mov_b32_e32 v170, v52
	v_mul_f32_e32 v169, 0x3d800000, v169
	v_pk_mul_f32 v[170:171], v[170:171], v[172:173]
	v_cndmask_b32_e32 v169, 1.0, v169, vcc
	v_sub_f32_e32 v170, v170, v171
	v_mul_f32_e32 v174, v169, v170
	v_mov_b32_e32 v170, v32
	v_mov_b32_e32 v171, v52
	v_pk_mul_f32 v[170:171], v[170:171], v[172:173]
	v_mov_b32_e32 v172, v188
	v_add_f32_e32 v170, v170, v171
	v_mul_f32_e32 v175, v169, v170
	v_mov_b32_e32 v170, v53
	v_mov_b32_e32 v171, v33
	v_pk_mul_f32 v[170:171], v[170:171], v[196:197]
	v_mov_b32_e32 v173, v198
	v_sub_f32_e32 v170, v170, v171
	v_mul_f32_e32 v176, v169, v170
	v_mov_b32_e32 v170, v33
	v_mov_b32_e32 v171, v53
	v_pk_mul_f32 v[170:171], v[170:171], v[196:197]
	v_mov_b32_e32 v198, v189
	v_add_f32_e32 v170, v170, v171
	v_mul_f32_e32 v177, v169, v170
	v_mov_b32_e32 v170, v54
	v_mov_b32_e32 v171, v34
	v_pk_mul_f32 v[170:171], v[170:171], v[172:173]
	s_nop 0
	v_sub_f32_e32 v170, v170, v171
	v_mul_f32_e32 v178, v169, v170
	v_mov_b32_e32 v170, v34
	v_mov_b32_e32 v171, v54
	v_pk_mul_f32 v[170:171], v[170:171], v[172:173]
	v_mov_b32_e32 v172, v164
	v_add_f32_e32 v170, v170, v171
	v_mul_f32_e32 v179, v169, v170
	v_mov_b32_e32 v170, v55
	v_mov_b32_e32 v171, v35
	v_pk_mul_f32 v[170:171], v[170:171], v[198:199]
	v_mov_b32_e32 v173, v160
	v_sub_f32_e32 v170, v170, v171
	v_mul_f32_e32 v180, v169, v170
	v_mov_b32_e32 v170, v35
	v_mov_b32_e32 v171, v55
	v_pk_mul_f32 v[170:171], v[170:171], v[198:199]
	s_nop 0
	v_add_f32_e32 v170, v170, v171
	v_mul_f32_e32 v181, v169, v170
	v_mov_b32_e32 v170, v44
	v_mov_b32_e32 v171, v24
	v_pk_mul_f32 v[170:171], v[170:171], v[172:173]
	s_nop 0
	v_sub_f32_e32 v160, v170, v171
	v_mov_b32_e32 v170, v24
	v_mov_b32_e32 v171, v44
	v_pk_mul_f32 v[170:171], v[170:171], v[172:173]
	v_mul_f32_e32 v182, v169, v160
	v_add_f32_e32 v160, v170, v171
	v_mul_f32_e32 v172, v169, v160
	v_mov_b32_e32 v170, v45
	v_mov_b32_e32 v171, v25
	v_mov_b32_e32 v160, v165
	v_pk_mul_f32 v[164:165], v[170:171], v[160:161]
	s_nop 0
	v_sub_f32_e32 v164, v164, v165
	v_mul_f32_e32 v170, v169, v164
	v_mov_b32_e32 v164, v25
	v_mov_b32_e32 v165, v45
	v_pk_mul_f32 v[160:161], v[164:165], v[160:161]
	v_mov_b32_e32 v164, v166
	v_add_f32_e32 v160, v160, v161
	v_mul_f32_e32 v171, v169, v160
	v_mov_b32_e32 v160, v46
	v_mov_b32_e32 v161, v26
	v_mov_b32_e32 v165, v162
	v_pk_mul_f32 v[160:161], v[160:161], v[164:165]
	v_mov_b32_e32 v162, v167
	v_sub_f32_e32 v160, v160, v161
	v_mul_f32_e32 v166, v169, v160
	v_mov_b32_e32 v160, v26
	v_mov_b32_e32 v161, v46
	v_pk_mul_f32 v[160:161], v[160:161], v[164:165]
	s_nop 0
	v_add_f32_e32 v160, v160, v161
	v_mul_f32_e32 v173, v169, v160
	v_mov_b32_e32 v160, v47
	v_mov_b32_e32 v161, v27
	v_pk_mul_f32 v[160:161], v[160:161], v[162:163]
	s_nop 0
	v_sub_f32_e32 v160, v160, v161
	v_mul_f32_e32 v164, v169, v160
	v_mov_b32_e32 v160, v27
	v_mov_b32_e32 v161, v47
	v_pk_mul_f32 v[160:161], v[160:161], v[162:163]
	s_nop 0
	v_add_f32_e32 v160, v160, v161
	v_mul_f32_e32 v167, v169, v160
	v_ashrrev_i32_e32 v169, 31, v168
	v_lshlrev_b64 v[168:169], 12, v[168:169]
	v_cvt_pk_bf16_f32 v160, v174, v176
	v_cvt_pk_bf16_f32 v161, v178, v180
	v_cvt_pk_bf16_f32 v162, v182, v170
	v_cvt_pk_bf16_f32 v163, v166, v164
	v_lshl_add_u64 v[168:169], v[230:231], 0, v[168:169]
	v_cvt_pk_bf16_f32 v164, v175, v177
	v_cvt_pk_bf16_f32 v165, v179, v181
	v_cvt_pk_bf16_f32 v166, v172, v171
	v_cvt_pk_bf16_f32 v167, v173, v167
	global_store_dwordx4 v[168:169], v[160:163], off
	global_store_dwordx4 v[168:169], v[164:167], off offset:256
	s_nop 0
	v_add_u32_e32 v160, 0xa0, v228
	v_and_b32_e32 v161, 0x6f, v160
	v_add_u32_e32 v161, 1, v161
	v_cvt_f32_ubyte0_e32 v161, v161
	v_mul_f32_e64 v162, v241, -v161
	v_cmp_gt_f32_e64 s[4:5], s7, v162
	v_mov_b32_e32 v163, v16
	v_mov_b32_e32 v164, v156
	v_cndmask_b32_e64 v162, 0, v234, s[4:5]
	v_fma_f32 v161, v241, -v161, v162
	v_exp_f32_e32 v161, v161
	v_cndmask_b32_e64 v162, 0, v235, s[4:5]
	v_mov_b32_e32 v165, v152
	v_ldexp_f32 v161, v161, v162
	v_mov_b32_e32 v162, v36
	v_pk_mul_f32 v[162:163], v[162:163], v[164:165]
	v_mul_f32_e32 v161, 0x3d800000, v161
	v_sub_f32_e32 v152, v162, v163
	v_mov_b32_e32 v162, v16
	v_mov_b32_e32 v163, v36
	v_cndmask_b32_e32 v161, 1.0, v161, vcc
	v_pk_mul_f32 v[162:163], v[162:163], v[164:165]
	v_mul_f32_e32 v166, v161, v152
	v_add_f32_e32 v152, v162, v163
	v_mul_f32_e32 v164, v161, v152
	v_mov_b32_e32 v162, v37
	v_mov_b32_e32 v163, v17
	v_mov_b32_e32 v152, v157
	v_pk_mul_f32 v[156:157], v[162:163], v[152:153]
	s_nop 0
	v_sub_f32_e32 v156, v156, v157
	v_mul_f32_e32 v162, v161, v156
	v_mov_b32_e32 v156, v17
	v_mov_b32_e32 v157, v37
	v_pk_mul_f32 v[152:153], v[156:157], v[152:153]
	v_mov_b32_e32 v156, v158
	v_add_f32_e32 v152, v152, v153
	v_mul_f32_e32 v163, v161, v152
	v_mov_b32_e32 v152, v38
	v_mov_b32_e32 v153, v18
	v_mov_b32_e32 v157, v154
	v_pk_mul_f32 v[152:153], v[152:153], v[156:157]
	v_mov_b32_e32 v154, v159
	v_sub_f32_e32 v152, v152, v153
	v_mul_f32_e32 v158, v161, v152
	v_mov_b32_e32 v152, v18
	v_mov_b32_e32 v153, v38
	v_pk_mul_f32 v[152:153], v[152:153], v[156:157]
	s_nop 0
	v_add_f32_e32 v152, v152, v153
	v_mul_f32_e32 v156, v161, v152
	v_mov_b32_e32 v152, v39
	v_mov_b32_e32 v153, v19
	v_pk_mul_f32 v[152:153], v[152:153], v[154:155]
	s_nop 0
	v_sub_f32_e32 v152, v152, v153
	v_mul_f32_e32 v157, v161, v152
	v_mov_b32_e32 v152, v19
	v_mov_b32_e32 v153, v39
	v_pk_mul_f32 v[152:153], v[152:153], v[154:155]
	v_mov_b32_e32 v154, v148
	v_add_f32_e32 v152, v152, v153
	v_mul_f32_e32 v159, v161, v152
	v_mov_b32_e32 v152, v28
	v_mov_b32_e32 v153, v8
	v_mov_b32_e32 v155, v144
	v_pk_mul_f32 v[152:153], v[152:153], v[154:155]
	s_nop 0
	v_sub_f32_e32 v144, v152, v153
	v_mov_b32_e32 v152, v8
	v_mov_b32_e32 v153, v28
	v_pk_mul_f32 v[152:153], v[152:153], v[154:155]
	v_mul_f32_e32 v165, v161, v144
	v_add_f32_e32 v144, v152, v153
	v_mul_f32_e32 v154, v161, v144
	v_mov_b32_e32 v152, v29
	v_mov_b32_e32 v153, v9
	v_mov_b32_e32 v144, v149
	v_pk_mul_f32 v[148:149], v[152:153], v[144:145]
	s_nop 0
	v_sub_f32_e32 v148, v148, v149
	v_mul_f32_e32 v152, v161, v148
	v_mov_b32_e32 v148, v9
	v_mov_b32_e32 v149, v29
	v_pk_mul_f32 v[144:145], v[148:149], v[144:145]
	v_mov_b32_e32 v148, v150
	v_add_f32_e32 v144, v144, v145
	v_mul_f32_e32 v153, v161, v144
	v_mov_b32_e32 v144, v30
	v_mov_b32_e32 v145, v10
	v_mov_b32_e32 v149, v146
	v_pk_mul_f32 v[144:145], v[144:145], v[148:149]
	v_mov_b32_e32 v146, v151
	v_sub_f32_e32 v144, v144, v145
	v_mul_f32_e32 v150, v161, v144
	v_mov_b32_e32 v144, v10
	v_mov_b32_e32 v145, v30
	v_pk_mul_f32 v[144:145], v[144:145], v[148:149]
	s_nop 0
	v_add_f32_e32 v144, v144, v145
	v_mul_f32_e32 v155, v161, v144
	v_mov_b32_e32 v144, v31
	v_mov_b32_e32 v145, v11
	v_pk_mul_f32 v[144:145], v[144:145], v[146:147]
	s_nop 0
	v_sub_f32_e32 v144, v144, v145
	v_mul_f32_e32 v148, v161, v144
	v_mov_b32_e32 v144, v11
	v_mov_b32_e32 v145, v31
	v_pk_mul_f32 v[144:145], v[144:145], v[146:147]
	s_nop 0
	v_add_f32_e32 v144, v144, v145
	v_mul_f32_e32 v151, v161, v144
	v_ashrrev_i32_e32 v161, 31, v160
	v_cvt_pk_bf16_f32 v144, v166, v162
	v_cvt_pk_bf16_f32 v145, v158, v157
	v_cvt_pk_bf16_f32 v146, v165, v152
	v_cvt_pk_bf16_f32 v147, v150, v148
	v_cvt_pk_bf16_f32 v148, v164, v163
	v_cvt_pk_bf16_f32 v149, v156, v159
	v_cvt_pk_bf16_f32 v150, v154, v153
	v_lshlrev_b64 v[152:153], 12, v[160:161]
	v_lshl_add_u64 v[152:153], v[230:231], 0, v[152:153]
	v_cvt_pk_bf16_f32 v151, v155, v151
	global_store_dwordx4 v[152:153], v[144:147], off
	global_store_dwordx4 v[152:153], v[148:151], off offset:256
	s_nop 0
	v_add_u32_e32 v144, 0xb0, v228
	v_and_b32_e32 v145, 0x7f, v144
	v_add_u32_e32 v145, 1, v145
	v_cvt_f32_ubyte0_e32 v145, v145
	v_mul_f32_e64 v146, v241, -v145
	v_cmp_gt_f32_e64 s[4:5], s7, v146
	v_mov_b32_e32 v147, v4
	v_mov_b32_e32 v148, v140
	v_cndmask_b32_e64 v146, 0, v234, s[4:5]
	v_fma_f32 v145, v241, -v145, v146
	v_exp_f32_e32 v145, v145
	v_cndmask_b32_e64 v146, 0, v235, s[4:5]
	v_mov_b32_e32 v149, v136
	s_mov_b64 s[4:5], 0
	v_ldexp_f32 v145, v145, v146
	v_mov_b32_e32 v146, v20
	v_pk_mul_f32 v[146:147], v[146:147], v[148:149]
	v_mul_f32_e32 v145, 0x3d800000, v145
	v_sub_f32_e32 v136, v146, v147
	v_mov_b32_e32 v146, v4
	v_mov_b32_e32 v147, v20
	v_cndmask_b32_e32 v145, 1.0, v145, vcc
	v_pk_mul_f32 v[146:147], v[146:147], v[148:149]
	v_mul_f32_e32 v150, v145, v136
	v_add_f32_e32 v136, v146, v147
	v_mul_f32_e32 v148, v145, v136
	v_mov_b32_e32 v146, v21
	v_mov_b32_e32 v147, v5
	v_mov_b32_e32 v136, v141
	v_pk_mul_f32 v[140:141], v[146:147], v[136:137]
	s_nop 0
	v_sub_f32_e32 v140, v140, v141
	v_mul_f32_e32 v146, v145, v140
	v_mov_b32_e32 v140, v5
	v_mov_b32_e32 v141, v21
	v_pk_mul_f32 v[136:137], v[140:141], v[136:137]
	v_mov_b32_e32 v140, v142
	v_add_f32_e32 v136, v136, v137
	v_mul_f32_e32 v147, v145, v136
	v_mov_b32_e32 v136, v22
	v_mov_b32_e32 v137, v6
	v_mov_b32_e32 v141, v138
	v_pk_mul_f32 v[136:137], v[136:137], v[140:141]
	v_mov_b32_e32 v138, v143
	v_sub_f32_e32 v136, v136, v137
	v_mul_f32_e32 v142, v145, v136
	v_mov_b32_e32 v136, v6
	v_mov_b32_e32 v137, v22
	v_pk_mul_f32 v[136:137], v[136:137], v[140:141]
	s_nop 0
	v_add_f32_e32 v136, v136, v137
	v_mul_f32_e32 v140, v145, v136
	v_mov_b32_e32 v136, v23
	v_mov_b32_e32 v137, v7
	v_pk_mul_f32 v[136:137], v[136:137], v[138:139]
	s_nop 0
	v_sub_f32_e32 v136, v136, v137
	v_mul_f32_e32 v141, v145, v136
	v_mov_b32_e32 v136, v7
	v_mov_b32_e32 v137, v23
	v_pk_mul_f32 v[136:137], v[136:137], v[138:139]
	v_mov_b32_e32 v138, v132
	v_add_f32_e32 v136, v136, v137
	v_mul_f32_e32 v143, v145, v136
	v_mov_b32_e32 v136, v12
	v_mov_b32_e32 v137, v0
	v_mov_b32_e32 v139, v128
	v_pk_mul_f32 v[136:137], v[136:137], v[138:139]
	s_nop 0
	v_sub_f32_e32 v128, v136, v137
	v_mov_b32_e32 v136, v0
	v_mov_b32_e32 v137, v12
	v_pk_mul_f32 v[136:137], v[136:137], v[138:139]
	v_mul_f32_e32 v149, v145, v128
	v_add_f32_e32 v128, v136, v137
	v_mul_f32_e32 v138, v145, v128
	v_mov_b32_e32 v136, v13
	v_mov_b32_e32 v137, v1
	v_mov_b32_e32 v128, v133
	v_pk_mul_f32 v[132:133], v[136:137], v[128:129]
	s_nop 0
	v_sub_f32_e32 v132, v132, v133
	v_mul_f32_e32 v136, v145, v132
	v_mov_b32_e32 v132, v1
	v_mov_b32_e32 v133, v13
	v_pk_mul_f32 v[128:129], v[132:133], v[128:129]
	v_mov_b32_e32 v132, v134
	v_add_f32_e32 v128, v128, v129
	v_mul_f32_e32 v139, v145, v128
	v_mov_b32_e32 v128, v14
	v_mov_b32_e32 v129, v2
	v_mov_b32_e32 v133, v130
	v_pk_mul_f32 v[128:129], v[128:129], v[132:133]
	v_mov_b32_e32 v130, v135
	v_sub_f32_e32 v128, v128, v129
	v_mul_f32_e32 v137, v145, v128
	v_mov_b32_e32 v128, v2
	v_mov_b32_e32 v129, v14
	v_pk_mul_f32 v[128:129], v[128:129], v[132:133]
	v_cvt_pk_bf16_f32 v134, v150, v146
	v_cvt_pk_bf16_f32 v135, v142, v141
	v_cvt_pk_bf16_f32 v136, v149, v136
	s_nop 0
	v_add_f32_e32 v128, v128, v129
	v_mul_f32_e32 v132, v145, v128
	v_mov_b32_e32 v128, v15
	v_mov_b32_e32 v129, v3
	v_pk_mul_f32 v[128:129], v[128:129], v[130:131]
	s_nop 0
	v_sub_f32_e32 v128, v128, v129
	v_mul_f32_e32 v133, v145, v128
	v_mov_b32_e32 v128, v3
	v_mov_b32_e32 v129, v15
	v_pk_mul_f32 v[128:129], v[128:129], v[130:131]
	v_cvt_pk_bf16_f32 v137, v137, v133
	s_nop 0
	v_add_f32_e32 v128, v128, v129
	v_mul_f32_e32 v131, v145, v128
	v_ashrrev_i32_e32 v145, 31, v144
	v_cvt_pk_bf16_f32 v128, v148, v147
	v_cvt_pk_bf16_f32 v129, v140, v143
	v_cvt_pk_bf16_f32 v130, v138, v139
	v_cvt_pk_bf16_f32 v131, v132, v131
	v_lshlrev_b64 v[132:133], 12, v[144:145]
	v_lshl_add_u64 v[132:133], v[230:231], 0, v[132:133]
	global_store_dwordx4 v[132:133], v[134:137], off

.LBB0_216:
	v_mov_b64_e32 v[0:1], 0x1600
	s_ashr_i32 s7, s6, 31
	v_cmp_lt_i64_e32 vcc, s[8:9], v[0:1]
	s_lshl_b64 s[8:9], s[6:7], 20
	s_add_u32 s8, s22, s8
	s_addc_u32 s9, s23, s9
	s_and_b64 s[10:11], vcc, exec
	s_cselect_b32 s7, s9, s15
	s_cselect_b32 s36, s8, s14
	s_ashr_i32 s5, s4, 31
	s_lshl_b64 s[10:11], s[4:5], 20
	s_add_u32 s10, s24, s10
	s_addc_u32 s11, s25, s11
	s_and_b64 s[18:19], vcc, exec
	s_cselect_b32 s5, s11, s17
	s_cselect_b32 s37, s10, s16
	s_add_u32 s14, s14, 0x80080
	s_addc_u32 s15, s15, 0
	s_add_u32 s38, s16, 0x100
	s_addc_u32 s39, s17, 0
	s_mov_b32 s40, -2
	s_mov_b64 s[48:49], 0x80
	v_add_u32_e32 v220, 0x10000, v141
	s_add_u32 s16, s14, 0xfff80080
	s_addc_u32 s17, s15, -1
	s_add_i32 s41, 0, 0x10000
	ds_read_b128 v[144:147], v220 offset:0
	ds_read_b128 v[148:151], v220 offset:1024
	ds_read_b128 v[152:155], v220 offset:2048
	ds_read_b128 v[156:159], v220 offset:3072
	s_cmp_eq_u32 s40, 28
	s_cselect_b32 s19, s7, s17
	s_cselect_b32 s18, s36, s16
	s_cselect_b32 s17, s5, s39
	s_cselect_b32 s16, s37, s38
	s_add_i32 m0, s13, 0xc000
	ds_read_b128 v[160:163], v143
	ds_read_b128 v[164:167], v143 offset:1024
	ds_read_b128 v[168:171], v143 offset:2048
	ds_read_b128 v[172:175], v143 offset:3072
	ds_read_b128 v[176:179], v143 offset:4096
	ds_read_b128 v[180:183], v143 offset:5120
	ds_read_b128 v[184:187], v143 offset:6144
	ds_read_b128 v[188:191], v143 offset:7168
	global_load_lds_dwordx4 v134, s[14:15]
	s_add_i32 m0, s13, 0xe000
	s_nop 0
	global_load_lds_dwordx4 v136, s[14:15]
	s_waitcnt lgkmcnt(8)
	s_barrier
	s_waitcnt lgkmcnt(0)
	v_mfma_f32_16x16x32_bf16 v[124:127], v[144:147], v[160:163], 0
	v_mfma_f32_16x16x32_bf16 v[116:119], v[152:155], v[160:163], 0
	v_mfma_f32_16x16x32_bf16 v[108:111], v[144:147], v[168:171], 0
	v_mfma_f32_16x16x32_bf16 v[100:103], v[152:155], v[168:171], 0
	s_add_i32 s44, 0, 0x14000
	s_add_i32 s41, s41, s26
	v_mfma_f32_16x16x32_bf16 v[92:95], v[144:147], v[176:179], 0
	s_mov_b32 m0, s41
	v_mfma_f32_16x16x32_bf16 v[84:87], v[152:155], v[176:179], 0
	v_mfma_f32_16x16x32_bf16 v[76:79], v[144:147], v[184:187], 0
	v_mfma_f32_16x16x32_bf16 v[68:71], v[152:155], v[184:187], 0
	v_mfma_f32_16x16x32_bf16 v[124:127], v[148:151], v[164:167], v[124:127]
	v_mfma_f32_16x16x32_bf16 v[116:119], v[156:159], v[164:167], v[116:119]
	v_mfma_f32_16x16x32_bf16 v[108:111], v[148:151], v[172:175], v[108:111]
	v_mfma_f32_16x16x32_bf16 v[100:103], v[156:159], v[172:175], v[100:103]
	v_mfma_f32_16x16x32_bf16 v[92:95], v[148:151], v[180:183], v[92:95]
	v_mfma_f32_16x16x32_bf16 v[84:87], v[156:159], v[180:183], v[84:87]
	v_mfma_f32_16x16x32_bf16 v[76:79], v[148:151], v[188:191], v[76:79]
	v_mfma_f32_16x16x32_bf16 v[68:71], v[156:159], v[188:191], v[68:71]
	s_barrier
	ds_read_b128 v[196:199], v220 offset:16384
	ds_read_b128 v[204:207], v220 offset:17408
	ds_read_b128 v[208:211], v220 offset:18432
	ds_read_b128 v[214:217], v220 offset:19456
	global_load_lds_dwordx4 v192, s[16:17]
	s_add_i32 m0, s41, 0x2000
	s_nop 0
	global_load_lds_dwordx4 v128, s[16:17]
	s_barrier
	s_waitcnt lgkmcnt(0)
	v_mfma_f32_16x16x32_bf16 v[120:123], v[196:199], v[160:163], 0
	v_mfma_f32_16x16x32_bf16 v[112:115], v[208:211], v[160:163], 0
	v_mfma_f32_16x16x32_bf16 v[104:107], v[196:199], v[168:171], 0
	v_mfma_f32_16x16x32_bf16 v[96:99], v[208:211], v[168:171], 0
	s_mov_b32 m0, s13
	v_mfma_f32_16x16x32_bf16 v[88:91], v[196:199], v[176:179], 0
	s_add_u32 s48, s18, 0x80
	s_addc_u32 s49, s19, 0
	v_mfma_f32_16x16x32_bf16 v[80:83], v[208:211], v[176:179], 0
	v_mfma_f32_16x16x32_bf16 v[72:75], v[196:199], v[184:187], 0
	v_mfma_f32_16x16x32_bf16 v[64:67], v[208:211], v[184:187], 0
	v_mfma_f32_16x16x32_bf16 v[120:123], v[204:207], v[164:167], v[120:123]
	v_mfma_f32_16x16x32_bf16 v[112:115], v[214:217], v[164:167], v[112:115]
	v_mfma_f32_16x16x32_bf16 v[104:107], v[204:207], v[172:175], v[104:107]
	v_mfma_f32_16x16x32_bf16 v[96:99], v[214:217], v[172:175], v[96:99]
	v_mfma_f32_16x16x32_bf16 v[88:91], v[204:207], v[180:183], v[88:91]
	v_mfma_f32_16x16x32_bf16 v[80:83], v[214:217], v[180:183], v[80:83]
	v_mfma_f32_16x16x32_bf16 v[72:75], v[204:207], v[188:191], v[72:75]
	v_mfma_f32_16x16x32_bf16 v[64:67], v[214:217], v[188:191], v[64:67]
	s_barrier
	ds_read_b128 v[160:163], v143 offset:16384
	ds_read_b128 v[164:167], v143 offset:17408
	ds_read_b128 v[168:171], v143 offset:18432
	ds_read_b128 v[172:175], v143 offset:19456
	ds_read_b128 v[176:179], v143 offset:20480
	ds_read_b128 v[180:183], v143 offset:21504
	ds_read_b128 v[184:187], v143 offset:22528
	ds_read_b128 v[188:191], v143 offset:23552
	global_load_lds_dwordx4 v132, s[18:19]
	s_mov_b32 m0, s28
	s_nop 0
	global_load_lds_dwordx4 v130, s[18:19]
	s_barrier
	s_waitcnt lgkmcnt(0)
	v_mfma_f32_16x16x32_bf16 v[60:63], v[144:147], v[160:163], 0
	v_mfma_f32_16x16x32_bf16 v[52:55], v[152:155], v[160:163], 0
	v_mfma_f32_16x16x32_bf16 v[44:47], v[144:147], v[168:171], 0
	v_mfma_f32_16x16x32_bf16 v[36:39], v[152:155], v[168:171], 0
	s_add_u32 s42, s16, 0x80000
	s_addc_u32 s43, s17, 0
	v_mfma_f32_16x16x32_bf16 v[28:31], v[144:147], v[176:179], 0
	s_add_i32 s41, s44, s26
	s_mov_b32 m0, s41
	v_mfma_f32_16x16x32_bf16 v[20:23], v[152:155], v[176:179], 0
	v_mfma_f32_16x16x32_bf16 v[12:15], v[144:147], v[184:187], 0
	v_mfma_f32_16x16x32_bf16 v[4:7], v[152:155], v[184:187], 0
	v_mfma_f32_16x16x32_bf16 v[60:63], v[148:151], v[164:167], v[60:63]
	v_mfma_f32_16x16x32_bf16 v[52:55], v[156:159], v[164:167], v[52:55]
	v_mfma_f32_16x16x32_bf16 v[44:47], v[148:151], v[172:175], v[44:47]
	v_mfma_f32_16x16x32_bf16 v[36:39], v[156:159], v[172:175], v[36:39]
	v_mfma_f32_16x16x32_bf16 v[28:31], v[148:151], v[180:183], v[28:31]
	v_mfma_f32_16x16x32_bf16 v[20:23], v[156:159], v[180:183], v[20:23]
	v_mfma_f32_16x16x32_bf16 v[12:15], v[148:151], v[188:191], v[12:15]
	v_mfma_f32_16x16x32_bf16 v[4:7], v[156:159], v[188:191], v[4:7]
	s_barrier
	global_load_lds_dwordx4 v192, s[42:43]
	s_add_i32 m0, s41, 0x2000
	s_nop 0
	global_load_lds_dwordx4 v128, s[42:43]
	s_waitcnt vmcnt(6)
	s_barrier
	v_mfma_f32_16x16x32_bf16 v[56:59], v[196:199], v[160:163], 0
	v_mfma_f32_16x16x32_bf16 v[48:51], v[208:211], v[160:163], 0
	v_mfma_f32_16x16x32_bf16 v[40:43], v[196:199], v[168:171], 0
	v_mfma_f32_16x16x32_bf16 v[32:35], v[208:211], v[168:171], 0
	s_add_i32 s41, 0, 0x18000
	v_mfma_f32_16x16x32_bf16 v[24:27], v[196:199], v[176:179], 0
	s_add_u32 s18, s18, 0x80000
	s_addc_u32 s19, s19, 0
	v_mfma_f32_16x16x32_bf16 v[16:19], v[208:211], v[176:179], 0
	s_mov_b32 m0, s29
	v_mfma_f32_16x16x32_bf16 v[8:11], v[196:199], v[184:187], 0
	v_mfma_f32_16x16x32_bf16 v[0:3], v[208:211], v[184:187], 0
	v_mfma_f32_16x16x32_bf16 v[56:59], v[204:207], v[164:167], v[56:59]
	v_mfma_f32_16x16x32_bf16 v[48:51], v[214:217], v[164:167], v[48:51]
	v_mfma_f32_16x16x32_bf16 v[40:43], v[204:207], v[172:175], v[40:43]
	v_mfma_f32_16x16x32_bf16 v[32:35], v[214:217], v[172:175], v[32:35]
	v_mfma_f32_16x16x32_bf16 v[24:27], v[204:207], v[180:183], v[24:27]
	v_mfma_f32_16x16x32_bf16 v[16:19], v[214:217], v[180:183], v[16:19]
	v_mfma_f32_16x16x32_bf16 v[8:11], v[204:207], v[188:191], v[8:11]
	v_mfma_f32_16x16x32_bf16 v[0:3], v[214:217], v[188:191], v[0:3]
	s_barrier
	ds_read_b128 v[144:147], v220 offset:32768
	ds_read_b128 v[148:151], v220 offset:33792
	ds_read_b128 v[152:155], v220 offset:34816
	ds_read_b128 v[156:159], v220 offset:35840
	ds_read_b128 v[160:163], v143 offset:32768
	ds_read_b128 v[164:167], v143 offset:33792
	ds_read_b128 v[168:171], v143 offset:34816
	ds_read_b128 v[172:175], v143 offset:35840
	ds_read_b128 v[176:179], v143 offset:36864
	ds_read_b128 v[180:183], v143 offset:37888
	ds_read_b128 v[184:187], v143 offset:38912
	ds_read_b128 v[188:191], v143 offset:39936
	global_load_lds_dwordx4 v132, s[18:19]
	s_mov_b32 m0, s30
	s_nop 0
	global_load_lds_dwordx4 v130, s[18:19]
	s_waitcnt lgkmcnt(8)
	s_barrier
	s_waitcnt lgkmcnt(0)
	v_mfma_f32_16x16x32_bf16 v[124:127], v[144:147], v[160:163], v[124:127]
	v_mfma_f32_16x16x32_bf16 v[116:119], v[152:155], v[160:163], v[116:119]
	v_mfma_f32_16x16x32_bf16 v[108:111], v[144:147], v[168:171], v[108:111]
	v_mfma_f32_16x16x32_bf16 v[100:103], v[152:155], v[168:171], v[100:103]
	s_add_i32 s18, 0, 0x1c000
	s_add_i32 s19, s41, s26
	v_mfma_f32_16x16x32_bf16 v[92:95], v[144:147], v[176:179], v[92:95]
	s_add_i32 m0, s19, 0xffffff80
	v_mfma_f32_16x16x32_bf16 v[84:87], v[152:155], v[176:179], v[84:87]
	v_mfma_f32_16x16x32_bf16 v[76:79], v[144:147], v[184:187], v[76:79]
	v_mfma_f32_16x16x32_bf16 v[68:71], v[152:155], v[184:187], v[68:71]
	v_mfma_f32_16x16x32_bf16 v[124:127], v[148:151], v[164:167], v[124:127]
	v_mfma_f32_16x16x32_bf16 v[116:119], v[156:159], v[164:167], v[116:119]
	v_mfma_f32_16x16x32_bf16 v[108:111], v[148:151], v[172:175], v[108:111]
	v_mfma_f32_16x16x32_bf16 v[100:103], v[156:159], v[172:175], v[100:103]
	v_mfma_f32_16x16x32_bf16 v[92:95], v[148:151], v[180:183], v[92:95]
	v_mfma_f32_16x16x32_bf16 v[84:87], v[156:159], v[180:183], v[84:87]
	v_mfma_f32_16x16x32_bf16 v[76:79], v[148:151], v[188:191], v[76:79]
	v_mfma_f32_16x16x32_bf16 v[68:71], v[156:159], v[188:191], v[68:71]
	s_barrier
	ds_read_b128 v[196:199], v220 offset:49152
	ds_read_b128 v[204:207], v220 offset:50176
	ds_read_b128 v[208:211], v220 offset:51200
	ds_read_b128 v[214:217], v220 offset:52224
	global_load_lds_dwordx4 v192, s[16:17] offset:128
	s_add_i32 m0, s19, 0x1f80
	s_nop 0
	global_load_lds_dwordx4 v128, s[16:17] offset:128
	s_barrier
	s_waitcnt lgkmcnt(0)
	v_mfma_f32_16x16x32_bf16 v[120:123], v[196:199], v[160:163], v[120:123]
	v_mfma_f32_16x16x32_bf16 v[112:115], v[208:211], v[160:163], v[112:115]
	v_mfma_f32_16x16x32_bf16 v[104:107], v[196:199], v[168:171], v[104:107]
	v_mfma_f32_16x16x32_bf16 v[96:99], v[208:211], v[168:171], v[96:99]
	s_mov_b32 m0, s33
	v_mfma_f32_16x16x32_bf16 v[88:91], v[196:199], v[176:179], v[88:91]
	v_mfma_f32_16x16x32_bf16 v[80:83], v[208:211], v[176:179], v[80:83]
	v_mfma_f32_16x16x32_bf16 v[72:75], v[196:199], v[184:187], v[72:75]
	v_mfma_f32_16x16x32_bf16 v[64:67], v[208:211], v[184:187], v[64:67]
	v_mfma_f32_16x16x32_bf16 v[120:123], v[204:207], v[164:167], v[120:123]
	v_mfma_f32_16x16x32_bf16 v[112:115], v[214:217], v[164:167], v[112:115]
	v_mfma_f32_16x16x32_bf16 v[104:107], v[204:207], v[172:175], v[104:107]
	v_mfma_f32_16x16x32_bf16 v[96:99], v[214:217], v[172:175], v[96:99]
	v_mfma_f32_16x16x32_bf16 v[88:91], v[204:207], v[180:183], v[88:91]
	v_mfma_f32_16x16x32_bf16 v[80:83], v[214:217], v[180:183], v[80:83]
	v_mfma_f32_16x16x32_bf16 v[72:75], v[204:207], v[188:191], v[72:75]
	v_mfma_f32_16x16x32_bf16 v[64:67], v[214:217], v[188:191], v[64:67]
	s_barrier
	ds_read_b128 v[160:163], v143 offset:49152
	ds_read_b128 v[164:167], v143 offset:50176
	ds_read_b128 v[168:171], v143 offset:51200
	ds_read_b128 v[172:175], v143 offset:52224
	ds_read_b128 v[176:179], v143 offset:53248
	ds_read_b128 v[180:183], v143 offset:54272
	ds_read_b128 v[184:187], v143 offset:55296
	ds_read_b128 v[188:191], v143 offset:56320
	global_load_lds_dwordx4 v132, s[48:49]
	s_mov_b32 m0, s34
	s_nop 0
	global_load_lds_dwordx4 v130, s[48:49]
	s_barrier
	s_waitcnt lgkmcnt(0)
	v_mfma_f32_16x16x32_bf16 v[60:63], v[144:147], v[160:163], v[60:63]
	v_mfma_f32_16x16x32_bf16 v[52:55], v[152:155], v[160:163], v[52:55]
	v_mfma_f32_16x16x32_bf16 v[44:47], v[144:147], v[168:171], v[44:47]
	v_mfma_f32_16x16x32_bf16 v[36:39], v[152:155], v[168:171], v[36:39]
	s_add_u32 s16, s16, 0x80080
	s_addc_u32 s17, s17, 0
	v_mfma_f32_16x16x32_bf16 v[28:31], v[144:147], v[176:179], v[28:31]
	s_add_i32 s18, s18, s26
	s_mov_b32 m0, s18
	v_mfma_f32_16x16x32_bf16 v[20:23], v[152:155], v[176:179], v[20:23]
	v_mfma_f32_16x16x32_bf16 v[12:15], v[144:147], v[184:187], v[12:15]
	v_mfma_f32_16x16x32_bf16 v[4:7], v[152:155], v[184:187], v[4:7]
	v_mfma_f32_16x16x32_bf16 v[60:63], v[148:151], v[164:167], v[60:63]
	v_mfma_f32_16x16x32_bf16 v[52:55], v[156:159], v[164:167], v[52:55]
	v_mfma_f32_16x16x32_bf16 v[44:47], v[148:151], v[172:175], v[44:47]
	v_mfma_f32_16x16x32_bf16 v[36:39], v[156:159], v[172:175], v[36:39]
	v_mfma_f32_16x16x32_bf16 v[28:31], v[148:151], v[180:183], v[28:31]
	v_mfma_f32_16x16x32_bf16 v[20:23], v[156:159], v[180:183], v[20:23]
	v_mfma_f32_16x16x32_bf16 v[12:15], v[148:151], v[188:191], v[12:15]
	v_mfma_f32_16x16x32_bf16 v[4:7], v[156:159], v[188:191], v[4:7]
	s_barrier
	global_load_lds_dwordx4 v192, s[16:17]
	s_add_i32 m0, s18, 0x2000
	s_nop 0
	global_load_lds_dwordx4 v128, s[16:17]
	s_waitcnt vmcnt(6)
	s_barrier
	v_mfma_f32_16x16x32_bf16 v[56:59], v[196:199], v[160:163], v[56:59]
	v_mfma_f32_16x16x32_bf16 v[48:51], v[208:211], v[160:163], v[48:51]
	v_mfma_f32_16x16x32_bf16 v[40:43], v[196:199], v[168:171], v[40:43]
	v_mfma_f32_16x16x32_bf16 v[32:35], v[208:211], v[168:171], v[32:35]
	s_add_i32 s40, s40, 2
	v_mfma_f32_16x16x32_bf16 v[24:27], v[196:199], v[176:179], v[24:27]
	s_add_u32 s14, s14, 0x100
	s_addc_u32 s15, s15, 0
	v_mfma_f32_16x16x32_bf16 v[16:19], v[208:211], v[176:179], v[16:19]
	s_add_u32 s38, s38, 0x100
	s_addc_u32 s39, s39, 0
	v_mfma_f32_16x16x32_bf16 v[8:11], v[196:199], v[184:187], v[8:11]
	s_add_u32 s16, s14, 0xfff80080
	s_addc_u32 s17, s15, -1
	v_mfma_f32_16x16x32_bf16 v[0:3], v[208:211], v[184:187], v[0:3]
	s_add_i32 s41, 0, 0x10000
	s_cmp_eq_u32 s40, 28
	v_mfma_f32_16x16x32_bf16 v[56:59], v[204:207], v[164:167], v[56:59]
	s_cselect_b32 s19, s7, s17
	s_cselect_b32 s18, s36, s16
	v_mfma_f32_16x16x32_bf16 v[48:51], v[214:217], v[164:167], v[48:51]
	s_cselect_b32 s17, s5, s39
	s_cselect_b32 s16, s37, s38
	v_mfma_f32_16x16x32_bf16 v[40:43], v[204:207], v[172:175], v[40:43]
	s_add_i32 m0, s13, 0xc000
	v_mfma_f32_16x16x32_bf16 v[32:35], v[214:217], v[172:175], v[32:35]
	v_mfma_f32_16x16x32_bf16 v[24:27], v[204:207], v[180:183], v[24:27]
	v_mfma_f32_16x16x32_bf16 v[16:19], v[214:217], v[180:183], v[16:19]
	v_mfma_f32_16x16x32_bf16 v[8:11], v[204:207], v[188:191], v[8:11]
	v_mfma_f32_16x16x32_bf16 v[0:3], v[214:217], v[188:191], v[0:3]
	s_cmp_gt_u32 s40, 29
	s_barrier
.LBB0_217:
	ds_read_b128 v[144:147], v220 offset:0
	ds_read_b128 v[148:151], v220 offset:1024
	ds_read_b128 v[152:155], v220 offset:2048
	ds_read_b128 v[156:159], v220 offset:3072
	ds_read_b128 v[160:163], v143
	ds_read_b128 v[164:167], v143 offset:1024
	ds_read_b128 v[168:171], v143 offset:2048
	ds_read_b128 v[172:175], v143 offset:3072
	ds_read_b128 v[176:179], v143 offset:4096
	ds_read_b128 v[180:183], v143 offset:5120
	ds_read_b128 v[184:187], v143 offset:6144
	ds_read_b128 v[188:191], v143 offset:7168
	global_load_lds_dwordx4 v134, s[14:15]
	s_add_i32 m0, s13, 0xe000
	s_nop 0
	global_load_lds_dwordx4 v136, s[14:15]
	s_waitcnt lgkmcnt(8)
	s_barrier
	s_waitcnt lgkmcnt(0)
	v_mfma_f32_16x16x32_bf16 v[124:127], v[144:147], v[160:163], v[124:127]
	v_mfma_f32_16x16x32_bf16 v[116:119], v[152:155], v[160:163], v[116:119]
	v_mfma_f32_16x16x32_bf16 v[108:111], v[144:147], v[168:171], v[108:111]
	v_mfma_f32_16x16x32_bf16 v[100:103], v[152:155], v[168:171], v[100:103]
	s_add_i32 s44, 0, 0x14000
	s_add_i32 s41, s41, s26
	v_mfma_f32_16x16x32_bf16 v[92:95], v[144:147], v[176:179], v[92:95]
	s_mov_b32 m0, s41
	v_mfma_f32_16x16x32_bf16 v[84:87], v[152:155], v[176:179], v[84:87]
	v_mfma_f32_16x16x32_bf16 v[76:79], v[144:147], v[184:187], v[76:79]
	v_mfma_f32_16x16x32_bf16 v[68:71], v[152:155], v[184:187], v[68:71]
	v_mfma_f32_16x16x32_bf16 v[124:127], v[148:151], v[164:167], v[124:127]
	v_mfma_f32_16x16x32_bf16 v[116:119], v[156:159], v[164:167], v[116:119]
	v_mfma_f32_16x16x32_bf16 v[108:111], v[148:151], v[172:175], v[108:111]
	v_mfma_f32_16x16x32_bf16 v[100:103], v[156:159], v[172:175], v[100:103]
	v_mfma_f32_16x16x32_bf16 v[92:95], v[148:151], v[180:183], v[92:95]
	v_mfma_f32_16x16x32_bf16 v[84:87], v[156:159], v[180:183], v[84:87]
	v_mfma_f32_16x16x32_bf16 v[76:79], v[148:151], v[188:191], v[76:79]
	v_mfma_f32_16x16x32_bf16 v[68:71], v[156:159], v[188:191], v[68:71]
	s_barrier
	ds_read_b128 v[196:199], v220 offset:16384
	ds_read_b128 v[204:207], v220 offset:17408
	ds_read_b128 v[208:211], v220 offset:18432
	ds_read_b128 v[214:217], v220 offset:19456
	global_load_lds_dwordx4 v192, s[16:17]
	s_add_i32 m0, s41, 0x2000
	s_nop 0
	global_load_lds_dwordx4 v128, s[16:17]
	s_barrier
	s_waitcnt lgkmcnt(0)
	v_mfma_f32_16x16x32_bf16 v[120:123], v[196:199], v[160:163], v[120:123]
	v_mfma_f32_16x16x32_bf16 v[112:115], v[208:211], v[160:163], v[112:115]
	v_mfma_f32_16x16x32_bf16 v[104:107], v[196:199], v[168:171], v[104:107]
	v_mfma_f32_16x16x32_bf16 v[96:99], v[208:211], v[168:171], v[96:99]
	s_mov_b32 m0, s13
	v_mfma_f32_16x16x32_bf16 v[88:91], v[196:199], v[176:179], v[88:91]
	s_add_u32 s48, s18, 0x80
	s_addc_u32 s49, s19, 0
	v_mfma_f32_16x16x32_bf16 v[80:83], v[208:211], v[176:179], v[80:83]
	v_mfma_f32_16x16x32_bf16 v[72:75], v[196:199], v[184:187], v[72:75]
	v_mfma_f32_16x16x32_bf16 v[64:67], v[208:211], v[184:187], v[64:67]
	v_mfma_f32_16x16x32_bf16 v[120:123], v[204:207], v[164:167], v[120:123]
	v_mfma_f32_16x16x32_bf16 v[112:115], v[214:217], v[164:167], v[112:115]
	v_mfma_f32_16x16x32_bf16 v[104:107], v[204:207], v[172:175], v[104:107]
	v_mfma_f32_16x16x32_bf16 v[96:99], v[214:217], v[172:175], v[96:99]
	v_mfma_f32_16x16x32_bf16 v[88:91], v[204:207], v[180:183], v[88:91]
	v_mfma_f32_16x16x32_bf16 v[80:83], v[214:217], v[180:183], v[80:83]
	v_mfma_f32_16x16x32_bf16 v[72:75], v[204:207], v[188:191], v[72:75]
	v_mfma_f32_16x16x32_bf16 v[64:67], v[214:217], v[188:191], v[64:67]
	s_barrier
	ds_read_b128 v[160:163], v143 offset:16384
	ds_read_b128 v[164:167], v143 offset:17408
	ds_read_b128 v[168:171], v143 offset:18432
	ds_read_b128 v[172:175], v143 offset:19456
	ds_read_b128 v[176:179], v143 offset:20480
	ds_read_b128 v[180:183], v143 offset:21504
	ds_read_b128 v[184:187], v143 offset:22528
	ds_read_b128 v[188:191], v143 offset:23552
	global_load_lds_dwordx4 v132, s[18:19]
	s_mov_b32 m0, s28
	s_nop 0
	global_load_lds_dwordx4 v130, s[18:19]
	s_barrier
	s_waitcnt lgkmcnt(0)
	v_mfma_f32_16x16x32_bf16 v[60:63], v[144:147], v[160:163], v[60:63]
	v_mfma_f32_16x16x32_bf16 v[52:55], v[152:155], v[160:163], v[52:55]
	v_mfma_f32_16x16x32_bf16 v[44:47], v[144:147], v[168:171], v[44:47]
	v_mfma_f32_16x16x32_bf16 v[36:39], v[152:155], v[168:171], v[36:39]
	s_add_u32 s42, s16, 0x80000
	s_addc_u32 s43, s17, 0
	v_mfma_f32_16x16x32_bf16 v[28:31], v[144:147], v[176:179], v[28:31]
	s_add_i32 s41, s44, s26
	s_mov_b32 m0, s41
	v_mfma_f32_16x16x32_bf16 v[20:23], v[152:155], v[176:179], v[20:23]
	v_mfma_f32_16x16x32_bf16 v[12:15], v[144:147], v[184:187], v[12:15]
	v_mfma_f32_16x16x32_bf16 v[4:7], v[152:155], v[184:187], v[4:7]
	v_mfma_f32_16x16x32_bf16 v[60:63], v[148:151], v[164:167], v[60:63]
	v_mfma_f32_16x16x32_bf16 v[52:55], v[156:159], v[164:167], v[52:55]
	v_mfma_f32_16x16x32_bf16 v[44:47], v[148:151], v[172:175], v[44:47]
	v_mfma_f32_16x16x32_bf16 v[36:39], v[156:159], v[172:175], v[36:39]
	v_mfma_f32_16x16x32_bf16 v[28:31], v[148:151], v[180:183], v[28:31]
	v_mfma_f32_16x16x32_bf16 v[20:23], v[156:159], v[180:183], v[20:23]
	v_mfma_f32_16x16x32_bf16 v[12:15], v[148:151], v[188:191], v[12:15]
	v_mfma_f32_16x16x32_bf16 v[4:7], v[156:159], v[188:191], v[4:7]
	s_barrier
	global_load_lds_dwordx4 v192, s[42:43]
	s_add_i32 m0, s41, 0x2000
	s_nop 0
	global_load_lds_dwordx4 v128, s[42:43]
	s_waitcnt vmcnt(6)
	s_barrier
	v_mfma_f32_16x16x32_bf16 v[56:59], v[196:199], v[160:163], v[56:59]
	v_mfma_f32_16x16x32_bf16 v[48:51], v[208:211], v[160:163], v[48:51]
	v_mfma_f32_16x16x32_bf16 v[40:43], v[196:199], v[168:171], v[40:43]
	v_mfma_f32_16x16x32_bf16 v[32:35], v[208:211], v[168:171], v[32:35]
	s_add_i32 s41, 0, 0x18000
	v_mfma_f32_16x16x32_bf16 v[24:27], v[196:199], v[176:179], v[24:27]
	s_add_u32 s18, s18, 0x80000
	s_addc_u32 s19, s19, 0
	v_mfma_f32_16x16x32_bf16 v[16:19], v[208:211], v[176:179], v[16:19]
	s_mov_b32 m0, s29
	v_mfma_f32_16x16x32_bf16 v[8:11], v[196:199], v[184:187], v[8:11]
	v_mfma_f32_16x16x32_bf16 v[0:3], v[208:211], v[184:187], v[0:3]
	v_mfma_f32_16x16x32_bf16 v[56:59], v[204:207], v[164:167], v[56:59]
	v_mfma_f32_16x16x32_bf16 v[48:51], v[214:217], v[164:167], v[48:51]
	v_mfma_f32_16x16x32_bf16 v[40:43], v[204:207], v[172:175], v[40:43]
	v_mfma_f32_16x16x32_bf16 v[32:35], v[214:217], v[172:175], v[32:35]
	v_mfma_f32_16x16x32_bf16 v[24:27], v[204:207], v[180:183], v[24:27]
	v_mfma_f32_16x16x32_bf16 v[16:19], v[214:217], v[180:183], v[16:19]
	v_mfma_f32_16x16x32_bf16 v[8:11], v[204:207], v[188:191], v[8:11]
	v_mfma_f32_16x16x32_bf16 v[0:3], v[214:217], v[188:191], v[0:3]
	s_barrier
	ds_read_b128 v[144:147], v220 offset:32768
	ds_read_b128 v[148:151], v220 offset:33792
	ds_read_b128 v[152:155], v220 offset:34816
	ds_read_b128 v[156:159], v220 offset:35840
	ds_read_b128 v[160:163], v143 offset:32768
	ds_read_b128 v[164:167], v143 offset:33792
	ds_read_b128 v[168:171], v143 offset:34816
	ds_read_b128 v[172:175], v143 offset:35840
	ds_read_b128 v[176:179], v143 offset:36864
	ds_read_b128 v[180:183], v143 offset:37888
	ds_read_b128 v[184:187], v143 offset:38912
	ds_read_b128 v[188:191], v143 offset:39936
	global_load_lds_dwordx4 v132, s[18:19]
	s_mov_b32 m0, s30
	s_nop 0
	global_load_lds_dwordx4 v130, s[18:19]
	s_waitcnt lgkmcnt(8)
	s_barrier
	s_waitcnt lgkmcnt(0)
	v_mfma_f32_16x16x32_bf16 v[124:127], v[144:147], v[160:163], v[124:127]
	v_mfma_f32_16x16x32_bf16 v[116:119], v[152:155], v[160:163], v[116:119]
	v_mfma_f32_16x16x32_bf16 v[108:111], v[144:147], v[168:171], v[108:111]
	v_mfma_f32_16x16x32_bf16 v[100:103], v[152:155], v[168:171], v[100:103]
	s_add_i32 s18, 0, 0x1c000
	s_add_i32 s19, s41, s26
	v_mfma_f32_16x16x32_bf16 v[92:95], v[144:147], v[176:179], v[92:95]
	s_add_i32 m0, s19, 0xffffff80
	v_mfma_f32_16x16x32_bf16 v[84:87], v[152:155], v[176:179], v[84:87]
	v_mfma_f32_16x16x32_bf16 v[76:79], v[144:147], v[184:187], v[76:79]
	v_mfma_f32_16x16x32_bf16 v[68:71], v[152:155], v[184:187], v[68:71]
	v_mfma_f32_16x16x32_bf16 v[124:127], v[148:151], v[164:167], v[124:127]
	v_mfma_f32_16x16x32_bf16 v[116:119], v[156:159], v[164:167], v[116:119]
	v_mfma_f32_16x16x32_bf16 v[108:111], v[148:151], v[172:175], v[108:111]
	v_mfma_f32_16x16x32_bf16 v[100:103], v[156:159], v[172:175], v[100:103]
	v_mfma_f32_16x16x32_bf16 v[92:95], v[148:151], v[180:183], v[92:95]
	v_mfma_f32_16x16x32_bf16 v[84:87], v[156:159], v[180:183], v[84:87]
	v_mfma_f32_16x16x32_bf16 v[76:79], v[148:151], v[188:191], v[76:79]
	v_mfma_f32_16x16x32_bf16 v[68:71], v[156:159], v[188:191], v[68:71]
	s_barrier
	ds_read_b128 v[196:199], v220 offset:49152
	ds_read_b128 v[204:207], v220 offset:50176
	ds_read_b128 v[208:211], v220 offset:51200
	ds_read_b128 v[214:217], v220 offset:52224
	global_load_lds_dwordx4 v192, s[16:17] offset:128
	s_add_i32 m0, s19, 0x1f80
	s_nop 0
	global_load_lds_dwordx4 v128, s[16:17] offset:128
	s_barrier
	s_waitcnt lgkmcnt(0)
	v_mfma_f32_16x16x32_bf16 v[120:123], v[196:199], v[160:163], v[120:123]
	v_mfma_f32_16x16x32_bf16 v[112:115], v[208:211], v[160:163], v[112:115]
	v_mfma_f32_16x16x32_bf16 v[104:107], v[196:199], v[168:171], v[104:107]
	v_mfma_f32_16x16x32_bf16 v[96:99], v[208:211], v[168:171], v[96:99]
	s_mov_b32 m0, s33
	v_mfma_f32_16x16x32_bf16 v[88:91], v[196:199], v[176:179], v[88:91]
	v_mfma_f32_16x16x32_bf16 v[80:83], v[208:211], v[176:179], v[80:83]
	v_mfma_f32_16x16x32_bf16 v[72:75], v[196:199], v[184:187], v[72:75]
	v_mfma_f32_16x16x32_bf16 v[64:67], v[208:211], v[184:187], v[64:67]
	v_mfma_f32_16x16x32_bf16 v[120:123], v[204:207], v[164:167], v[120:123]
	v_mfma_f32_16x16x32_bf16 v[112:115], v[214:217], v[164:167], v[112:115]
	v_mfma_f32_16x16x32_bf16 v[104:107], v[204:207], v[172:175], v[104:107]
	v_mfma_f32_16x16x32_bf16 v[96:99], v[214:217], v[172:175], v[96:99]
	v_mfma_f32_16x16x32_bf16 v[88:91], v[204:207], v[180:183], v[88:91]
	v_mfma_f32_16x16x32_bf16 v[80:83], v[214:217], v[180:183], v[80:83]
	v_mfma_f32_16x16x32_bf16 v[72:75], v[204:207], v[188:191], v[72:75]
	v_mfma_f32_16x16x32_bf16 v[64:67], v[214:217], v[188:191], v[64:67]
	s_barrier
	ds_read_b128 v[160:163], v143 offset:49152
	ds_read_b128 v[164:167], v143 offset:50176
	ds_read_b128 v[168:171], v143 offset:51200
	ds_read_b128 v[172:175], v143 offset:52224
	ds_read_b128 v[176:179], v143 offset:53248
	ds_read_b128 v[180:183], v143 offset:54272
	ds_read_b128 v[184:187], v143 offset:55296
	ds_read_b128 v[188:191], v143 offset:56320
	global_load_lds_dwordx4 v132, s[48:49]
	s_mov_b32 m0, s34
	s_nop 0
	global_load_lds_dwordx4 v130, s[48:49]
	s_barrier
	s_waitcnt lgkmcnt(0)
	v_mfma_f32_16x16x32_bf16 v[60:63], v[144:147], v[160:163], v[60:63]
	v_mfma_f32_16x16x32_bf16 v[52:55], v[152:155], v[160:163], v[52:55]
	v_mfma_f32_16x16x32_bf16 v[44:47], v[144:147], v[168:171], v[44:47]
	v_mfma_f32_16x16x32_bf16 v[36:39], v[152:155], v[168:171], v[36:39]
	s_add_u32 s16, s16, 0x80080
	s_addc_u32 s17, s17, 0
	v_mfma_f32_16x16x32_bf16 v[28:31], v[144:147], v[176:179], v[28:31]
	s_add_i32 s18, s18, s26
	s_mov_b32 m0, s18
	v_mfma_f32_16x16x32_bf16 v[20:23], v[152:155], v[176:179], v[20:23]
	v_mfma_f32_16x16x32_bf16 v[12:15], v[144:147], v[184:187], v[12:15]
	v_mfma_f32_16x16x32_bf16 v[4:7], v[152:155], v[184:187], v[4:7]
	v_mfma_f32_16x16x32_bf16 v[60:63], v[148:151], v[164:167], v[60:63]
	v_mfma_f32_16x16x32_bf16 v[52:55], v[156:159], v[164:167], v[52:55]
	v_mfma_f32_16x16x32_bf16 v[44:47], v[148:151], v[172:175], v[44:47]
	v_mfma_f32_16x16x32_bf16 v[36:39], v[156:159], v[172:175], v[36:39]
	v_mfma_f32_16x16x32_bf16 v[28:31], v[148:151], v[180:183], v[28:31]
	v_mfma_f32_16x16x32_bf16 v[20:23], v[156:159], v[180:183], v[20:23]
	v_mfma_f32_16x16x32_bf16 v[12:15], v[148:151], v[188:191], v[12:15]
	v_mfma_f32_16x16x32_bf16 v[4:7], v[156:159], v[188:191], v[4:7]
	s_barrier
	global_load_lds_dwordx4 v192, s[16:17]
	s_add_i32 m0, s18, 0x2000
	s_nop 0
	global_load_lds_dwordx4 v128, s[16:17]
	s_waitcnt vmcnt(6)
	s_barrier
	v_mfma_f32_16x16x32_bf16 v[56:59], v[196:199], v[160:163], v[56:59]
	v_mfma_f32_16x16x32_bf16 v[48:51], v[208:211], v[160:163], v[48:51]
	v_mfma_f32_16x16x32_bf16 v[40:43], v[196:199], v[168:171], v[40:43]
	v_mfma_f32_16x16x32_bf16 v[32:35], v[208:211], v[168:171], v[32:35]
	s_add_i32 s40, s40, 2
	v_mfma_f32_16x16x32_bf16 v[24:27], v[196:199], v[176:179], v[24:27]
	s_add_u32 s14, s14, 0x100
	s_addc_u32 s15, s15, 0
	v_mfma_f32_16x16x32_bf16 v[16:19], v[208:211], v[176:179], v[16:19]
	s_add_u32 s38, s38, 0x100
	s_addc_u32 s39, s39, 0
	v_mfma_f32_16x16x32_bf16 v[8:11], v[196:199], v[184:187], v[8:11]
	s_add_u32 s16, s14, 0xfff80080
	s_addc_u32 s17, s15, -1
	v_mfma_f32_16x16x32_bf16 v[0:3], v[208:211], v[184:187], v[0:3]
	s_add_i32 s41, 0, 0x10000
	s_cmp_eq_u32 s40, 28
	v_mfma_f32_16x16x32_bf16 v[56:59], v[204:207], v[164:167], v[56:59]
	s_cselect_b32 s19, s7, s17
	s_cselect_b32 s18, s36, s16
	v_mfma_f32_16x16x32_bf16 v[48:51], v[214:217], v[164:167], v[48:51]
	s_cselect_b32 s17, s5, s39
	s_cselect_b32 s16, s37, s38
	v_mfma_f32_16x16x32_bf16 v[40:43], v[204:207], v[172:175], v[40:43]
	s_add_i32 m0, s13, 0xc000
	v_mfma_f32_16x16x32_bf16 v[32:35], v[214:217], v[172:175], v[32:35]
	v_mfma_f32_16x16x32_bf16 v[24:27], v[204:207], v[180:183], v[24:27]
	v_mfma_f32_16x16x32_bf16 v[16:19], v[214:217], v[180:183], v[16:19]
	v_mfma_f32_16x16x32_bf16 v[8:11], v[204:207], v[188:191], v[8:11]
	v_mfma_f32_16x16x32_bf16 v[0:3], v[214:217], v[188:191], v[0:3]
	s_cmp_gt_u32 s40, 29
	s_barrier
	s_cbranch_scc0 .LBB0_217
	v_mul_f32_e32 v145, 0xbfb8aa3b, v124
	v_exp_f32_e32 v145, v145
	v_lshl_or_b32 v146, s35, 7, v142
	v_lshl_add_u32 v144, s12, 8, v140
	v_ashrrev_i32_e32 v147, 31, v146
	v_add_f32_e32 v145, 1.0, v145
	v_rcp_f32_e32 v145, v145
	v_mov_b64_e32 v[138:139], s[2:3]
	s_movk_i32 s5, 0x2c00
	v_mad_i64_i32 v[148:149], s[14:15], v144, s5, v[138:139]
	v_mul_f32_e32 v124, v124, v145
	v_mul_f32_e32 v120, v124, v120
	v_mul_f32_e32 v124, 0xbfb8aa3b, v125
	v_exp_f32_e32 v124, v124
	s_and_b64 vcc, exec, s[0:1]
	s_mov_b32 s35, s4
	s_mov_b32 s12, s6
	v_add_f32_e32 v124, 1.0, v124
	v_rcp_f32_e32 v124, v124
	s_mov_b64 s[16:17], s[10:11]
	v_mul_f32_e32 v124, v125, v124
	v_mul_f32_e32 v121, v124, v121
	v_mul_f32_e32 v124, 0xbfb8aa3b, v126
	v_exp_f32_e32 v124, v124
	s_nop 0
	v_add_f32_e32 v124, 1.0, v124
	v_rcp_f32_e32 v124, v124
	s_nop 0
	v_mul_f32_e32 v124, v126, v124
	v_mul_f32_e32 v122, v124, v122
	v_mul_f32_e32 v124, 0xbfb8aa3b, v127
	v_exp_f32_e32 v124, v124
	s_nop 0
	v_add_f32_e32 v124, 1.0, v124
	v_rcp_f32_e32 v124, v124
	s_nop 0
	v_mul_f32_e32 v124, v127, v124
	v_mul_f32_e32 v123, v124, v123
	v_mul_f32_e32 v124, 0xbfb8aa3b, v116
	v_exp_f32_e32 v124, v124
	s_nop 0
	v_add_f32_e32 v124, 1.0, v124
	v_rcp_f32_e32 v124, v124
	s_nop 0
	v_mul_f32_e32 v116, v116, v124
	v_mul_f32_e32 v116, v116, v112
	v_mul_f32_e32 v112, 0xbfb8aa3b, v117
	v_exp_f32_e32 v112, v112
	s_nop 0
	v_add_f32_e32 v112, 1.0, v112
	v_rcp_f32_e32 v112, v112
	s_nop 0
	v_mul_f32_e32 v112, v117, v112
	v_mul_f32_e32 v117, v112, v113
	v_mul_f32_e32 v112, 0xbfb8aa3b, v118
	v_exp_f32_e32 v112, v112
	s_nop 0
	v_add_f32_e32 v112, 1.0, v112
	v_rcp_f32_e32 v112, v112
	s_nop 0
	v_mul_f32_e32 v112, v118, v112
	v_mul_f32_e32 v124, v112, v114
	v_mul_f32_e32 v112, 0xbfb8aa3b, v119
	v_exp_f32_e32 v112, v112
	v_cvt_pk_bf16_f32 v114, v120, v121
	s_nop 0
	v_add_f32_e32 v112, 1.0, v112
	v_rcp_f32_e32 v112, v112
	s_nop 0
	v_mul_f32_e32 v112, v119, v112
	v_mul_f32_e32 v125, v112, v115
	v_lshlrev_b64 v[112:113], 1, v[146:147]
	v_lshl_add_u64 v[118:119], v[148:149], 0, v[112:113]
	v_cvt_pk_bf16_f32 v115, v122, v123
	v_cvt_pk_bf16_f32 v116, v116, v117
	v_cvt_pk_bf16_f32 v117, v124, v125
	global_store_dwordx4 v[118:119], v[114:117], off
	s_nop 1
	v_mul_f32_e32 v116, 0xbfb8aa3b, v108
	v_exp_f32_e32 v116, v116
	v_or_b32_e32 v114, 16, v144
	v_mad_i64_i32 v[114:115], s[14:15], v114, s5, v[138:139]
	v_add_f32_e32 v116, 1.0, v116
	v_rcp_f32_e32 v116, v116
	s_nop 0
	v_mul_f32_e32 v108, v108, v116
	v_mul_f32_e32 v104, v108, v104
	v_mul_f32_e32 v108, 0xbfb8aa3b, v109
	v_exp_f32_e32 v108, v108
	s_nop 0
	v_add_f32_e32 v108, 1.0, v108
	v_rcp_f32_e32 v108, v108
	s_nop 0
	v_mul_f32_e32 v108, v109, v108
	v_mul_f32_e32 v105, v108, v105
	v_mul_f32_e32 v108, 0xbfb8aa3b, v110
	v_exp_f32_e32 v108, v108
	s_nop 0
	v_add_f32_e32 v108, 1.0, v108
	v_rcp_f32_e32 v108, v108
	s_nop 0
	v_mul_f32_e32 v108, v110, v108
	v_mul_f32_e32 v106, v108, v106
	v_mul_f32_e32 v108, 0xbfb8aa3b, v111
	v_exp_f32_e32 v108, v108
	s_nop 0
	v_add_f32_e32 v108, 1.0, v108
	v_rcp_f32_e32 v108, v108
	s_nop 0
	v_mul_f32_e32 v108, v111, v108
	v_mul_f32_e32 v107, v108, v107
	v_mul_f32_e32 v108, 0xbfb8aa3b, v100
	v_exp_f32_e32 v108, v108
	s_nop 0
	v_add_f32_e32 v108, 1.0, v108
	v_rcp_f32_e32 v108, v108
	s_nop 0
	v_mul_f32_e32 v100, v100, v108
	v_mul_f32_e32 v108, v100, v96
	v_mul_f32_e32 v96, 0xbfb8aa3b, v101
	v_exp_f32_e32 v96, v96
	s_nop 0
	v_add_f32_e32 v96, 1.0, v96
	v_rcp_f32_e32 v96, v96
	s_nop 0
	v_mul_f32_e32 v96, v101, v96
	v_mul_f32_e32 v109, v96, v97
	v_mul_f32_e32 v96, 0xbfb8aa3b, v102
	v_exp_f32_e32 v96, v96
	v_lshl_add_u64 v[100:101], v[114:115], 0, v[112:113]
	v_add_f32_e32 v96, 1.0, v96
	v_rcp_f32_e32 v96, v96
	s_nop 0
	v_mul_f32_e32 v96, v102, v96
	v_mul_f32_e32 v102, v96, v98
	v_mul_f32_e32 v96, 0xbfb8aa3b, v103
	v_exp_f32_e32 v96, v96
	s_nop 0
	v_add_f32_e32 v96, 1.0, v96
	v_rcp_f32_e32 v96, v96
	s_nop 0
	v_mul_f32_e32 v96, v103, v96
	v_mul_f32_e32 v99, v96, v99
	v_cvt_pk_bf16_f32 v96, v104, v105
	v_cvt_pk_bf16_f32 v97, v106, v107
	v_cvt_pk_bf16_f32 v98, v108, v109
	v_cvt_pk_bf16_f32 v99, v102, v99
	global_store_dwordx4 v[100:101], v[96:99], off
	s_nop 1
	v_mul_f32_e32 v98, 0xbfb8aa3b, v92
	v_exp_f32_e32 v98, v98
	v_or_b32_e32 v96, 32, v144
	v_mad_i64_i32 v[96:97], s[14:15], v96, s5, v[138:139]
	v_add_f32_e32 v98, 1.0, v98
	v_rcp_f32_e32 v98, v98
	s_nop 0
	v_mul_f32_e32 v92, v92, v98
	v_mul_f32_e32 v88, v92, v88
	v_mul_f32_e32 v92, 0xbfb8aa3b, v93
	v_exp_f32_e32 v92, v92
	s_nop 0
	v_add_f32_e32 v92, 1.0, v92
	v_rcp_f32_e32 v92, v92
	s_nop 0
	v_mul_f32_e32 v92, v93, v92
	v_mul_f32_e32 v89, v92, v89
	v_mul_f32_e32 v92, 0xbfb8aa3b, v94
	v_exp_f32_e32 v92, v92
	s_nop 0
	v_add_f32_e32 v92, 1.0, v92
	v_rcp_f32_e32 v92, v92
	s_nop 0
	v_mul_f32_e32 v92, v94, v92
	v_mul_f32_e32 v90, v92, v90
	v_mul_f32_e32 v92, 0xbfb8aa3b, v95
	v_exp_f32_e32 v92, v92
	s_nop 0
	v_add_f32_e32 v92, 1.0, v92
	v_rcp_f32_e32 v92, v92
	s_nop 0
	v_mul_f32_e32 v92, v95, v92
	v_mul_f32_e32 v91, v92, v91
	v_mul_f32_e32 v92, 0xbfb8aa3b, v84
	v_exp_f32_e32 v92, v92
	s_nop 0
	v_add_f32_e32 v92, 1.0, v92
	v_rcp_f32_e32 v92, v92
	s_nop 0
	v_mul_f32_e32 v84, v84, v92
	v_mul_f32_e32 v92, v84, v80
	v_mul_f32_e32 v80, 0xbfb8aa3b, v85
	v_exp_f32_e32 v80, v80
	s_nop 0
	v_add_f32_e32 v80, 1.0, v80
	v_rcp_f32_e32 v80, v80
	s_nop 0
	v_mul_f32_e32 v80, v85, v80
	v_mul_f32_e32 v93, v80, v81
	v_mul_f32_e32 v80, 0xbfb8aa3b, v86
	v_exp_f32_e32 v80, v80
	v_lshl_add_u64 v[84:85], v[96:97], 0, v[112:113]
	v_add_f32_e32 v80, 1.0, v80
	v_rcp_f32_e32 v80, v80
	s_nop 0
	v_mul_f32_e32 v80, v86, v80
	v_mul_f32_e32 v86, v80, v82
	v_mul_f32_e32 v80, 0xbfb8aa3b, v87
	v_exp_f32_e32 v80, v80
	s_nop 0
	v_add_f32_e32 v80, 1.0, v80
	v_rcp_f32_e32 v80, v80
	s_nop 0
	v_mul_f32_e32 v80, v87, v80
	v_mul_f32_e32 v83, v80, v83
	v_cvt_pk_bf16_f32 v80, v88, v89
	v_cvt_pk_bf16_f32 v81, v90, v91
	v_cvt_pk_bf16_f32 v82, v92, v93
	v_cvt_pk_bf16_f32 v83, v86, v83
	global_store_dwordx4 v[84:85], v[80:83], off
	s_nop 1
	v_mul_f32_e32 v82, 0xbfb8aa3b, v76
	v_exp_f32_e32 v82, v82
	v_or_b32_e32 v80, 48, v144
	v_mad_i64_i32 v[80:81], s[14:15], v80, s5, v[138:139]
	v_add_f32_e32 v82, 1.0, v82
	v_rcp_f32_e32 v82, v82
	s_nop 0
	v_mul_f32_e32 v76, v76, v82
	v_mul_f32_e32 v72, v76, v72
	v_mul_f32_e32 v76, 0xbfb8aa3b, v77
	v_exp_f32_e32 v76, v76
	s_nop 0
	v_add_f32_e32 v76, 1.0, v76
	v_rcp_f32_e32 v76, v76
	s_nop 0
	v_mul_f32_e32 v76, v77, v76
	v_mul_f32_e32 v73, v76, v73
	v_mul_f32_e32 v76, 0xbfb8aa3b, v78
	v_exp_f32_e32 v76, v76
	s_nop 0
	v_add_f32_e32 v76, 1.0, v76
	v_rcp_f32_e32 v76, v76
	s_nop 0
	v_mul_f32_e32 v76, v78, v76
	v_mul_f32_e32 v74, v76, v74
	v_mul_f32_e32 v76, 0xbfb8aa3b, v79
	v_exp_f32_e32 v76, v76
	s_nop 0
	v_add_f32_e32 v76, 1.0, v76
	v_rcp_f32_e32 v76, v76
	s_nop 0
	v_mul_f32_e32 v76, v79, v76
	v_mul_f32_e32 v75, v76, v75
	v_mul_f32_e32 v76, 0xbfb8aa3b, v68
	v_exp_f32_e32 v76, v76
	s_nop 0
	v_add_f32_e32 v76, 1.0, v76
	v_rcp_f32_e32 v76, v76
	s_nop 0
	v_mul_f32_e32 v68, v68, v76
	v_mul_f32_e32 v76, v68, v64
	v_mul_f32_e32 v64, 0xbfb8aa3b, v69
	v_exp_f32_e32 v64, v64
	s_nop 0
	v_add_f32_e32 v64, 1.0, v64
	v_rcp_f32_e32 v64, v64
	s_nop 0
	v_mul_f32_e32 v64, v69, v64
	v_mul_f32_e32 v77, v64, v65
	v_mul_f32_e32 v64, 0xbfb8aa3b, v70
	v_exp_f32_e32 v64, v64
	v_lshl_add_u64 v[68:69], v[80:81], 0, v[112:113]
	v_add_f32_e32 v64, 1.0, v64
	v_rcp_f32_e32 v64, v64
	s_nop 0
	v_mul_f32_e32 v64, v70, v64
	v_mul_f32_e32 v70, v64, v66
	v_mul_f32_e32 v64, 0xbfb8aa3b, v71
	v_exp_f32_e32 v64, v64
	s_nop 0
	v_add_f32_e32 v64, 1.0, v64
	v_rcp_f32_e32 v64, v64
	s_nop 0
	v_mul_f32_e32 v64, v71, v64
	v_mul_f32_e32 v67, v64, v67
	v_cvt_pk_bf16_f32 v64, v72, v73
	v_cvt_pk_bf16_f32 v65, v74, v75
	v_cvt_pk_bf16_f32 v66, v76, v77
	v_cvt_pk_bf16_f32 v67, v70, v67
	global_store_dwordx4 v[68:69], v[64:67], off
	s_nop 1
	v_mul_f32_e32 v66, 0xbfb8aa3b, v60
	v_exp_f32_e32 v66, v66
	v_add_u32_e32 v64, 0x80, v144
	v_mad_i64_i32 v[64:65], s[14:15], v64, s5, v[138:139]
	v_add_f32_e32 v66, 1.0, v66
	v_rcp_f32_e32 v66, v66
	s_nop 0
	v_mul_f32_e32 v60, v60, v66
	v_mul_f32_e32 v56, v60, v56
	v_mul_f32_e32 v60, 0xbfb8aa3b, v61
	v_exp_f32_e32 v60, v60
	s_nop 0
	v_add_f32_e32 v60, 1.0, v60
	v_rcp_f32_e32 v60, v60
	s_nop 0
	v_mul_f32_e32 v60, v61, v60
	v_mul_f32_e32 v57, v60, v57
	v_mul_f32_e32 v60, 0xbfb8aa3b, v62
	v_exp_f32_e32 v60, v60
	s_nop 0
	v_add_f32_e32 v60, 1.0, v60
	v_rcp_f32_e32 v60, v60
	s_nop 0
	v_mul_f32_e32 v60, v62, v60
	v_mul_f32_e32 v58, v60, v58
	v_mul_f32_e32 v60, 0xbfb8aa3b, v63
	v_exp_f32_e32 v60, v60
	s_nop 0
	v_add_f32_e32 v60, 1.0, v60
	v_rcp_f32_e32 v60, v60
	s_nop 0
	v_mul_f32_e32 v60, v63, v60
	v_mul_f32_e32 v59, v60, v59
	v_mul_f32_e32 v60, 0xbfb8aa3b, v52
	v_exp_f32_e32 v60, v60
	s_nop 0
	v_add_f32_e32 v60, 1.0, v60
	v_rcp_f32_e32 v60, v60
	s_nop 0
	v_mul_f32_e32 v52, v52, v60
	v_mul_f32_e32 v60, v52, v48
	v_mul_f32_e32 v48, 0xbfb8aa3b, v53
	v_exp_f32_e32 v48, v48
	s_nop 0
	v_add_f32_e32 v48, 1.0, v48
	v_rcp_f32_e32 v48, v48
	s_nop 0
	v_mul_f32_e32 v48, v53, v48
	v_mul_f32_e32 v61, v48, v49
	v_mul_f32_e32 v48, 0xbfb8aa3b, v54
	v_exp_f32_e32 v48, v48
	v_lshl_add_u64 v[52:53], v[64:65], 0, v[112:113]
	v_add_f32_e32 v48, 1.0, v48
	v_rcp_f32_e32 v48, v48
	s_nop 0
	v_mul_f32_e32 v48, v54, v48
	v_mul_f32_e32 v54, v48, v50
	v_mul_f32_e32 v48, 0xbfb8aa3b, v55
	v_exp_f32_e32 v48, v48
	s_nop 0
	v_add_f32_e32 v48, 1.0, v48
	v_rcp_f32_e32 v48, v48
	s_nop 0
	v_mul_f32_e32 v48, v55, v48
	v_mul_f32_e32 v51, v48, v51
	v_cvt_pk_bf16_f32 v48, v56, v57
	v_cvt_pk_bf16_f32 v49, v58, v59
	v_cvt_pk_bf16_f32 v50, v60, v61
	v_cvt_pk_bf16_f32 v51, v54, v51
	global_store_dwordx4 v[52:53], v[48:51], off
	s_nop 1
	v_mul_f32_e32 v50, 0xbfb8aa3b, v44
	v_exp_f32_e32 v50, v50
	v_add_u32_e32 v48, 0x90, v144
	v_mad_i64_i32 v[48:49], s[14:15], v48, s5, v[138:139]
	v_add_f32_e32 v50, 1.0, v50
	v_rcp_f32_e32 v50, v50
	s_nop 0
	v_mul_f32_e32 v44, v44, v50
	v_mul_f32_e32 v40, v44, v40
	v_mul_f32_e32 v44, 0xbfb8aa3b, v45
	v_exp_f32_e32 v44, v44
	s_nop 0
	v_add_f32_e32 v44, 1.0, v44
	v_rcp_f32_e32 v44, v44
	s_nop 0
	v_mul_f32_e32 v44, v45, v44
	v_mul_f32_e32 v41, v44, v41
	v_mul_f32_e32 v44, 0xbfb8aa3b, v46
	v_exp_f32_e32 v44, v44
	s_nop 0
	v_add_f32_e32 v44, 1.0, v44
	v_rcp_f32_e32 v44, v44
	s_nop 0
	v_mul_f32_e32 v44, v46, v44
	v_mul_f32_e32 v42, v44, v42
	v_mul_f32_e32 v44, 0xbfb8aa3b, v47
	v_exp_f32_e32 v44, v44
	s_nop 0
	v_add_f32_e32 v44, 1.0, v44
	v_rcp_f32_e32 v44, v44
	s_nop 0
	v_mul_f32_e32 v44, v47, v44
	v_mul_f32_e32 v43, v44, v43
	v_mul_f32_e32 v44, 0xbfb8aa3b, v36
	v_exp_f32_e32 v44, v44
	s_nop 0
	v_add_f32_e32 v44, 1.0, v44
	v_rcp_f32_e32 v44, v44
	s_nop 0
	v_mul_f32_e32 v36, v36, v44
	v_mul_f32_e32 v44, v36, v32
	v_mul_f32_e32 v32, 0xbfb8aa3b, v37
	v_exp_f32_e32 v32, v32
	s_nop 0
	v_add_f32_e32 v32, 1.0, v32
	v_rcp_f32_e32 v32, v32
	s_nop 0
	v_mul_f32_e32 v32, v37, v32
	v_mul_f32_e32 v45, v32, v33
	v_mul_f32_e32 v32, 0xbfb8aa3b, v38
	v_exp_f32_e32 v32, v32
	v_lshl_add_u64 v[36:37], v[48:49], 0, v[112:113]
	v_add_f32_e32 v32, 1.0, v32
	v_rcp_f32_e32 v32, v32
	s_nop 0
	v_mul_f32_e32 v32, v38, v32
	v_mul_f32_e32 v38, v32, v34
	v_mul_f32_e32 v32, 0xbfb8aa3b, v39
	v_exp_f32_e32 v32, v32
	s_nop 0
	v_add_f32_e32 v32, 1.0, v32
	v_rcp_f32_e32 v32, v32
	s_nop 0
	v_mul_f32_e32 v32, v39, v32
	v_mul_f32_e32 v35, v32, v35
	v_cvt_pk_bf16_f32 v32, v40, v41
	v_cvt_pk_bf16_f32 v33, v42, v43
	v_cvt_pk_bf16_f32 v34, v44, v45
	v_cvt_pk_bf16_f32 v35, v38, v35
	global_store_dwordx4 v[36:37], v[32:35], off
	s_nop 1
	v_mul_f32_e32 v34, 0xbfb8aa3b, v28
	v_exp_f32_e32 v34, v34
	v_add_u32_e32 v32, 0xa0, v144
	v_mad_i64_i32 v[32:33], s[14:15], v32, s5, v[138:139]
	v_add_f32_e32 v34, 1.0, v34
	v_rcp_f32_e32 v34, v34
	s_nop 0
	v_mul_f32_e32 v28, v28, v34
	v_mul_f32_e32 v24, v28, v24
	v_mul_f32_e32 v28, 0xbfb8aa3b, v29
	v_exp_f32_e32 v28, v28
	s_nop 0
	v_add_f32_e32 v28, 1.0, v28
	v_rcp_f32_e32 v28, v28
	s_nop 0
	v_mul_f32_e32 v28, v29, v28
	v_mul_f32_e32 v25, v28, v25
	v_mul_f32_e32 v28, 0xbfb8aa3b, v30
	v_exp_f32_e32 v28, v28
	s_nop 0
	v_add_f32_e32 v28, 1.0, v28
	v_rcp_f32_e32 v28, v28
	s_nop 0
	v_mul_f32_e32 v28, v30, v28
	v_mul_f32_e32 v26, v28, v26
	v_mul_f32_e32 v28, 0xbfb8aa3b, v31
	v_exp_f32_e32 v28, v28
	s_nop 0
	v_add_f32_e32 v28, 1.0, v28
	v_rcp_f32_e32 v28, v28
	s_nop 0
	v_mul_f32_e32 v28, v31, v28
	v_mul_f32_e32 v27, v28, v27
	v_mul_f32_e32 v28, 0xbfb8aa3b, v20
	v_exp_f32_e32 v28, v28
	s_nop 0
	v_add_f32_e32 v28, 1.0, v28
	v_rcp_f32_e32 v28, v28
	s_nop 0
	v_mul_f32_e32 v20, v20, v28
	v_mul_f32_e32 v28, v20, v16
	v_mul_f32_e32 v16, 0xbfb8aa3b, v21
	v_exp_f32_e32 v16, v16
	s_nop 0
	v_add_f32_e32 v16, 1.0, v16
	v_rcp_f32_e32 v16, v16
	s_nop 0
	v_mul_f32_e32 v16, v21, v16
	v_mul_f32_e32 v29, v16, v17
	v_mul_f32_e32 v16, 0xbfb8aa3b, v22
	v_exp_f32_e32 v16, v16
	v_lshl_add_u64 v[20:21], v[32:33], 0, v[112:113]
	v_add_f32_e32 v16, 1.0, v16
	v_rcp_f32_e32 v16, v16
	s_nop 0
	v_mul_f32_e32 v16, v22, v16
	v_mul_f32_e32 v22, v16, v18
	v_mul_f32_e32 v16, 0xbfb8aa3b, v23
	v_exp_f32_e32 v16, v16
	s_nop 0
	v_add_f32_e32 v16, 1.0, v16
	v_rcp_f32_e32 v16, v16
	s_nop 0
	v_mul_f32_e32 v16, v23, v16
	v_mul_f32_e32 v19, v16, v19
	v_cvt_pk_bf16_f32 v16, v24, v25
	v_cvt_pk_bf16_f32 v17, v26, v27
	v_cvt_pk_bf16_f32 v18, v28, v29
	v_cvt_pk_bf16_f32 v19, v22, v19
	global_store_dwordx4 v[20:21], v[16:19], off
	s_nop 1
	v_mul_f32_e32 v18, 0xbfb8aa3b, v12
	v_exp_f32_e32 v18, v18
	v_add_u32_e32 v16, 0xb0, v144
	v_mad_i64_i32 v[16:17], s[14:15], v16, s5, v[138:139]
	v_add_f32_e32 v18, 1.0, v18
	v_rcp_f32_e32 v18, v18
	s_mov_b64 s[14:15], s[8:9]
	v_mul_f32_e32 v12, v12, v18
	v_mul_f32_e32 v8, v12, v8
	v_mul_f32_e32 v12, 0xbfb8aa3b, v13
	v_exp_f32_e32 v12, v12
	s_nop 0
	v_add_f32_e32 v12, 1.0, v12
	v_rcp_f32_e32 v12, v12
	s_nop 0
	v_mul_f32_e32 v12, v13, v12
	v_mul_f32_e32 v9, v12, v9
	v_mul_f32_e32 v12, 0xbfb8aa3b, v14
	v_exp_f32_e32 v12, v12
	s_nop 0
	v_add_f32_e32 v12, 1.0, v12
	v_rcp_f32_e32 v12, v12
	s_nop 0
	v_mul_f32_e32 v12, v14, v12
	v_mul_f32_e32 v10, v12, v10
	v_mul_f32_e32 v12, 0xbfb8aa3b, v15
	v_exp_f32_e32 v12, v12
	s_nop 0
	v_add_f32_e32 v12, 1.0, v12
	v_rcp_f32_e32 v12, v12
	s_nop 0
	v_mul_f32_e32 v12, v15, v12
	v_mul_f32_e32 v11, v12, v11
	v_mul_f32_e32 v12, 0xbfb8aa3b, v4
	v_exp_f32_e32 v12, v12
	s_nop 0
	v_add_f32_e32 v12, 1.0, v12
	v_rcp_f32_e32 v12, v12
	s_nop 0
	v_mul_f32_e32 v4, v4, v12
	v_mul_f32_e32 v12, v4, v0
	v_mul_f32_e32 v0, 0xbfb8aa3b, v5
	v_exp_f32_e32 v0, v0
	s_nop 0
	v_add_f32_e32 v0, 1.0, v0
	v_rcp_f32_e32 v0, v0
	s_nop 0
	v_mul_f32_e32 v0, v5, v0
	v_mul_f32_e32 v13, v0, v1
	v_mul_f32_e32 v0, 0xbfb8aa3b, v6
	v_exp_f32_e32 v0, v0
	v_lshl_add_u64 v[4:5], v[16:17], 0, v[112:113]
	v_add_f32_e32 v0, 1.0, v0
	v_rcp_f32_e32 v0, v0
	s_nop 0
	v_mul_f32_e32 v0, v6, v0
	v_mul_f32_e32 v6, v0, v2
	v_mul_f32_e32 v0, 0xbfb8aa3b, v7
	v_exp_f32_e32 v0, v0
	s_nop 0
	v_add_f32_e32 v0, 1.0, v0
	v_rcp_f32_e32 v0, v0
	s_nop 0
	v_mul_f32_e32 v0, v7, v0
	v_mul_f32_e32 v3, v0, v3
	v_cvt_pk_bf16_f32 v0, v8, v9
	v_cvt_pk_bf16_f32 v1, v10, v11
	v_cvt_pk_bf16_f32 v2, v12, v13
	v_cvt_pk_bf16_f32 v3, v6, v3
	global_store_dwordx4 v[4:5], v[0:3], off
	s_cbranch_vccz .LBB0_214
	s_waitcnt vmcnt(0)
	v_readlane_b32 s34, v254, 18
	s_cmpk_gt_u32 s21, 0xff
	v_readlane_b32 s35, v254, 19
	v_readlane_b32 s31, v254, 20
	s_cbranch_scc1 .LBB0_221
	s_barrier

.LBB0_271:
	s_add_u32 s39, s10, 0x100
	s_addc_u32 s40, s11, 0
	s_mov_b32 s41, -2
	s_mov_b64 s[44:45], 0x80
	v_add_u32_e32 v220, 0x10000, v187
	s_add_u32 s10, s8, 0x100
	s_addc_u32 s11, s9, 0
	s_add_i32 s42, 0, 0x10000
	ds_read_b128 v[108:111], v220 offset:0
	ds_read_b128 v[112:115], v220 offset:1024
	ds_read_b128 v[116:119], v220 offset:2048
	ds_read_b128 v[120:123], v220 offset:3072
	s_cmpk_eq_i32 s41, 0x54
	s_cselect_b32 s15, s5, s11
	s_cselect_b32 s14, s4, s10
	s_cselect_b32 s13, s7, s40
	s_cselect_b32 s12, s6, s39
	s_add_i32 m0, s25, 0xc000
	ds_read_b128 v[144:147], v189
	ds_read_b128 v[148:151], v189 offset:1024
	ds_read_b128 v[152:155], v189 offset:2048
	ds_read_b128 v[156:159], v189 offset:3072
	ds_read_b128 v[160:163], v189 offset:4096
	ds_read_b128 v[174:177], v189 offset:5120
	ds_read_b128 v[178:181], v189 offset:6144
	ds_read_b128 v[182:185], v189 offset:7168
	global_load_lds_dwordx4 v170, s[8:9]
	s_add_i32 m0, s25, 0xe000
	s_nop 0
	global_load_lds_dwordx4 v172, s[8:9]
	s_waitcnt lgkmcnt(8)
	s_barrier
	s_waitcnt lgkmcnt(0)
	v_mfma_f32_16x16x32_bf16 v[140:143], v[108:111], v[144:147], 0
	v_mfma_f32_16x16x32_bf16 v[136:139], v[116:119], v[144:147], 0
	v_mfma_f32_16x16x32_bf16 v[132:135], v[108:111], v[152:155], 0
	v_mfma_f32_16x16x32_bf16 v[104:107], v[116:119], v[152:155], 0
	s_add_i32 s43, 0, 0x14000
	s_add_i32 s8, s42, s19
	v_mfma_f32_16x16x32_bf16 v[96:99], v[108:111], v[160:163], 0
	s_mov_b32 m0, s8
	v_mfma_f32_16x16x32_bf16 v[88:91], v[116:119], v[160:163], 0
	v_mfma_f32_16x16x32_bf16 v[80:83], v[108:111], v[178:181], 0
	v_mfma_f32_16x16x32_bf16 v[72:75], v[116:119], v[178:181], 0
	v_mfma_f32_16x16x32_bf16 v[140:143], v[112:115], v[148:151], v[140:143]
	v_mfma_f32_16x16x32_bf16 v[136:139], v[120:123], v[148:151], v[136:139]
	v_mfma_f32_16x16x32_bf16 v[132:135], v[112:115], v[156:159], v[132:135]
	v_mfma_f32_16x16x32_bf16 v[104:107], v[120:123], v[156:159], v[104:107]
	v_mfma_f32_16x16x32_bf16 v[96:99], v[112:115], v[174:177], v[96:99]
	v_mfma_f32_16x16x32_bf16 v[88:91], v[120:123], v[174:177], v[88:91]
	v_mfma_f32_16x16x32_bf16 v[80:83], v[112:115], v[182:185], v[80:83]
	v_mfma_f32_16x16x32_bf16 v[72:75], v[120:123], v[182:185], v[72:75]
	s_barrier
	ds_read_b128 v[196:199], v220 offset:16384
	ds_read_b128 v[204:207], v220 offset:17408
	ds_read_b128 v[208:211], v220 offset:18432
	ds_read_b128 v[214:217], v220 offset:19456
	global_load_lds_dwordx4 v192, s[12:13]
	s_add_i32 m0, s8, 0x2000
	s_nop 0
	global_load_lds_dwordx4 v168, s[12:13]
	s_barrier
	s_waitcnt lgkmcnt(0)
	v_mfma_f32_16x16x32_bf16 v[128:131], v[196:199], v[144:147], 0
	v_mfma_f32_16x16x32_bf16 v[124:127], v[208:211], v[144:147], 0
	v_mfma_f32_16x16x32_bf16 v[100:103], v[196:199], v[152:155], 0
	v_mfma_f32_16x16x32_bf16 v[92:95], v[208:211], v[152:155], 0
	s_mov_b32 m0, s25
	v_mfma_f32_16x16x32_bf16 v[84:87], v[196:199], v[160:163], 0
	s_add_u32 s44, s14, 0x80
	s_addc_u32 s45, s15, 0
	v_mfma_f32_16x16x32_bf16 v[76:79], v[208:211], v[160:163], 0
	v_mfma_f32_16x16x32_bf16 v[68:71], v[196:199], v[178:181], 0
	v_mfma_f32_16x16x32_bf16 v[64:67], v[208:211], v[178:181], 0
	v_mfma_f32_16x16x32_bf16 v[128:131], v[204:207], v[148:151], v[128:131]
	v_mfma_f32_16x16x32_bf16 v[124:127], v[214:217], v[148:151], v[124:127]
	v_mfma_f32_16x16x32_bf16 v[100:103], v[204:207], v[156:159], v[100:103]
	v_mfma_f32_16x16x32_bf16 v[92:95], v[214:217], v[156:159], v[92:95]
	v_mfma_f32_16x16x32_bf16 v[84:87], v[204:207], v[174:177], v[84:87]
	v_mfma_f32_16x16x32_bf16 v[76:79], v[214:217], v[174:177], v[76:79]
	v_mfma_f32_16x16x32_bf16 v[68:71], v[204:207], v[182:185], v[68:71]
	v_mfma_f32_16x16x32_bf16 v[64:67], v[214:217], v[182:185], v[64:67]
	s_barrier
	ds_read_b128 v[144:147], v189 offset:16384
	ds_read_b128 v[148:151], v189 offset:17408
	ds_read_b128 v[152:155], v189 offset:18432
	ds_read_b128 v[156:159], v189 offset:19456
	ds_read_b128 v[160:163], v189 offset:20480
	ds_read_b128 v[174:177], v189 offset:21504
	ds_read_b128 v[178:181], v189 offset:22528
	ds_read_b128 v[182:185], v189 offset:23552
	global_load_lds_dwordx4 v164, s[14:15]
	s_mov_b32 m0, s26
	s_nop 0
	global_load_lds_dwordx4 v166, s[14:15]
	s_barrier
	s_waitcnt lgkmcnt(0)
	v_mfma_f32_16x16x32_bf16 v[60:63], v[108:111], v[144:147], 0
	v_mfma_f32_16x16x32_bf16 v[56:59], v[116:119], v[144:147], 0
	v_mfma_f32_16x16x32_bf16 v[48:51], v[108:111], v[152:155], 0
	v_mfma_f32_16x16x32_bf16 v[40:43], v[116:119], v[152:155], 0
	s_add_u32 s8, s12, 0x160000
	s_addc_u32 s9, s13, 0
	v_mfma_f32_16x16x32_bf16 v[32:35], v[108:111], v[160:163], 0
	s_add_i32 s42, s43, s19
	s_mov_b32 m0, s42
	v_mfma_f32_16x16x32_bf16 v[24:27], v[116:119], v[160:163], 0
	v_mfma_f32_16x16x32_bf16 v[16:19], v[108:111], v[178:181], 0
	v_mfma_f32_16x16x32_bf16 v[8:11], v[116:119], v[178:181], 0
	v_mfma_f32_16x16x32_bf16 v[60:63], v[112:115], v[148:151], v[60:63]
	v_mfma_f32_16x16x32_bf16 v[56:59], v[120:123], v[148:151], v[56:59]
	v_mfma_f32_16x16x32_bf16 v[48:51], v[112:115], v[156:159], v[48:51]
	v_mfma_f32_16x16x32_bf16 v[40:43], v[120:123], v[156:159], v[40:43]
	v_mfma_f32_16x16x32_bf16 v[32:35], v[112:115], v[174:177], v[32:35]
	v_mfma_f32_16x16x32_bf16 v[24:27], v[120:123], v[174:177], v[24:27]
	v_mfma_f32_16x16x32_bf16 v[16:19], v[112:115], v[182:185], v[16:19]
	v_mfma_f32_16x16x32_bf16 v[8:11], v[120:123], v[182:185], v[8:11]
	s_barrier
	global_load_lds_dwordx4 v192, s[8:9]
	s_add_i32 m0, s42, 0x2000
	s_nop 0
	global_load_lds_dwordx4 v168, s[8:9]
	s_waitcnt vmcnt(6)
	s_barrier
	v_mfma_f32_16x16x32_bf16 v[52:55], v[196:199], v[144:147], 0
	v_mfma_f32_16x16x32_bf16 v[44:47], v[208:211], v[144:147], 0
	v_mfma_f32_16x16x32_bf16 v[36:39], v[196:199], v[152:155], 0
	v_mfma_f32_16x16x32_bf16 v[28:31], v[208:211], v[152:155], 0
	s_add_i32 s42, 0, 0x18000
	v_mfma_f32_16x16x32_bf16 v[20:23], v[196:199], v[160:163], 0
	s_add_u32 s8, s14, 0x160000
	s_addc_u32 s9, s15, 0
	v_mfma_f32_16x16x32_bf16 v[12:15], v[208:211], v[160:163], 0
	s_mov_b32 m0, s27
	v_mfma_f32_16x16x32_bf16 v[4:7], v[196:199], v[178:181], 0
	v_mfma_f32_16x16x32_bf16 v[0:3], v[208:211], v[178:181], 0
	v_mfma_f32_16x16x32_bf16 v[52:55], v[204:207], v[148:151], v[52:55]
	v_mfma_f32_16x16x32_bf16 v[44:47], v[214:217], v[148:151], v[44:47]
	v_mfma_f32_16x16x32_bf16 v[36:39], v[204:207], v[156:159], v[36:39]
	v_mfma_f32_16x16x32_bf16 v[28:31], v[214:217], v[156:159], v[28:31]
	v_mfma_f32_16x16x32_bf16 v[20:23], v[204:207], v[174:177], v[20:23]
	v_mfma_f32_16x16x32_bf16 v[12:15], v[214:217], v[174:177], v[12:15]
	v_mfma_f32_16x16x32_bf16 v[4:7], v[204:207], v[182:185], v[4:7]
	v_mfma_f32_16x16x32_bf16 v[0:3], v[214:217], v[182:185], v[0:3]
	s_barrier
	ds_read_b128 v[108:111], v220 offset:32768
	ds_read_b128 v[112:115], v220 offset:33792
	ds_read_b128 v[116:119], v220 offset:34816
	ds_read_b128 v[120:123], v220 offset:35840
	ds_read_b128 v[144:147], v189 offset:32768
	ds_read_b128 v[148:151], v189 offset:33792
	ds_read_b128 v[152:155], v189 offset:34816
	ds_read_b128 v[156:159], v189 offset:35840
	ds_read_b128 v[160:163], v189 offset:36864
	ds_read_b128 v[174:177], v189 offset:37888
	ds_read_b128 v[178:181], v189 offset:38912
	ds_read_b128 v[182:185], v189 offset:39936
	global_load_lds_dwordx4 v164, s[8:9]
	s_mov_b32 m0, s28
	s_nop 0
	global_load_lds_dwordx4 v166, s[8:9]
	s_waitcnt lgkmcnt(8)
	s_barrier
	s_waitcnt lgkmcnt(0)
	v_mfma_f32_16x16x32_bf16 v[140:143], v[108:111], v[144:147], v[140:143]
	v_mfma_f32_16x16x32_bf16 v[136:139], v[116:119], v[144:147], v[136:139]
	v_mfma_f32_16x16x32_bf16 v[132:135], v[108:111], v[152:155], v[132:135]
	v_mfma_f32_16x16x32_bf16 v[104:107], v[116:119], v[152:155], v[104:107]
	s_add_i32 s14, 0, 0x1c000
	s_add_i32 s8, s42, s19
	v_mfma_f32_16x16x32_bf16 v[96:99], v[108:111], v[160:163], v[96:99]
	s_add_i32 m0, s8, 0xffffff80
	v_mfma_f32_16x16x32_bf16 v[88:91], v[116:119], v[160:163], v[88:91]
	v_mfma_f32_16x16x32_bf16 v[80:83], v[108:111], v[178:181], v[80:83]
	v_mfma_f32_16x16x32_bf16 v[72:75], v[116:119], v[178:181], v[72:75]
	v_mfma_f32_16x16x32_bf16 v[140:143], v[112:115], v[148:151], v[140:143]
	v_mfma_f32_16x16x32_bf16 v[136:139], v[120:123], v[148:151], v[136:139]
	v_mfma_f32_16x16x32_bf16 v[132:135], v[112:115], v[156:159], v[132:135]
	v_mfma_f32_16x16x32_bf16 v[104:107], v[120:123], v[156:159], v[104:107]
	v_mfma_f32_16x16x32_bf16 v[96:99], v[112:115], v[174:177], v[96:99]
	v_mfma_f32_16x16x32_bf16 v[88:91], v[120:123], v[174:177], v[88:91]
	v_mfma_f32_16x16x32_bf16 v[80:83], v[112:115], v[182:185], v[80:83]
	v_mfma_f32_16x16x32_bf16 v[72:75], v[120:123], v[182:185], v[72:75]
	s_barrier
	ds_read_b128 v[196:199], v220 offset:49152
	ds_read_b128 v[204:207], v220 offset:50176
	ds_read_b128 v[208:211], v220 offset:51200
	ds_read_b128 v[214:217], v220 offset:52224
	global_load_lds_dwordx4 v192, s[12:13] offset:128
	s_add_i32 m0, s8, 0x1f80
	s_nop 0
	global_load_lds_dwordx4 v168, s[12:13] offset:128
	s_barrier
	s_waitcnt lgkmcnt(0)
	v_mfma_f32_16x16x32_bf16 v[128:131], v[196:199], v[144:147], v[128:131]
	v_mfma_f32_16x16x32_bf16 v[124:127], v[208:211], v[144:147], v[124:127]
	v_mfma_f32_16x16x32_bf16 v[100:103], v[196:199], v[152:155], v[100:103]
	v_mfma_f32_16x16x32_bf16 v[92:95], v[208:211], v[152:155], v[92:95]
	s_mov_b32 m0, s31
	v_mfma_f32_16x16x32_bf16 v[84:87], v[196:199], v[160:163], v[84:87]
	v_mfma_f32_16x16x32_bf16 v[76:79], v[208:211], v[160:163], v[76:79]
	v_mfma_f32_16x16x32_bf16 v[68:71], v[196:199], v[178:181], v[68:71]
	v_mfma_f32_16x16x32_bf16 v[64:67], v[208:211], v[178:181], v[64:67]
	v_mfma_f32_16x16x32_bf16 v[128:131], v[204:207], v[148:151], v[128:131]
	v_mfma_f32_16x16x32_bf16 v[124:127], v[214:217], v[148:151], v[124:127]
	v_mfma_f32_16x16x32_bf16 v[100:103], v[204:207], v[156:159], v[100:103]
	v_mfma_f32_16x16x32_bf16 v[92:95], v[214:217], v[156:159], v[92:95]
	v_mfma_f32_16x16x32_bf16 v[84:87], v[204:207], v[174:177], v[84:87]
	v_mfma_f32_16x16x32_bf16 v[76:79], v[214:217], v[174:177], v[76:79]
	v_mfma_f32_16x16x32_bf16 v[68:71], v[204:207], v[182:185], v[68:71]
	v_mfma_f32_16x16x32_bf16 v[64:67], v[214:217], v[182:185], v[64:67]
	s_barrier
	ds_read_b128 v[144:147], v189 offset:49152
	ds_read_b128 v[148:151], v189 offset:50176
	ds_read_b128 v[152:155], v189 offset:51200
	ds_read_b128 v[156:159], v189 offset:52224
	ds_read_b128 v[160:163], v189 offset:53248
	ds_read_b128 v[174:177], v189 offset:54272
	ds_read_b128 v[178:181], v189 offset:55296
	ds_read_b128 v[182:185], v189 offset:56320
	global_load_lds_dwordx4 v164, s[44:45]
	s_mov_b32 m0, s33
	s_nop 0
	global_load_lds_dwordx4 v166, s[44:45]
	s_barrier
	s_waitcnt lgkmcnt(0)
	v_mfma_f32_16x16x32_bf16 v[60:63], v[108:111], v[144:147], v[60:63]
	v_mfma_f32_16x16x32_bf16 v[56:59], v[116:119], v[144:147], v[56:59]
	v_mfma_f32_16x16x32_bf16 v[48:51], v[108:111], v[152:155], v[48:51]
	v_mfma_f32_16x16x32_bf16 v[40:43], v[116:119], v[152:155], v[40:43]
	s_add_u32 s8, s12, 0x160080
	s_addc_u32 s9, s13, 0
	v_mfma_f32_16x16x32_bf16 v[32:35], v[108:111], v[160:163], v[32:35]
	s_add_i32 s12, s14, s19
	s_mov_b32 m0, s12
	v_mfma_f32_16x16x32_bf16 v[24:27], v[116:119], v[160:163], v[24:27]
	v_mfma_f32_16x16x32_bf16 v[16:19], v[108:111], v[178:181], v[16:19]
	v_mfma_f32_16x16x32_bf16 v[8:11], v[116:119], v[178:181], v[8:11]
	v_mfma_f32_16x16x32_bf16 v[60:63], v[112:115], v[148:151], v[60:63]
	v_mfma_f32_16x16x32_bf16 v[56:59], v[120:123], v[148:151], v[56:59]
	v_mfma_f32_16x16x32_bf16 v[48:51], v[112:115], v[156:159], v[48:51]
	v_mfma_f32_16x16x32_bf16 v[40:43], v[120:123], v[156:159], v[40:43]
	v_mfma_f32_16x16x32_bf16 v[32:35], v[112:115], v[174:177], v[32:35]
	v_mfma_f32_16x16x32_bf16 v[24:27], v[120:123], v[174:177], v[24:27]
	v_mfma_f32_16x16x32_bf16 v[16:19], v[112:115], v[182:185], v[16:19]
	v_mfma_f32_16x16x32_bf16 v[8:11], v[120:123], v[182:185], v[8:11]
	s_barrier
	global_load_lds_dwordx4 v192, s[8:9]
	s_add_i32 m0, s12, 0x2000
	s_nop 0
	global_load_lds_dwordx4 v168, s[8:9]
	s_waitcnt vmcnt(6)
	s_barrier
	v_mfma_f32_16x16x32_bf16 v[52:55], v[196:199], v[144:147], v[52:55]
	v_mfma_f32_16x16x32_bf16 v[44:47], v[208:211], v[144:147], v[44:47]
	v_mfma_f32_16x16x32_bf16 v[36:39], v[196:199], v[152:155], v[36:39]
	v_mfma_f32_16x16x32_bf16 v[28:31], v[208:211], v[152:155], v[28:31]
	s_add_i32 s41, s41, 2
	v_mfma_f32_16x16x32_bf16 v[20:23], v[196:199], v[160:163], v[20:23]
	s_add_u32 s39, s39, 0x100
	s_addc_u32 s40, s40, 0
	v_mfma_f32_16x16x32_bf16 v[12:15], v[208:211], v[160:163], v[12:15]
	s_mov_b64 s[8:9], s[10:11]
	v_mfma_f32_16x16x32_bf16 v[4:7], v[196:199], v[178:181], v[4:7]
	s_add_u32 s10, s8, 0x100
	s_addc_u32 s11, s9, 0
	v_mfma_f32_16x16x32_bf16 v[0:3], v[208:211], v[178:181], v[0:3]
	s_add_i32 s42, 0, 0x10000
	s_cmpk_eq_i32 s41, 0x54
	v_mfma_f32_16x16x32_bf16 v[52:55], v[204:207], v[148:151], v[52:55]
	s_cselect_b32 s15, s5, s11
	s_cselect_b32 s14, s4, s10
	v_mfma_f32_16x16x32_bf16 v[44:47], v[214:217], v[148:151], v[44:47]
	s_cselect_b32 s13, s7, s40
	s_cselect_b32 s12, s6, s39
	v_mfma_f32_16x16x32_bf16 v[36:39], v[204:207], v[156:159], v[36:39]
	s_add_i32 m0, s25, 0xc000
	v_mfma_f32_16x16x32_bf16 v[28:31], v[214:217], v[156:159], v[28:31]
	v_mfma_f32_16x16x32_bf16 v[20:23], v[204:207], v[174:177], v[20:23]
	v_mfma_f32_16x16x32_bf16 v[12:15], v[214:217], v[174:177], v[12:15]
	v_mfma_f32_16x16x32_bf16 v[4:7], v[204:207], v[182:185], v[4:7]
	v_mfma_f32_16x16x32_bf16 v[0:3], v[214:217], v[182:185], v[0:3]
	s_cmpk_gt_u32 s41, 0x55
	s_barrier
.LBB0_272:
	ds_read_b128 v[108:111], v220 offset:0
	ds_read_b128 v[112:115], v220 offset:1024
	ds_read_b128 v[116:119], v220 offset:2048
	ds_read_b128 v[120:123], v220 offset:3072
	ds_read_b128 v[144:147], v189
	ds_read_b128 v[148:151], v189 offset:1024
	ds_read_b128 v[152:155], v189 offset:2048
	ds_read_b128 v[156:159], v189 offset:3072
	ds_read_b128 v[160:163], v189 offset:4096
	ds_read_b128 v[174:177], v189 offset:5120
	ds_read_b128 v[178:181], v189 offset:6144
	ds_read_b128 v[182:185], v189 offset:7168
	global_load_lds_dwordx4 v170, s[8:9]
	s_add_i32 m0, s25, 0xe000
	s_nop 0
	global_load_lds_dwordx4 v172, s[8:9]
	s_waitcnt lgkmcnt(8)
	s_barrier
	s_waitcnt lgkmcnt(0)
	v_mfma_f32_16x16x32_bf16 v[140:143], v[108:111], v[144:147], v[140:143]
	v_mfma_f32_16x16x32_bf16 v[136:139], v[116:119], v[144:147], v[136:139]
	v_mfma_f32_16x16x32_bf16 v[132:135], v[108:111], v[152:155], v[132:135]
	v_mfma_f32_16x16x32_bf16 v[104:107], v[116:119], v[152:155], v[104:107]
	s_add_i32 s43, 0, 0x14000
	s_add_i32 s8, s42, s19
	v_mfma_f32_16x16x32_bf16 v[96:99], v[108:111], v[160:163], v[96:99]
	s_mov_b32 m0, s8
	v_mfma_f32_16x16x32_bf16 v[88:91], v[116:119], v[160:163], v[88:91]
	v_mfma_f32_16x16x32_bf16 v[80:83], v[108:111], v[178:181], v[80:83]
	v_mfma_f32_16x16x32_bf16 v[72:75], v[116:119], v[178:181], v[72:75]
	v_mfma_f32_16x16x32_bf16 v[140:143], v[112:115], v[148:151], v[140:143]
	v_mfma_f32_16x16x32_bf16 v[136:139], v[120:123], v[148:151], v[136:139]
	v_mfma_f32_16x16x32_bf16 v[132:135], v[112:115], v[156:159], v[132:135]
	v_mfma_f32_16x16x32_bf16 v[104:107], v[120:123], v[156:159], v[104:107]
	v_mfma_f32_16x16x32_bf16 v[96:99], v[112:115], v[174:177], v[96:99]
	v_mfma_f32_16x16x32_bf16 v[88:91], v[120:123], v[174:177], v[88:91]
	v_mfma_f32_16x16x32_bf16 v[80:83], v[112:115], v[182:185], v[80:83]
	v_mfma_f32_16x16x32_bf16 v[72:75], v[120:123], v[182:185], v[72:75]
	s_barrier
	ds_read_b128 v[196:199], v220 offset:16384
	ds_read_b128 v[204:207], v220 offset:17408
	ds_read_b128 v[208:211], v220 offset:18432
	ds_read_b128 v[214:217], v220 offset:19456
	global_load_lds_dwordx4 v192, s[12:13]
	s_add_i32 m0, s8, 0x2000
	s_nop 0
	global_load_lds_dwordx4 v168, s[12:13]
	s_barrier
	s_waitcnt lgkmcnt(0)
	v_mfma_f32_16x16x32_bf16 v[128:131], v[196:199], v[144:147], v[128:131]
	v_mfma_f32_16x16x32_bf16 v[124:127], v[208:211], v[144:147], v[124:127]
	v_mfma_f32_16x16x32_bf16 v[100:103], v[196:199], v[152:155], v[100:103]
	v_mfma_f32_16x16x32_bf16 v[92:95], v[208:211], v[152:155], v[92:95]
	s_mov_b32 m0, s25
	v_mfma_f32_16x16x32_bf16 v[84:87], v[196:199], v[160:163], v[84:87]
	s_add_u32 s44, s14, 0x80
	s_addc_u32 s45, s15, 0
	v_mfma_f32_16x16x32_bf16 v[76:79], v[208:211], v[160:163], v[76:79]
	v_mfma_f32_16x16x32_bf16 v[68:71], v[196:199], v[178:181], v[68:71]
	v_mfma_f32_16x16x32_bf16 v[64:67], v[208:211], v[178:181], v[64:67]
	v_mfma_f32_16x16x32_bf16 v[128:131], v[204:207], v[148:151], v[128:131]
	v_mfma_f32_16x16x32_bf16 v[124:127], v[214:217], v[148:151], v[124:127]
	v_mfma_f32_16x16x32_bf16 v[100:103], v[204:207], v[156:159], v[100:103]
	v_mfma_f32_16x16x32_bf16 v[92:95], v[214:217], v[156:159], v[92:95]
	v_mfma_f32_16x16x32_bf16 v[84:87], v[204:207], v[174:177], v[84:87]
	v_mfma_f32_16x16x32_bf16 v[76:79], v[214:217], v[174:177], v[76:79]
	v_mfma_f32_16x16x32_bf16 v[68:71], v[204:207], v[182:185], v[68:71]
	v_mfma_f32_16x16x32_bf16 v[64:67], v[214:217], v[182:185], v[64:67]
	s_barrier
	ds_read_b128 v[144:147], v189 offset:16384
	ds_read_b128 v[148:151], v189 offset:17408
	ds_read_b128 v[152:155], v189 offset:18432
	ds_read_b128 v[156:159], v189 offset:19456
	ds_read_b128 v[160:163], v189 offset:20480
	ds_read_b128 v[174:177], v189 offset:21504
	ds_read_b128 v[178:181], v189 offset:22528
	ds_read_b128 v[182:185], v189 offset:23552
	global_load_lds_dwordx4 v164, s[14:15]
	s_mov_b32 m0, s26
	s_nop 0
	global_load_lds_dwordx4 v166, s[14:15]
	s_barrier
	s_waitcnt lgkmcnt(0)
	v_mfma_f32_16x16x32_bf16 v[60:63], v[108:111], v[144:147], v[60:63]
	v_mfma_f32_16x16x32_bf16 v[56:59], v[116:119], v[144:147], v[56:59]
	v_mfma_f32_16x16x32_bf16 v[48:51], v[108:111], v[152:155], v[48:51]
	v_mfma_f32_16x16x32_bf16 v[40:43], v[116:119], v[152:155], v[40:43]
	s_add_u32 s8, s12, 0x160000
	s_addc_u32 s9, s13, 0
	v_mfma_f32_16x16x32_bf16 v[32:35], v[108:111], v[160:163], v[32:35]
	s_add_i32 s42, s43, s19
	s_mov_b32 m0, s42
	v_mfma_f32_16x16x32_bf16 v[24:27], v[116:119], v[160:163], v[24:27]
	v_mfma_f32_16x16x32_bf16 v[16:19], v[108:111], v[178:181], v[16:19]
	v_mfma_f32_16x16x32_bf16 v[8:11], v[116:119], v[178:181], v[8:11]
	v_mfma_f32_16x16x32_bf16 v[60:63], v[112:115], v[148:151], v[60:63]
	v_mfma_f32_16x16x32_bf16 v[56:59], v[120:123], v[148:151], v[56:59]
	v_mfma_f32_16x16x32_bf16 v[48:51], v[112:115], v[156:159], v[48:51]
	v_mfma_f32_16x16x32_bf16 v[40:43], v[120:123], v[156:159], v[40:43]
	v_mfma_f32_16x16x32_bf16 v[32:35], v[112:115], v[174:177], v[32:35]
	v_mfma_f32_16x16x32_bf16 v[24:27], v[120:123], v[174:177], v[24:27]
	v_mfma_f32_16x16x32_bf16 v[16:19], v[112:115], v[182:185], v[16:19]
	v_mfma_f32_16x16x32_bf16 v[8:11], v[120:123], v[182:185], v[8:11]
	s_barrier
	global_load_lds_dwordx4 v192, s[8:9]
	s_add_i32 m0, s42, 0x2000
	s_nop 0
	global_load_lds_dwordx4 v168, s[8:9]
	s_waitcnt vmcnt(6)
	s_barrier
	v_mfma_f32_16x16x32_bf16 v[52:55], v[196:199], v[144:147], v[52:55]
	v_mfma_f32_16x16x32_bf16 v[44:47], v[208:211], v[144:147], v[44:47]
	v_mfma_f32_16x16x32_bf16 v[36:39], v[196:199], v[152:155], v[36:39]
	v_mfma_f32_16x16x32_bf16 v[28:31], v[208:211], v[152:155], v[28:31]
	s_add_i32 s42, 0, 0x18000
	v_mfma_f32_16x16x32_bf16 v[20:23], v[196:199], v[160:163], v[20:23]
	s_add_u32 s8, s14, 0x160000
	s_addc_u32 s9, s15, 0
	v_mfma_f32_16x16x32_bf16 v[12:15], v[208:211], v[160:163], v[12:15]
	s_mov_b32 m0, s27
	v_mfma_f32_16x16x32_bf16 v[4:7], v[196:199], v[178:181], v[4:7]
	v_mfma_f32_16x16x32_bf16 v[0:3], v[208:211], v[178:181], v[0:3]
	v_mfma_f32_16x16x32_bf16 v[52:55], v[204:207], v[148:151], v[52:55]
	v_mfma_f32_16x16x32_bf16 v[44:47], v[214:217], v[148:151], v[44:47]
	v_mfma_f32_16x16x32_bf16 v[36:39], v[204:207], v[156:159], v[36:39]
	v_mfma_f32_16x16x32_bf16 v[28:31], v[214:217], v[156:159], v[28:31]
	v_mfma_f32_16x16x32_bf16 v[20:23], v[204:207], v[174:177], v[20:23]
	v_mfma_f32_16x16x32_bf16 v[12:15], v[214:217], v[174:177], v[12:15]
	v_mfma_f32_16x16x32_bf16 v[4:7], v[204:207], v[182:185], v[4:7]
	v_mfma_f32_16x16x32_bf16 v[0:3], v[214:217], v[182:185], v[0:3]
	s_barrier
	ds_read_b128 v[108:111], v220 offset:32768
	ds_read_b128 v[112:115], v220 offset:33792
	ds_read_b128 v[116:119], v220 offset:34816
	ds_read_b128 v[120:123], v220 offset:35840
	ds_read_b128 v[144:147], v189 offset:32768
	ds_read_b128 v[148:151], v189 offset:33792
	ds_read_b128 v[152:155], v189 offset:34816
	ds_read_b128 v[156:159], v189 offset:35840
	ds_read_b128 v[160:163], v189 offset:36864
	ds_read_b128 v[174:177], v189 offset:37888
	ds_read_b128 v[178:181], v189 offset:38912
	ds_read_b128 v[182:185], v189 offset:39936
	global_load_lds_dwordx4 v164, s[8:9]
	s_mov_b32 m0, s28
	s_nop 0
	global_load_lds_dwordx4 v166, s[8:9]
	s_waitcnt lgkmcnt(8)
	s_barrier
	s_waitcnt lgkmcnt(0)
	v_mfma_f32_16x16x32_bf16 v[140:143], v[108:111], v[144:147], v[140:143]
	v_mfma_f32_16x16x32_bf16 v[136:139], v[116:119], v[144:147], v[136:139]
	v_mfma_f32_16x16x32_bf16 v[132:135], v[108:111], v[152:155], v[132:135]
	v_mfma_f32_16x16x32_bf16 v[104:107], v[116:119], v[152:155], v[104:107]
	s_add_i32 s14, 0, 0x1c000
	s_add_i32 s8, s42, s19
	v_mfma_f32_16x16x32_bf16 v[96:99], v[108:111], v[160:163], v[96:99]
	s_add_i32 m0, s8, 0xffffff80
	v_mfma_f32_16x16x32_bf16 v[88:91], v[116:119], v[160:163], v[88:91]
	v_mfma_f32_16x16x32_bf16 v[80:83], v[108:111], v[178:181], v[80:83]
	v_mfma_f32_16x16x32_bf16 v[72:75], v[116:119], v[178:181], v[72:75]
	v_mfma_f32_16x16x32_bf16 v[140:143], v[112:115], v[148:151], v[140:143]
	v_mfma_f32_16x16x32_bf16 v[136:139], v[120:123], v[148:151], v[136:139]
	v_mfma_f32_16x16x32_bf16 v[132:135], v[112:115], v[156:159], v[132:135]
	v_mfma_f32_16x16x32_bf16 v[104:107], v[120:123], v[156:159], v[104:107]
	v_mfma_f32_16x16x32_bf16 v[96:99], v[112:115], v[174:177], v[96:99]
	v_mfma_f32_16x16x32_bf16 v[88:91], v[120:123], v[174:177], v[88:91]
	v_mfma_f32_16x16x32_bf16 v[80:83], v[112:115], v[182:185], v[80:83]
	v_mfma_f32_16x16x32_bf16 v[72:75], v[120:123], v[182:185], v[72:75]
	s_barrier
	ds_read_b128 v[196:199], v220 offset:49152
	ds_read_b128 v[204:207], v220 offset:50176
	ds_read_b128 v[208:211], v220 offset:51200
	ds_read_b128 v[214:217], v220 offset:52224
	global_load_lds_dwordx4 v192, s[12:13] offset:128
	s_add_i32 m0, s8, 0x1f80
	s_nop 0
	global_load_lds_dwordx4 v168, s[12:13] offset:128
	s_barrier
	s_waitcnt lgkmcnt(0)
	v_mfma_f32_16x16x32_bf16 v[128:131], v[196:199], v[144:147], v[128:131]
	v_mfma_f32_16x16x32_bf16 v[124:127], v[208:211], v[144:147], v[124:127]
	v_mfma_f32_16x16x32_bf16 v[100:103], v[196:199], v[152:155], v[100:103]
	v_mfma_f32_16x16x32_bf16 v[92:95], v[208:211], v[152:155], v[92:95]
	s_mov_b32 m0, s31
	v_mfma_f32_16x16x32_bf16 v[84:87], v[196:199], v[160:163], v[84:87]
	v_mfma_f32_16x16x32_bf16 v[76:79], v[208:211], v[160:163], v[76:79]
	v_mfma_f32_16x16x32_bf16 v[68:71], v[196:199], v[178:181], v[68:71]
	v_mfma_f32_16x16x32_bf16 v[64:67], v[208:211], v[178:181], v[64:67]
	v_mfma_f32_16x16x32_bf16 v[128:131], v[204:207], v[148:151], v[128:131]
	v_mfma_f32_16x16x32_bf16 v[124:127], v[214:217], v[148:151], v[124:127]
	v_mfma_f32_16x16x32_bf16 v[100:103], v[204:207], v[156:159], v[100:103]
	v_mfma_f32_16x16x32_bf16 v[92:95], v[214:217], v[156:159], v[92:95]
	v_mfma_f32_16x16x32_bf16 v[84:87], v[204:207], v[174:177], v[84:87]
	v_mfma_f32_16x16x32_bf16 v[76:79], v[214:217], v[174:177], v[76:79]
	v_mfma_f32_16x16x32_bf16 v[68:71], v[204:207], v[182:185], v[68:71]
	v_mfma_f32_16x16x32_bf16 v[64:67], v[214:217], v[182:185], v[64:67]
	s_barrier
	ds_read_b128 v[144:147], v189 offset:49152
	ds_read_b128 v[148:151], v189 offset:50176
	ds_read_b128 v[152:155], v189 offset:51200
	ds_read_b128 v[156:159], v189 offset:52224
	ds_read_b128 v[160:163], v189 offset:53248
	ds_read_b128 v[174:177], v189 offset:54272
	ds_read_b128 v[178:181], v189 offset:55296
	ds_read_b128 v[182:185], v189 offset:56320
	global_load_lds_dwordx4 v164, s[44:45]
	s_mov_b32 m0, s33
	s_nop 0
	global_load_lds_dwordx4 v166, s[44:45]
	s_barrier
	s_waitcnt lgkmcnt(0)
	v_mfma_f32_16x16x32_bf16 v[60:63], v[108:111], v[144:147], v[60:63]
	v_mfma_f32_16x16x32_bf16 v[56:59], v[116:119], v[144:147], v[56:59]
	v_mfma_f32_16x16x32_bf16 v[48:51], v[108:111], v[152:155], v[48:51]
	v_mfma_f32_16x16x32_bf16 v[40:43], v[116:119], v[152:155], v[40:43]
	s_add_u32 s8, s12, 0x160080
	s_addc_u32 s9, s13, 0
	v_mfma_f32_16x16x32_bf16 v[32:35], v[108:111], v[160:163], v[32:35]
	s_add_i32 s12, s14, s19
	s_mov_b32 m0, s12
	v_mfma_f32_16x16x32_bf16 v[24:27], v[116:119], v[160:163], v[24:27]
	v_mfma_f32_16x16x32_bf16 v[16:19], v[108:111], v[178:181], v[16:19]
	v_mfma_f32_16x16x32_bf16 v[8:11], v[116:119], v[178:181], v[8:11]
	v_mfma_f32_16x16x32_bf16 v[60:63], v[112:115], v[148:151], v[60:63]
	v_mfma_f32_16x16x32_bf16 v[56:59], v[120:123], v[148:151], v[56:59]
	v_mfma_f32_16x16x32_bf16 v[48:51], v[112:115], v[156:159], v[48:51]
	v_mfma_f32_16x16x32_bf16 v[40:43], v[120:123], v[156:159], v[40:43]
	v_mfma_f32_16x16x32_bf16 v[32:35], v[112:115], v[174:177], v[32:35]
	v_mfma_f32_16x16x32_bf16 v[24:27], v[120:123], v[174:177], v[24:27]
	v_mfma_f32_16x16x32_bf16 v[16:19], v[112:115], v[182:185], v[16:19]
	v_mfma_f32_16x16x32_bf16 v[8:11], v[120:123], v[182:185], v[8:11]
	s_barrier
	global_load_lds_dwordx4 v192, s[8:9]
	s_add_i32 m0, s12, 0x2000
	s_nop 0
	global_load_lds_dwordx4 v168, s[8:9]
	s_waitcnt vmcnt(6)
	s_barrier
	v_mfma_f32_16x16x32_bf16 v[52:55], v[196:199], v[144:147], v[52:55]
	v_mfma_f32_16x16x32_bf16 v[44:47], v[208:211], v[144:147], v[44:47]
	v_mfma_f32_16x16x32_bf16 v[36:39], v[196:199], v[152:155], v[36:39]
	v_mfma_f32_16x16x32_bf16 v[28:31], v[208:211], v[152:155], v[28:31]
	s_add_i32 s41, s41, 2
	v_mfma_f32_16x16x32_bf16 v[20:23], v[196:199], v[160:163], v[20:23]
	s_add_u32 s39, s39, 0x100
	s_addc_u32 s40, s40, 0
	v_mfma_f32_16x16x32_bf16 v[12:15], v[208:211], v[160:163], v[12:15]
	s_mov_b64 s[8:9], s[10:11]
	v_mfma_f32_16x16x32_bf16 v[4:7], v[196:199], v[178:181], v[4:7]
	s_add_u32 s10, s8, 0x100
	s_addc_u32 s11, s9, 0
	v_mfma_f32_16x16x32_bf16 v[0:3], v[208:211], v[178:181], v[0:3]
	s_add_i32 s42, 0, 0x10000
	s_cmpk_eq_i32 s41, 0x54
	v_mfma_f32_16x16x32_bf16 v[52:55], v[204:207], v[148:151], v[52:55]
	s_cselect_b32 s15, s5, s11
	s_cselect_b32 s14, s4, s10
	v_mfma_f32_16x16x32_bf16 v[44:47], v[214:217], v[148:151], v[44:47]
	s_cselect_b32 s13, s7, s40
	s_cselect_b32 s12, s6, s39
	v_mfma_f32_16x16x32_bf16 v[36:39], v[204:207], v[156:159], v[36:39]
	s_add_i32 m0, s25, 0xc000
	v_mfma_f32_16x16x32_bf16 v[28:31], v[214:217], v[156:159], v[28:31]
	v_mfma_f32_16x16x32_bf16 v[20:23], v[204:207], v[174:177], v[20:23]
	v_mfma_f32_16x16x32_bf16 v[12:15], v[214:217], v[174:177], v[12:15]
	v_mfma_f32_16x16x32_bf16 v[4:7], v[204:207], v[182:185], v[4:7]
	v_mfma_f32_16x16x32_bf16 v[0:3], v[214:217], v[182:185], v[0:3]
	s_cmpk_gt_u32 s41, 0x55
	s_barrier
	s_cbranch_scc0 .LBB0_272
	s_ashr_i32 s8, s37, 4
	v_lshl_or_b32 v144, s38, 8, v188
	s_mul_hi_i32 s9, s8, 0xc000
	s_mul_i32 s8, s8, 0xc000
	v_lshl_add_u32 v178, s37, 8, v186
	s_add_u32 s8, s29, s8
	v_ashrrev_i32_e32 v145, 31, v144
	v_ashrrev_i32_e32 v179, 31, v178
	s_addc_u32 s9, s30, s9
	v_lshlrev_b64 v[174:175], 2, v[144:145]
	v_lshl_add_u64 v[176:177], v[144:145], 1, s[2:3]
	v_lshlrev_b64 v[144:145], 12, v[178:179]
	v_lshl_add_u64 v[112:113], s[8:9], 0, v[174:175]
	v_lshl_add_u64 v[144:145], v[176:177], 0, v[144:145]
	global_load_dwordx4 v[116:119], v[112:113], off offset:16
	global_load_dwordx4 v[120:123], v[112:113], off
	global_load_dwordx4 v[108:111], v[112:113], off offset:528
	s_nop 0
	global_load_dwordx4 v[112:115], v[112:113], off offset:512
	s_nop 0
	global_load_dwordx4 v[196:199], v[144:145], off
	global_load_dwordx4 v[204:207], v[144:145], off offset:256
	v_or_b32_e32 v184, 16, v178
	v_ashrrev_i32_e32 v185, 31, v184
	v_lshlrev_b64 v[144:145], 12, v[184:185]
	v_lshl_add_u64 v[144:145], v[176:177], 0, v[144:145]
	global_load_dwordx4 v[208:211], v[144:145], off
	global_load_dwordx4 v[160:163], v[144:145], off offset:256
	v_or_b32_e32 v182, 32, v178
	v_ashrrev_i32_e32 v183, 31, v182
	v_lshlrev_b64 v[144:145], 12, v[182:183]
	v_lshl_add_u64 v[144:145], v[176:177], 0, v[144:145]
	global_load_dwordx4 v[156:159], v[144:145], off
	global_load_dwordx4 v[152:155], v[144:145], off offset:256
	v_or_b32_e32 v180, 48, v178
	v_ashrrev_i32_e32 v181, 31, v180
	v_lshlrev_b64 v[144:145], 12, v[180:181]
	v_lshl_add_u64 v[144:145], v[176:177], 0, v[144:145]
	global_load_dwordx4 v[148:151], v[144:145], off
	s_nop 0
	global_load_dwordx4 v[144:147], v[144:145], off offset:256
	v_readlane_b32 s52, v254, 39
	v_readlane_b32 s66, v254, 53
	v_readlane_b32 s67, v254, 54
	s_and_b64 vcc, exec, s[0:1]
	s_mov_b32 s38, s35
	s_mov_b32 s37, s36
	s_mov_b64 s[10:11], s[6:7]
	s_mov_b64 s[8:9], s[4:5]
	v_readlane_b32 s14, v254, 21
	s_movk_i32 s15, 0x2000
	v_readlane_b32 s53, v254, 40
	v_readlane_b32 s54, v254, 41
	v_readlane_b32 s55, v254, 42
	v_readlane_b32 s56, v254, 43
	v_readlane_b32 s57, v254, 44
	v_readlane_b32 s58, v254, 45
	v_readlane_b32 s59, v254, 46
	v_readlane_b32 s60, v254, 47
	v_readlane_b32 s61, v254, 48
	v_readlane_b32 s62, v254, 49
	v_readlane_b32 s63, v254, 50
	v_readlane_b32 s64, v254, 51
	v_readlane_b32 s65, v254, 52
	s_waitcnt vmcnt(0)
	v_lshlrev_b32_e32 v190, 16, v196
	v_and_b32_e32 v191, 0xffff0000, v196
	v_pk_fma_f32 v[140:141], v[140:141], v[120:121], v[190:191]
	v_lshlrev_b64 v[190:191], 13, v[178:179]
	v_lshlrev_b32_e32 v196, 16, v197
	v_and_b32_e32 v197, 0xffff0000, v197
	v_lshl_add_u64 v[190:191], s[66:67], 0, v[190:191]
	v_pk_fma_f32 v[142:143], v[142:143], v[122:123], v[196:197]
	v_lshl_add_u64 v[190:191], v[190:191], 0, v[174:175]
	global_store_dwordx4 v[190:191], v[140:143], off
	v_lshlrev_b32_e32 v214, 16, v198
	v_and_b32_e32 v215, 0xffff0000, v198
	v_lshlrev_b32_e32 v140, 16, v206
	v_and_b32_e32 v141, 0xffff0000, v206
	v_lshlrev_b32_e32 v142, 16, v207
	v_and_b32_e32 v143, 0xffff0000, v207
	v_pk_fma_f32 v[126:127], v[126:127], v[110:111], v[142:143]
	v_pk_fma_f32 v[124:125], v[124:125], v[108:109], v[140:141]
	global_store_dwordx4 v[190:191], v[124:127], off offset:528
	v_lshlrev_b32_e32 v198, 16, v199
	v_and_b32_e32 v199, 0xffff0000, v199
	v_lshlrev_b32_e32 v124, 16, v208
	v_and_b32_e32 v125, 0xffff0000, v208
	v_pk_fma_f32 v[124:125], v[132:133], v[120:121], v[124:125]
	v_lshlrev_b64 v[132:133], 13, v[184:185]
	v_lshlrev_b32_e32 v126, 16, v209
	v_and_b32_e32 v127, 0xffff0000, v209
	v_lshl_add_u64 v[132:133], s[66:67], 0, v[132:133]
	v_pk_fma_f32 v[126:127], v[134:135], v[122:123], v[126:127]
	v_lshl_add_u64 v[132:133], v[132:133], 0, v[174:175]
	v_pk_fma_f32 v[138:139], v[138:139], v[118:119], v[198:199]
	v_pk_fma_f32 v[136:137], v[136:137], v[116:117], v[214:215]
	global_store_dwordx4 v[132:133], v[124:127], off
	global_store_dwordx4 v[190:191], v[136:139], off offset:16
	s_nop 0
	v_lshlrev_b32_e32 v124, 16, v162
	v_and_b32_e32 v125, 0xffff0000, v162
	v_lshlrev_b32_e32 v126, 16, v163
	v_and_b32_e32 v127, 0xffff0000, v163
	v_lshlrev_b32_e32 v136, 16, v204
	v_and_b32_e32 v137, 0xffff0000, v204
	v_lshlrev_b32_e32 v138, 16, v205
	v_and_b32_e32 v139, 0xffff0000, v205
	v_pk_fma_f32 v[94:95], v[94:95], v[110:111], v[126:127]
	v_pk_fma_f32 v[92:93], v[92:93], v[108:109], v[124:125]
	v_pk_fma_f32 v[130:131], v[130:131], v[114:115], v[138:139]
	v_pk_fma_f32 v[128:129], v[128:129], v[112:113], v[136:137]
	global_store_dwordx4 v[132:133], v[92:95], off offset:528
	global_store_dwordx4 v[190:191], v[128:131], off offset:512
	s_nop 0
	v_lshlrev_b32_e32 v92, 16, v156
	v_and_b32_e32 v93, 0xffff0000, v156
	v_lshlrev_b32_e32 v128, 16, v210
	v_and_b32_e32 v129, 0xffff0000, v210
	v_lshlrev_b32_e32 v130, 16, v211
	v_and_b32_e32 v131, 0xffff0000, v211
	v_pk_fma_f32 v[92:93], v[96:97], v[120:121], v[92:93]
	v_lshlrev_b64 v[96:97], 13, v[182:183]
	v_pk_fma_f32 v[106:107], v[106:107], v[118:119], v[130:131]
	v_pk_fma_f32 v[104:105], v[104:105], v[116:117], v[128:129]
	v_lshlrev_b32_e32 v94, 16, v157
	v_and_b32_e32 v95, 0xffff0000, v157
	v_lshl_add_u64 v[96:97], s[66:67], 0, v[96:97]
	global_store_dwordx4 v[132:133], v[104:107], off offset:16
	v_pk_fma_f32 v[94:95], v[98:99], v[122:123], v[94:95]
	v_lshl_add_u64 v[96:97], v[96:97], 0, v[174:175]
	v_lshlrev_b32_e32 v104, 16, v160
	v_and_b32_e32 v105, 0xffff0000, v160
	v_lshlrev_b32_e32 v106, 16, v161
	v_and_b32_e32 v107, 0xffff0000, v161
	v_pk_fma_f32 v[102:103], v[102:103], v[114:115], v[106:107]
	v_pk_fma_f32 v[100:101], v[100:101], v[112:113], v[104:105]
	global_store_dwordx4 v[96:97], v[92:95], off
	global_store_dwordx4 v[132:133], v[100:103], off offset:512
	v_add_u32_e32 v98, 0x90, v178
	v_lshlrev_b32_e32 v92, 16, v154
	v_and_b32_e32 v93, 0xffff0000, v154
	v_lshlrev_b32_e32 v94, 16, v155
	v_and_b32_e32 v95, 0xffff0000, v155
	v_lshlrev_b32_e32 v100, 16, v158
	v_and_b32_e32 v101, 0xffff0000, v158
	v_lshlrev_b32_e32 v102, 16, v159
	v_and_b32_e32 v103, 0xffff0000, v159
	v_pk_fma_f32 v[78:79], v[78:79], v[110:111], v[94:95]
	v_pk_fma_f32 v[76:77], v[76:77], v[108:109], v[92:93]
	v_pk_fma_f32 v[90:91], v[90:91], v[118:119], v[102:103]
	v_pk_fma_f32 v[88:89], v[88:89], v[116:117], v[100:101]
	global_store_dwordx4 v[96:97], v[76:79], off offset:528
	global_store_dwordx4 v[96:97], v[88:91], off offset:16
	v_ashrrev_i32_e32 v99, 31, v98
	v_lshlrev_b32_e32 v76, 16, v148
	v_and_b32_e32 v77, 0xffff0000, v148
	v_lshlrev_b32_e32 v88, 16, v152
	v_and_b32_e32 v89, 0xffff0000, v152
	v_lshlrev_b32_e32 v90, 16, v153
	v_and_b32_e32 v91, 0xffff0000, v153
	v_pk_fma_f32 v[76:77], v[80:81], v[120:121], v[76:77]
	v_lshlrev_b64 v[80:81], 13, v[180:181]
	v_pk_fma_f32 v[86:87], v[86:87], v[114:115], v[90:91]
	v_pk_fma_f32 v[84:85], v[84:85], v[112:113], v[88:89]
	v_lshlrev_b32_e32 v78, 16, v149
	v_and_b32_e32 v79, 0xffff0000, v149
	v_lshl_add_u64 v[80:81], s[66:67], 0, v[80:81]
	global_store_dwordx4 v[96:97], v[84:87], off offset:512
	v_pk_fma_f32 v[78:79], v[82:83], v[122:123], v[78:79]
	v_lshl_add_u64 v[80:81], v[80:81], 0, v[174:175]
	v_lshlrev_b32_e32 v84, 16, v150
	v_and_b32_e32 v85, 0xffff0000, v150
	v_lshlrev_b32_e32 v86, 16, v151
	v_and_b32_e32 v87, 0xffff0000, v151
	global_store_dwordx4 v[80:81], v[76:79], off
	v_pk_fma_f32 v[74:75], v[74:75], v[118:119], v[86:87]
	v_pk_fma_f32 v[72:73], v[72:73], v[116:117], v[84:85]
	v_lshlrev_b32_e32 v76, 16, v146
	v_and_b32_e32 v77, 0xffff0000, v146
	v_lshlrev_b32_e32 v78, 16, v147
	v_and_b32_e32 v79, 0xffff0000, v147
	v_add_u32_e32 v96, 0x80, v178
	global_store_dwordx4 v[80:81], v[72:75], off offset:16
	v_pk_fma_f32 v[66:67], v[66:67], v[110:111], v[78:79]
	v_pk_fma_f32 v[64:65], v[64:65], v[108:109], v[76:77]
	v_lshlrev_b32_e32 v72, 16, v144
	v_and_b32_e32 v73, 0xffff0000, v144
	v_lshlrev_b32_e32 v74, 16, v145
	v_and_b32_e32 v75, 0xffff0000, v145
	v_ashrrev_i32_e32 v97, 31, v96
	v_pk_fma_f32 v[70:71], v[70:71], v[114:115], v[74:75]
	v_pk_fma_f32 v[68:69], v[68:69], v[112:113], v[72:73]
	global_store_dwordx4 v[80:81], v[64:67], off offset:528
	global_store_dwordx4 v[80:81], v[68:71], off offset:512
	v_add_u32_e32 v100, 0xa0, v178
	v_lshlrev_b64 v[64:65], 12, v[96:97]
	v_lshl_add_u64 v[64:65], v[176:177], 0, v[64:65]
	global_load_dwordx4 v[68:71], v[64:65], off
	global_load_dwordx4 v[72:75], v[64:65], off offset:256
	v_lshlrev_b64 v[64:65], 12, v[98:99]
	v_lshl_add_u64 v[64:65], v[176:177], 0, v[64:65]
	global_load_dwordx4 v[76:79], v[64:65], off
	global_load_dwordx4 v[80:83], v[64:65], off offset:256
	v_ashrrev_i32_e32 v101, 31, v100
	v_lshlrev_b64 v[64:65], 12, v[100:101]
	v_lshl_add_u64 v[64:65], v[176:177], 0, v[64:65]
	global_load_dwordx4 v[84:87], v[64:65], off
	global_load_dwordx4 v[88:91], v[64:65], off offset:256
	v_add_u32_e32 v102, 0xb0, v178
	v_ashrrev_i32_e32 v103, 31, v102
	v_lshlrev_b64 v[64:65], 12, v[102:103]
	v_lshl_add_u64 v[64:65], v[176:177], 0, v[64:65]
	global_load_dwordx4 v[92:95], v[64:65], off
	s_nop 0
	global_load_dwordx4 v[64:67], v[64:65], off offset:256
	s_waitcnt vmcnt(0)
	v_lshlrev_b32_e32 v104, 16, v68
	v_and_b32_e32 v105, 0xffff0000, v68
	v_lshlrev_b32_e32 v68, 16, v69
	v_and_b32_e32 v69, 0xffff0000, v69
	v_pk_fma_f32 v[62:63], v[62:63], v[122:123], v[68:69]
	v_lshlrev_b64 v[68:69], 13, v[96:97]
	v_lshl_add_u64 v[68:69], s[66:67], 0, v[68:69]
	v_pk_fma_f32 v[60:61], v[60:61], v[120:121], v[104:105]
	v_lshl_add_u64 v[68:69], v[68:69], 0, v[174:175]
	global_store_dwordx4 v[68:69], v[60:63], off
	v_lshlrev_b32_e32 v106, 16, v70
	v_and_b32_e32 v107, 0xffff0000, v70
	v_lshlrev_b32_e32 v60, 16, v74
	v_and_b32_e32 v61, 0xffff0000, v74
	v_lshlrev_b32_e32 v62, 16, v75
	v_and_b32_e32 v63, 0xffff0000, v75
	v_pk_fma_f32 v[46:47], v[46:47], v[110:111], v[62:63]
	v_pk_fma_f32 v[44:45], v[44:45], v[108:109], v[60:61]
	global_store_dwordx4 v[68:69], v[44:47], off offset:528
	v_lshlrev_b32_e32 v70, 16, v71
	v_and_b32_e32 v71, 0xffff0000, v71
	v_lshlrev_b32_e32 v44, 16, v76
	v_and_b32_e32 v45, 0xffff0000, v76
	v_pk_fma_f32 v[44:45], v[48:49], v[120:121], v[44:45]
	v_lshlrev_b64 v[48:49], 13, v[98:99]
	v_lshlrev_b32_e32 v46, 16, v77
	v_and_b32_e32 v47, 0xffff0000, v77
	v_lshl_add_u64 v[48:49], s[66:67], 0, v[48:49]
	v_pk_fma_f32 v[58:59], v[58:59], v[118:119], v[70:71]
	v_pk_fma_f32 v[56:57], v[56:57], v[116:117], v[106:107]
	v_pk_fma_f32 v[46:47], v[50:51], v[122:123], v[46:47]
	v_lshl_add_u64 v[48:49], v[48:49], 0, v[174:175]
	global_store_dwordx4 v[68:69], v[56:59], off offset:16
	global_store_dwordx4 v[48:49], v[44:47], off
	s_nop 0
	v_lshlrev_b32_e32 v56, 16, v72
	v_and_b32_e32 v57, 0xffff0000, v72
	v_lshlrev_b32_e32 v58, 16, v73
	v_and_b32_e32 v59, 0xffff0000, v73
	v_lshlrev_b32_e32 v44, 16, v82
	v_and_b32_e32 v45, 0xffff0000, v82
	v_lshlrev_b32_e32 v46, 16, v83
	v_and_b32_e32 v47, 0xffff0000, v83
	v_pk_fma_f32 v[54:55], v[54:55], v[114:115], v[58:59]
	v_pk_fma_f32 v[52:53], v[52:53], v[112:113], v[56:57]
	v_pk_fma_f32 v[30:31], v[30:31], v[110:111], v[46:47]
	v_pk_fma_f32 v[28:29], v[28:29], v[108:109], v[44:45]
	global_store_dwordx4 v[68:69], v[52:55], off offset:512
	global_store_dwordx4 v[48:49], v[28:31], off offset:528
	s_nop 0
	v_lshlrev_b32_e32 v52, 16, v78
	v_and_b32_e32 v53, 0xffff0000, v78
	v_lshlrev_b32_e32 v54, 16, v79
	v_and_b32_e32 v55, 0xffff0000, v79
	v_lshlrev_b32_e32 v28, 16, v84
	v_and_b32_e32 v29, 0xffff0000, v84
	v_pk_fma_f32 v[42:43], v[42:43], v[118:119], v[54:55]
	v_pk_fma_f32 v[40:41], v[40:41], v[116:117], v[52:53]
	v_pk_fma_f32 v[28:29], v[32:33], v[120:121], v[28:29]
	v_lshlrev_b64 v[32:33], 13, v[100:101]
	global_store_dwordx4 v[48:49], v[40:43], off offset:16
	v_lshlrev_b32_e32 v30, 16, v85
	v_and_b32_e32 v31, 0xffff0000, v85
	v_lshlrev_b32_e32 v40, 16, v80
	v_and_b32_e32 v41, 0xffff0000, v80
	v_lshlrev_b32_e32 v42, 16, v81
	v_and_b32_e32 v43, 0xffff0000, v81
	v_lshl_add_u64 v[32:33], s[66:67], 0, v[32:33]
	v_pk_fma_f32 v[38:39], v[38:39], v[114:115], v[42:43]
	v_pk_fma_f32 v[36:37], v[36:37], v[112:113], v[40:41]
	v_pk_fma_f32 v[30:31], v[34:35], v[122:123], v[30:31]
	v_lshl_add_u64 v[32:33], v[32:33], 0, v[174:175]
	global_store_dwordx4 v[48:49], v[36:39], off offset:512
	global_store_dwordx4 v[32:33], v[28:31], off
	s_nop 0
	v_lshlrev_b32_e32 v36, 16, v86
	v_and_b32_e32 v37, 0xffff0000, v86
	v_lshlrev_b32_e32 v38, 16, v87
	v_and_b32_e32 v39, 0xffff0000, v87
	v_lshlrev_b32_e32 v28, 16, v90
	v_and_b32_e32 v29, 0xffff0000, v90
	v_lshlrev_b32_e32 v30, 16, v91
	v_and_b32_e32 v31, 0xffff0000, v91
	v_pk_fma_f32 v[26:27], v[26:27], v[118:119], v[38:39]
	v_pk_fma_f32 v[24:25], v[24:25], v[116:117], v[36:37]
	v_pk_fma_f32 v[14:15], v[14:15], v[110:111], v[30:31]
	v_pk_fma_f32 v[12:13], v[12:13], v[108:109], v[28:29]
	global_store_dwordx4 v[32:33], v[24:27], off offset:16
	global_store_dwordx4 v[32:33], v[12:15], off offset:528
	s_nop 0
	v_lshlrev_b32_e32 v24, 16, v88
	v_and_b32_e32 v25, 0xffff0000, v88
	v_lshlrev_b32_e32 v26, 16, v89
	v_and_b32_e32 v27, 0xffff0000, v89
	v_lshlrev_b32_e32 v12, 16, v92
	v_and_b32_e32 v13, 0xffff0000, v92
	v_pk_fma_f32 v[22:23], v[22:23], v[114:115], v[26:27]
	v_pk_fma_f32 v[20:21], v[20:21], v[112:113], v[24:25]
	v_pk_fma_f32 v[12:13], v[16:17], v[120:121], v[12:13]
	v_lshlrev_b64 v[16:17], 13, v[102:103]
	global_store_dwordx4 v[32:33], v[20:23], off offset:512
	v_lshlrev_b32_e32 v14, 16, v93
	v_and_b32_e32 v15, 0xffff0000, v93
	v_lshlrev_b32_e32 v20, 16, v94
	v_and_b32_e32 v21, 0xffff0000, v94
	v_lshlrev_b32_e32 v22, 16, v95
	v_and_b32_e32 v23, 0xffff0000, v95
	v_lshl_add_u64 v[16:17], s[66:67], 0, v[16:17]
	v_pk_fma_f32 v[14:15], v[18:19], v[122:123], v[14:15]
	v_lshl_add_u64 v[16:17], v[16:17], 0, v[174:175]
	v_pk_fma_f32 v[10:11], v[10:11], v[118:119], v[22:23]
	v_pk_fma_f32 v[8:9], v[8:9], v[116:117], v[20:21]
	global_store_dwordx4 v[16:17], v[12:15], off
	global_store_dwordx4 v[16:17], v[8:11], off offset:16
	s_nop 0
	v_lshlrev_b32_e32 v12, 16, v66
	v_lshlrev_b32_e32 v8, 16, v64
	v_and_b32_e32 v9, 0xffff0000, v64
	v_lshlrev_b32_e32 v10, 16, v65
	v_and_b32_e32 v11, 0xffff0000, v65
	v_and_b32_e32 v13, 0xffff0000, v66
	v_lshlrev_b32_e32 v14, 16, v67
	v_and_b32_e32 v15, 0xffff0000, v67
	v_pk_fma_f32 v[6:7], v[6:7], v[114:115], v[10:11]
	v_pk_fma_f32 v[4:5], v[4:5], v[112:113], v[8:9]
	v_pk_fma_f32 v[2:3], v[2:3], v[110:111], v[14:15]
	v_pk_fma_f32 v[0:1], v[0:1], v[108:109], v[12:13]
	global_store_dwordx4 v[16:17], v[4:7], off offset:512
	global_store_dwordx4 v[16:17], v[0:3], off offset:528
	s_cbranch_vccz .LBB0_261
	s_waitcnt vmcnt(0)
	s_cmpk_gt_u32 s16, 0xff
	s_cbranch_scc1 .LBB0_276
	s_barrier

.LBB0_293:
	v_mov_b64_e32 v[0:1], 0x400
	s_ashr_i32 s7, s6, 31
	v_cmp_lt_i64_e32 vcc, s[8:9], v[0:1]
	s_lshl_b64 s[8:9], s[6:7], 20
	s_add_u32 s8, s20, s8
	s_addc_u32 s9, s21, s9
	s_and_b64 s[10:11], vcc, exec
	s_cselect_b32 s7, s9, s15
	s_cselect_b32 s38, s8, s14
	s_ashr_i32 s5, s4, 31
	s_lshl_b64 s[10:11], s[4:5], 20
	s_add_u32 s10, s22, s10
	s_addc_u32 s11, s23, s11
	s_and_b64 s[18:19], vcc, exec
	s_cselect_b32 s5, s11, s17
	s_cselect_b32 s39, s10, s16
	s_add_u32 s14, s14, 0x80080
	s_addc_u32 s15, s15, 0
	s_add_u32 s40, s16, 0x100
	s_addc_u32 s41, s17, 0
	s_mov_b32 s42, -2
	s_mov_b64 s[48:49], 0x80
	v_add_u32_e32 v220, 0x10000, v159
	s_add_u32 s16, s14, 0xfff80080
	s_addc_u32 s17, s15, -1
	s_add_i32 s43, 0, 0x10000
	ds_read_b128 v[64:67], v220 offset:0
	ds_read_b128 v[68:71], v220 offset:1024
	ds_read_b128 v[72:75], v220 offset:2048
	ds_read_b128 v[76:79], v220 offset:3072
	s_cmp_eq_u32 s42, 28
	s_cselect_b32 s19, s7, s17
	s_cselect_b32 s18, s38, s16
	s_cselect_b32 s17, s5, s41
	s_cselect_b32 s16, s39, s40
	s_add_i32 m0, s13, 0xc000
	ds_read_b128 v[154:157], v161
	ds_read_b128 v[162:165], v161 offset:1024
	ds_read_b128 v[166:169], v161 offset:2048
	ds_read_b128 v[170:173], v161 offset:3072
	ds_read_b128 v[174:177], v161 offset:4096
	ds_read_b128 v[178:181], v161 offset:5120
	ds_read_b128 v[182:185], v161 offset:6144
	ds_read_b128 v[186:189], v161 offset:7168
	global_load_lds_dwordx4 v150, s[14:15]
	s_add_i32 m0, s13, 0xe000
	s_nop 0
	global_load_lds_dwordx4 v152, s[14:15]
	s_waitcnt lgkmcnt(8)
	s_barrier
	s_waitcnt lgkmcnt(0)
	v_mfma_f32_16x16x32_bf16 v[140:143], v[64:67], v[154:157], 0
	v_mfma_f32_16x16x32_bf16 v[136:139], v[72:75], v[154:157], 0
	v_mfma_f32_16x16x32_bf16 v[132:135], v[64:67], v[166:169], 0
	v_mfma_f32_16x16x32_bf16 v[128:131], v[72:75], v[166:169], 0
	s_add_i32 s46, 0, 0x14000
	s_add_i32 s43, s43, s27
	v_mfma_f32_16x16x32_bf16 v[108:111], v[64:67], v[174:177], 0
	s_mov_b32 m0, s43
	v_mfma_f32_16x16x32_bf16 v[104:107], v[72:75], v[174:177], 0
	v_mfma_f32_16x16x32_bf16 v[100:103], v[64:67], v[182:185], 0
	v_mfma_f32_16x16x32_bf16 v[96:99], v[72:75], v[182:185], 0
	v_mfma_f32_16x16x32_bf16 v[140:143], v[68:71], v[162:165], v[140:143]
	v_mfma_f32_16x16x32_bf16 v[136:139], v[76:79], v[162:165], v[136:139]
	v_mfma_f32_16x16x32_bf16 v[132:135], v[68:71], v[170:173], v[132:135]
	v_mfma_f32_16x16x32_bf16 v[128:131], v[76:79], v[170:173], v[128:131]
	v_mfma_f32_16x16x32_bf16 v[108:111], v[68:71], v[178:181], v[108:111]
	v_mfma_f32_16x16x32_bf16 v[104:107], v[76:79], v[178:181], v[104:107]
	v_mfma_f32_16x16x32_bf16 v[100:103], v[68:71], v[186:189], v[100:103]
	v_mfma_f32_16x16x32_bf16 v[96:99], v[76:79], v[186:189], v[96:99]
	s_barrier
	ds_read_b128 v[196:199], v220 offset:16384
	ds_read_b128 v[204:207], v220 offset:17408
	ds_read_b128 v[208:211], v220 offset:18432
	ds_read_b128 v[214:217], v220 offset:19456
	global_load_lds_dwordx4 v192, s[16:17]
	s_add_i32 m0, s43, 0x2000
	s_nop 0
	global_load_lds_dwordx4 v148, s[16:17]
	s_barrier
	s_waitcnt lgkmcnt(0)
	v_mfma_f32_16x16x32_bf16 v[124:127], v[196:199], v[154:157], 0
	v_mfma_f32_16x16x32_bf16 v[120:123], v[208:211], v[154:157], 0
	v_mfma_f32_16x16x32_bf16 v[116:119], v[196:199], v[166:169], 0
	v_mfma_f32_16x16x32_bf16 v[112:115], v[208:211], v[166:169], 0
	s_mov_b32 m0, s13
	v_mfma_f32_16x16x32_bf16 v[92:95], v[196:199], v[174:177], 0
	s_add_u32 s48, s18, 0x80
	s_addc_u32 s49, s19, 0
	v_mfma_f32_16x16x32_bf16 v[88:91], v[208:211], v[174:177], 0
	v_mfma_f32_16x16x32_bf16 v[84:87], v[196:199], v[182:185], 0
	v_mfma_f32_16x16x32_bf16 v[80:83], v[208:211], v[182:185], 0
	v_mfma_f32_16x16x32_bf16 v[124:127], v[204:207], v[162:165], v[124:127]
	v_mfma_f32_16x16x32_bf16 v[120:123], v[214:217], v[162:165], v[120:123]
	v_mfma_f32_16x16x32_bf16 v[116:119], v[204:207], v[170:173], v[116:119]
	v_mfma_f32_16x16x32_bf16 v[112:115], v[214:217], v[170:173], v[112:115]
	v_mfma_f32_16x16x32_bf16 v[92:95], v[204:207], v[178:181], v[92:95]
	v_mfma_f32_16x16x32_bf16 v[88:91], v[214:217], v[178:181], v[88:91]
	v_mfma_f32_16x16x32_bf16 v[84:87], v[204:207], v[186:189], v[84:87]
	v_mfma_f32_16x16x32_bf16 v[80:83], v[214:217], v[186:189], v[80:83]
	s_barrier
	ds_read_b128 v[154:157], v161 offset:16384
	ds_read_b128 v[162:165], v161 offset:17408
	ds_read_b128 v[166:169], v161 offset:18432
	ds_read_b128 v[170:173], v161 offset:19456
	ds_read_b128 v[174:177], v161 offset:20480
	ds_read_b128 v[178:181], v161 offset:21504
	ds_read_b128 v[182:185], v161 offset:22528
	ds_read_b128 v[186:189], v161 offset:23552
	global_load_lds_dwordx4 v144, s[18:19]
	s_mov_b32 m0, s28
	s_nop 0
	global_load_lds_dwordx4 v146, s[18:19]
	s_barrier
	s_waitcnt lgkmcnt(0)
	v_mfma_f32_16x16x32_bf16 v[60:63], v[64:67], v[154:157], 0
	v_mfma_f32_16x16x32_bf16 v[56:59], v[72:75], v[154:157], 0
	v_mfma_f32_16x16x32_bf16 v[52:55], v[64:67], v[166:169], 0
	v_mfma_f32_16x16x32_bf16 v[48:51], v[72:75], v[166:169], 0
	s_add_u32 s44, s16, 0x80000
	s_addc_u32 s45, s17, 0
	v_mfma_f32_16x16x32_bf16 v[28:31], v[64:67], v[174:177], 0
	s_add_i32 s43, s46, s27
	s_mov_b32 m0, s43
	v_mfma_f32_16x16x32_bf16 v[24:27], v[72:75], v[174:177], 0
	v_mfma_f32_16x16x32_bf16 v[20:23], v[64:67], v[182:185], 0
	v_mfma_f32_16x16x32_bf16 v[16:19], v[72:75], v[182:185], 0
	v_mfma_f32_16x16x32_bf16 v[60:63], v[68:71], v[162:165], v[60:63]
	v_mfma_f32_16x16x32_bf16 v[56:59], v[76:79], v[162:165], v[56:59]
	v_mfma_f32_16x16x32_bf16 v[52:55], v[68:71], v[170:173], v[52:55]
	v_mfma_f32_16x16x32_bf16 v[48:51], v[76:79], v[170:173], v[48:51]
	v_mfma_f32_16x16x32_bf16 v[28:31], v[68:71], v[178:181], v[28:31]
	v_mfma_f32_16x16x32_bf16 v[24:27], v[76:79], v[178:181], v[24:27]
	v_mfma_f32_16x16x32_bf16 v[20:23], v[68:71], v[186:189], v[20:23]
	v_mfma_f32_16x16x32_bf16 v[16:19], v[76:79], v[186:189], v[16:19]
	s_barrier
	global_load_lds_dwordx4 v192, s[44:45]
	s_add_i32 m0, s43, 0x2000
	s_nop 0
	global_load_lds_dwordx4 v148, s[44:45]
	s_waitcnt vmcnt(6)
	s_barrier
	v_mfma_f32_16x16x32_bf16 v[44:47], v[196:199], v[154:157], 0
	v_mfma_f32_16x16x32_bf16 v[40:43], v[208:211], v[154:157], 0
	v_mfma_f32_16x16x32_bf16 v[36:39], v[196:199], v[166:169], 0
	v_mfma_f32_16x16x32_bf16 v[32:35], v[208:211], v[166:169], 0
	s_add_i32 s43, 0, 0x18000
	v_mfma_f32_16x16x32_bf16 v[12:15], v[196:199], v[174:177], 0
	s_add_u32 s18, s18, 0x80000
	s_addc_u32 s19, s19, 0
	v_mfma_f32_16x16x32_bf16 v[8:11], v[208:211], v[174:177], 0
	s_mov_b32 m0, s29
	v_mfma_f32_16x16x32_bf16 v[4:7], v[196:199], v[182:185], 0
	v_mfma_f32_16x16x32_bf16 v[0:3], v[208:211], v[182:185], 0
	v_mfma_f32_16x16x32_bf16 v[44:47], v[204:207], v[162:165], v[44:47]
	v_mfma_f32_16x16x32_bf16 v[40:43], v[214:217], v[162:165], v[40:43]
	v_mfma_f32_16x16x32_bf16 v[36:39], v[204:207], v[170:173], v[36:39]
	v_mfma_f32_16x16x32_bf16 v[32:35], v[214:217], v[170:173], v[32:35]
	v_mfma_f32_16x16x32_bf16 v[12:15], v[204:207], v[178:181], v[12:15]
	v_mfma_f32_16x16x32_bf16 v[8:11], v[214:217], v[178:181], v[8:11]
	v_mfma_f32_16x16x32_bf16 v[4:7], v[204:207], v[186:189], v[4:7]
	v_mfma_f32_16x16x32_bf16 v[0:3], v[214:217], v[186:189], v[0:3]
	s_barrier
	ds_read_b128 v[64:67], v220 offset:32768
	ds_read_b128 v[68:71], v220 offset:33792
	ds_read_b128 v[72:75], v220 offset:34816
	ds_read_b128 v[76:79], v220 offset:35840
	ds_read_b128 v[154:157], v161 offset:32768
	ds_read_b128 v[162:165], v161 offset:33792
	ds_read_b128 v[166:169], v161 offset:34816
	ds_read_b128 v[170:173], v161 offset:35840
	ds_read_b128 v[174:177], v161 offset:36864
	ds_read_b128 v[178:181], v161 offset:37888
	ds_read_b128 v[182:185], v161 offset:38912
	ds_read_b128 v[186:189], v161 offset:39936
	global_load_lds_dwordx4 v144, s[18:19]
	s_mov_b32 m0, s30
	s_nop 0
	global_load_lds_dwordx4 v146, s[18:19]
	s_waitcnt lgkmcnt(8)
	s_barrier
	s_waitcnt lgkmcnt(0)
	v_mfma_f32_16x16x32_bf16 v[140:143], v[64:67], v[154:157], v[140:143]
	v_mfma_f32_16x16x32_bf16 v[136:139], v[72:75], v[154:157], v[136:139]
	v_mfma_f32_16x16x32_bf16 v[132:135], v[64:67], v[166:169], v[132:135]
	v_mfma_f32_16x16x32_bf16 v[128:131], v[72:75], v[166:169], v[128:131]
	s_add_i32 s18, 0, 0x1c000
	s_add_i32 s19, s43, s27
	v_mfma_f32_16x16x32_bf16 v[108:111], v[64:67], v[174:177], v[108:111]
	s_add_i32 m0, s19, 0xffffff80
	v_mfma_f32_16x16x32_bf16 v[104:107], v[72:75], v[174:177], v[104:107]
	v_mfma_f32_16x16x32_bf16 v[100:103], v[64:67], v[182:185], v[100:103]
	v_mfma_f32_16x16x32_bf16 v[96:99], v[72:75], v[182:185], v[96:99]
	v_mfma_f32_16x16x32_bf16 v[140:143], v[68:71], v[162:165], v[140:143]
	v_mfma_f32_16x16x32_bf16 v[136:139], v[76:79], v[162:165], v[136:139]
	v_mfma_f32_16x16x32_bf16 v[132:135], v[68:71], v[170:173], v[132:135]
	v_mfma_f32_16x16x32_bf16 v[128:131], v[76:79], v[170:173], v[128:131]
	v_mfma_f32_16x16x32_bf16 v[108:111], v[68:71], v[178:181], v[108:111]
	v_mfma_f32_16x16x32_bf16 v[104:107], v[76:79], v[178:181], v[104:107]
	v_mfma_f32_16x16x32_bf16 v[100:103], v[68:71], v[186:189], v[100:103]
	v_mfma_f32_16x16x32_bf16 v[96:99], v[76:79], v[186:189], v[96:99]
	s_barrier
	ds_read_b128 v[196:199], v220 offset:49152
	ds_read_b128 v[204:207], v220 offset:50176
	ds_read_b128 v[208:211], v220 offset:51200
	ds_read_b128 v[214:217], v220 offset:52224
	global_load_lds_dwordx4 v192, s[16:17] offset:128
	s_add_i32 m0, s19, 0x1f80
	s_nop 0
	global_load_lds_dwordx4 v148, s[16:17] offset:128
	s_barrier
	s_waitcnt lgkmcnt(0)
	v_mfma_f32_16x16x32_bf16 v[124:127], v[196:199], v[154:157], v[124:127]
	v_mfma_f32_16x16x32_bf16 v[120:123], v[208:211], v[154:157], v[120:123]
	v_mfma_f32_16x16x32_bf16 v[116:119], v[196:199], v[166:169], v[116:119]
	v_mfma_f32_16x16x32_bf16 v[112:115], v[208:211], v[166:169], v[112:115]
	s_mov_b32 m0, s34
	v_mfma_f32_16x16x32_bf16 v[92:95], v[196:199], v[174:177], v[92:95]
	v_mfma_f32_16x16x32_bf16 v[88:91], v[208:211], v[174:177], v[88:91]
	v_mfma_f32_16x16x32_bf16 v[84:87], v[196:199], v[182:185], v[84:87]
	v_mfma_f32_16x16x32_bf16 v[80:83], v[208:211], v[182:185], v[80:83]
	v_mfma_f32_16x16x32_bf16 v[124:127], v[204:207], v[162:165], v[124:127]
	v_mfma_f32_16x16x32_bf16 v[120:123], v[214:217], v[162:165], v[120:123]
	v_mfma_f32_16x16x32_bf16 v[116:119], v[204:207], v[170:173], v[116:119]
	v_mfma_f32_16x16x32_bf16 v[112:115], v[214:217], v[170:173], v[112:115]
	v_mfma_f32_16x16x32_bf16 v[92:95], v[204:207], v[178:181], v[92:95]
	v_mfma_f32_16x16x32_bf16 v[88:91], v[214:217], v[178:181], v[88:91]
	v_mfma_f32_16x16x32_bf16 v[84:87], v[204:207], v[186:189], v[84:87]
	v_mfma_f32_16x16x32_bf16 v[80:83], v[214:217], v[186:189], v[80:83]
	s_barrier
	ds_read_b128 v[154:157], v161 offset:49152
	ds_read_b128 v[162:165], v161 offset:50176
	ds_read_b128 v[166:169], v161 offset:51200
	ds_read_b128 v[170:173], v161 offset:52224
	ds_read_b128 v[174:177], v161 offset:53248
	ds_read_b128 v[178:181], v161 offset:54272
	ds_read_b128 v[182:185], v161 offset:55296
	ds_read_b128 v[186:189], v161 offset:56320
	global_load_lds_dwordx4 v144, s[48:49]
	s_mov_b32 m0, s35
	s_nop 0
	global_load_lds_dwordx4 v146, s[48:49]
	s_barrier
	s_waitcnt lgkmcnt(0)
	v_mfma_f32_16x16x32_bf16 v[60:63], v[64:67], v[154:157], v[60:63]
	v_mfma_f32_16x16x32_bf16 v[56:59], v[72:75], v[154:157], v[56:59]
	v_mfma_f32_16x16x32_bf16 v[52:55], v[64:67], v[166:169], v[52:55]
	v_mfma_f32_16x16x32_bf16 v[48:51], v[72:75], v[166:169], v[48:51]
	s_add_u32 s16, s16, 0x80080
	s_addc_u32 s17, s17, 0
	v_mfma_f32_16x16x32_bf16 v[28:31], v[64:67], v[174:177], v[28:31]
	s_add_i32 s18, s18, s27
	s_mov_b32 m0, s18
	v_mfma_f32_16x16x32_bf16 v[24:27], v[72:75], v[174:177], v[24:27]
	v_mfma_f32_16x16x32_bf16 v[20:23], v[64:67], v[182:185], v[20:23]
	v_mfma_f32_16x16x32_bf16 v[16:19], v[72:75], v[182:185], v[16:19]
	v_mfma_f32_16x16x32_bf16 v[60:63], v[68:71], v[162:165], v[60:63]
	v_mfma_f32_16x16x32_bf16 v[56:59], v[76:79], v[162:165], v[56:59]
	v_mfma_f32_16x16x32_bf16 v[52:55], v[68:71], v[170:173], v[52:55]
	v_mfma_f32_16x16x32_bf16 v[48:51], v[76:79], v[170:173], v[48:51]
	v_mfma_f32_16x16x32_bf16 v[28:31], v[68:71], v[178:181], v[28:31]
	v_mfma_f32_16x16x32_bf16 v[24:27], v[76:79], v[178:181], v[24:27]
	v_mfma_f32_16x16x32_bf16 v[20:23], v[68:71], v[186:189], v[20:23]
	v_mfma_f32_16x16x32_bf16 v[16:19], v[76:79], v[186:189], v[16:19]
	s_barrier
	global_load_lds_dwordx4 v192, s[16:17]
	s_add_i32 m0, s18, 0x2000
	s_nop 0
	global_load_lds_dwordx4 v148, s[16:17]
	s_waitcnt vmcnt(6)
	s_barrier
	v_mfma_f32_16x16x32_bf16 v[44:47], v[196:199], v[154:157], v[44:47]
	v_mfma_f32_16x16x32_bf16 v[40:43], v[208:211], v[154:157], v[40:43]
	v_mfma_f32_16x16x32_bf16 v[36:39], v[196:199], v[166:169], v[36:39]
	v_mfma_f32_16x16x32_bf16 v[32:35], v[208:211], v[166:169], v[32:35]
	s_add_i32 s42, s42, 2
	v_mfma_f32_16x16x32_bf16 v[12:15], v[196:199], v[174:177], v[12:15]
	s_add_u32 s14, s14, 0x100
	s_addc_u32 s15, s15, 0
	v_mfma_f32_16x16x32_bf16 v[8:11], v[208:211], v[174:177], v[8:11]
	s_add_u32 s40, s40, 0x100
	s_addc_u32 s41, s41, 0
	v_mfma_f32_16x16x32_bf16 v[4:7], v[196:199], v[182:185], v[4:7]
	s_add_u32 s16, s14, 0xfff80080
	s_addc_u32 s17, s15, -1
	v_mfma_f32_16x16x32_bf16 v[0:3], v[208:211], v[182:185], v[0:3]
	s_add_i32 s43, 0, 0x10000
	s_cmp_eq_u32 s42, 28
	v_mfma_f32_16x16x32_bf16 v[44:47], v[204:207], v[162:165], v[44:47]
	s_cselect_b32 s19, s7, s17
	s_cselect_b32 s18, s38, s16
	v_mfma_f32_16x16x32_bf16 v[40:43], v[214:217], v[162:165], v[40:43]
	s_cselect_b32 s17, s5, s41
	s_cselect_b32 s16, s39, s40
	v_mfma_f32_16x16x32_bf16 v[36:39], v[204:207], v[170:173], v[36:39]
	s_add_i32 m0, s13, 0xc000
	v_mfma_f32_16x16x32_bf16 v[32:35], v[214:217], v[170:173], v[32:35]
	v_mfma_f32_16x16x32_bf16 v[12:15], v[204:207], v[178:181], v[12:15]
	v_mfma_f32_16x16x32_bf16 v[8:11], v[214:217], v[178:181], v[8:11]
	v_mfma_f32_16x16x32_bf16 v[4:7], v[204:207], v[186:189], v[4:7]
	v_mfma_f32_16x16x32_bf16 v[0:3], v[214:217], v[186:189], v[0:3]
	s_cmp_gt_u32 s42, 29
	s_barrier
.LBB0_294:
	ds_read_b128 v[64:67], v220 offset:0
	ds_read_b128 v[68:71], v220 offset:1024
	ds_read_b128 v[72:75], v220 offset:2048
	ds_read_b128 v[76:79], v220 offset:3072
	ds_read_b128 v[154:157], v161
	ds_read_b128 v[162:165], v161 offset:1024
	ds_read_b128 v[166:169], v161 offset:2048
	ds_read_b128 v[170:173], v161 offset:3072
	ds_read_b128 v[174:177], v161 offset:4096
	ds_read_b128 v[178:181], v161 offset:5120
	ds_read_b128 v[182:185], v161 offset:6144
	ds_read_b128 v[186:189], v161 offset:7168
	global_load_lds_dwordx4 v150, s[14:15]
	s_add_i32 m0, s13, 0xe000
	s_nop 0
	global_load_lds_dwordx4 v152, s[14:15]
	s_waitcnt lgkmcnt(8)
	s_barrier
	s_waitcnt lgkmcnt(0)
	v_mfma_f32_16x16x32_bf16 v[140:143], v[64:67], v[154:157], v[140:143]
	v_mfma_f32_16x16x32_bf16 v[136:139], v[72:75], v[154:157], v[136:139]
	v_mfma_f32_16x16x32_bf16 v[132:135], v[64:67], v[166:169], v[132:135]
	v_mfma_f32_16x16x32_bf16 v[128:131], v[72:75], v[166:169], v[128:131]
	s_add_i32 s46, 0, 0x14000
	s_add_i32 s43, s43, s27
	v_mfma_f32_16x16x32_bf16 v[108:111], v[64:67], v[174:177], v[108:111]
	s_mov_b32 m0, s43
	v_mfma_f32_16x16x32_bf16 v[104:107], v[72:75], v[174:177], v[104:107]
	v_mfma_f32_16x16x32_bf16 v[100:103], v[64:67], v[182:185], v[100:103]
	v_mfma_f32_16x16x32_bf16 v[96:99], v[72:75], v[182:185], v[96:99]
	v_mfma_f32_16x16x32_bf16 v[140:143], v[68:71], v[162:165], v[140:143]
	v_mfma_f32_16x16x32_bf16 v[136:139], v[76:79], v[162:165], v[136:139]
	v_mfma_f32_16x16x32_bf16 v[132:135], v[68:71], v[170:173], v[132:135]
	v_mfma_f32_16x16x32_bf16 v[128:131], v[76:79], v[170:173], v[128:131]
	v_mfma_f32_16x16x32_bf16 v[108:111], v[68:71], v[178:181], v[108:111]
	v_mfma_f32_16x16x32_bf16 v[104:107], v[76:79], v[178:181], v[104:107]
	v_mfma_f32_16x16x32_bf16 v[100:103], v[68:71], v[186:189], v[100:103]
	v_mfma_f32_16x16x32_bf16 v[96:99], v[76:79], v[186:189], v[96:99]
	s_barrier
	ds_read_b128 v[196:199], v220 offset:16384
	ds_read_b128 v[204:207], v220 offset:17408
	ds_read_b128 v[208:211], v220 offset:18432
	ds_read_b128 v[214:217], v220 offset:19456
	global_load_lds_dwordx4 v192, s[16:17]
	s_add_i32 m0, s43, 0x2000
	s_nop 0
	global_load_lds_dwordx4 v148, s[16:17]
	s_barrier
	s_waitcnt lgkmcnt(0)
	v_mfma_f32_16x16x32_bf16 v[124:127], v[196:199], v[154:157], v[124:127]
	v_mfma_f32_16x16x32_bf16 v[120:123], v[208:211], v[154:157], v[120:123]
	v_mfma_f32_16x16x32_bf16 v[116:119], v[196:199], v[166:169], v[116:119]
	v_mfma_f32_16x16x32_bf16 v[112:115], v[208:211], v[166:169], v[112:115]
	s_mov_b32 m0, s13
	v_mfma_f32_16x16x32_bf16 v[92:95], v[196:199], v[174:177], v[92:95]
	s_add_u32 s48, s18, 0x80
	s_addc_u32 s49, s19, 0
	v_mfma_f32_16x16x32_bf16 v[88:91], v[208:211], v[174:177], v[88:91]
	v_mfma_f32_16x16x32_bf16 v[84:87], v[196:199], v[182:185], v[84:87]
	v_mfma_f32_16x16x32_bf16 v[80:83], v[208:211], v[182:185], v[80:83]
	v_mfma_f32_16x16x32_bf16 v[124:127], v[204:207], v[162:165], v[124:127]
	v_mfma_f32_16x16x32_bf16 v[120:123], v[214:217], v[162:165], v[120:123]
	v_mfma_f32_16x16x32_bf16 v[116:119], v[204:207], v[170:173], v[116:119]
	v_mfma_f32_16x16x32_bf16 v[112:115], v[214:217], v[170:173], v[112:115]
	v_mfma_f32_16x16x32_bf16 v[92:95], v[204:207], v[178:181], v[92:95]
	v_mfma_f32_16x16x32_bf16 v[88:91], v[214:217], v[178:181], v[88:91]
	v_mfma_f32_16x16x32_bf16 v[84:87], v[204:207], v[186:189], v[84:87]
	v_mfma_f32_16x16x32_bf16 v[80:83], v[214:217], v[186:189], v[80:83]
	s_barrier
	ds_read_b128 v[154:157], v161 offset:16384
	ds_read_b128 v[162:165], v161 offset:17408
	ds_read_b128 v[166:169], v161 offset:18432
	ds_read_b128 v[170:173], v161 offset:19456
	ds_read_b128 v[174:177], v161 offset:20480
	ds_read_b128 v[178:181], v161 offset:21504
	ds_read_b128 v[182:185], v161 offset:22528
	ds_read_b128 v[186:189], v161 offset:23552
	global_load_lds_dwordx4 v144, s[18:19]
	s_mov_b32 m0, s28
	s_nop 0
	global_load_lds_dwordx4 v146, s[18:19]
	s_barrier
	s_waitcnt lgkmcnt(0)
	v_mfma_f32_16x16x32_bf16 v[60:63], v[64:67], v[154:157], v[60:63]
	v_mfma_f32_16x16x32_bf16 v[56:59], v[72:75], v[154:157], v[56:59]
	v_mfma_f32_16x16x32_bf16 v[52:55], v[64:67], v[166:169], v[52:55]
	v_mfma_f32_16x16x32_bf16 v[48:51], v[72:75], v[166:169], v[48:51]
	s_add_u32 s44, s16, 0x80000
	s_addc_u32 s45, s17, 0
	v_mfma_f32_16x16x32_bf16 v[28:31], v[64:67], v[174:177], v[28:31]
	s_add_i32 s43, s46, s27
	s_mov_b32 m0, s43
	v_mfma_f32_16x16x32_bf16 v[24:27], v[72:75], v[174:177], v[24:27]
	v_mfma_f32_16x16x32_bf16 v[20:23], v[64:67], v[182:185], v[20:23]
	v_mfma_f32_16x16x32_bf16 v[16:19], v[72:75], v[182:185], v[16:19]
	v_mfma_f32_16x16x32_bf16 v[60:63], v[68:71], v[162:165], v[60:63]
	v_mfma_f32_16x16x32_bf16 v[56:59], v[76:79], v[162:165], v[56:59]
	v_mfma_f32_16x16x32_bf16 v[52:55], v[68:71], v[170:173], v[52:55]
	v_mfma_f32_16x16x32_bf16 v[48:51], v[76:79], v[170:173], v[48:51]
	v_mfma_f32_16x16x32_bf16 v[28:31], v[68:71], v[178:181], v[28:31]
	v_mfma_f32_16x16x32_bf16 v[24:27], v[76:79], v[178:181], v[24:27]
	v_mfma_f32_16x16x32_bf16 v[20:23], v[68:71], v[186:189], v[20:23]
	v_mfma_f32_16x16x32_bf16 v[16:19], v[76:79], v[186:189], v[16:19]
	s_barrier
	global_load_lds_dwordx4 v192, s[44:45]
	s_add_i32 m0, s43, 0x2000
	s_nop 0
	global_load_lds_dwordx4 v148, s[44:45]
	s_waitcnt vmcnt(6)
	s_barrier
	v_mfma_f32_16x16x32_bf16 v[44:47], v[196:199], v[154:157], v[44:47]
	v_mfma_f32_16x16x32_bf16 v[40:43], v[208:211], v[154:157], v[40:43]
	v_mfma_f32_16x16x32_bf16 v[36:39], v[196:199], v[166:169], v[36:39]
	v_mfma_f32_16x16x32_bf16 v[32:35], v[208:211], v[166:169], v[32:35]
	s_add_i32 s43, 0, 0x18000
	v_mfma_f32_16x16x32_bf16 v[12:15], v[196:199], v[174:177], v[12:15]
	s_add_u32 s18, s18, 0x80000
	s_addc_u32 s19, s19, 0
	v_mfma_f32_16x16x32_bf16 v[8:11], v[208:211], v[174:177], v[8:11]
	s_mov_b32 m0, s29
	v_mfma_f32_16x16x32_bf16 v[4:7], v[196:199], v[182:185], v[4:7]
	v_mfma_f32_16x16x32_bf16 v[0:3], v[208:211], v[182:185], v[0:3]
	v_mfma_f32_16x16x32_bf16 v[44:47], v[204:207], v[162:165], v[44:47]
	v_mfma_f32_16x16x32_bf16 v[40:43], v[214:217], v[162:165], v[40:43]
	v_mfma_f32_16x16x32_bf16 v[36:39], v[204:207], v[170:173], v[36:39]
	v_mfma_f32_16x16x32_bf16 v[32:35], v[214:217], v[170:173], v[32:35]
	v_mfma_f32_16x16x32_bf16 v[12:15], v[204:207], v[178:181], v[12:15]
	v_mfma_f32_16x16x32_bf16 v[8:11], v[214:217], v[178:181], v[8:11]
	v_mfma_f32_16x16x32_bf16 v[4:7], v[204:207], v[186:189], v[4:7]
	v_mfma_f32_16x16x32_bf16 v[0:3], v[214:217], v[186:189], v[0:3]
	s_barrier
	ds_read_b128 v[64:67], v220 offset:32768
	ds_read_b128 v[68:71], v220 offset:33792
	ds_read_b128 v[72:75], v220 offset:34816
	ds_read_b128 v[76:79], v220 offset:35840
	ds_read_b128 v[154:157], v161 offset:32768
	ds_read_b128 v[162:165], v161 offset:33792
	ds_read_b128 v[166:169], v161 offset:34816
	ds_read_b128 v[170:173], v161 offset:35840
	ds_read_b128 v[174:177], v161 offset:36864
	ds_read_b128 v[178:181], v161 offset:37888
	ds_read_b128 v[182:185], v161 offset:38912
	ds_read_b128 v[186:189], v161 offset:39936
	global_load_lds_dwordx4 v144, s[18:19]
	s_mov_b32 m0, s30
	s_nop 0
	global_load_lds_dwordx4 v146, s[18:19]
	s_waitcnt lgkmcnt(8)
	s_barrier
	s_waitcnt lgkmcnt(0)
	v_mfma_f32_16x16x32_bf16 v[140:143], v[64:67], v[154:157], v[140:143]
	v_mfma_f32_16x16x32_bf16 v[136:139], v[72:75], v[154:157], v[136:139]
	v_mfma_f32_16x16x32_bf16 v[132:135], v[64:67], v[166:169], v[132:135]
	v_mfma_f32_16x16x32_bf16 v[128:131], v[72:75], v[166:169], v[128:131]
	s_add_i32 s18, 0, 0x1c000
	s_add_i32 s19, s43, s27
	v_mfma_f32_16x16x32_bf16 v[108:111], v[64:67], v[174:177], v[108:111]
	s_add_i32 m0, s19, 0xffffff80
	v_mfma_f32_16x16x32_bf16 v[104:107], v[72:75], v[174:177], v[104:107]
	v_mfma_f32_16x16x32_bf16 v[100:103], v[64:67], v[182:185], v[100:103]
	v_mfma_f32_16x16x32_bf16 v[96:99], v[72:75], v[182:185], v[96:99]
	v_mfma_f32_16x16x32_bf16 v[140:143], v[68:71], v[162:165], v[140:143]
	v_mfma_f32_16x16x32_bf16 v[136:139], v[76:79], v[162:165], v[136:139]
	v_mfma_f32_16x16x32_bf16 v[132:135], v[68:71], v[170:173], v[132:135]
	v_mfma_f32_16x16x32_bf16 v[128:131], v[76:79], v[170:173], v[128:131]
	v_mfma_f32_16x16x32_bf16 v[108:111], v[68:71], v[178:181], v[108:111]
	v_mfma_f32_16x16x32_bf16 v[104:107], v[76:79], v[178:181], v[104:107]
	v_mfma_f32_16x16x32_bf16 v[100:103], v[68:71], v[186:189], v[100:103]
	v_mfma_f32_16x16x32_bf16 v[96:99], v[76:79], v[186:189], v[96:99]
	s_barrier
	ds_read_b128 v[196:199], v220 offset:49152
	ds_read_b128 v[204:207], v220 offset:50176
	ds_read_b128 v[208:211], v220 offset:51200
	ds_read_b128 v[214:217], v220 offset:52224
	global_load_lds_dwordx4 v192, s[16:17] offset:128
	s_add_i32 m0, s19, 0x1f80
	s_nop 0
	global_load_lds_dwordx4 v148, s[16:17] offset:128
	s_barrier
	s_waitcnt lgkmcnt(0)
	v_mfma_f32_16x16x32_bf16 v[124:127], v[196:199], v[154:157], v[124:127]
	v_mfma_f32_16x16x32_bf16 v[120:123], v[208:211], v[154:157], v[120:123]
	v_mfma_f32_16x16x32_bf16 v[116:119], v[196:199], v[166:169], v[116:119]
	v_mfma_f32_16x16x32_bf16 v[112:115], v[208:211], v[166:169], v[112:115]
	s_mov_b32 m0, s34
	v_mfma_f32_16x16x32_bf16 v[92:95], v[196:199], v[174:177], v[92:95]
	v_mfma_f32_16x16x32_bf16 v[88:91], v[208:211], v[174:177], v[88:91]
	v_mfma_f32_16x16x32_bf16 v[84:87], v[196:199], v[182:185], v[84:87]
	v_mfma_f32_16x16x32_bf16 v[80:83], v[208:211], v[182:185], v[80:83]
	v_mfma_f32_16x16x32_bf16 v[124:127], v[204:207], v[162:165], v[124:127]
	v_mfma_f32_16x16x32_bf16 v[120:123], v[214:217], v[162:165], v[120:123]
	v_mfma_f32_16x16x32_bf16 v[116:119], v[204:207], v[170:173], v[116:119]
	v_mfma_f32_16x16x32_bf16 v[112:115], v[214:217], v[170:173], v[112:115]
	v_mfma_f32_16x16x32_bf16 v[92:95], v[204:207], v[178:181], v[92:95]
	v_mfma_f32_16x16x32_bf16 v[88:91], v[214:217], v[178:181], v[88:91]
	v_mfma_f32_16x16x32_bf16 v[84:87], v[204:207], v[186:189], v[84:87]
	v_mfma_f32_16x16x32_bf16 v[80:83], v[214:217], v[186:189], v[80:83]
	s_barrier
	ds_read_b128 v[154:157], v161 offset:49152
	ds_read_b128 v[162:165], v161 offset:50176
	ds_read_b128 v[166:169], v161 offset:51200
	ds_read_b128 v[170:173], v161 offset:52224
	ds_read_b128 v[174:177], v161 offset:53248
	ds_read_b128 v[178:181], v161 offset:54272
	ds_read_b128 v[182:185], v161 offset:55296
	ds_read_b128 v[186:189], v161 offset:56320
	global_load_lds_dwordx4 v144, s[48:49]
	s_mov_b32 m0, s35
	s_nop 0
	global_load_lds_dwordx4 v146, s[48:49]
	s_barrier
	s_waitcnt lgkmcnt(0)
	v_mfma_f32_16x16x32_bf16 v[60:63], v[64:67], v[154:157], v[60:63]
	v_mfma_f32_16x16x32_bf16 v[56:59], v[72:75], v[154:157], v[56:59]
	v_mfma_f32_16x16x32_bf16 v[52:55], v[64:67], v[166:169], v[52:55]
	v_mfma_f32_16x16x32_bf16 v[48:51], v[72:75], v[166:169], v[48:51]
	s_add_u32 s16, s16, 0x80080
	s_addc_u32 s17, s17, 0
	v_mfma_f32_16x16x32_bf16 v[28:31], v[64:67], v[174:177], v[28:31]
	s_add_i32 s18, s18, s27
	s_mov_b32 m0, s18
	v_mfma_f32_16x16x32_bf16 v[24:27], v[72:75], v[174:177], v[24:27]
	v_mfma_f32_16x16x32_bf16 v[20:23], v[64:67], v[182:185], v[20:23]
	v_mfma_f32_16x16x32_bf16 v[16:19], v[72:75], v[182:185], v[16:19]
	v_mfma_f32_16x16x32_bf16 v[60:63], v[68:71], v[162:165], v[60:63]
	v_mfma_f32_16x16x32_bf16 v[56:59], v[76:79], v[162:165], v[56:59]
	v_mfma_f32_16x16x32_bf16 v[52:55], v[68:71], v[170:173], v[52:55]
	v_mfma_f32_16x16x32_bf16 v[48:51], v[76:79], v[170:173], v[48:51]
	v_mfma_f32_16x16x32_bf16 v[28:31], v[68:71], v[178:181], v[28:31]
	v_mfma_f32_16x16x32_bf16 v[24:27], v[76:79], v[178:181], v[24:27]
	v_mfma_f32_16x16x32_bf16 v[20:23], v[68:71], v[186:189], v[20:23]
	v_mfma_f32_16x16x32_bf16 v[16:19], v[76:79], v[186:189], v[16:19]
	s_barrier
	global_load_lds_dwordx4 v192, s[16:17]
	s_add_i32 m0, s18, 0x2000
	s_nop 0
	global_load_lds_dwordx4 v148, s[16:17]
	s_waitcnt vmcnt(6)
	s_barrier
	v_mfma_f32_16x16x32_bf16 v[44:47], v[196:199], v[154:157], v[44:47]
	v_mfma_f32_16x16x32_bf16 v[40:43], v[208:211], v[154:157], v[40:43]
	v_mfma_f32_16x16x32_bf16 v[36:39], v[196:199], v[166:169], v[36:39]
	v_mfma_f32_16x16x32_bf16 v[32:35], v[208:211], v[166:169], v[32:35]
	s_add_i32 s42, s42, 2
	v_mfma_f32_16x16x32_bf16 v[12:15], v[196:199], v[174:177], v[12:15]
	s_add_u32 s14, s14, 0x100
	s_addc_u32 s15, s15, 0
	v_mfma_f32_16x16x32_bf16 v[8:11], v[208:211], v[174:177], v[8:11]
	s_add_u32 s40, s40, 0x100
	s_addc_u32 s41, s41, 0
	v_mfma_f32_16x16x32_bf16 v[4:7], v[196:199], v[182:185], v[4:7]
	s_add_u32 s16, s14, 0xfff80080
	s_addc_u32 s17, s15, -1
	v_mfma_f32_16x16x32_bf16 v[0:3], v[208:211], v[182:185], v[0:3]
	s_add_i32 s43, 0, 0x10000
	s_cmp_eq_u32 s42, 28
	v_mfma_f32_16x16x32_bf16 v[44:47], v[204:207], v[162:165], v[44:47]
	s_cselect_b32 s19, s7, s17
	s_cselect_b32 s18, s38, s16
	v_mfma_f32_16x16x32_bf16 v[40:43], v[214:217], v[162:165], v[40:43]
	s_cselect_b32 s17, s5, s41
	s_cselect_b32 s16, s39, s40
	v_mfma_f32_16x16x32_bf16 v[36:39], v[204:207], v[170:173], v[36:39]
	s_add_i32 m0, s13, 0xc000
	v_mfma_f32_16x16x32_bf16 v[32:35], v[214:217], v[170:173], v[32:35]
	v_mfma_f32_16x16x32_bf16 v[12:15], v[204:207], v[178:181], v[12:15]
	v_mfma_f32_16x16x32_bf16 v[8:11], v[214:217], v[178:181], v[8:11]
	v_mfma_f32_16x16x32_bf16 v[4:7], v[204:207], v[186:189], v[4:7]
	v_mfma_f32_16x16x32_bf16 v[0:3], v[214:217], v[186:189], v[0:3]
	s_cmp_gt_u32 s42, 29
	s_barrier
	s_cbranch_scc0 .LBB0_294
	s_ashr_i32 s5, s12, 4
	v_lshl_or_b32 v190, s37, 8, v160
	s_mul_hi_i32 s7, s5, 0xc000
	s_mul_i32 s5, s5, 0xc000
	s_add_u32 s14, s31, s5
	v_ashrrev_i32_e32 v191, 31, v190
	v_lshl_add_u32 v154, s12, 8, v158
	v_readlane_b32 s52, v254, 23
	s_addc_u32 s15, s33, s7
	v_lshlrev_b64 v[156:157], 2, v[190:191]
	v_readlane_b32 s53, v254, 24
	v_ashrrev_i32_e32 v155, 31, v154
	v_lshl_add_u64 v[68:69], s[14:15], 0, v[156:157]
	v_lshl_add_u64 v[156:157], s[52:53], 0, v[156:157]
	v_lshlrev_b64 v[162:163], 13, v[154:155]
	v_lshl_add_u64 v[174:175], v[156:157], 0, v[162:163]
	global_load_dwordx4 v[72:75], v[68:69], off offset:16
	global_load_dwordx4 v[76:79], v[68:69], off
	global_load_dwordx4 v[64:67], v[68:69], off offset:528
	s_nop 0
	global_load_dwordx4 v[68:71], v[68:69], off offset:512
	s_nop 0
	global_load_dwordx4 v[162:165], v[174:175], off offset:16
	global_load_dwordx4 v[166:169], v[174:175], off
	global_load_dwordx4 v[170:173], v[174:175], off offset:528
	s_nop 0
	global_load_dwordx4 v[174:177], v[174:175], off offset:512
	v_or_b32_e32 v204, 16, v154
	v_ashrrev_i32_e32 v205, 31, v204
	v_lshlrev_b64 v[178:179], 13, v[204:205]
	v_lshl_add_u64 v[196:197], v[156:157], 0, v[178:179]
	global_load_dwordx4 v[178:181], v[196:197], off offset:16
	global_load_dwordx4 v[182:185], v[196:197], off
	global_load_dwordx4 v[186:189], v[196:197], off offset:528
	s_nop 0
	global_load_dwordx4 v[196:199], v[196:197], off offset:512
	v_lshlrev_b64 v[206:207], 12, v[154:155]
	s_and_b64 vcc, exec, s[0:1]
	s_mov_b32 s37, s4
	s_mov_b32 s12, s6
	s_mov_b64 s[16:17], s[10:11]
	s_mov_b64 s[14:15], s[8:9]
	s_mov_b32 s11, 0xc000
	v_readlane_b32 s54, v254, 25
	v_readlane_b32 s55, v254, 26
	v_readlane_b32 s56, v254, 27
	v_readlane_b32 s57, v254, 28
	v_readlane_b32 s58, v254, 29
	v_readlane_b32 s59, v254, 30
	v_readlane_b32 s60, v254, 31
	v_readlane_b32 s61, v254, 32
	v_readlane_b32 s62, v254, 33
	v_readlane_b32 s63, v254, 34
	v_readlane_b32 s64, v254, 35
	v_readlane_b32 s65, v254, 36
	v_readlane_b32 s66, v254, 37
	v_readlane_b32 s67, v254, 38
	s_waitcnt vmcnt(0)
	v_pk_fma_f32 v[136:137], v[136:137], v[72:73], v[162:163]
	v_pk_fma_f32 v[142:143], v[142:143], v[78:79], v[168:169]
	v_pk_fma_f32 v[140:141], v[140:141], v[76:77], v[166:167]
	v_pk_fma_f32 v[164:165], v[138:139], v[74:75], v[164:165]
	v_cvt_pk_bf16_f32 v138, v140, v141
	v_cvt_pk_bf16_f32 v139, v142, v143
	v_cvt_pk_bf16_f32 v140, v136, v137
	v_lshl_add_u64 v[142:143], s[2:3], 0, v[206:207]
	v_lshlrev_b64 v[136:137], 1, v[190:191]
	v_lshl_add_u64 v[142:143], v[142:143], 0, v[136:137]
	v_pk_fma_f32 v[124:125], v[124:125], v[68:69], v[174:175]
	v_cvt_pk_bf16_f32 v141, v164, v165
	global_store_dwordx4 v[142:143], v[138:141], off
	v_pk_fma_f32 v[126:127], v[126:127], v[70:71], v[176:177]
	v_pk_fma_f32 v[128:129], v[128:129], v[72:73], v[178:179]
	v_pk_fma_f32 v[138:139], v[122:123], v[66:67], v[172:173]
	v_pk_fma_f32 v[122:123], v[120:121], v[64:65], v[170:171]
	v_cvt_pk_bf16_f32 v120, v124, v125
	v_cvt_pk_bf16_f32 v121, v126, v127
	v_lshlrev_b64 v[124:125], 12, v[204:205]
	v_cvt_pk_bf16_f32 v122, v122, v123
	v_cvt_pk_bf16_f32 v123, v138, v139
	global_store_dwordx4 v[142:143], v[120:123], off offset:256
	v_lshl_add_u64 v[124:125], s[2:3], 0, v[124:125]
	v_lshl_add_u64 v[124:125], v[124:125], 0, v[136:137]
	v_pk_fma_f32 v[120:121], v[132:133], v[76:77], v[182:183]
	v_pk_fma_f32 v[122:123], v[134:135], v[78:79], v[184:185]
	v_cvt_pk_bf16_f32 v120, v120, v121
	v_or_b32_e32 v142, 32, v154
	v_cvt_pk_bf16_f32 v121, v122, v123
	v_pk_fma_f32 v[126:127], v[130:131], v[74:75], v[180:181]
	v_cvt_pk_bf16_f32 v122, v128, v129
	v_pk_fma_f32 v[118:119], v[118:119], v[70:71], v[198:199]
	v_cvt_pk_bf16_f32 v123, v126, v127
	global_store_dwordx4 v[124:125], v[120:123], off
	v_pk_fma_f32 v[116:117], v[116:117], v[68:69], v[196:197]
	v_ashrrev_i32_e32 v143, 31, v142
	v_pk_fma_f32 v[120:121], v[114:115], v[66:67], v[188:189]
	v_pk_fma_f32 v[114:115], v[112:113], v[64:65], v[186:187]
	v_cvt_pk_bf16_f32 v112, v116, v117
	v_cvt_pk_bf16_f32 v113, v118, v119
	v_or_b32_e32 v166, 48, v154
	v_cvt_pk_bf16_f32 v114, v114, v115
	v_cvt_pk_bf16_f32 v115, v120, v121
	global_store_dwordx4 v[124:125], v[112:115], off offset:256
	v_ashrrev_i32_e32 v167, 31, v166
	v_lshlrev_b64 v[128:129], 13, v[166:167]
	v_lshlrev_b64 v[112:113], 13, v[142:143]
	v_lshl_add_u64 v[124:125], v[156:157], 0, v[112:113]
	global_load_dwordx4 v[112:115], v[124:125], off offset:16
	global_load_dwordx4 v[116:119], v[124:125], off
	global_load_dwordx4 v[120:123], v[124:125], off offset:528
	s_nop 0
	global_load_dwordx4 v[124:127], v[124:125], off offset:512
	v_lshl_add_u64 v[162:163], v[156:157], 0, v[128:129]
	global_load_dwordx4 v[128:131], v[162:163], off offset:16
	global_load_dwordx4 v[132:135], v[162:163], off
	global_load_dwordx4 v[138:141], v[162:163], off offset:528
	s_nop 0
	global_load_dwordx4 v[162:165], v[162:163], off offset:512
	v_lshlrev_b64 v[142:143], 12, v[142:143]
	s_waitcnt vmcnt(0)
	v_pk_fma_f32 v[114:115], v[106:107], v[74:75], v[114:115]
	v_pk_fma_f32 v[108:109], v[108:109], v[76:77], v[116:117]
	v_pk_fma_f32 v[106:107], v[104:105], v[72:73], v[112:113]
	v_cvt_pk_bf16_f32 v104, v108, v109
	v_lshl_add_u64 v[108:109], s[2:3], 0, v[142:143]
	v_pk_fma_f32 v[110:111], v[110:111], v[78:79], v[118:119]
	v_lshl_add_u64 v[108:109], v[108:109], 0, v[136:137]
	v_cvt_pk_bf16_f32 v105, v110, v111
	v_pk_fma_f32 v[92:93], v[92:93], v[68:69], v[124:125]
	v_cvt_pk_bf16_f32 v106, v106, v107
	v_cvt_pk_bf16_f32 v107, v114, v115
	global_store_dwordx4 v[108:109], v[104:107], off
	v_pk_fma_f32 v[94:95], v[94:95], v[70:71], v[126:127]
	v_add_u32_e32 v112, 0x80, v154
	v_pk_fma_f32 v[104:105], v[90:91], v[66:67], v[122:123]
	v_pk_fma_f32 v[90:91], v[88:89], v[64:65], v[120:121]
	v_cvt_pk_bf16_f32 v88, v92, v93
	v_cvt_pk_bf16_f32 v89, v94, v95
	v_lshlrev_b64 v[92:93], 12, v[166:167]
	v_cvt_pk_bf16_f32 v90, v90, v91
	v_cvt_pk_bf16_f32 v91, v104, v105
	global_store_dwordx4 v[108:109], v[88:91], off offset:256
	v_lshl_add_u64 v[92:93], s[2:3], 0, v[92:93]
	v_lshl_add_u64 v[92:93], v[92:93], 0, v[136:137]
	v_pk_fma_f32 v[88:89], v[100:101], v[76:77], v[132:133]
	v_pk_fma_f32 v[90:91], v[102:103], v[78:79], v[134:135]
	v_cvt_pk_bf16_f32 v88, v88, v89
	v_pk_fma_f32 v[94:95], v[98:99], v[74:75], v[130:131]
	v_cvt_pk_bf16_f32 v89, v90, v91
	v_pk_fma_f32 v[96:97], v[96:97], v[72:73], v[128:129]
	v_pk_fma_f32 v[86:87], v[86:87], v[70:71], v[164:165]
	v_cvt_pk_bf16_f32 v90, v96, v97
	v_cvt_pk_bf16_f32 v91, v94, v95
	global_store_dwordx4 v[92:93], v[88:91], off
	v_pk_fma_f32 v[84:85], v[84:85], v[68:69], v[162:163]
	v_ashrrev_i32_e32 v113, 31, v112
	v_pk_fma_f32 v[88:89], v[82:83], v[66:67], v[140:141]
	v_pk_fma_f32 v[82:83], v[80:81], v[64:65], v[138:139]
	v_cvt_pk_bf16_f32 v80, v84, v85
	v_cvt_pk_bf16_f32 v81, v86, v87
	v_add_u32_e32 v114, 0x90, v154
	v_cvt_pk_bf16_f32 v82, v82, v83
	v_cvt_pk_bf16_f32 v83, v88, v89
	global_store_dwordx4 v[92:93], v[80:83], off offset:256
	v_ashrrev_i32_e32 v115, 31, v114
	v_lshlrev_b64 v[96:97], 13, v[114:115]
	v_lshlrev_b64 v[80:81], 13, v[112:113]
	v_lshl_add_u64 v[92:93], v[156:157], 0, v[80:81]
	global_load_dwordx4 v[80:83], v[92:93], off offset:16
	global_load_dwordx4 v[84:87], v[92:93], off
	global_load_dwordx4 v[88:91], v[92:93], off offset:528
	s_nop 0
	global_load_dwordx4 v[92:95], v[92:93], off offset:512
	v_lshl_add_u64 v[108:109], v[156:157], 0, v[96:97]
	global_load_dwordx4 v[96:99], v[108:109], off offset:16
	global_load_dwordx4 v[100:103], v[108:109], off
	global_load_dwordx4 v[104:107], v[108:109], off offset:528
	s_nop 0
	global_load_dwordx4 v[108:111], v[108:109], off offset:512
	v_lshlrev_b64 v[112:113], 12, v[112:113]
	s_waitcnt vmcnt(0)
	v_pk_fma_f32 v[82:83], v[58:59], v[74:75], v[82:83]
	v_pk_fma_f32 v[60:61], v[60:61], v[76:77], v[84:85]
	v_pk_fma_f32 v[58:59], v[56:57], v[72:73], v[80:81]
	v_cvt_pk_bf16_f32 v56, v60, v61
	v_lshl_add_u64 v[60:61], s[2:3], 0, v[112:113]
	v_pk_fma_f32 v[62:63], v[62:63], v[78:79], v[86:87]
	v_lshl_add_u64 v[60:61], v[60:61], 0, v[136:137]
	v_cvt_pk_bf16_f32 v57, v62, v63
	v_pk_fma_f32 v[44:45], v[44:45], v[68:69], v[92:93]
	v_cvt_pk_bf16_f32 v58, v58, v59
	v_cvt_pk_bf16_f32 v59, v82, v83
	global_store_dwordx4 v[60:61], v[56:59], off
	v_pk_fma_f32 v[46:47], v[46:47], v[70:71], v[94:95]
	v_add_u32_e32 v80, 0xa0, v154
	v_pk_fma_f32 v[56:57], v[42:43], v[66:67], v[90:91]
	v_pk_fma_f32 v[42:43], v[40:41], v[64:65], v[88:89]
	v_cvt_pk_bf16_f32 v40, v44, v45
	v_cvt_pk_bf16_f32 v41, v46, v47
	v_lshlrev_b64 v[44:45], 12, v[114:115]
	v_cvt_pk_bf16_f32 v42, v42, v43
	v_cvt_pk_bf16_f32 v43, v56, v57
	global_store_dwordx4 v[60:61], v[40:43], off offset:256
	v_lshl_add_u64 v[44:45], s[2:3], 0, v[44:45]
	v_lshl_add_u64 v[44:45], v[44:45], 0, v[136:137]
	v_pk_fma_f32 v[40:41], v[52:53], v[76:77], v[100:101]
	v_pk_fma_f32 v[42:43], v[54:55], v[78:79], v[102:103]
	v_cvt_pk_bf16_f32 v40, v40, v41
	v_pk_fma_f32 v[46:47], v[50:51], v[74:75], v[98:99]
	v_cvt_pk_bf16_f32 v41, v42, v43
	v_pk_fma_f32 v[48:49], v[48:49], v[72:73], v[96:97]
	v_pk_fma_f32 v[38:39], v[38:39], v[70:71], v[110:111]
	v_cvt_pk_bf16_f32 v42, v48, v49
	v_cvt_pk_bf16_f32 v43, v46, v47
	global_store_dwordx4 v[44:45], v[40:43], off
	v_pk_fma_f32 v[36:37], v[36:37], v[68:69], v[108:109]
	v_ashrrev_i32_e32 v81, 31, v80
	v_pk_fma_f32 v[40:41], v[34:35], v[66:67], v[106:107]
	v_pk_fma_f32 v[34:35], v[32:33], v[64:65], v[104:105]
	v_cvt_pk_bf16_f32 v32, v36, v37
	v_cvt_pk_bf16_f32 v33, v38, v39
	v_add_u32_e32 v82, 0xb0, v154
	v_cvt_pk_bf16_f32 v34, v34, v35
	v_cvt_pk_bf16_f32 v35, v40, v41
	global_store_dwordx4 v[44:45], v[32:35], off offset:256
	v_ashrrev_i32_e32 v83, 31, v82
	v_lshlrev_b64 v[48:49], 13, v[82:83]
	v_lshlrev_b64 v[32:33], 13, v[80:81]
	v_lshl_add_u64 v[44:45], v[156:157], 0, v[32:33]
	global_load_dwordx4 v[32:35], v[44:45], off offset:16
	global_load_dwordx4 v[36:39], v[44:45], off
	global_load_dwordx4 v[40:43], v[44:45], off offset:528
	s_nop 0
	global_load_dwordx4 v[44:47], v[44:45], off offset:512
	v_lshl_add_u64 v[60:61], v[156:157], 0, v[48:49]
	global_load_dwordx4 v[48:51], v[60:61], off offset:16
	global_load_dwordx4 v[52:55], v[60:61], off
	global_load_dwordx4 v[56:59], v[60:61], off offset:528
	s_nop 0
	global_load_dwordx4 v[60:63], v[60:61], off offset:512
	v_lshlrev_b64 v[80:81], 12, v[80:81]
	s_waitcnt vmcnt(0)
	v_pk_fma_f32 v[34:35], v[26:27], v[74:75], v[34:35]
	v_pk_fma_f32 v[28:29], v[28:29], v[76:77], v[36:37]
	v_pk_fma_f32 v[26:27], v[24:25], v[72:73], v[32:33]
	v_cvt_pk_bf16_f32 v24, v28, v29
	v_lshl_add_u64 v[28:29], s[2:3], 0, v[80:81]
	v_pk_fma_f32 v[30:31], v[30:31], v[78:79], v[38:39]
	v_lshl_add_u64 v[28:29], v[28:29], 0, v[136:137]
	v_cvt_pk_bf16_f32 v25, v30, v31
	v_pk_fma_f32 v[12:13], v[12:13], v[68:69], v[44:45]
	v_cvt_pk_bf16_f32 v26, v26, v27
	v_cvt_pk_bf16_f32 v27, v34, v35
	global_store_dwordx4 v[28:29], v[24:27], off
	v_pk_fma_f32 v[14:15], v[14:15], v[70:71], v[46:47]
	v_pk_fma_f32 v[16:17], v[16:17], v[72:73], v[48:49]
	v_pk_fma_f32 v[24:25], v[10:11], v[66:67], v[42:43]
	v_pk_fma_f32 v[10:11], v[8:9], v[64:65], v[40:41]
	v_cvt_pk_bf16_f32 v8, v12, v13
	v_cvt_pk_bf16_f32 v9, v14, v15
	v_lshlrev_b64 v[12:13], 12, v[82:83]
	v_cvt_pk_bf16_f32 v10, v10, v11
	v_cvt_pk_bf16_f32 v11, v24, v25
	global_store_dwordx4 v[28:29], v[8:11], off offset:256
	v_lshl_add_u64 v[12:13], s[2:3], 0, v[12:13]
	v_lshl_add_u64 v[12:13], v[12:13], 0, v[136:137]
	v_pk_fma_f32 v[8:9], v[20:21], v[76:77], v[52:53]
	v_pk_fma_f32 v[10:11], v[22:23], v[78:79], v[54:55]
	v_cvt_pk_bf16_f32 v8, v8, v9
	v_pk_fma_f32 v[14:15], v[18:19], v[74:75], v[50:51]
	v_cvt_pk_bf16_f32 v9, v10, v11
	v_cvt_pk_bf16_f32 v10, v16, v17
	v_pk_fma_f32 v[6:7], v[6:7], v[70:71], v[62:63]
	v_cvt_pk_bf16_f32 v11, v14, v15
	global_store_dwordx4 v[12:13], v[8:11], off
	v_pk_fma_f32 v[4:5], v[4:5], v[68:69], v[60:61]
	s_nop 0
	v_pk_fma_f32 v[8:9], v[2:3], v[66:67], v[58:59]
	v_pk_fma_f32 v[2:3], v[0:1], v[64:65], v[56:57]
	v_cvt_pk_bf16_f32 v0, v4, v5
	v_cvt_pk_bf16_f32 v1, v6, v7
	s_nop 0
	v_cvt_pk_bf16_f32 v2, v2, v3
	v_cvt_pk_bf16_f32 v3, v8, v9
	global_store_dwordx4 v[12:13], v[0:3], off offset:256
	s_cbranch_vccz .LBB0_287
	s_waitcnt vmcnt(0)
	s_cmpk_gt_u32 s25, 0xff
	s_cbranch_scc1 .LBB0_298
	s_barrier

.LBB0_414:
	s_ashr_i32 s9, s8, 31
	v_cmp_lt_i64_e32 vcc, s[10:11], v[202:203]
	s_lshl_b64 s[10:11], s[8:9], 20
	s_add_u32 s10, s24, s10
	s_addc_u32 s11, s25, s11
	s_and_b64 s[12:13], vcc, exec
	s_cselect_b32 s9, s11, s17
	s_cselect_b32 s38, s10, s16
	s_ashr_i32 s7, s6, 31
	s_lshl_b64 s[12:13], s[6:7], 20
	s_add_u32 s12, s26, s12
	s_addc_u32 s13, s27, s13
	s_and_b64 s[20:21], vcc, exec
	s_cselect_b32 s7, s13, s19
	s_cselect_b32 s39, s12, s18
	s_add_u32 s16, s16, 0x80080
	s_addc_u32 s17, s17, 0
	s_add_u32 s40, s18, 0x100
	s_addc_u32 s41, s19, 0
	s_mov_b32 s42, -2
	s_mov_b64 s[48:49], 0x80
	v_add_u32_e32 v196, 0x10000, v143
	s_add_u32 s18, s16, 0xfff80080
	s_addc_u32 s19, s17, -1
	s_add_i32 s43, 0, 0x10000
	ds_read_b128 v[146:149], v196 offset:0
	ds_read_b128 v[150:153], v196 offset:1024
	ds_read_b128 v[154:157], v196 offset:2048
	ds_read_b128 v[158:161], v196 offset:3072
	s_cmp_eq_u32 s42, 28
	s_cselect_b32 s21, s9, s19
	s_cselect_b32 s20, s38, s18
	s_cselect_b32 s19, s7, s41
	s_cselect_b32 s18, s39, s40
	s_add_i32 m0, s30, 0xc000
	ds_read_b128 v[162:165], v145
	ds_read_b128 v[166:169], v145 offset:1024
	ds_read_b128 v[170:173], v145 offset:2048
	ds_read_b128 v[174:177], v145 offset:3072
	ds_read_b128 v[178:181], v145 offset:4096
	ds_read_b128 v[182:185], v145 offset:5120
	ds_read_b128 v[186:189], v145 offset:6144
	ds_read_b128 v[204:207], v145 offset:7168
	global_load_lds_dwordx4 v136, s[16:17]
	s_add_i32 m0, s30, 0xe000
	s_nop 0
	global_load_lds_dwordx4 v138, s[16:17]
	s_waitcnt lgkmcnt(8)
	s_barrier
	s_waitcnt lgkmcnt(0)
	v_mfma_f32_16x16x32_bf16 v[124:127], v[146:149], v[162:165], 0
	v_mfma_f32_16x16x32_bf16 v[120:123], v[154:157], v[162:165], 0
	v_mfma_f32_16x16x32_bf16 v[116:119], v[146:149], v[170:173], 0
	v_mfma_f32_16x16x32_bf16 v[108:111], v[154:157], v[170:173], 0
	s_add_i32 s46, 0, 0x14000
	s_add_i32 s43, s43, s28
	v_mfma_f32_16x16x32_bf16 v[100:103], v[146:149], v[178:181], 0
	s_mov_b32 m0, s43
	v_mfma_f32_16x16x32_bf16 v[92:95], v[154:157], v[178:181], 0
	v_mfma_f32_16x16x32_bf16 v[84:87], v[146:149], v[186:189], 0
	v_mfma_f32_16x16x32_bf16 v[76:79], v[154:157], v[186:189], 0
	v_mfma_f32_16x16x32_bf16 v[124:127], v[150:153], v[166:169], v[124:127]
	v_mfma_f32_16x16x32_bf16 v[120:123], v[158:161], v[166:169], v[120:123]
	v_mfma_f32_16x16x32_bf16 v[116:119], v[150:153], v[174:177], v[116:119]
	v_mfma_f32_16x16x32_bf16 v[108:111], v[158:161], v[174:177], v[108:111]
	v_mfma_f32_16x16x32_bf16 v[100:103], v[150:153], v[182:185], v[100:103]
	v_mfma_f32_16x16x32_bf16 v[92:95], v[158:161], v[182:185], v[92:95]
	v_mfma_f32_16x16x32_bf16 v[84:87], v[150:153], v[204:207], v[84:87]
	v_mfma_f32_16x16x32_bf16 v[76:79], v[158:161], v[204:207], v[76:79]
	s_barrier
	ds_read_b128 v[208:211], v196 offset:16384
	ds_read_b128 v[214:217], v196 offset:17408
	ds_read_b128 v[218:221], v196 offset:18432
	ds_read_b128 v[222:225], v196 offset:19456
	global_load_lds_dwordx4 v192, s[18:19]
	s_add_i32 m0, s43, 0x2000
	s_nop 0
	global_load_lds_dwordx4 v128, s[18:19]
	s_barrier
	s_waitcnt lgkmcnt(0)
	v_mfma_f32_16x16x32_bf16 v[112:115], v[208:211], v[162:165], 0
	v_mfma_f32_16x16x32_bf16 v[104:107], v[218:221], v[162:165], 0
	v_mfma_f32_16x16x32_bf16 v[96:99], v[208:211], v[170:173], 0
	v_mfma_f32_16x16x32_bf16 v[88:91], v[218:221], v[170:173], 0
	s_mov_b32 m0, s30
	v_mfma_f32_16x16x32_bf16 v[80:83], v[208:211], v[178:181], 0
	s_add_u32 s48, s20, 0x80
	s_addc_u32 s49, s21, 0
	v_mfma_f32_16x16x32_bf16 v[72:75], v[218:221], v[178:181], 0
	v_mfma_f32_16x16x32_bf16 v[68:71], v[208:211], v[186:189], 0
	v_mfma_f32_16x16x32_bf16 v[64:67], v[218:221], v[186:189], 0
	v_mfma_f32_16x16x32_bf16 v[112:115], v[214:217], v[166:169], v[112:115]
	v_mfma_f32_16x16x32_bf16 v[104:107], v[222:225], v[166:169], v[104:107]
	v_mfma_f32_16x16x32_bf16 v[96:99], v[214:217], v[174:177], v[96:99]
	v_mfma_f32_16x16x32_bf16 v[88:91], v[222:225], v[174:177], v[88:91]
	v_mfma_f32_16x16x32_bf16 v[80:83], v[214:217], v[182:185], v[80:83]
	v_mfma_f32_16x16x32_bf16 v[72:75], v[222:225], v[182:185], v[72:75]
	v_mfma_f32_16x16x32_bf16 v[68:71], v[214:217], v[204:207], v[68:71]
	v_mfma_f32_16x16x32_bf16 v[64:67], v[222:225], v[204:207], v[64:67]
	s_barrier
	ds_read_b128 v[162:165], v145 offset:16384
	ds_read_b128 v[166:169], v145 offset:17408
	ds_read_b128 v[170:173], v145 offset:18432
	ds_read_b128 v[174:177], v145 offset:19456
	ds_read_b128 v[178:181], v145 offset:20480
	ds_read_b128 v[182:185], v145 offset:21504
	ds_read_b128 v[186:189], v145 offset:22528
	ds_read_b128 v[204:207], v145 offset:23552
	global_load_lds_dwordx4 v132, s[20:21]
	s_mov_b32 m0, s31
	s_nop 0
	global_load_lds_dwordx4 v130, s[20:21]
	s_barrier
	s_waitcnt lgkmcnt(0)
	v_mfma_f32_16x16x32_bf16 v[60:63], v[146:149], v[162:165], 0
	v_mfma_f32_16x16x32_bf16 v[56:59], v[154:157], v[162:165], 0
	v_mfma_f32_16x16x32_bf16 v[52:55], v[146:149], v[170:173], 0
	v_mfma_f32_16x16x32_bf16 v[44:47], v[154:157], v[170:173], 0
	s_add_u32 s44, s18, 0x80000
	s_addc_u32 s45, s19, 0
	v_mfma_f32_16x16x32_bf16 v[36:39], v[146:149], v[178:181], 0
	s_add_i32 s43, s46, s28
	s_mov_b32 m0, s43
	v_mfma_f32_16x16x32_bf16 v[28:31], v[154:157], v[178:181], 0
	v_mfma_f32_16x16x32_bf16 v[20:23], v[146:149], v[186:189], 0
	v_mfma_f32_16x16x32_bf16 v[12:15], v[154:157], v[186:189], 0
	v_mfma_f32_16x16x32_bf16 v[60:63], v[150:153], v[166:169], v[60:63]
	v_mfma_f32_16x16x32_bf16 v[56:59], v[158:161], v[166:169], v[56:59]
	v_mfma_f32_16x16x32_bf16 v[52:55], v[150:153], v[174:177], v[52:55]
	v_mfma_f32_16x16x32_bf16 v[44:47], v[158:161], v[174:177], v[44:47]
	v_mfma_f32_16x16x32_bf16 v[36:39], v[150:153], v[182:185], v[36:39]
	v_mfma_f32_16x16x32_bf16 v[28:31], v[158:161], v[182:185], v[28:31]
	v_mfma_f32_16x16x32_bf16 v[20:23], v[150:153], v[204:207], v[20:23]
	v_mfma_f32_16x16x32_bf16 v[12:15], v[158:161], v[204:207], v[12:15]
	s_barrier
	global_load_lds_dwordx4 v192, s[44:45]
	s_add_i32 m0, s43, 0x2000
	s_nop 0
	global_load_lds_dwordx4 v128, s[44:45]
	s_waitcnt vmcnt(6)
	s_barrier
	v_mfma_f32_16x16x32_bf16 v[48:51], v[208:211], v[162:165], 0
	v_mfma_f32_16x16x32_bf16 v[40:43], v[218:221], v[162:165], 0
	v_mfma_f32_16x16x32_bf16 v[32:35], v[208:211], v[170:173], 0
	v_mfma_f32_16x16x32_bf16 v[24:27], v[218:221], v[170:173], 0
	s_add_i32 s43, 0, 0x18000
	v_mfma_f32_16x16x32_bf16 v[16:19], v[208:211], v[178:181], 0
	s_add_u32 s20, s20, 0x80000
	s_addc_u32 s21, s21, 0
	v_mfma_f32_16x16x32_bf16 v[8:11], v[218:221], v[178:181], 0
	s_mov_b32 m0, s33
	v_mfma_f32_16x16x32_bf16 v[4:7], v[208:211], v[186:189], 0
	v_mfma_f32_16x16x32_bf16 v[0:3], v[218:221], v[186:189], 0
	v_mfma_f32_16x16x32_bf16 v[48:51], v[214:217], v[166:169], v[48:51]
	v_mfma_f32_16x16x32_bf16 v[40:43], v[222:225], v[166:169], v[40:43]
	v_mfma_f32_16x16x32_bf16 v[32:35], v[214:217], v[174:177], v[32:35]
	v_mfma_f32_16x16x32_bf16 v[24:27], v[222:225], v[174:177], v[24:27]
	v_mfma_f32_16x16x32_bf16 v[16:19], v[214:217], v[182:185], v[16:19]
	v_mfma_f32_16x16x32_bf16 v[8:11], v[222:225], v[182:185], v[8:11]
	v_mfma_f32_16x16x32_bf16 v[4:7], v[214:217], v[204:207], v[4:7]
	v_mfma_f32_16x16x32_bf16 v[0:3], v[222:225], v[204:207], v[0:3]
	s_barrier
	ds_read_b128 v[146:149], v196 offset:32768
	ds_read_b128 v[150:153], v196 offset:33792
	ds_read_b128 v[154:157], v196 offset:34816
	ds_read_b128 v[158:161], v196 offset:35840
	ds_read_b128 v[162:165], v145 offset:32768
	ds_read_b128 v[166:169], v145 offset:33792
	ds_read_b128 v[170:173], v145 offset:34816
	ds_read_b128 v[174:177], v145 offset:35840
	ds_read_b128 v[178:181], v145 offset:36864
	ds_read_b128 v[182:185], v145 offset:37888
	ds_read_b128 v[186:189], v145 offset:38912
	ds_read_b128 v[204:207], v145 offset:39936
	global_load_lds_dwordx4 v132, s[20:21]
	s_mov_b32 m0, s34
	s_nop 0
	global_load_lds_dwordx4 v130, s[20:21]
	s_waitcnt lgkmcnt(8)
	s_barrier
	s_waitcnt lgkmcnt(0)
	v_mfma_f32_16x16x32_bf16 v[124:127], v[146:149], v[162:165], v[124:127]
	v_mfma_f32_16x16x32_bf16 v[120:123], v[154:157], v[162:165], v[120:123]
	v_mfma_f32_16x16x32_bf16 v[116:119], v[146:149], v[170:173], v[116:119]
	v_mfma_f32_16x16x32_bf16 v[108:111], v[154:157], v[170:173], v[108:111]
	s_add_i32 s20, 0, 0x1c000
	s_add_i32 s21, s43, s28
	v_mfma_f32_16x16x32_bf16 v[100:103], v[146:149], v[178:181], v[100:103]
	s_add_i32 m0, s21, 0xffffff80
	v_mfma_f32_16x16x32_bf16 v[92:95], v[154:157], v[178:181], v[92:95]
	v_mfma_f32_16x16x32_bf16 v[84:87], v[146:149], v[186:189], v[84:87]
	v_mfma_f32_16x16x32_bf16 v[76:79], v[154:157], v[186:189], v[76:79]
	v_mfma_f32_16x16x32_bf16 v[124:127], v[150:153], v[166:169], v[124:127]
	v_mfma_f32_16x16x32_bf16 v[120:123], v[158:161], v[166:169], v[120:123]
	v_mfma_f32_16x16x32_bf16 v[116:119], v[150:153], v[174:177], v[116:119]
	v_mfma_f32_16x16x32_bf16 v[108:111], v[158:161], v[174:177], v[108:111]
	v_mfma_f32_16x16x32_bf16 v[100:103], v[150:153], v[182:185], v[100:103]
	v_mfma_f32_16x16x32_bf16 v[92:95], v[158:161], v[182:185], v[92:95]
	v_mfma_f32_16x16x32_bf16 v[84:87], v[150:153], v[204:207], v[84:87]
	v_mfma_f32_16x16x32_bf16 v[76:79], v[158:161], v[204:207], v[76:79]
	s_barrier
	ds_read_b128 v[208:211], v196 offset:49152
	ds_read_b128 v[214:217], v196 offset:50176
	ds_read_b128 v[218:221], v196 offset:51200
	ds_read_b128 v[222:225], v196 offset:52224
	global_load_lds_dwordx4 v192, s[18:19] offset:128
	s_add_i32 m0, s21, 0x1f80
	s_nop 0
	global_load_lds_dwordx4 v128, s[18:19] offset:128
	s_barrier
	s_waitcnt lgkmcnt(0)
	v_mfma_f32_16x16x32_bf16 v[112:115], v[208:211], v[162:165], v[112:115]
	v_mfma_f32_16x16x32_bf16 v[104:107], v[218:221], v[162:165], v[104:107]
	v_mfma_f32_16x16x32_bf16 v[96:99], v[208:211], v[170:173], v[96:99]
	v_mfma_f32_16x16x32_bf16 v[88:91], v[218:221], v[170:173], v[88:91]
	s_mov_b32 m0, s35
	v_mfma_f32_16x16x32_bf16 v[80:83], v[208:211], v[178:181], v[80:83]
	v_mfma_f32_16x16x32_bf16 v[72:75], v[218:221], v[178:181], v[72:75]
	v_mfma_f32_16x16x32_bf16 v[68:71], v[208:211], v[186:189], v[68:71]
	v_mfma_f32_16x16x32_bf16 v[64:67], v[218:221], v[186:189], v[64:67]
	v_mfma_f32_16x16x32_bf16 v[112:115], v[214:217], v[166:169], v[112:115]
	v_mfma_f32_16x16x32_bf16 v[104:107], v[222:225], v[166:169], v[104:107]
	v_mfma_f32_16x16x32_bf16 v[96:99], v[214:217], v[174:177], v[96:99]
	v_mfma_f32_16x16x32_bf16 v[88:91], v[222:225], v[174:177], v[88:91]
	v_mfma_f32_16x16x32_bf16 v[80:83], v[214:217], v[182:185], v[80:83]
	v_mfma_f32_16x16x32_bf16 v[72:75], v[222:225], v[182:185], v[72:75]
	v_mfma_f32_16x16x32_bf16 v[68:71], v[214:217], v[204:207], v[68:71]
	v_mfma_f32_16x16x32_bf16 v[64:67], v[222:225], v[204:207], v[64:67]
	s_barrier
	ds_read_b128 v[162:165], v145 offset:49152
	ds_read_b128 v[166:169], v145 offset:50176
	ds_read_b128 v[170:173], v145 offset:51200
	ds_read_b128 v[174:177], v145 offset:52224
	ds_read_b128 v[178:181], v145 offset:53248
	ds_read_b128 v[182:185], v145 offset:54272
	ds_read_b128 v[186:189], v145 offset:55296
	ds_read_b128 v[204:207], v145 offset:56320
	global_load_lds_dwordx4 v132, s[48:49]
	s_mov_b32 m0, s36
	s_nop 0
	global_load_lds_dwordx4 v130, s[48:49]
	s_barrier
	s_waitcnt lgkmcnt(0)
	v_mfma_f32_16x16x32_bf16 v[60:63], v[146:149], v[162:165], v[60:63]
	v_mfma_f32_16x16x32_bf16 v[56:59], v[154:157], v[162:165], v[56:59]
	v_mfma_f32_16x16x32_bf16 v[52:55], v[146:149], v[170:173], v[52:55]
	v_mfma_f32_16x16x32_bf16 v[44:47], v[154:157], v[170:173], v[44:47]
	s_add_u32 s18, s18, 0x80080
	s_addc_u32 s19, s19, 0
	v_mfma_f32_16x16x32_bf16 v[36:39], v[146:149], v[178:181], v[36:39]
	s_add_i32 s20, s20, s28
	s_mov_b32 m0, s20
	v_mfma_f32_16x16x32_bf16 v[28:31], v[154:157], v[178:181], v[28:31]
	v_mfma_f32_16x16x32_bf16 v[20:23], v[146:149], v[186:189], v[20:23]
	v_mfma_f32_16x16x32_bf16 v[12:15], v[154:157], v[186:189], v[12:15]
	v_mfma_f32_16x16x32_bf16 v[60:63], v[150:153], v[166:169], v[60:63]
	v_mfma_f32_16x16x32_bf16 v[56:59], v[158:161], v[166:169], v[56:59]
	v_mfma_f32_16x16x32_bf16 v[52:55], v[150:153], v[174:177], v[52:55]
	v_mfma_f32_16x16x32_bf16 v[44:47], v[158:161], v[174:177], v[44:47]
	v_mfma_f32_16x16x32_bf16 v[36:39], v[150:153], v[182:185], v[36:39]
	v_mfma_f32_16x16x32_bf16 v[28:31], v[158:161], v[182:185], v[28:31]
	v_mfma_f32_16x16x32_bf16 v[20:23], v[150:153], v[204:207], v[20:23]
	v_mfma_f32_16x16x32_bf16 v[12:15], v[158:161], v[204:207], v[12:15]
	s_barrier
	global_load_lds_dwordx4 v192, s[18:19]
	s_add_i32 m0, s20, 0x2000
	s_nop 0
	global_load_lds_dwordx4 v128, s[18:19]
	s_waitcnt vmcnt(6)
	s_barrier
	v_mfma_f32_16x16x32_bf16 v[48:51], v[208:211], v[162:165], v[48:51]
	v_mfma_f32_16x16x32_bf16 v[40:43], v[218:221], v[162:165], v[40:43]
	v_mfma_f32_16x16x32_bf16 v[32:35], v[208:211], v[170:173], v[32:35]
	v_mfma_f32_16x16x32_bf16 v[24:27], v[218:221], v[170:173], v[24:27]
	s_add_i32 s42, s42, 2
	v_mfma_f32_16x16x32_bf16 v[16:19], v[208:211], v[178:181], v[16:19]
	s_add_u32 s16, s16, 0x100
	s_addc_u32 s17, s17, 0
	v_mfma_f32_16x16x32_bf16 v[8:11], v[218:221], v[178:181], v[8:11]
	s_add_u32 s40, s40, 0x100
	s_addc_u32 s41, s41, 0
	v_mfma_f32_16x16x32_bf16 v[4:7], v[208:211], v[186:189], v[4:7]
	s_add_u32 s18, s16, 0xfff80080
	s_addc_u32 s19, s17, -1
	v_mfma_f32_16x16x32_bf16 v[0:3], v[218:221], v[186:189], v[0:3]
	s_add_i32 s43, 0, 0x10000
	s_cmp_eq_u32 s42, 28
	v_mfma_f32_16x16x32_bf16 v[48:51], v[214:217], v[166:169], v[48:51]
	s_cselect_b32 s21, s9, s19
	s_cselect_b32 s20, s38, s18
	v_mfma_f32_16x16x32_bf16 v[40:43], v[222:225], v[166:169], v[40:43]
	s_cselect_b32 s19, s7, s41
	s_cselect_b32 s18, s39, s40
	v_mfma_f32_16x16x32_bf16 v[32:35], v[214:217], v[174:177], v[32:35]
	s_add_i32 m0, s30, 0xc000
	v_mfma_f32_16x16x32_bf16 v[24:27], v[222:225], v[174:177], v[24:27]
	v_mfma_f32_16x16x32_bf16 v[16:19], v[214:217], v[182:185], v[16:19]
	v_mfma_f32_16x16x32_bf16 v[8:11], v[222:225], v[182:185], v[8:11]
	v_mfma_f32_16x16x32_bf16 v[4:7], v[214:217], v[204:207], v[4:7]
	v_mfma_f32_16x16x32_bf16 v[0:3], v[222:225], v[204:207], v[0:3]
	s_cmp_gt_u32 s42, 29
	s_barrier
.LBB0_415:
	ds_read_b128 v[146:149], v196 offset:0
	ds_read_b128 v[150:153], v196 offset:1024
	ds_read_b128 v[154:157], v196 offset:2048
	ds_read_b128 v[158:161], v196 offset:3072
	ds_read_b128 v[162:165], v145
	ds_read_b128 v[166:169], v145 offset:1024
	ds_read_b128 v[170:173], v145 offset:2048
	ds_read_b128 v[174:177], v145 offset:3072
	ds_read_b128 v[178:181], v145 offset:4096
	ds_read_b128 v[182:185], v145 offset:5120
	ds_read_b128 v[186:189], v145 offset:6144
	ds_read_b128 v[204:207], v145 offset:7168
	global_load_lds_dwordx4 v136, s[16:17]
	s_add_i32 m0, s30, 0xe000
	s_nop 0
	global_load_lds_dwordx4 v138, s[16:17]
	s_waitcnt lgkmcnt(8)
	s_barrier
	s_waitcnt lgkmcnt(0)
	v_mfma_f32_16x16x32_bf16 v[124:127], v[146:149], v[162:165], v[124:127]
	v_mfma_f32_16x16x32_bf16 v[120:123], v[154:157], v[162:165], v[120:123]
	v_mfma_f32_16x16x32_bf16 v[116:119], v[146:149], v[170:173], v[116:119]
	v_mfma_f32_16x16x32_bf16 v[108:111], v[154:157], v[170:173], v[108:111]
	s_add_i32 s46, 0, 0x14000
	s_add_i32 s43, s43, s28
	v_mfma_f32_16x16x32_bf16 v[100:103], v[146:149], v[178:181], v[100:103]
	s_mov_b32 m0, s43
	v_mfma_f32_16x16x32_bf16 v[92:95], v[154:157], v[178:181], v[92:95]
	v_mfma_f32_16x16x32_bf16 v[84:87], v[146:149], v[186:189], v[84:87]
	v_mfma_f32_16x16x32_bf16 v[76:79], v[154:157], v[186:189], v[76:79]
	v_mfma_f32_16x16x32_bf16 v[124:127], v[150:153], v[166:169], v[124:127]
	v_mfma_f32_16x16x32_bf16 v[120:123], v[158:161], v[166:169], v[120:123]
	v_mfma_f32_16x16x32_bf16 v[116:119], v[150:153], v[174:177], v[116:119]
	v_mfma_f32_16x16x32_bf16 v[108:111], v[158:161], v[174:177], v[108:111]
	v_mfma_f32_16x16x32_bf16 v[100:103], v[150:153], v[182:185], v[100:103]
	v_mfma_f32_16x16x32_bf16 v[92:95], v[158:161], v[182:185], v[92:95]
	v_mfma_f32_16x16x32_bf16 v[84:87], v[150:153], v[204:207], v[84:87]
	v_mfma_f32_16x16x32_bf16 v[76:79], v[158:161], v[204:207], v[76:79]
	s_barrier
	ds_read_b128 v[208:211], v196 offset:16384
	ds_read_b128 v[214:217], v196 offset:17408
	ds_read_b128 v[218:221], v196 offset:18432
	ds_read_b128 v[222:225], v196 offset:19456
	global_load_lds_dwordx4 v192, s[18:19]
	s_add_i32 m0, s43, 0x2000
	s_nop 0
	global_load_lds_dwordx4 v128, s[18:19]
	s_barrier
	s_waitcnt lgkmcnt(0)
	v_mfma_f32_16x16x32_bf16 v[112:115], v[208:211], v[162:165], v[112:115]
	v_mfma_f32_16x16x32_bf16 v[104:107], v[218:221], v[162:165], v[104:107]
	v_mfma_f32_16x16x32_bf16 v[96:99], v[208:211], v[170:173], v[96:99]
	v_mfma_f32_16x16x32_bf16 v[88:91], v[218:221], v[170:173], v[88:91]
	s_mov_b32 m0, s30
	v_mfma_f32_16x16x32_bf16 v[80:83], v[208:211], v[178:181], v[80:83]
	s_add_u32 s48, s20, 0x80
	s_addc_u32 s49, s21, 0
	v_mfma_f32_16x16x32_bf16 v[72:75], v[218:221], v[178:181], v[72:75]
	v_mfma_f32_16x16x32_bf16 v[68:71], v[208:211], v[186:189], v[68:71]
	v_mfma_f32_16x16x32_bf16 v[64:67], v[218:221], v[186:189], v[64:67]
	v_mfma_f32_16x16x32_bf16 v[112:115], v[214:217], v[166:169], v[112:115]
	v_mfma_f32_16x16x32_bf16 v[104:107], v[222:225], v[166:169], v[104:107]
	v_mfma_f32_16x16x32_bf16 v[96:99], v[214:217], v[174:177], v[96:99]
	v_mfma_f32_16x16x32_bf16 v[88:91], v[222:225], v[174:177], v[88:91]
	v_mfma_f32_16x16x32_bf16 v[80:83], v[214:217], v[182:185], v[80:83]
	v_mfma_f32_16x16x32_bf16 v[72:75], v[222:225], v[182:185], v[72:75]
	v_mfma_f32_16x16x32_bf16 v[68:71], v[214:217], v[204:207], v[68:71]
	v_mfma_f32_16x16x32_bf16 v[64:67], v[222:225], v[204:207], v[64:67]
	s_barrier
	ds_read_b128 v[162:165], v145 offset:16384
	ds_read_b128 v[166:169], v145 offset:17408
	ds_read_b128 v[170:173], v145 offset:18432
	ds_read_b128 v[174:177], v145 offset:19456
	ds_read_b128 v[178:181], v145 offset:20480
	ds_read_b128 v[182:185], v145 offset:21504
	ds_read_b128 v[186:189], v145 offset:22528
	ds_read_b128 v[204:207], v145 offset:23552
	global_load_lds_dwordx4 v132, s[20:21]
	s_mov_b32 m0, s31
	s_nop 0
	global_load_lds_dwordx4 v130, s[20:21]
	s_barrier
	s_waitcnt lgkmcnt(0)
	v_mfma_f32_16x16x32_bf16 v[60:63], v[146:149], v[162:165], v[60:63]
	v_mfma_f32_16x16x32_bf16 v[56:59], v[154:157], v[162:165], v[56:59]
	v_mfma_f32_16x16x32_bf16 v[52:55], v[146:149], v[170:173], v[52:55]
	v_mfma_f32_16x16x32_bf16 v[44:47], v[154:157], v[170:173], v[44:47]
	s_add_u32 s44, s18, 0x80000
	s_addc_u32 s45, s19, 0
	v_mfma_f32_16x16x32_bf16 v[36:39], v[146:149], v[178:181], v[36:39]
	s_add_i32 s43, s46, s28
	s_mov_b32 m0, s43
	v_mfma_f32_16x16x32_bf16 v[28:31], v[154:157], v[178:181], v[28:31]
	v_mfma_f32_16x16x32_bf16 v[20:23], v[146:149], v[186:189], v[20:23]
	v_mfma_f32_16x16x32_bf16 v[12:15], v[154:157], v[186:189], v[12:15]
	v_mfma_f32_16x16x32_bf16 v[60:63], v[150:153], v[166:169], v[60:63]
	v_mfma_f32_16x16x32_bf16 v[56:59], v[158:161], v[166:169], v[56:59]
	v_mfma_f32_16x16x32_bf16 v[52:55], v[150:153], v[174:177], v[52:55]
	v_mfma_f32_16x16x32_bf16 v[44:47], v[158:161], v[174:177], v[44:47]
	v_mfma_f32_16x16x32_bf16 v[36:39], v[150:153], v[182:185], v[36:39]
	v_mfma_f32_16x16x32_bf16 v[28:31], v[158:161], v[182:185], v[28:31]
	v_mfma_f32_16x16x32_bf16 v[20:23], v[150:153], v[204:207], v[20:23]
	v_mfma_f32_16x16x32_bf16 v[12:15], v[158:161], v[204:207], v[12:15]
	s_barrier
	global_load_lds_dwordx4 v192, s[44:45]
	s_add_i32 m0, s43, 0x2000
	s_nop 0
	global_load_lds_dwordx4 v128, s[44:45]
	s_waitcnt vmcnt(6)
	s_barrier
	v_mfma_f32_16x16x32_bf16 v[48:51], v[208:211], v[162:165], v[48:51]
	v_mfma_f32_16x16x32_bf16 v[40:43], v[218:221], v[162:165], v[40:43]
	v_mfma_f32_16x16x32_bf16 v[32:35], v[208:211], v[170:173], v[32:35]
	v_mfma_f32_16x16x32_bf16 v[24:27], v[218:221], v[170:173], v[24:27]
	s_add_i32 s43, 0, 0x18000
	v_mfma_f32_16x16x32_bf16 v[16:19], v[208:211], v[178:181], v[16:19]
	s_add_u32 s20, s20, 0x80000
	s_addc_u32 s21, s21, 0
	v_mfma_f32_16x16x32_bf16 v[8:11], v[218:221], v[178:181], v[8:11]
	s_mov_b32 m0, s33
	v_mfma_f32_16x16x32_bf16 v[4:7], v[208:211], v[186:189], v[4:7]
	v_mfma_f32_16x16x32_bf16 v[0:3], v[218:221], v[186:189], v[0:3]
	v_mfma_f32_16x16x32_bf16 v[48:51], v[214:217], v[166:169], v[48:51]
	v_mfma_f32_16x16x32_bf16 v[40:43], v[222:225], v[166:169], v[40:43]
	v_mfma_f32_16x16x32_bf16 v[32:35], v[214:217], v[174:177], v[32:35]
	v_mfma_f32_16x16x32_bf16 v[24:27], v[222:225], v[174:177], v[24:27]
	v_mfma_f32_16x16x32_bf16 v[16:19], v[214:217], v[182:185], v[16:19]
	v_mfma_f32_16x16x32_bf16 v[8:11], v[222:225], v[182:185], v[8:11]
	v_mfma_f32_16x16x32_bf16 v[4:7], v[214:217], v[204:207], v[4:7]
	v_mfma_f32_16x16x32_bf16 v[0:3], v[222:225], v[204:207], v[0:3]
	s_barrier
	ds_read_b128 v[146:149], v196 offset:32768
	ds_read_b128 v[150:153], v196 offset:33792
	ds_read_b128 v[154:157], v196 offset:34816
	ds_read_b128 v[158:161], v196 offset:35840
	ds_read_b128 v[162:165], v145 offset:32768
	ds_read_b128 v[166:169], v145 offset:33792
	ds_read_b128 v[170:173], v145 offset:34816
	ds_read_b128 v[174:177], v145 offset:35840
	ds_read_b128 v[178:181], v145 offset:36864
	ds_read_b128 v[182:185], v145 offset:37888
	ds_read_b128 v[186:189], v145 offset:38912
	ds_read_b128 v[204:207], v145 offset:39936
	global_load_lds_dwordx4 v132, s[20:21]
	s_mov_b32 m0, s34
	s_nop 0
	global_load_lds_dwordx4 v130, s[20:21]
	s_waitcnt lgkmcnt(8)
	s_barrier
	s_waitcnt lgkmcnt(0)
	v_mfma_f32_16x16x32_bf16 v[124:127], v[146:149], v[162:165], v[124:127]
	v_mfma_f32_16x16x32_bf16 v[120:123], v[154:157], v[162:165], v[120:123]
	v_mfma_f32_16x16x32_bf16 v[116:119], v[146:149], v[170:173], v[116:119]
	v_mfma_f32_16x16x32_bf16 v[108:111], v[154:157], v[170:173], v[108:111]
	s_add_i32 s20, 0, 0x1c000
	s_add_i32 s21, s43, s28
	v_mfma_f32_16x16x32_bf16 v[100:103], v[146:149], v[178:181], v[100:103]
	s_add_i32 m0, s21, 0xffffff80
	v_mfma_f32_16x16x32_bf16 v[92:95], v[154:157], v[178:181], v[92:95]
	v_mfma_f32_16x16x32_bf16 v[84:87], v[146:149], v[186:189], v[84:87]
	v_mfma_f32_16x16x32_bf16 v[76:79], v[154:157], v[186:189], v[76:79]
	v_mfma_f32_16x16x32_bf16 v[124:127], v[150:153], v[166:169], v[124:127]
	v_mfma_f32_16x16x32_bf16 v[120:123], v[158:161], v[166:169], v[120:123]
	v_mfma_f32_16x16x32_bf16 v[116:119], v[150:153], v[174:177], v[116:119]
	v_mfma_f32_16x16x32_bf16 v[108:111], v[158:161], v[174:177], v[108:111]
	v_mfma_f32_16x16x32_bf16 v[100:103], v[150:153], v[182:185], v[100:103]
	v_mfma_f32_16x16x32_bf16 v[92:95], v[158:161], v[182:185], v[92:95]
	v_mfma_f32_16x16x32_bf16 v[84:87], v[150:153], v[204:207], v[84:87]
	v_mfma_f32_16x16x32_bf16 v[76:79], v[158:161], v[204:207], v[76:79]
	s_barrier
	ds_read_b128 v[208:211], v196 offset:49152
	ds_read_b128 v[214:217], v196 offset:50176
	ds_read_b128 v[218:221], v196 offset:51200
	ds_read_b128 v[222:225], v196 offset:52224
	global_load_lds_dwordx4 v192, s[18:19] offset:128
	s_add_i32 m0, s21, 0x1f80
	s_nop 0
	global_load_lds_dwordx4 v128, s[18:19] offset:128
	s_barrier
	s_waitcnt lgkmcnt(0)
	v_mfma_f32_16x16x32_bf16 v[112:115], v[208:211], v[162:165], v[112:115]
	v_mfma_f32_16x16x32_bf16 v[104:107], v[218:221], v[162:165], v[104:107]
	v_mfma_f32_16x16x32_bf16 v[96:99], v[208:211], v[170:173], v[96:99]
	v_mfma_f32_16x16x32_bf16 v[88:91], v[218:221], v[170:173], v[88:91]
	s_mov_b32 m0, s35
	v_mfma_f32_16x16x32_bf16 v[80:83], v[208:211], v[178:181], v[80:83]
	v_mfma_f32_16x16x32_bf16 v[72:75], v[218:221], v[178:181], v[72:75]
	v_mfma_f32_16x16x32_bf16 v[68:71], v[208:211], v[186:189], v[68:71]
	v_mfma_f32_16x16x32_bf16 v[64:67], v[218:221], v[186:189], v[64:67]
	v_mfma_f32_16x16x32_bf16 v[112:115], v[214:217], v[166:169], v[112:115]
	v_mfma_f32_16x16x32_bf16 v[104:107], v[222:225], v[166:169], v[104:107]
	v_mfma_f32_16x16x32_bf16 v[96:99], v[214:217], v[174:177], v[96:99]
	v_mfma_f32_16x16x32_bf16 v[88:91], v[222:225], v[174:177], v[88:91]
	v_mfma_f32_16x16x32_bf16 v[80:83], v[214:217], v[182:185], v[80:83]
	v_mfma_f32_16x16x32_bf16 v[72:75], v[222:225], v[182:185], v[72:75]
	v_mfma_f32_16x16x32_bf16 v[68:71], v[214:217], v[204:207], v[68:71]
	v_mfma_f32_16x16x32_bf16 v[64:67], v[222:225], v[204:207], v[64:67]
	s_barrier
	ds_read_b128 v[162:165], v145 offset:49152
	ds_read_b128 v[166:169], v145 offset:50176
	ds_read_b128 v[170:173], v145 offset:51200
	ds_read_b128 v[174:177], v145 offset:52224
	ds_read_b128 v[178:181], v145 offset:53248
	ds_read_b128 v[182:185], v145 offset:54272
	ds_read_b128 v[186:189], v145 offset:55296
	ds_read_b128 v[204:207], v145 offset:56320
	global_load_lds_dwordx4 v132, s[48:49]
	s_mov_b32 m0, s36
	s_nop 0
	global_load_lds_dwordx4 v130, s[48:49]
	s_barrier
	s_waitcnt lgkmcnt(0)
	v_mfma_f32_16x16x32_bf16 v[60:63], v[146:149], v[162:165], v[60:63]
	v_mfma_f32_16x16x32_bf16 v[56:59], v[154:157], v[162:165], v[56:59]
	v_mfma_f32_16x16x32_bf16 v[52:55], v[146:149], v[170:173], v[52:55]
	v_mfma_f32_16x16x32_bf16 v[44:47], v[154:157], v[170:173], v[44:47]
	s_add_u32 s18, s18, 0x80080
	s_addc_u32 s19, s19, 0
	v_mfma_f32_16x16x32_bf16 v[36:39], v[146:149], v[178:181], v[36:39]
	s_add_i32 s20, s20, s28
	s_mov_b32 m0, s20
	v_mfma_f32_16x16x32_bf16 v[28:31], v[154:157], v[178:181], v[28:31]
	v_mfma_f32_16x16x32_bf16 v[20:23], v[146:149], v[186:189], v[20:23]
	v_mfma_f32_16x16x32_bf16 v[12:15], v[154:157], v[186:189], v[12:15]
	v_mfma_f32_16x16x32_bf16 v[60:63], v[150:153], v[166:169], v[60:63]
	v_mfma_f32_16x16x32_bf16 v[56:59], v[158:161], v[166:169], v[56:59]
	v_mfma_f32_16x16x32_bf16 v[52:55], v[150:153], v[174:177], v[52:55]
	v_mfma_f32_16x16x32_bf16 v[44:47], v[158:161], v[174:177], v[44:47]
	v_mfma_f32_16x16x32_bf16 v[36:39], v[150:153], v[182:185], v[36:39]
	v_mfma_f32_16x16x32_bf16 v[28:31], v[158:161], v[182:185], v[28:31]
	v_mfma_f32_16x16x32_bf16 v[20:23], v[150:153], v[204:207], v[20:23]
	v_mfma_f32_16x16x32_bf16 v[12:15], v[158:161], v[204:207], v[12:15]
	s_barrier
	global_load_lds_dwordx4 v192, s[18:19]
	s_add_i32 m0, s20, 0x2000
	s_nop 0
	global_load_lds_dwordx4 v128, s[18:19]
	s_waitcnt vmcnt(6)
	s_barrier
	v_mfma_f32_16x16x32_bf16 v[48:51], v[208:211], v[162:165], v[48:51]
	v_mfma_f32_16x16x32_bf16 v[40:43], v[218:221], v[162:165], v[40:43]
	v_mfma_f32_16x16x32_bf16 v[32:35], v[208:211], v[170:173], v[32:35]
	v_mfma_f32_16x16x32_bf16 v[24:27], v[218:221], v[170:173], v[24:27]
	s_add_i32 s42, s42, 2
	v_mfma_f32_16x16x32_bf16 v[16:19], v[208:211], v[178:181], v[16:19]
	s_add_u32 s16, s16, 0x100
	s_addc_u32 s17, s17, 0
	v_mfma_f32_16x16x32_bf16 v[8:11], v[218:221], v[178:181], v[8:11]
	s_add_u32 s40, s40, 0x100
	s_addc_u32 s41, s41, 0
	v_mfma_f32_16x16x32_bf16 v[4:7], v[208:211], v[186:189], v[4:7]
	s_add_u32 s18, s16, 0xfff80080
	s_addc_u32 s19, s17, -1
	v_mfma_f32_16x16x32_bf16 v[0:3], v[218:221], v[186:189], v[0:3]
	s_add_i32 s43, 0, 0x10000
	s_cmp_eq_u32 s42, 28
	v_mfma_f32_16x16x32_bf16 v[48:51], v[214:217], v[166:169], v[48:51]
	s_cselect_b32 s21, s9, s19
	s_cselect_b32 s20, s38, s18
	v_mfma_f32_16x16x32_bf16 v[40:43], v[222:225], v[166:169], v[40:43]
	s_cselect_b32 s19, s7, s41
	s_cselect_b32 s18, s39, s40
	v_mfma_f32_16x16x32_bf16 v[32:35], v[214:217], v[174:177], v[32:35]
	s_add_i32 m0, s30, 0xc000
	v_mfma_f32_16x16x32_bf16 v[24:27], v[222:225], v[174:177], v[24:27]
	v_mfma_f32_16x16x32_bf16 v[16:19], v[214:217], v[182:185], v[16:19]
	v_mfma_f32_16x16x32_bf16 v[8:11], v[222:225], v[182:185], v[8:11]
	v_mfma_f32_16x16x32_bf16 v[4:7], v[214:217], v[204:207], v[4:7]
	v_mfma_f32_16x16x32_bf16 v[0:3], v[222:225], v[204:207], v[0:3]
	s_cmp_gt_u32 s42, 29
	s_barrier
	s_cbranch_scc0 .LBB0_415
	s_mul_hi_i32 s9, s15, 0x2aaaaaab
	v_lshl_add_u32 v153, s14, 8, v142
	s_lshr_b32 s14, s9, 31
	s_lshr_b32 s9, s9, 2
	s_add_i32 s9, s9, s14
	s_lshl_b32 s7, s15, 8
	s_mul_i32 s16, s9, 0x1800
	v_readlane_b32 s40, v254, 14
	v_readlane_b32 s41, v254, 15
	s_sub_i32 s40, s7, s16
	s_mov_b64 s[20:21], s[40:41]
	v_readlane_b32 s42, v254, 16
	v_readlane_b32 s43, v254, 17
	v_writelane_b32 v254, s20, 14
	s_mov_b64 s[14:15], -1
	s_cmpk_gt_i32 s40, 0xfff
	v_writelane_b32 v254, s21, 15
	v_writelane_b32 v254, s22, 16
	v_writelane_b32 v254, s23, 17
	v_or_b32_e32 v152, 16, v153
	v_or_b32_e32 v151, 32, v153
	v_or_b32_e32 v150, 48, v153
	v_add_u32_e32 v149, 0x80, v153
	v_add_u32_e32 v148, 0x90, v153
	v_add_u32_e32 v147, 0xa0, v153
	v_add_u32_e32 v146, 0xb0, v153
	s_cbranch_scc0 .LBB0_418
	v_mov_b32_e32 v156, v193
	v_mov_b32_e32 v157, v193
	s_ashr_i32 s17, s16, 31
	v_mov_b64_e32 v[140:141], s[2:3]
	s_mov_b32 s9, 0x9000
	v_cvt_pk_fp8_f32 v156, v124, v125
	v_cvt_pk_fp8_f32 v157, v120, v121
	s_lshl_b64 s[14:15], s[16:17], 1
	v_mad_i64_i32 v[154:155], s[16:17], v153, s9, v[140:141]
	s_add_u32 s14, s14, 0x2000
	v_readlane_b32 s16, v254, 14
	s_addc_u32 s15, s15, 0
	v_readlane_b32 s17, v254, 15
	v_lshl_add_u64 v[154:155], v[154:155], 0, s[14:15]
	s_mov_b64 s[20:21], s[16:17]
	v_cvt_pk_fp8_f32 v156, v126, v127 op_sel:[0,0,1]
	v_cvt_pk_fp8_f32 v157, v122, v123 op_sel:[0,0,1]
	v_lshl_add_u64 v[154:155], v[154:155], 0, s[20:21]
	v_lshl_add_u64 v[154:155], v[154:155], 0, s[4:5]
	v_lshl_add_u64 v[154:155], v[154:155], 0, v[134:135]
	global_store_dwordx2 v[154:155], v[156:157], off offset:-4096
	v_mov_b32_e32 v156, v193
	v_mov_b32_e32 v157, v193
	v_cvt_pk_fp8_f32 v156, v112, v113
	v_cvt_pk_fp8_f32 v157, v104, v105
	v_readlane_b32 s18, v254, 16
	v_readlane_b32 s19, v254, 17
	v_cvt_pk_fp8_f32 v156, v114, v115 op_sel:[0,0,1]
	v_cvt_pk_fp8_f32 v157, v106, v107 op_sel:[0,0,1]
	global_store_dwordx2 v[154:155], v[156:157], off offset:-3968
	v_mov_b32_e32 v156, v193
	v_mov_b32_e32 v157, v193
	v_cvt_pk_fp8_f32 v156, v116, v117
	v_cvt_pk_fp8_f32 v157, v108, v109
	v_mad_i64_i32 v[154:155], s[16:17], v152, s9, v[140:141]
	v_lshl_add_u64 v[154:155], v[154:155], 0, s[14:15]
	v_cvt_pk_fp8_f32 v156, v118, v119 op_sel:[0,0,1]
	v_cvt_pk_fp8_f32 v157, v110, v111 op_sel:[0,0,1]
	v_lshl_add_u64 v[154:155], v[154:155], 0, s[20:21]
	v_lshl_add_u64 v[154:155], v[154:155], 0, s[4:5]
	v_lshl_add_u64 v[154:155], v[154:155], 0, v[134:135]
	global_store_dwordx2 v[154:155], v[156:157], off offset:-4096
	v_mov_b32_e32 v156, v193
	v_mov_b32_e32 v157, v193
	v_cvt_pk_fp8_f32 v156, v96, v97
	v_cvt_pk_fp8_f32 v157, v88, v89
	v_cvt_pk_fp8_f32 v156, v98, v99 op_sel:[0,0,1]
	v_cvt_pk_fp8_f32 v157, v90, v91 op_sel:[0,0,1]
	global_store_dwordx2 v[154:155], v[156:157], off offset:-3968
	v_mov_b32_e32 v156, v193
	v_mov_b32_e32 v157, v193
	v_cvt_pk_fp8_f32 v156, v100, v101
	v_cvt_pk_fp8_f32 v157, v92, v93
	v_mad_i64_i32 v[154:155], s[16:17], v151, s9, v[140:141]
	v_lshl_add_u64 v[154:155], v[154:155], 0, s[14:15]
	v_cvt_pk_fp8_f32 v156, v102, v103 op_sel:[0,0,1]
	v_cvt_pk_fp8_f32 v157, v94, v95 op_sel:[0,0,1]
	v_lshl_add_u64 v[154:155], v[154:155], 0, s[20:21]
	v_lshl_add_u64 v[154:155], v[154:155], 0, s[4:5]
	v_lshl_add_u64 v[154:155], v[154:155], 0, v[134:135]
	global_store_dwordx2 v[154:155], v[156:157], off offset:-4096
	v_mov_b32_e32 v156, v193
	v_mov_b32_e32 v157, v193
	v_cvt_pk_fp8_f32 v156, v80, v81
	v_cvt_pk_fp8_f32 v157, v72, v73
	v_cvt_pk_fp8_f32 v156, v82, v83 op_sel:[0,0,1]
	v_cvt_pk_fp8_f32 v157, v74, v75 op_sel:[0,0,1]
	global_store_dwordx2 v[154:155], v[156:157], off offset:-3968
	v_mov_b32_e32 v156, v193
	v_mov_b32_e32 v157, v193
	v_cvt_pk_fp8_f32 v156, v84, v85
	v_cvt_pk_fp8_f32 v157, v76, v77
	v_mad_i64_i32 v[154:155], s[16:17], v150, s9, v[140:141]
	v_lshl_add_u64 v[154:155], v[154:155], 0, s[14:15]
	v_cvt_pk_fp8_f32 v156, v86, v87 op_sel:[0,0,1]
	v_cvt_pk_fp8_f32 v157, v78, v79 op_sel:[0,0,1]
	v_lshl_add_u64 v[154:155], v[154:155], 0, s[20:21]
	v_lshl_add_u64 v[154:155], v[154:155], 0, s[4:5]
	v_lshl_add_u64 v[154:155], v[154:155], 0, v[134:135]
	global_store_dwordx2 v[154:155], v[156:157], off offset:-4096
	v_mov_b32_e32 v156, v193
	v_mov_b32_e32 v157, v193
	v_cvt_pk_fp8_f32 v156, v68, v69
	v_cvt_pk_fp8_f32 v157, v64, v65
	v_cvt_pk_fp8_f32 v156, v70, v71 op_sel:[0,0,1]
	v_cvt_pk_fp8_f32 v157, v66, v67 op_sel:[0,0,1]
	global_store_dwordx2 v[154:155], v[156:157], off offset:-3968
	v_mov_b32_e32 v156, v193
	v_mov_b32_e32 v157, v193
	v_cvt_pk_fp8_f32 v156, v60, v61
	v_cvt_pk_fp8_f32 v157, v56, v57
	v_mad_i64_i32 v[154:155], s[16:17], v149, s9, v[140:141]
	v_lshl_add_u64 v[154:155], v[154:155], 0, s[14:15]
	v_cvt_pk_fp8_f32 v156, v62, v63 op_sel:[0,0,1]
	v_cvt_pk_fp8_f32 v157, v58, v59 op_sel:[0,0,1]
	v_lshl_add_u64 v[154:155], v[154:155], 0, s[20:21]
	v_lshl_add_u64 v[154:155], v[154:155], 0, s[4:5]
	v_lshl_add_u64 v[154:155], v[154:155], 0, v[134:135]
	global_store_dwordx2 v[154:155], v[156:157], off offset:-4096
	v_mov_b32_e32 v156, v193
	v_mov_b32_e32 v157, v193
	v_cvt_pk_fp8_f32 v156, v48, v49
	v_cvt_pk_fp8_f32 v157, v40, v41
	v_cvt_pk_fp8_f32 v156, v50, v51 op_sel:[0,0,1]
	v_cvt_pk_fp8_f32 v157, v42, v43 op_sel:[0,0,1]
	global_store_dwordx2 v[154:155], v[156:157], off offset:-3968
	v_mov_b32_e32 v156, v193
	v_mov_b32_e32 v157, v193
	v_cvt_pk_fp8_f32 v156, v52, v53
	v_cvt_pk_fp8_f32 v157, v44, v45
	v_mad_i64_i32 v[154:155], s[16:17], v148, s9, v[140:141]
	v_lshl_add_u64 v[154:155], v[154:155], 0, s[14:15]
	v_cvt_pk_fp8_f32 v156, v54, v55 op_sel:[0,0,1]
	v_cvt_pk_fp8_f32 v157, v46, v47 op_sel:[0,0,1]
	v_lshl_add_u64 v[154:155], v[154:155], 0, s[20:21]
	v_lshl_add_u64 v[154:155], v[154:155], 0, s[4:5]
	v_lshl_add_u64 v[154:155], v[154:155], 0, v[134:135]
	global_store_dwordx2 v[154:155], v[156:157], off offset:-4096
	v_mov_b32_e32 v156, v193
	v_mov_b32_e32 v157, v193
	v_cvt_pk_fp8_f32 v156, v32, v33
	v_cvt_pk_fp8_f32 v157, v24, v25
	v_cvt_pk_fp8_f32 v156, v34, v35 op_sel:[0,0,1]
	v_cvt_pk_fp8_f32 v157, v26, v27 op_sel:[0,0,1]
	global_store_dwordx2 v[154:155], v[156:157], off offset:-3968
	v_mov_b32_e32 v156, v193
	v_mov_b32_e32 v157, v193
	v_cvt_pk_fp8_f32 v156, v36, v37
	v_cvt_pk_fp8_f32 v157, v28, v29
	v_mad_i64_i32 v[154:155], s[16:17], v147, s9, v[140:141]
	v_lshl_add_u64 v[154:155], v[154:155], 0, s[14:15]
	v_cvt_pk_fp8_f32 v156, v38, v39 op_sel:[0,0,1]
	v_cvt_pk_fp8_f32 v157, v30, v31 op_sel:[0,0,1]
	v_lshl_add_u64 v[154:155], v[154:155], 0, s[20:21]
	v_lshl_add_u64 v[154:155], v[154:155], 0, s[4:5]
	v_lshl_add_u64 v[154:155], v[154:155], 0, v[134:135]
	global_store_dwordx2 v[154:155], v[156:157], off offset:-4096
	v_mov_b32_e32 v156, v193
	v_mov_b32_e32 v157, v193
	v_cvt_pk_fp8_f32 v156, v16, v17
	v_cvt_pk_fp8_f32 v157, v8, v9
	v_mad_i64_i32 v[140:141], s[16:17], v146, s9, v[140:141]
	v_cvt_pk_fp8_f32 v156, v18, v19 op_sel:[0,0,1]
	v_cvt_pk_fp8_f32 v157, v10, v11 op_sel:[0,0,1]
	v_lshl_add_u64 v[140:141], v[140:141], 0, s[14:15]
	v_lshl_add_u64 v[140:141], v[140:141], 0, s[20:21]
	v_lshl_add_u64 v[140:141], v[140:141], 0, s[4:5]
	global_store_dwordx2 v[154:155], v[156:157], off offset:-3968
	v_mov_b32_e32 v154, v193
	v_mov_b32_e32 v155, v193
	v_cvt_pk_fp8_f32 v154, v20, v21
	v_cvt_pk_fp8_f32 v155, v12, v13
	v_lshl_add_u64 v[140:141], v[140:141], 0, v[134:135]
	s_mov_b64 s[14:15], 0
	v_cvt_pk_fp8_f32 v154, v22, v23 op_sel:[0,0,1]
	v_cvt_pk_fp8_f32 v155, v14, v15 op_sel:[0,0,1]
	global_store_dwordx2 v[140:141], v[154:155], off offset:-4096
	v_mov_b32_e32 v154, v193
	v_mov_b32_e32 v155, v193
	v_cvt_pk_fp8_f32 v154, v4, v5
	v_cvt_pk_fp8_f32 v155, v0, v1
	v_cvt_pk_fp8_f32 v154, v6, v7 op_sel:[0,0,1]
	v_cvt_pk_fp8_f32 v155, v2, v3 op_sel:[0,0,1]
	global_store_dwordx2 v[140:141], v[154:155], off offset:-3968
